# v92 + GEMM loop place-holder s_nop removal
# speedup vs baseline: 1.0151x; 1.0046x over previous
.LBB0_94:
	s_ashr_i32 s0, s2, 31
	s_lshr_b32 s0, s0, 29
	s_add_i32 s0, s2, s0
	v_mov_b32_e32 v78, v133
	s_and_b32 s1, s0, 0x1fffff8
	s_lshl_b32 s0, s0, 5
	s_and_b32 s22, s0, 0xffffff00
	v_ashrrev_i32_e32 v6, 6, v78
	v_bfe_u32 v7, v78, 3, 3
	v_lshl_or_b32 v8, v6, 5, v7
	v_add_u32_e32 v0, s22, v8
	s_waitcnt lgkmcnt(0)
	v_ashrrev_i32_e32 v1, 31, v0
	v_lshlrev_b64 v[2:3], 11, v[0:1]
	v_bfe_u32 v1, v78, 4, 2
	v_readlane_b32 s20, v214, 4
	v_xor_b32_e32 v1, v1, v78
	v_readlane_b32 s21, v214, 5
	v_lshlrev_b32_e32 v1, 4, v1
	v_and_b32_e32 v64, 0x70, v1
	v_lshl_add_u64 v[2:3], s[20:21], 0, v[2:3]
	v_or_b32_e32 v1, 8, v8
	v_lshl_add_u64 v[66:67], v[2:3], 0, v[64:65]
	v_add_u32_e32 v2, s22, v1
	v_lshrrev_b32_e32 v1, 1, v1
	v_xor_b32_e32 v1, v1, v78
	v_ashrrev_i32_e32 v3, 31, v2
	v_lshlrev_b32_e32 v1, 4, v1
	v_or_b32_e32 v0, 16, v0
	v_lshlrev_b64 v[2:3], 11, v[2:3]
	v_and_b32_e32 v4, 0x70, v1
	v_ashrrev_i32_e32 v1, 31, v0
	v_lshl_add_u64 v[2:3], s[20:21], 0, v[2:3]
	v_mov_b32_e32 v5, v65
	v_lshlrev_b64 v[0:1], 11, v[0:1]
	v_lshl_add_u64 v[68:69], v[2:3], 0, v[4:5]
	v_lshl_add_u64 v[0:1], s[20:21], 0, v[0:1]
	v_or_b32_e32 v2, 24, v8
	v_lshl_add_u64 v[70:71], v[0:1], 0, v[64:65]
	v_add_u32_e32 v0, s22, v2
	v_lshrrev_b32_e32 v2, 1, v2
	v_ashrrev_i32_e32 v1, 31, v0
	v_xor_b32_e32 v2, v2, v78
	v_lshlrev_b64 v[0:1], 11, v[0:1]
	v_lshlrev_b32_e32 v2, 4, v2
	s_sub_i32 s1, s2, s1
	v_lshl_add_u64 v[0:1], s[20:21], 0, v[0:1]
	v_and_b32_e32 v2, 0x70, v2
	v_mov_b32_e32 v3, v65
	s_lshl_b32 s0, s1, 7
	v_lshl_add_u64 v[72:73], v[0:1], 0, v[2:3]
	v_lshl_or_b32 v2, v6, 4, v7
	v_add_u32_e32 v0, s0, v2
	v_lshlrev_b32_e32 v3, 12, v6
	v_ashrrev_i32_e32 v1, 31, v0
	v_add_u32_e32 v126, 0, v3
	v_lshlrev_b64 v[0:1], 11, v[0:1]
	s_waitcnt vmcnt(0)
	v_readfirstlane_b32 s38, v126
	v_add_u32_e32 v127, 0x400, v126
	v_lshl_add_u64 v[0:1], s[40:41], 0, v[0:1]
	v_or_b32_e32 v2, 8, v2
	s_waitcnt lgkmcnt(0)
	s_barrier
	s_mov_b32 m0, s38
	v_readfirstlane_b32 s39, v127
	v_add_u32_e32 v128, 0x800, v126
	v_lshlrev_b32_e32 v5, 11, v6
	v_and_b32_e32 v80, 1, v6
	v_lshl_add_u64 v[74:75], v[0:1], 0, v[64:65]
	v_add_u32_e32 v0, s0, v2
	v_lshrrev_b32_e32 v2, 1, v2
	global_load_lds_dwordx4 v[66:67], off
	s_mov_b32 m0, s39
	v_readfirstlane_b32 s48, v128
	v_add_u32_e32 v129, 0xc00, v126
	v_add_u32_e32 v6, 0, v5
	v_ashrrev_i32_e32 v1, 31, v0
	v_xor_b32_e32 v2, v2, v78
	global_load_lds_dwordx4 v[68:69], off
	s_mov_b32 m0, s48
	v_readfirstlane_b32 s49, v129
	v_add_u32_e32 v131, 0x8000, v6
	v_lshlrev_b64 v[0:1], 11, v[0:1]
	v_lshlrev_b32_e32 v2, 4, v2
	global_load_lds_dwordx4 v[70:71], off
	s_mov_b32 m0, s49
	v_readfirstlane_b32 s53, v131
	v_add_u32_e32 v130, 0x8400, v6
	v_lshl_add_u64 v[0:1], s[40:41], 0, v[0:1]
	v_and_b32_e32 v64, 0x70, v2
	global_load_lds_dwordx4 v[72:73], off
	s_mov_b32 m0, s53
	v_readfirstlane_b32 s54, v130
	v_add_u32_e32 v120, 0xc000, v126
	v_lshl_add_u64 v[76:77], v[0:1], 0, v[64:65]
	global_load_lds_dwordx4 v[74:75], off
	s_mov_b32 m0, s54
	s_mov_b64 s[20:21], 0x80
	v_readfirstlane_b32 s29, v120
	v_add_u32_e32 v121, 0xc400, v126
	global_load_lds_dwordx4 v[76:77], off
	v_lshl_add_u64 v[0:1], v[66:67], 0, s[20:21]
	s_mov_b32 m0, s29
	v_readfirstlane_b32 s33, v121
	v_add_u32_e32 v122, 0xc800, v126
	global_load_lds_dwordx4 v[0:1], off
	v_lshl_add_u64 v[0:1], v[68:69], 0, s[20:21]
	s_mov_b32 m0, s33
	v_readfirstlane_b32 s34, v122
	v_add_u32_e32 v123, 0xcc00, v126
	global_load_lds_dwordx4 v[0:1], off
	v_lshl_add_u64 v[0:1], v[70:71], 0, s[20:21]
	s_mov_b32 m0, s34
	v_readfirstlane_b32 s35, v123
	v_add_u32_e32 v124, s85, v5
	global_load_lds_dwordx4 v[0:1], off
	v_lshl_add_u64 v[0:1], v[72:73], 0, s[20:21]
	s_mov_b32 m0, s35
	v_readfirstlane_b32 s36, v124
	v_add_u32_e32 v125, 0x14400, v6
	global_load_lds_dwordx4 v[0:1], off
	v_lshl_add_u64 v[0:1], v[74:75], 0, s[20:21]
	s_mov_b32 m0, s36
	v_readfirstlane_b32 s37, v125
	global_load_lds_dwordx4 v[0:1], off
	v_lshl_add_u64 v[0:1], v[76:77], 0, s[20:21]
	s_mov_b32 m0, s37
	v_lshrrev_b32_e32 v2, 1, v78
	v_bfe_u32 v64, v78, 5, 1
	global_load_lds_dwordx4 v[0:1], off
	v_add_u32_e32 v114, s3, v3
	v_bitop3_b32 v0, v2, v64, 7 bitop3:0x6c
	s_waitcnt vmcnt(6)
	s_mov_b64 s[30:31], 0x100
	v_readfirstlane_b32 s1, v114
	v_add_u32_e32 v115, 0x400, v114
	v_lshlrev_b32_e32 v132, 4, v0
	s_waitcnt lgkmcnt(0)
	s_barrier
	v_lshl_add_u64 v[0:1], v[66:67], 0, s[30:31]
	s_mov_b32 m0, s1
	v_readfirstlane_b32 s20, v115
	v_add_u32_e32 v116, 0x800, v114
	global_load_lds_dwordx4 v[0:1], off
	v_lshl_add_u64 v[0:1], v[68:69], 0, s[30:31]
	s_mov_b32 m0, s20
	v_readfirstlane_b32 s21, v116
	v_add_u32_e32 v117, 0xc00, v114
	v_readlane_b32 s24, v212, 31
	v_and_b32_e32 v79, 31, v78
	global_load_lds_dwordx4 v[0:1], off
	v_lshl_add_u64 v[0:1], v[70:71], 0, s[30:31]
	s_mov_b32 m0, s21
	v_readfirstlane_b32 s23, v117
	v_add_u32_e32 v118, s24, v5
	v_add_u32_e32 v2, s3, v5
	v_lshlrev_b32_e32 v4, 7, v79
	global_load_lds_dwordx4 v[0:1], off
	v_lshl_add_u64 v[0:1], v[72:73], 0, s[30:31]
	s_mov_b32 m0, s23
	v_readfirstlane_b32 s24, v118
	v_add_u32_e32 v119, 0x8400, v2
	v_lshl_or_b32 v102, v80, 13, v4
	global_load_lds_dwordx4 v[0:1], off
	v_lshl_add_u64 v[0:1], v[74:75], 0, s[30:31]
	s_mov_b32 m0, s24
	v_readfirstlane_b32 s28, v119
	global_load_lds_dwordx4 v[0:1], off
	v_lshl_add_u64 v[0:1], v[76:77], 0, s[30:31]
	s_mov_b32 m0, s28
	v_add_u32_e32 v100, 0, v102
	global_load_lds_dwordx4 v[0:1], off
	v_add_u32_e32 v83, v100, v132
	v_ashrrev_i32_e32 v81, 7, v78
	ds_read_b128 a[0:3], v83 offset:32768
	ds_read_b128 a[4:7], v83 offset:36864
	v_lshl_or_b32 v134, v81, 13, v4
	v_add_u32_e32 v101, 0, v134
	v_add_u32_e32 v82, v101, v132
	ds_read_b128 a[8:11], v82
	ds_read_b128 a[12:15], v82 offset:4096
	v_lshrrev_b32_e32 v182, 6, v133
	s_nop 0
	v_readfirstlane_b32 s32, v182
	s_waitcnt lgkmcnt(1)
	v_mfma_f32_32x32x16_bf16 v[48:63], a[0:3], a[8:11], 0
	v_bfe_u32 v103, v78, 1, 3
	s_mov_b64 s[30:31], 0x180
	v_or_b32_e32 v143, 0x8000, v102
	v_or_b32_e32 v144, 0x9000, v102
	v_add_u32_e32 v145, s3, v134
	v_lshl_or_b32 v81, v81, 6, v79
	s_waitcnt vmcnt(12)
	v_mfma_f32_32x32x16_bf16 v[32:47], a[4:7], a[8:11], 0
	v_mul_lo_u32 v81, v81, s26
	s_mov_b64 s[80:81], 0x200
	s_waitcnt lgkmcnt(0)
	v_mfma_f32_32x32x16_bf16 v[16:31], a[0:3], a[12:15], 0
	v_bitop3_b32 v0, v64, v103, 2 bitop3:0x36
	v_lshlrev_b32_e32 v138, 4, v0
	v_add_u32_e32 v84, v101, v138
	ds_read_b128 a[28:31], v84 offset:4096
	ds_read_b128 a[24:27], v84
	v_add_u32_e32 v85, v100, v138
	ds_read_b128 a[20:23], v85 offset:36864
	ds_read_b128 a[16:19], v85 offset:32768
	v_mfma_f32_32x32x16_bf16 v[0:15], a[4:7], a[12:15], 0
	s_waitcnt lgkmcnt(0)
	v_mfma_f32_32x32x16_bf16 v[48:63], a[16:19], a[24:27], v[48:63]
	v_mfma_f32_32x32x16_bf16 v[32:47], a[20:23], a[24:27], v[32:47]
	v_mfma_f32_32x32x16_bf16 v[16:31], a[16:19], a[28:31], v[16:31]
	v_bitop3_b32 v86, v64, v103, 4 bitop3:0x36
	v_lshlrev_b32_e32 v139, 4, v86
	v_add_u32_e32 v86, v101, v139
	ds_read_b128 a[12:15], v86 offset:4096
	ds_read_b128 a[8:11], v86
	v_add_u32_e32 v87, v100, v139
	ds_read_b128 a[4:7], v87 offset:36864
	ds_read_b128 a[0:3], v87 offset:32768
	v_mfma_f32_32x32x16_bf16 v[0:15], a[20:23], a[28:31], v[0:15]
	s_waitcnt lgkmcnt(0)
	v_mfma_f32_32x32x16_bf16 v[48:63], a[0:3], a[8:11], v[48:63]
	v_mfma_f32_32x32x16_bf16 v[32:47], a[4:7], a[8:11], v[32:47]
	v_mfma_f32_32x32x16_bf16 v[16:31], a[0:3], a[12:15], v[16:31]
	v_bitop3_b32 v88, v64, v103, 6 bitop3:0x36
	v_lshlrev_b32_e32 v142, 4, v88
	v_add_u32_e32 v88, v101, v142
	ds_read_b128 a[28:31], v88 offset:4096
	ds_read_b128 a[24:27], v88
	v_add_u32_e32 v89, v100, v142
	ds_read_b128 a[20:23], v89 offset:36864
	ds_read_b128 a[16:19], v89 offset:32768
	v_lshlrev_b32_e32 v64, 4, v64
	v_lshl_or_b32 v64, v80, 8, v64
	v_add3_u32 v64, 0, v81, v64
	v_mfma_f32_32x32x16_bf16 v[0:15], a[4:7], a[12:15], v[0:15]
	s_waitcnt lgkmcnt(0)
	v_mfma_f32_32x32x16_bf16 v[48:63], a[16:19], a[24:27], v[48:63]
	v_mfma_f32_32x32x16_bf16 v[32:47], a[20:23], a[24:27], v[32:47]
	s_waitcnt vmcnt(6)
	s_waitcnt lgkmcnt(0)
	s_barrier
	ds_read_b128 a[12:15], v82 offset:53248
	ds_read_b128 a[8:11], v82 offset:49152
	v_mfma_f32_32x32x16_bf16 v[16:31], a[16:19], a[28:31], v[16:31]
	v_lshl_add_u64 v[158:159], v[66:67], 0, s[30:31]
	v_lshl_add_u64 v[160:161], v[68:69], 0, s[30:31]
	v_lshl_add_u64 v[162:163], v[70:71], 0, s[30:31]
	v_mfma_f32_32x32x16_bf16 v[0:15], a[20:23], a[28:31], v[0:15]
	s_and_b32 m0, s32, 7
	s_lshl_b32 m0, m0, 12
	s_add_i32 m0, m0, 0x0
	s_nop 0
	global_load_lds_dwordx4 v[158:159], off
	v_lshl_add_u64 v[164:165], v[72:73], 0, s[30:31]
	v_lshl_add_u64 v[166:167], v[74:75], 0, s[30:31]
	v_lshl_add_u64 v[168:169], v[76:77], 0, s[30:31]
	s_add_i32 s30, 0, 0xc000
	v_add_u32_e32 v90, s30, v132
	v_add_u32_e32 v92, v90, v143
	v_add_u32_e32 v90, v90, v144
	ds_read_b128 a[4:7], v90
	ds_read_b128 a[0:3], v92
	v_add_u32_e32 v91, s30, v138
	v_add_u32_e32 v93, v91, v143
	ds_read_b128 a[16:19], v93
	v_add_u32_e32 v91, v91, v144
	ds_read_b128 a[20:23], v91
	ds_read_b128 a[24:27], v84 offset:49152
	ds_read_b128 a[28:31], v84 offset:53248
	s_waitcnt lgkmcnt(4)
	v_mfma_f32_32x32x16_bf16 v[48:63], a[0:3], a[8:11], v[48:63]
	v_mfma_f32_32x32x16_bf16 v[32:47], a[4:7], a[8:11], v[32:47]
	v_mfma_f32_32x32x16_bf16 v[16:31], a[0:3], a[12:15], v[16:31]
	s_and_b32 m0, s32, 7
	s_lshl_b32 m0, m0, 12
	s_add_i32 m0, m0, 0x400
	s_nop 0
	global_load_lds_dwordx4 v[160:161], off
	v_mfma_f32_32x32x16_bf16 v[0:15], a[4:7], a[12:15], v[0:15]
	v_add_u32_e32 v94, s30, v139
	v_add_u32_e32 v95, v94, v143
	ds_read_b128 a[0:3], v95
	v_add_u32_e32 v94, v94, v144
	ds_read_b128 a[4:7], v94
	ds_read_b128 a[8:11], v86 offset:49152
	ds_read_b128 a[12:15], v86 offset:53248
	s_waitcnt lgkmcnt(5)
	v_mfma_f32_32x32x16_bf16 v[48:63], a[16:19], a[24:27], v[48:63]
	v_mfma_f32_32x32x16_bf16 v[32:47], a[20:23], a[24:27], v[32:47]
	s_and_b32 m0, s32, 7
	s_lshl_b32 m0, m0, 12
	s_add_i32 m0, m0, 0x800
	s_nop 0
	global_load_lds_dwordx4 v[162:163], off
	s_waitcnt lgkmcnt(4)
	v_mfma_f32_32x32x16_bf16 v[16:31], a[16:19], a[28:31], v[16:31]
	v_mfma_f32_32x32x16_bf16 v[0:15], a[20:23], a[28:31], v[0:15]
	v_add_u32_e32 v96, s30, v142
	v_add_u32_e32 v97, v96, v143
	ds_read_b128 a[16:19], v97
	v_add_u32_e32 v96, v96, v144
	ds_read_b128 a[20:23], v96
	ds_read_b128 a[24:27], v88 offset:49152
	ds_read_b128 a[28:31], v88 offset:53248
	s_waitcnt lgkmcnt(5)
	v_mfma_f32_32x32x16_bf16 v[48:63], a[0:3], a[8:11], v[48:63]
	s_and_b32 m0, s32, 7
	s_lshl_b32 m0, m0, 12
	s_add_i32 m0, m0, 0xc00
	s_nop 0
	global_load_lds_dwordx4 v[164:165], off
	v_mfma_f32_32x32x16_bf16 v[32:47], a[4:7], a[8:11], v[32:47]
	s_waitcnt lgkmcnt(4)
	v_mfma_f32_32x32x16_bf16 v[16:31], a[0:3], a[12:15], v[16:31]
	s_mov_b64 s[30:31], 0x200
	v_mfma_f32_32x32x16_bf16 v[0:15], a[4:7], a[12:15], v[0:15]
	s_and_b32 m0, s32, 7
	s_lshl_b32 m0, m0, 11
	s_add_i32 m0, m0, 0x8000
	s_nop 0
	global_load_lds_dwordx4 v[166:167], off
	s_waitcnt lgkmcnt(1)
	v_mfma_f32_32x32x16_bf16 v[48:63], a[16:19], a[24:27], v[48:63]
	v_mfma_f32_32x32x16_bf16 v[32:47], a[20:23], a[24:27], v[32:47]
	s_and_b32 m0, s32, 7
	s_lshl_b32 m0, m0, 11
	s_add_i32 m0, m0, 0x8400
	s_nop 0
	global_load_lds_dwordx4 v[168:169], off
	s_waitcnt vmcnt(6)
	s_waitcnt lgkmcnt(0)
	s_barrier
	v_add_u32_e32 v100, v145, v132
	ds_read_b128 a[8:11], v100
	v_add_u32_e32 v101, s3, v132
	v_add_u32_e32 v99, v101, v144
	ds_read_b128 a[4:7], v99
	v_add_u32_e32 v98, v101, v143
	v_or_b32_e32 v132, 0x1000, v134
	v_add_u32_e32 v101, v101, v132
	ds_read_b128 a[12:15], v101
	ds_read_b128 a[0:3], v98
	v_mfma_f32_32x32x16_bf16 v[16:31], a[16:19], a[28:31], v[16:31]
	v_lshl_add_u64 v[170:171], v[66:67], 0, s[30:31]
	v_lshl_add_u64 v[172:173], v[68:69], 0, s[30:31]
	v_lshl_add_u64 v[174:175], v[70:71], 0, s[30:31]
	v_mfma_f32_32x32x16_bf16 v[0:15], a[20:23], a[28:31], v[0:15]
	s_and_b32 m0, s32, 7
	s_lshl_b32 m0, m0, 12
	s_add_i32 m0, m0, 0xc000
	s_nop 0
	global_load_lds_dwordx4 v[170:171], off
	v_lshl_add_u64 v[176:177], v[72:73], 0, s[30:31]
	v_lshl_add_u64 v[178:179], v[74:75], 0, s[30:31]
	v_lshl_add_u64 v[180:181], v[76:77], 0, s[30:31]
	s_mov_b64 s[30:31], 0x280
	v_add_u32_e32 v105, s3, v138
	v_add_u32_e32 v102, v105, v143
	ds_read_b128 a[16:19], v102
	v_add_u32_e32 v103, v105, v144
	ds_read_b128 a[20:23], v103
	v_add_u32_e32 v104, v145, v138
	ds_read_b128 a[24:27], v104
	v_add_u32_e32 v105, v105, v132
	ds_read_b128 a[28:31], v105
	s_waitcnt lgkmcnt(4)
	v_mfma_f32_32x32x16_bf16 v[48:63], a[0:3], a[8:11], v[48:63]
	v_mfma_f32_32x32x16_bf16 v[32:47], a[4:7], a[8:11], v[32:47]
	v_mfma_f32_32x32x16_bf16 v[16:31], a[0:3], a[12:15], v[16:31]
	s_and_b32 m0, s32, 7
	s_lshl_b32 m0, m0, 12
	s_add_i32 m0, m0, 0xc400
	s_nop 0
	global_load_lds_dwordx4 v[172:173], off
	v_mfma_f32_32x32x16_bf16 v[0:15], a[4:7], a[12:15], v[0:15]
	v_add_u32_e32 v109, s3, v139
	v_add_u32_e32 v106, v109, v143
	ds_read_b128 a[0:3], v106
	v_add_u32_e32 v107, v109, v144
	ds_read_b128 a[4:7], v107
	v_add_u32_e32 v108, v145, v139
	ds_read_b128 a[8:11], v108
	v_add_u32_e32 v109, v109, v132
	ds_read_b128 a[12:15], v109
	s_waitcnt lgkmcnt(5)
	v_mfma_f32_32x32x16_bf16 v[48:63], a[16:19], a[24:27], v[48:63]
	v_mfma_f32_32x32x16_bf16 v[32:47], a[20:23], a[24:27], v[32:47]
	s_and_b32 m0, s32, 7
	s_lshl_b32 m0, m0, 12
	s_add_i32 m0, m0, 0xc800
	s_nop 0
	global_load_lds_dwordx4 v[174:175], off
	s_waitcnt lgkmcnt(4)
	v_mfma_f32_32x32x16_bf16 v[16:31], a[16:19], a[28:31], v[16:31]
	v_mfma_f32_32x32x16_bf16 v[0:15], a[20:23], a[28:31], v[0:15]
	v_add_u32_e32 v113, s3, v142
	v_add_u32_e32 v110, v113, v143
	ds_read_b128 a[16:19], v110
	v_add_u32_e32 v111, v113, v144
	ds_read_b128 a[20:23], v111
	v_add_u32_e32 v112, v145, v142
	ds_read_b128 a[24:27], v112
	v_add_u32_e32 v113, v113, v132
	ds_read_b128 a[28:31], v113
	s_waitcnt lgkmcnt(5)
	v_mfma_f32_32x32x16_bf16 v[48:63], a[0:3], a[8:11], v[48:63]
	s_and_b32 m0, s32, 7
	s_lshl_b32 m0, m0, 12
	s_add_i32 m0, m0, 0xcc00
	s_nop 0
	global_load_lds_dwordx4 v[176:177], off
	v_mfma_f32_32x32x16_bf16 v[32:47], a[4:7], a[8:11], v[32:47]
	s_waitcnt lgkmcnt(4)
	v_mfma_f32_32x32x16_bf16 v[16:31], a[0:3], a[12:15], v[16:31]
	v_mfma_f32_32x32x16_bf16 v[0:15], a[4:7], a[12:15], v[0:15]
	s_and_b32 m0, s32, 7
	s_lshl_b32 m0, m0, 11
	s_add_i32 m0, m0, 0x14000
	s_nop 0
	global_load_lds_dwordx4 v[178:179], off
	s_waitcnt lgkmcnt(1)
	v_mfma_f32_32x32x16_bf16 v[48:63], a[16:19], a[24:27], v[48:63]
	v_mfma_f32_32x32x16_bf16 v[32:47], a[20:23], a[24:27], v[32:47]
	s_and_b32 m0, s32, 7
	s_lshl_b32 m0, m0, 11
	s_add_i32 m0, m0, 0x14400
	s_nop 0
	global_load_lds_dwordx4 v[180:181], off
	s_waitcnt vmcnt(6)
	s_waitcnt lgkmcnt(0)
	s_barrier
	ds_read_b128 a[12:15], v82 offset:4096
	ds_read_b128 a[8:11], v82
	ds_read_b128 a[4:7], v83 offset:36864
	ds_read_b128 a[0:3], v83 offset:32768
	v_mfma_f32_32x32x16_bf16 v[16:31], a[16:19], a[28:31], v[16:31]
	v_lshl_add_u64 v[158:159], v[66:67], 0, s[30:31]
	v_lshl_add_u64 v[160:161], v[68:69], 0, s[30:31]
	v_lshl_add_u64 v[162:163], v[70:71], 0, s[30:31]
	v_mfma_f32_32x32x16_bf16 v[0:15], a[20:23], a[28:31], v[0:15]
	s_and_b32 m0, s32, 7
	s_lshl_b32 m0, m0, 12
	s_add_i32 m0, m0, 0x18000
	s_nop 0
	global_load_lds_dwordx4 v[158:159], off
	v_lshl_add_u64 v[164:165], v[72:73], 0, s[30:31]
	v_lshl_add_u64 v[166:167], v[74:75], 0, s[30:31]
	v_lshl_add_u64 v[168:169], v[76:77], 0, s[30:31]
	s_mov_b64 s[30:31], 0x300
	ds_read_b128 a[16:19], v85 offset:32768
	ds_read_b128 a[20:23], v85 offset:36864
	ds_read_b128 a[24:27], v84
	ds_read_b128 a[28:31], v84 offset:4096
	s_waitcnt lgkmcnt(4)
	v_mfma_f32_32x32x16_bf16 v[48:63], a[0:3], a[8:11], v[48:63]
	s_nop 0
	v_readfirstlane_b32 s38, v114
	v_mfma_f32_32x32x16_bf16 v[32:47], a[4:7], a[8:11], v[32:47]
	v_mfma_f32_32x32x16_bf16 v[16:31], a[0:3], a[12:15], v[16:31]
	s_and_b32 m0, s32, 7
	s_lshl_b32 m0, m0, 12
	s_add_i32 m0, m0, 0x18400
	s_nop 0
	global_load_lds_dwordx4 v[160:161], off
	v_mfma_f32_32x32x16_bf16 v[0:15], a[4:7], a[12:15], v[0:15]
	ds_read_b128 a[0:3], v87 offset:32768
	ds_read_b128 a[4:7], v87 offset:36864
	ds_read_b128 a[8:11], v86
	ds_read_b128 a[12:15], v86 offset:4096
	s_waitcnt lgkmcnt(5)
	v_mfma_f32_32x32x16_bf16 v[48:63], a[16:19], a[24:27], v[48:63]
	v_mfma_f32_32x32x16_bf16 v[32:47], a[20:23], a[24:27], v[32:47]
	s_and_b32 m0, s32, 7
	s_lshl_b32 m0, m0, 12
	s_add_i32 m0, m0, 0x18800
	s_nop 0
	global_load_lds_dwordx4 v[162:163], off
	s_waitcnt lgkmcnt(4)
	v_mfma_f32_32x32x16_bf16 v[16:31], a[16:19], a[28:31], v[16:31]
	v_mfma_f32_32x32x16_bf16 v[0:15], a[20:23], a[28:31], v[0:15]
	ds_read_b128 a[16:19], v89 offset:32768
	ds_read_b128 a[20:23], v89 offset:36864
	ds_read_b128 a[24:27], v88
	ds_read_b128 a[28:31], v88 offset:4096
	s_waitcnt lgkmcnt(5)
	v_mfma_f32_32x32x16_bf16 v[48:63], a[0:3], a[8:11], v[48:63]
	s_and_b32 m0, s32, 7
	s_lshl_b32 m0, m0, 12
	s_add_i32 m0, m0, 0x18c00
	s_nop 0
	global_load_lds_dwordx4 v[164:165], off
	v_mfma_f32_32x32x16_bf16 v[32:47], a[4:7], a[8:11], v[32:47]
	s_waitcnt lgkmcnt(4)
	v_mfma_f32_32x32x16_bf16 v[16:31], a[0:3], a[12:15], v[16:31]
	v_mfma_f32_32x32x16_bf16 v[0:15], a[4:7], a[12:15], v[0:15]
	s_and_b32 m0, s32, 7
	s_lshl_b32 m0, m0, 11
	s_add_i32 m0, m0, 0x20000
	s_nop 0
	global_load_lds_dwordx4 v[166:167], off
	s_waitcnt lgkmcnt(1)
	v_mfma_f32_32x32x16_bf16 v[48:63], a[16:19], a[24:27], v[48:63]
	v_mfma_f32_32x32x16_bf16 v[32:47], a[20:23], a[24:27], v[32:47]
	s_and_b32 m0, s32, 7
	s_lshl_b32 m0, m0, 11
	s_add_i32 m0, m0, 0x20400
	s_nop 0
	global_load_lds_dwordx4 v[168:169], off
	s_waitcnt vmcnt(6)
	s_waitcnt lgkmcnt(0)
	s_barrier
	ds_read_b128 a[12:15], v82 offset:53248
	ds_read_b128 a[8:11], v82 offset:49152
	ds_read_b128 a[4:7], v90
	ds_read_b128 a[0:3], v92
	v_mfma_f32_32x32x16_bf16 v[16:31], a[16:19], a[28:31], v[16:31]
	v_lshl_add_u64 v[170:171], v[66:67], 0, s[30:31]
	v_lshl_add_u64 v[172:173], v[68:69], 0, s[30:31]
	s_nop 0
	v_readfirstlane_b32 s39, v115
	s_nop 0
	v_lshl_add_u64 v[174:175], v[70:71], 0, s[30:31]
	s_nop 0
	v_mfma_f32_32x32x16_bf16 v[0:15], a[20:23], a[28:31], v[0:15]
	s_and_b32 m0, s32, 7
	s_lshl_b32 m0, m0, 12
	s_add_i32 m0, m0, 0x0
	s_nop 0
	global_load_lds_dwordx4 v[170:171], off
	v_lshl_add_u64 v[176:177], v[72:73], 0, s[30:31]
	s_nop 0
	v_readfirstlane_b32 s48, v116
	s_nop 0
	v_lshl_add_u64 v[178:179], v[74:75], 0, s[30:31]
	s_nop 0
	v_readfirstlane_b32 s49, v117
	s_nop 0
	v_lshl_add_u64 v[180:181], v[76:77], 0, s[30:31]
	s_nop 0
	s_mov_b64 s[30:31], 0x380
	ds_read_b128 a[16:19], v93
	ds_read_b128 a[20:23], v91
	ds_read_b128 a[24:27], v84 offset:49152
	ds_read_b128 a[28:31], v84 offset:53248
	s_waitcnt lgkmcnt(4)
	v_mfma_f32_32x32x16_bf16 v[48:63], a[0:3], a[8:11], v[48:63]
	s_nop 0
	v_readfirstlane_b32 s53, v118
	v_readfirstlane_b32 s54, v119
	v_mfma_f32_32x32x16_bf16 v[32:47], a[4:7], a[8:11], v[32:47]
	v_mfma_f32_32x32x16_bf16 v[16:31], a[0:3], a[12:15], v[16:31]
	s_and_b32 m0, s32, 7
	s_lshl_b32 m0, m0, 12
	s_add_i32 m0, m0, 0x400
	s_nop 0
	global_load_lds_dwordx4 v[172:173], off
	v_mfma_f32_32x32x16_bf16 v[0:15], a[4:7], a[12:15], v[0:15]
	ds_read_b128 a[0:3], v95
	ds_read_b128 a[4:7], v94
	ds_read_b128 a[8:11], v86 offset:49152
	ds_read_b128 a[12:15], v86 offset:53248
	s_waitcnt lgkmcnt(5)
	v_mfma_f32_32x32x16_bf16 v[48:63], a[16:19], a[24:27], v[48:63]
	v_mfma_f32_32x32x16_bf16 v[32:47], a[20:23], a[24:27], v[32:47]
	s_and_b32 m0, s32, 7
	s_lshl_b32 m0, m0, 12
	s_add_i32 m0, m0, 0x800
	s_nop 0
	global_load_lds_dwordx4 v[174:175], off
	s_waitcnt lgkmcnt(4)
	v_mfma_f32_32x32x16_bf16 v[16:31], a[16:19], a[28:31], v[16:31]
	v_mfma_f32_32x32x16_bf16 v[0:15], a[20:23], a[28:31], v[0:15]
	ds_read_b128 a[16:19], v97
	ds_read_b128 a[20:23], v96
	ds_read_b128 a[24:27], v88 offset:49152
	ds_read_b128 a[28:31], v88 offset:53248
	s_waitcnt lgkmcnt(5)
	v_mfma_f32_32x32x16_bf16 v[48:63], a[0:3], a[8:11], v[48:63]
	s_and_b32 m0, s32, 7
	s_lshl_b32 m0, m0, 12
	s_add_i32 m0, m0, 0xc00
	s_nop 0
	global_load_lds_dwordx4 v[176:177], off
	v_mfma_f32_32x32x16_bf16 v[32:47], a[4:7], a[8:11], v[32:47]
	s_waitcnt lgkmcnt(4)
	v_mfma_f32_32x32x16_bf16 v[16:31], a[0:3], a[12:15], v[16:31]
	v_mfma_f32_32x32x16_bf16 v[0:15], a[4:7], a[12:15], v[0:15]
	s_and_b32 m0, s32, 7
	s_lshl_b32 m0, m0, 11
	s_add_i32 m0, m0, 0x8000
	s_nop 0
	global_load_lds_dwordx4 v[178:179], off
	s_waitcnt lgkmcnt(1)
	v_mfma_f32_32x32x16_bf16 v[48:63], a[16:19], a[24:27], v[48:63]
	v_mfma_f32_32x32x16_bf16 v[32:47], a[20:23], a[24:27], v[32:47]
	s_and_b32 m0, s32, 7
	s_lshl_b32 m0, m0, 11
	s_add_i32 m0, m0, 0x8400
	s_nop 0
	global_load_lds_dwordx4 v[180:181], off
	s_waitcnt vmcnt(6)
	s_waitcnt lgkmcnt(0)
	s_barrier
	ds_read_b128 a[12:15], v101
	ds_read_b128 a[8:11], v100
	ds_read_b128 a[4:7], v99
	ds_read_b128 a[0:3], v98
	v_mfma_f32_32x32x16_bf16 v[16:31], a[16:19], a[28:31], v[16:31]
	v_lshl_add_u64 v[158:159], v[66:67], 0, s[30:31]
	v_lshl_add_u64 v[160:161], v[68:69], 0, s[30:31]
	s_nop 0
	v_readfirstlane_b32 s33, v121
	s_nop 0
	v_lshl_add_u64 v[162:163], v[70:71], 0, s[30:31]
	s_nop 0
	v_mfma_f32_32x32x16_bf16 v[0:15], a[20:23], a[28:31], v[0:15]
	s_and_b32 m0, s32, 7
	s_lshl_b32 m0, m0, 12
	s_add_i32 m0, m0, 0xc000
	s_nop 0
	global_load_lds_dwordx4 v[158:159], off
	v_lshl_add_u64 v[164:165], v[72:73], 0, s[30:31]
	s_nop 0
	v_readfirstlane_b32 s34, v122
	s_nop 0
	v_lshl_add_u64 v[166:167], v[74:75], 0, s[30:31]
	s_nop 0
	v_readfirstlane_b32 s35, v123
	s_nop 0
	v_lshl_add_u64 v[168:169], v[76:77], 0, s[30:31]
	s_nop 0
	s_mov_b64 s[30:31], 0x400
	ds_read_b128 a[16:19], v102
	ds_read_b128 a[20:23], v103
	ds_read_b128 a[24:27], v104
	ds_read_b128 a[28:31], v105
	s_waitcnt lgkmcnt(4)
	v_mfma_f32_32x32x16_bf16 v[48:63], a[0:3], a[8:11], v[48:63]
	s_nop 0
	v_readfirstlane_b32 s1, v126
	v_readfirstlane_b32 s36, v124
	v_readfirstlane_b32 s37, v125
	v_mfma_f32_32x32x16_bf16 v[32:47], a[4:7], a[8:11], v[32:47]
	v_mfma_f32_32x32x16_bf16 v[16:31], a[0:3], a[12:15], v[16:31]
	s_and_b32 m0, s32, 7
	s_lshl_b32 m0, m0, 12
	s_add_i32 m0, m0, 0xc400
	s_nop 0
	global_load_lds_dwordx4 v[160:161], off
	v_mfma_f32_32x32x16_bf16 v[0:15], a[4:7], a[12:15], v[0:15]
	ds_read_b128 a[0:3], v106
	ds_read_b128 a[4:7], v107
	ds_read_b128 a[8:11], v108
	ds_read_b128 a[12:15], v109
	s_waitcnt lgkmcnt(5)
	v_mfma_f32_32x32x16_bf16 v[48:63], a[16:19], a[24:27], v[48:63]
	v_mfma_f32_32x32x16_bf16 v[32:47], a[20:23], a[24:27], v[32:47]
	s_and_b32 m0, s32, 7
	s_lshl_b32 m0, m0, 12
	s_add_i32 m0, m0, 0xc800
	s_nop 0
	global_load_lds_dwordx4 v[162:163], off
	s_waitcnt lgkmcnt(4)
	v_mfma_f32_32x32x16_bf16 v[16:31], a[16:19], a[28:31], v[16:31]
	v_mfma_f32_32x32x16_bf16 v[0:15], a[20:23], a[28:31], v[0:15]
	ds_read_b128 a[16:19], v110
	ds_read_b128 a[20:23], v111
	ds_read_b128 a[24:27], v112
	ds_read_b128 a[28:31], v113
	s_waitcnt lgkmcnt(5)
	v_mfma_f32_32x32x16_bf16 v[48:63], a[0:3], a[8:11], v[48:63]
	s_and_b32 m0, s32, 7
	s_lshl_b32 m0, m0, 12
	s_add_i32 m0, m0, 0xcc00
	s_nop 0
	global_load_lds_dwordx4 v[164:165], off
	v_mfma_f32_32x32x16_bf16 v[32:47], a[4:7], a[8:11], v[32:47]
	s_waitcnt lgkmcnt(4)
	v_mfma_f32_32x32x16_bf16 v[16:31], a[0:3], a[12:15], v[16:31]
	v_mfma_f32_32x32x16_bf16 v[0:15], a[4:7], a[12:15], v[0:15]
	s_and_b32 m0, s32, 7
	s_lshl_b32 m0, m0, 11
	s_add_i32 m0, m0, 0x14000
	s_nop 0
	global_load_lds_dwordx4 v[166:167], off
	s_waitcnt lgkmcnt(1)
	v_mfma_f32_32x32x16_bf16 v[48:63], a[16:19], a[24:27], v[48:63]
	v_mfma_f32_32x32x16_bf16 v[32:47], a[20:23], a[24:27], v[32:47]
	s_and_b32 m0, s32, 7
	s_lshl_b32 m0, m0, 11
	s_add_i32 m0, m0, 0x14400
	s_nop 0
	global_load_lds_dwordx4 v[168:169], off
	s_waitcnt vmcnt(6)
	s_waitcnt lgkmcnt(0)
	s_barrier
	ds_read_b128 a[12:15], v82 offset:4096
	ds_read_b128 a[8:11], v82
	ds_read_b128 a[4:7], v83 offset:36864
	ds_read_b128 a[0:3], v83 offset:32768
	v_mfma_f32_32x32x16_bf16 v[16:31], a[16:19], a[28:31], v[16:31]
	v_lshl_add_u64 v[170:171], v[66:67], 0, s[30:31]
	v_lshl_add_u64 v[172:173], v[68:69], 0, s[30:31]
	s_nop 0
	v_readfirstlane_b32 s20, v127
	s_nop 0
	v_lshl_add_u64 v[174:175], v[70:71], 0, s[30:31]
	s_nop 0
	v_mfma_f32_32x32x16_bf16 v[0:15], a[20:23], a[28:31], v[0:15]
	s_and_b32 m0, s32, 7
	s_lshl_b32 m0, m0, 12
	s_add_i32 m0, m0, 0x18000
	s_nop 0
	global_load_lds_dwordx4 v[170:171], off
	v_lshl_add_u64 v[176:177], v[72:73], 0, s[30:31]
	s_nop 0
	v_readfirstlane_b32 s21, v128
	s_nop 0
	v_lshl_add_u64 v[178:179], v[74:75], 0, s[30:31]
	s_nop 0
	v_readfirstlane_b32 s23, v129
	s_nop 0
	v_lshl_add_u64 v[180:181], v[76:77], 0, s[30:31]
	s_nop 0
	s_mov_b64 s[28:29], 0x480
	ds_read_b128 a[16:19], v85 offset:32768
	ds_read_b128 a[20:23], v85 offset:36864
	ds_read_b128 a[24:27], v84
	ds_read_b128 a[28:31], v84 offset:4096
	s_waitcnt lgkmcnt(4)
	v_mfma_f32_32x32x16_bf16 v[48:63], a[0:3], a[8:11], v[48:63]
	s_nop 0
	v_lshl_add_u64 v[162:163], v[70:71], 0, s[28:29]
	v_readfirstlane_b32 s24, v131
	s_mov_b64 s[30:31], 0x500
	v_mfma_f32_32x32x16_bf16 v[32:47], a[4:7], a[8:11], v[32:47]
	v_mfma_f32_32x32x16_bf16 v[16:31], a[0:3], a[12:15], v[16:31]
	s_and_b32 m0, s32, 7
	s_lshl_b32 m0, m0, 12
	s_add_i32 m0, m0, 0x18400
	s_nop 0
	global_load_lds_dwordx4 v[172:173], off
	v_mfma_f32_32x32x16_bf16 v[0:15], a[4:7], a[12:15], v[0:15]
	ds_read_b128 a[0:3], v87 offset:32768
	ds_read_b128 a[4:7], v87 offset:36864
	ds_read_b128 a[8:11], v86
	ds_read_b128 a[12:15], v86 offset:4096
	s_waitcnt lgkmcnt(5)
	v_mfma_f32_32x32x16_bf16 v[48:63], a[16:19], a[24:27], v[48:63]
	v_mfma_f32_32x32x16_bf16 v[32:47], a[20:23], a[24:27], v[32:47]
	s_and_b32 m0, s32, 7
	s_lshl_b32 m0, m0, 12
	s_add_i32 m0, m0, 0x18800
	s_nop 0
	global_load_lds_dwordx4 v[174:175], off
	s_waitcnt lgkmcnt(4)
	v_mfma_f32_32x32x16_bf16 v[16:31], a[16:19], a[28:31], v[16:31]
	v_mfma_f32_32x32x16_bf16 v[0:15], a[20:23], a[28:31], v[0:15]
	ds_read_b128 a[16:19], v89 offset:32768
	ds_read_b128 a[20:23], v89 offset:36864
	ds_read_b128 a[24:27], v88
	ds_read_b128 a[28:31], v88 offset:4096
	s_waitcnt lgkmcnt(5)
	v_mfma_f32_32x32x16_bf16 v[48:63], a[0:3], a[8:11], v[48:63]
	s_and_b32 m0, s32, 7
	s_lshl_b32 m0, m0, 12
	s_add_i32 m0, m0, 0x18c00
	s_nop 0
	global_load_lds_dwordx4 v[176:177], off
	v_mfma_f32_32x32x16_bf16 v[32:47], a[4:7], a[8:11], v[32:47]
	s_waitcnt lgkmcnt(4)
	v_mfma_f32_32x32x16_bf16 v[16:31], a[0:3], a[12:15], v[16:31]
	v_mfma_f32_32x32x16_bf16 v[0:15], a[4:7], a[12:15], v[0:15]
	s_and_b32 m0, s32, 7
	s_lshl_b32 m0, m0, 11
	s_add_i32 m0, m0, 0x20000
	s_nop 0
	global_load_lds_dwordx4 v[178:179], off
	s_waitcnt lgkmcnt(1)
	v_mfma_f32_32x32x16_bf16 v[48:63], a[16:19], a[24:27], v[48:63]
	v_mfma_f32_32x32x16_bf16 v[32:47], a[20:23], a[24:27], v[32:47]
	s_and_b32 m0, s32, 7
	s_lshl_b32 m0, m0, 11
	s_add_i32 m0, m0, 0x20400
	s_nop 0
	global_load_lds_dwordx4 v[180:181], off
	s_waitcnt vmcnt(6)
	s_waitcnt lgkmcnt(0)
	s_barrier
	ds_read_b128 a[12:15], v82 offset:53248
	ds_read_b128 a[8:11], v82 offset:49152
	ds_read_b128 a[4:7], v90
	ds_read_b128 a[0:3], v92
	v_mfma_f32_32x32x16_bf16 v[16:31], a[16:19], a[28:31], v[16:31]
	v_lshl_add_u64 v[158:159], v[66:67], 0, s[28:29]
	v_lshl_add_u64 v[160:161], v[68:69], 0, s[28:29]
	v_mfma_f32_32x32x16_bf16 v[0:15], a[20:23], a[28:31], v[0:15]
	s_and_b32 m0, s32, 7
	s_lshl_b32 m0, m0, 12
	s_add_i32 m0, m0, 0x0
	s_nop 0
	global_load_lds_dwordx4 v[158:159], off
	v_lshl_add_u64 v[164:165], v[72:73], 0, s[28:29]
	v_lshl_add_u64 v[166:167], v[74:75], 0, s[28:29]
	s_nop 0
	v_lshl_add_u64 v[168:169], v[76:77], 0, s[28:29]
	v_readfirstlane_b32 s28, v130
	s_nop 0
	v_readfirstlane_b32 s29, v120
	s_nop 0
	s_nop 0
	s_nop 0
	s_nop 0
	ds_read_b128 a[16:19], v93
	ds_read_b128 a[20:23], v91
	ds_read_b128 a[24:27], v84 offset:49152
	ds_read_b128 a[28:31], v84 offset:53248
	s_waitcnt lgkmcnt(4)
	v_mfma_f32_32x32x16_bf16 v[48:63], a[0:3], a[8:11], v[48:63]
	v_lshl_add_u64 v[174:175], v[70:71], 0, s[30:31]
	v_mfma_f32_32x32x16_bf16 v[32:47], a[4:7], a[8:11], v[32:47]
	v_mfma_f32_32x32x16_bf16 v[16:31], a[0:3], a[12:15], v[16:31]
	s_and_b32 m0, s32, 7
	s_lshl_b32 m0, m0, 12
	s_add_i32 m0, m0, 0x400
	s_nop 0
	global_load_lds_dwordx4 v[160:161], off
	v_mfma_f32_32x32x16_bf16 v[0:15], a[4:7], a[12:15], v[0:15]
	ds_read_b128 a[0:3], v95
	ds_read_b128 a[4:7], v94
	ds_read_b128 a[8:11], v86 offset:49152
	ds_read_b128 a[12:15], v86 offset:53248
	s_waitcnt lgkmcnt(5)
	v_mfma_f32_32x32x16_bf16 v[48:63], a[16:19], a[24:27], v[48:63]
	v_mfma_f32_32x32x16_bf16 v[32:47], a[20:23], a[24:27], v[32:47]
	s_and_b32 m0, s32, 7
	s_lshl_b32 m0, m0, 12
	s_add_i32 m0, m0, 0x800
	s_nop 0
	global_load_lds_dwordx4 v[162:163], off
	s_waitcnt lgkmcnt(4)
	v_mfma_f32_32x32x16_bf16 v[16:31], a[16:19], a[28:31], v[16:31]
	v_mfma_f32_32x32x16_bf16 v[0:15], a[20:23], a[28:31], v[0:15]
	ds_read_b128 a[16:19], v97
	ds_read_b128 a[20:23], v96
	ds_read_b128 a[24:27], v88 offset:49152
	ds_read_b128 a[28:31], v88 offset:53248
	s_waitcnt lgkmcnt(5)
	v_mfma_f32_32x32x16_bf16 v[48:63], a[0:3], a[8:11], v[48:63]
	s_and_b32 m0, s32, 7
	s_lshl_b32 m0, m0, 12
	s_add_i32 m0, m0, 0xc00
	s_nop 0
	global_load_lds_dwordx4 v[164:165], off
	v_mfma_f32_32x32x16_bf16 v[32:47], a[4:7], a[8:11], v[32:47]
	s_waitcnt lgkmcnt(4)
	v_mfma_f32_32x32x16_bf16 v[16:31], a[0:3], a[12:15], v[16:31]
	v_mfma_f32_32x32x16_bf16 v[0:15], a[4:7], a[12:15], v[0:15]
	s_and_b32 m0, s32, 7
	s_lshl_b32 m0, m0, 11
	s_add_i32 m0, m0, 0x8000
	s_nop 0
	global_load_lds_dwordx4 v[166:167], off
	s_waitcnt lgkmcnt(1)
	v_mfma_f32_32x32x16_bf16 v[48:63], a[16:19], a[24:27], v[48:63]
	v_mfma_f32_32x32x16_bf16 v[32:47], a[20:23], a[24:27], v[32:47]
	s_and_b32 m0, s32, 7
	s_lshl_b32 m0, m0, 11
	s_add_i32 m0, m0, 0x8400
	s_nop 0
	global_load_lds_dwordx4 v[168:169], off
	s_waitcnt vmcnt(6)
	s_waitcnt lgkmcnt(0)
	s_barrier
	ds_read_b128 a[12:15], v101
	ds_read_b128 a[8:11], v100
	ds_read_b128 a[4:7], v99
	ds_read_b128 a[0:3], v98
	v_mfma_f32_32x32x16_bf16 v[16:31], a[16:19], a[28:31], v[16:31]
	v_lshl_add_u64 v[170:171], v[66:67], 0, s[30:31]
	v_lshl_add_u64 v[172:173], v[68:69], 0, s[30:31]
	v_mfma_f32_32x32x16_bf16 v[0:15], a[20:23], a[28:31], v[0:15]
	s_and_b32 m0, s32, 7
	s_lshl_b32 m0, m0, 12
	s_add_i32 m0, m0, 0xc000
	s_nop 0
	global_load_lds_dwordx4 v[170:171], off
	v_lshl_add_u64 v[176:177], v[72:73], 0, s[30:31]
	v_lshl_add_u64 v[178:179], v[74:75], 0, s[30:31]
	v_lshl_add_u64 v[180:181], v[76:77], 0, s[30:31]
	s_mov_b64 s[30:31], 0x580
	ds_read_b128 a[16:19], v102
	ds_read_b128 a[20:23], v103
	ds_read_b128 a[24:27], v104
	ds_read_b128 a[28:31], v105
	s_waitcnt lgkmcnt(4)
	v_mfma_f32_32x32x16_bf16 v[48:63], a[0:3], a[8:11], v[48:63]
	v_lshl_add_u64 v[162:163], v[70:71], 0, s[30:31]
	v_mfma_f32_32x32x16_bf16 v[32:47], a[4:7], a[8:11], v[32:47]
	v_mfma_f32_32x32x16_bf16 v[16:31], a[0:3], a[12:15], v[16:31]
	s_and_b32 m0, s32, 7
	s_lshl_b32 m0, m0, 12
	s_add_i32 m0, m0, 0xc400
	s_nop 0
	global_load_lds_dwordx4 v[172:173], off
	v_mfma_f32_32x32x16_bf16 v[0:15], a[4:7], a[12:15], v[0:15]
	ds_read_b128 a[0:3], v106
	ds_read_b128 a[4:7], v107
	ds_read_b128 a[8:11], v108
	ds_read_b128 a[12:15], v109
	s_waitcnt lgkmcnt(5)
	v_mfma_f32_32x32x16_bf16 v[48:63], a[16:19], a[24:27], v[48:63]
	v_mfma_f32_32x32x16_bf16 v[32:47], a[20:23], a[24:27], v[32:47]
	s_and_b32 m0, s32, 7
	s_lshl_b32 m0, m0, 12
	s_add_i32 m0, m0, 0xc800
	s_nop 0
	global_load_lds_dwordx4 v[174:175], off
	s_waitcnt lgkmcnt(4)
	v_mfma_f32_32x32x16_bf16 v[16:31], a[16:19], a[28:31], v[16:31]
	v_mfma_f32_32x32x16_bf16 v[0:15], a[20:23], a[28:31], v[0:15]
	ds_read_b128 a[16:19], v110
	ds_read_b128 a[20:23], v111
	ds_read_b128 a[24:27], v112
	ds_read_b128 a[28:31], v113
	s_waitcnt lgkmcnt(5)
	v_mfma_f32_32x32x16_bf16 v[48:63], a[0:3], a[8:11], v[48:63]
	s_and_b32 m0, s32, 7
	s_lshl_b32 m0, m0, 12
	s_add_i32 m0, m0, 0xcc00
	s_nop 0
	global_load_lds_dwordx4 v[176:177], off
	v_mfma_f32_32x32x16_bf16 v[32:47], a[4:7], a[8:11], v[32:47]
	s_waitcnt lgkmcnt(4)
	v_mfma_f32_32x32x16_bf16 v[16:31], a[0:3], a[12:15], v[16:31]
	v_mfma_f32_32x32x16_bf16 v[0:15], a[4:7], a[12:15], v[0:15]
	s_and_b32 m0, s32, 7
	s_lshl_b32 m0, m0, 11
	s_add_i32 m0, m0, 0x14000
	s_nop 0
	global_load_lds_dwordx4 v[178:179], off
	s_waitcnt lgkmcnt(1)
	v_mfma_f32_32x32x16_bf16 v[48:63], a[16:19], a[24:27], v[48:63]
	v_mfma_f32_32x32x16_bf16 v[32:47], a[20:23], a[24:27], v[32:47]
	s_and_b32 m0, s32, 7
	s_lshl_b32 m0, m0, 11
	s_add_i32 m0, m0, 0x14400
	s_nop 0
	global_load_lds_dwordx4 v[180:181], off
	s_waitcnt vmcnt(6)
	s_waitcnt lgkmcnt(0)
	s_barrier
	ds_read_b128 a[12:15], v82 offset:4096
	ds_read_b128 a[8:11], v82
	ds_read_b128 a[4:7], v83 offset:36864
	ds_read_b128 a[0:3], v83 offset:32768
	v_mfma_f32_32x32x16_bf16 v[16:31], a[16:19], a[28:31], v[16:31]
	v_lshl_add_u64 v[158:159], v[66:67], 0, s[30:31]
	v_lshl_add_u64 v[160:161], v[68:69], 0, s[30:31]
	v_mfma_f32_32x32x16_bf16 v[0:15], a[20:23], a[28:31], v[0:15]
	s_and_b32 m0, s32, 7
	s_lshl_b32 m0, m0, 12
	s_add_i32 m0, m0, 0x18000
	s_nop 0
	global_load_lds_dwordx4 v[158:159], off
	v_lshl_add_u64 v[164:165], v[72:73], 0, s[30:31]
	v_lshl_add_u64 v[166:167], v[74:75], 0, s[30:31]
	v_lshl_add_u64 v[168:169], v[76:77], 0, s[30:31]
	s_mov_b64 s[30:31], 0x600
	ds_read_b128 a[16:19], v85 offset:32768
	ds_read_b128 a[20:23], v85 offset:36864
	ds_read_b128 a[24:27], v84
	ds_read_b128 a[28:31], v84 offset:4096
	s_waitcnt lgkmcnt(4)
	v_mfma_f32_32x32x16_bf16 v[48:63], a[0:3], a[8:11], v[48:63]
	v_mfma_f32_32x32x16_bf16 v[32:47], a[4:7], a[8:11], v[32:47]
	v_mfma_f32_32x32x16_bf16 v[16:31], a[0:3], a[12:15], v[16:31]
	s_and_b32 m0, s32, 7
	s_lshl_b32 m0, m0, 12
	s_add_i32 m0, m0, 0x18400
	s_nop 0
	global_load_lds_dwordx4 v[160:161], off
	v_mfma_f32_32x32x16_bf16 v[0:15], a[4:7], a[12:15], v[0:15]
	ds_read_b128 a[0:3], v87 offset:32768
	ds_read_b128 a[4:7], v87 offset:36864
	ds_read_b128 a[8:11], v86
	ds_read_b128 a[12:15], v86 offset:4096
	s_waitcnt lgkmcnt(5)
	v_mfma_f32_32x32x16_bf16 v[48:63], a[16:19], a[24:27], v[48:63]
	v_mfma_f32_32x32x16_bf16 v[32:47], a[20:23], a[24:27], v[32:47]
	s_and_b32 m0, s32, 7
	s_lshl_b32 m0, m0, 12
	s_add_i32 m0, m0, 0x18800
	s_nop 0
	global_load_lds_dwordx4 v[162:163], off
	s_waitcnt lgkmcnt(4)
	v_mfma_f32_32x32x16_bf16 v[16:31], a[16:19], a[28:31], v[16:31]
	v_mfma_f32_32x32x16_bf16 v[0:15], a[20:23], a[28:31], v[0:15]
	ds_read_b128 a[16:19], v89 offset:32768
	ds_read_b128 a[20:23], v89 offset:36864
	ds_read_b128 a[24:27], v88
	ds_read_b128 a[28:31], v88 offset:4096
	s_waitcnt lgkmcnt(5)
	v_mfma_f32_32x32x16_bf16 v[48:63], a[0:3], a[8:11], v[48:63]
	s_and_b32 m0, s32, 7
	s_lshl_b32 m0, m0, 12
	s_add_i32 m0, m0, 0x18c00
	s_nop 0
	global_load_lds_dwordx4 v[164:165], off
	v_mfma_f32_32x32x16_bf16 v[32:47], a[4:7], a[8:11], v[32:47]
	s_waitcnt lgkmcnt(4)
	v_mfma_f32_32x32x16_bf16 v[16:31], a[0:3], a[12:15], v[16:31]
	v_mfma_f32_32x32x16_bf16 v[0:15], a[4:7], a[12:15], v[0:15]
	s_and_b32 m0, s32, 7
	s_lshl_b32 m0, m0, 11
	s_add_i32 m0, m0, 0x20000
	s_nop 0
	global_load_lds_dwordx4 v[166:167], off
	s_waitcnt lgkmcnt(1)
	v_mfma_f32_32x32x16_bf16 v[48:63], a[16:19], a[24:27], v[48:63]
	v_mfma_f32_32x32x16_bf16 v[32:47], a[20:23], a[24:27], v[32:47]
	s_and_b32 m0, s32, 7
	s_lshl_b32 m0, m0, 11
	s_add_i32 m0, m0, 0x20400
	s_nop 0
	global_load_lds_dwordx4 v[168:169], off
	s_waitcnt vmcnt(6)
	s_waitcnt lgkmcnt(0)
	s_barrier
	ds_read_b128 a[12:15], v82 offset:53248
	ds_read_b128 a[8:11], v82 offset:49152
	ds_read_b128 a[4:7], v90
	ds_read_b128 a[0:3], v92
	v_mfma_f32_32x32x16_bf16 v[16:31], a[16:19], a[28:31], v[16:31]
	v_lshl_add_u64 v[170:171], v[66:67], 0, s[30:31]
	v_lshl_add_u64 v[172:173], v[68:69], 0, s[30:31]
	v_lshl_add_u64 v[174:175], v[70:71], 0, s[30:31]
	v_mfma_f32_32x32x16_bf16 v[0:15], a[20:23], a[28:31], v[0:15]
	s_and_b32 m0, s32, 7
	s_lshl_b32 m0, m0, 12
	s_add_i32 m0, m0, 0x0
	s_nop 0
	global_load_lds_dwordx4 v[170:171], off
	v_lshl_add_u64 v[176:177], v[72:73], 0, s[30:31]
	v_lshl_add_u64 v[178:179], v[74:75], 0, s[30:31]
	v_lshl_add_u64 v[180:181], v[76:77], 0, s[30:31]
	s_mov_b64 s[30:31], 0x680
	ds_read_b128 a[16:19], v93
	ds_read_b128 a[20:23], v91
	ds_read_b128 a[24:27], v84 offset:49152
	ds_read_b128 a[28:31], v84 offset:53248
	s_waitcnt lgkmcnt(4)
	v_mfma_f32_32x32x16_bf16 v[48:63], a[0:3], a[8:11], v[48:63]
	v_mfma_f32_32x32x16_bf16 v[32:47], a[4:7], a[8:11], v[32:47]
	v_mfma_f32_32x32x16_bf16 v[16:31], a[0:3], a[12:15], v[16:31]
	s_and_b32 m0, s32, 7
	s_lshl_b32 m0, m0, 12
	s_add_i32 m0, m0, 0x400
	s_nop 0
	global_load_lds_dwordx4 v[172:173], off
	v_mfma_f32_32x32x16_bf16 v[0:15], a[4:7], a[12:15], v[0:15]
	ds_read_b128 a[0:3], v95
	ds_read_b128 a[4:7], v94
	ds_read_b128 a[8:11], v86 offset:49152
	ds_read_b128 a[12:15], v86 offset:53248
	s_waitcnt lgkmcnt(5)
	v_mfma_f32_32x32x16_bf16 v[48:63], a[16:19], a[24:27], v[48:63]
	v_mfma_f32_32x32x16_bf16 v[32:47], a[20:23], a[24:27], v[32:47]
	s_and_b32 m0, s32, 7
	s_lshl_b32 m0, m0, 12
	s_add_i32 m0, m0, 0x800
	s_nop 0
	global_load_lds_dwordx4 v[174:175], off
	s_waitcnt lgkmcnt(4)
	v_mfma_f32_32x32x16_bf16 v[16:31], a[16:19], a[28:31], v[16:31]
	v_mfma_f32_32x32x16_bf16 v[0:15], a[20:23], a[28:31], v[0:15]
	ds_read_b128 a[16:19], v97
	ds_read_b128 a[20:23], v96
	ds_read_b128 a[24:27], v88 offset:49152
	ds_read_b128 a[28:31], v88 offset:53248
	s_waitcnt lgkmcnt(5)
	v_mfma_f32_32x32x16_bf16 v[48:63], a[0:3], a[8:11], v[48:63]
	s_and_b32 m0, s32, 7
	s_lshl_b32 m0, m0, 12
	s_add_i32 m0, m0, 0xc00
	s_nop 0
	global_load_lds_dwordx4 v[176:177], off
	v_mfma_f32_32x32x16_bf16 v[32:47], a[4:7], a[8:11], v[32:47]
	s_waitcnt lgkmcnt(4)
	v_mfma_f32_32x32x16_bf16 v[16:31], a[0:3], a[12:15], v[16:31]
	v_mfma_f32_32x32x16_bf16 v[0:15], a[4:7], a[12:15], v[0:15]
	s_and_b32 m0, s32, 7
	s_lshl_b32 m0, m0, 11
	s_add_i32 m0, m0, 0x8000
	s_nop 0
	global_load_lds_dwordx4 v[178:179], off
	s_waitcnt lgkmcnt(1)
	v_mfma_f32_32x32x16_bf16 v[48:63], a[16:19], a[24:27], v[48:63]
	v_mfma_f32_32x32x16_bf16 v[32:47], a[20:23], a[24:27], v[32:47]
	s_and_b32 m0, s32, 7
	s_lshl_b32 m0, m0, 11
	s_add_i32 m0, m0, 0x8400
	s_nop 0
	global_load_lds_dwordx4 v[180:181], off
	s_waitcnt vmcnt(6)
	s_waitcnt lgkmcnt(0)
	s_barrier
	ds_read_b128 a[12:15], v101
	ds_read_b128 a[8:11], v100
	ds_read_b128 a[4:7], v99
	ds_read_b128 a[0:3], v98
	v_mfma_f32_32x32x16_bf16 v[16:31], a[16:19], a[28:31], v[16:31]
	v_lshl_add_u64 v[158:159], v[66:67], 0, s[30:31]
	v_lshl_add_u64 v[160:161], v[68:69], 0, s[30:31]
	v_lshl_add_u64 v[162:163], v[70:71], 0, s[30:31]
	v_mfma_f32_32x32x16_bf16 v[0:15], a[20:23], a[28:31], v[0:15]
	s_and_b32 m0, s32, 7
	s_lshl_b32 m0, m0, 12
	s_add_i32 m0, m0, 0xc000
	s_nop 0
	global_load_lds_dwordx4 v[158:159], off
	v_lshl_add_u64 v[164:165], v[72:73], 0, s[30:31]
	v_lshl_add_u64 v[166:167], v[74:75], 0, s[30:31]
	v_lshl_add_u64 v[168:169], v[76:77], 0, s[30:31]
	s_mov_b64 s[30:31], 0x700
	ds_read_b128 a[16:19], v102
	ds_read_b128 a[20:23], v103
	ds_read_b128 a[24:27], v104
	ds_read_b128 a[28:31], v105
	s_waitcnt lgkmcnt(4)
	v_mfma_f32_32x32x16_bf16 v[48:63], a[0:3], a[8:11], v[48:63]
	v_mfma_f32_32x32x16_bf16 v[32:47], a[4:7], a[8:11], v[32:47]
	v_mfma_f32_32x32x16_bf16 v[16:31], a[0:3], a[12:15], v[16:31]
	s_and_b32 m0, s32, 7
	s_lshl_b32 m0, m0, 12
	s_add_i32 m0, m0, 0xc400
	s_nop 0
	global_load_lds_dwordx4 v[160:161], off
	v_mfma_f32_32x32x16_bf16 v[0:15], a[4:7], a[12:15], v[0:15]
	ds_read_b128 a[0:3], v106
	ds_read_b128 a[4:7], v107
	ds_read_b128 a[8:11], v108
	ds_read_b128 a[12:15], v109
	s_waitcnt lgkmcnt(5)
	v_mfma_f32_32x32x16_bf16 v[48:63], a[16:19], a[24:27], v[48:63]
	v_mfma_f32_32x32x16_bf16 v[32:47], a[20:23], a[24:27], v[32:47]
	s_and_b32 m0, s32, 7
	s_lshl_b32 m0, m0, 12
	s_add_i32 m0, m0, 0xc800
	s_nop 0
	global_load_lds_dwordx4 v[162:163], off
	s_waitcnt lgkmcnt(4)
	v_mfma_f32_32x32x16_bf16 v[16:31], a[16:19], a[28:31], v[16:31]
	v_mfma_f32_32x32x16_bf16 v[0:15], a[20:23], a[28:31], v[0:15]
	ds_read_b128 a[16:19], v110
	ds_read_b128 a[20:23], v111
	ds_read_b128 a[24:27], v112
	ds_read_b128 a[28:31], v113
	s_waitcnt lgkmcnt(5)
	v_mfma_f32_32x32x16_bf16 v[48:63], a[0:3], a[8:11], v[48:63]
	s_and_b32 m0, s32, 7
	s_lshl_b32 m0, m0, 12
	s_add_i32 m0, m0, 0xcc00
	s_nop 0
	global_load_lds_dwordx4 v[164:165], off
	v_mfma_f32_32x32x16_bf16 v[32:47], a[4:7], a[8:11], v[32:47]
	s_waitcnt lgkmcnt(4)
	v_mfma_f32_32x32x16_bf16 v[16:31], a[0:3], a[12:15], v[16:31]
	v_mfma_f32_32x32x16_bf16 v[0:15], a[4:7], a[12:15], v[0:15]
	s_and_b32 m0, s32, 7
	s_lshl_b32 m0, m0, 11
	s_add_i32 m0, m0, 0x14000
	s_nop 0
	global_load_lds_dwordx4 v[166:167], off
	s_waitcnt lgkmcnt(1)
	v_mfma_f32_32x32x16_bf16 v[48:63], a[16:19], a[24:27], v[48:63]
	v_mfma_f32_32x32x16_bf16 v[32:47], a[20:23], a[24:27], v[32:47]
	s_and_b32 m0, s32, 7
	s_lshl_b32 m0, m0, 11
	s_add_i32 m0, m0, 0x14400
	s_nop 0
	global_load_lds_dwordx4 v[168:169], off
	s_waitcnt vmcnt(6)
	s_waitcnt lgkmcnt(0)
	s_barrier
	ds_read_b128 a[12:15], v82 offset:4096
	ds_read_b128 a[8:11], v82
	ds_read_b128 a[4:7], v83 offset:36864
	ds_read_b128 a[0:3], v83 offset:32768
	v_mfma_f32_32x32x16_bf16 v[16:31], a[16:19], a[28:31], v[16:31]
	v_lshl_add_u64 v[170:171], v[66:67], 0, s[30:31]
	v_lshl_add_u64 v[172:173], v[68:69], 0, s[30:31]
	v_lshl_add_u64 v[174:175], v[70:71], 0, s[30:31]
	v_mfma_f32_32x32x16_bf16 v[0:15], a[20:23], a[28:31], v[0:15]
	s_and_b32 m0, s32, 7
	s_lshl_b32 m0, m0, 12
	s_add_i32 m0, m0, 0x18000
	s_nop 0
	global_load_lds_dwordx4 v[170:171], off
	v_lshl_add_u64 v[176:177], v[72:73], 0, s[30:31]
	v_lshl_add_u64 v[178:179], v[74:75], 0, s[30:31]
	v_lshl_add_u64 v[180:181], v[76:77], 0, s[30:31]
	s_mov_b64 s[30:31], 0x780
	ds_read_b128 a[16:19], v85 offset:32768
	ds_read_b128 a[20:23], v85 offset:36864
	ds_read_b128 a[24:27], v84
	ds_read_b128 a[28:31], v84 offset:4096
	s_waitcnt lgkmcnt(4)
	v_mfma_f32_32x32x16_bf16 v[48:63], a[0:3], a[8:11], v[48:63]
	v_lshl_add_u64 v[158:159], v[66:67], 0, s[30:31]
	v_mfma_f32_32x32x16_bf16 v[32:47], a[4:7], a[8:11], v[32:47]
	v_mfma_f32_32x32x16_bf16 v[16:31], a[0:3], a[12:15], v[16:31]
	s_and_b32 m0, s32, 7
	s_lshl_b32 m0, m0, 12
	s_add_i32 m0, m0, 0x18400
	s_nop 0
	global_load_lds_dwordx4 v[172:173], off
	v_mfma_f32_32x32x16_bf16 v[0:15], a[4:7], a[12:15], v[0:15]
	ds_read_b128 a[0:3], v87 offset:32768
	ds_read_b128 a[4:7], v87 offset:36864
	ds_read_b128 a[8:11], v86
	ds_read_b128 a[12:15], v86 offset:4096
	s_waitcnt lgkmcnt(5)
	v_mfma_f32_32x32x16_bf16 v[48:63], a[16:19], a[24:27], v[48:63]
	v_mfma_f32_32x32x16_bf16 v[32:47], a[20:23], a[24:27], v[32:47]
	s_and_b32 m0, s32, 7
	s_lshl_b32 m0, m0, 12
	s_add_i32 m0, m0, 0x18800
	s_nop 0
	global_load_lds_dwordx4 v[174:175], off
	s_waitcnt lgkmcnt(4)
	v_mfma_f32_32x32x16_bf16 v[16:31], a[16:19], a[28:31], v[16:31]
	v_mfma_f32_32x32x16_bf16 v[0:15], a[20:23], a[28:31], v[0:15]
	ds_read_b128 a[16:19], v89 offset:32768
	ds_read_b128 a[20:23], v89 offset:36864
	ds_read_b128 a[24:27], v88
	ds_read_b128 a[28:31], v88 offset:4096
	s_waitcnt lgkmcnt(5)
	v_mfma_f32_32x32x16_bf16 v[48:63], a[0:3], a[8:11], v[48:63]
	s_and_b32 m0, s32, 7
	s_lshl_b32 m0, m0, 12
	s_add_i32 m0, m0, 0x18c00
	s_nop 0
	global_load_lds_dwordx4 v[176:177], off
	v_mfma_f32_32x32x16_bf16 v[32:47], a[4:7], a[8:11], v[32:47]
	s_waitcnt lgkmcnt(4)
	v_mfma_f32_32x32x16_bf16 v[16:31], a[0:3], a[12:15], v[16:31]
	v_mfma_f32_32x32x16_bf16 v[0:15], a[4:7], a[12:15], v[0:15]
	s_and_b32 m0, s32, 7
	s_lshl_b32 m0, m0, 11
	s_add_i32 m0, m0, 0x20000
	s_nop 0
	global_load_lds_dwordx4 v[178:179], off
	s_waitcnt lgkmcnt(1)
	v_mfma_f32_32x32x16_bf16 v[48:63], a[16:19], a[24:27], v[48:63]
	v_mfma_f32_32x32x16_bf16 v[32:47], a[20:23], a[24:27], v[32:47]
	s_and_b32 m0, s32, 7
	s_lshl_b32 m0, m0, 11
	s_add_i32 m0, m0, 0x20400
	s_nop 0
	global_load_lds_dwordx4 v[180:181], off
	s_waitcnt vmcnt(6)
	s_waitcnt lgkmcnt(0)
	s_barrier
	ds_read_b128 a[12:15], v82 offset:53248
	ds_read_b128 a[8:11], v82 offset:49152
	ds_read_b128 a[4:7], v90
	ds_read_b128 a[0:3], v92
	v_lshl_add_u64 v[160:161], v[68:69], 0, s[30:31]
	v_mfma_f32_32x32x16_bf16 v[16:31], a[16:19], a[28:31], v[16:31]
	v_lshl_add_u64 v[162:163], v[70:71], 0, s[30:31]
	s_nop 0
	v_readlane_b32 s20, v215, 52
	s_nop 0
	v_lshl_add_u64 v[164:165], v[72:73], 0, s[30:31]
	s_nop 0
	v_mfma_f32_32x32x16_bf16 v[0:15], a[20:23], a[28:31], v[0:15]
	s_and_b32 m0, s32, 7
	s_lshl_b32 m0, m0, 12
	s_add_i32 m0, m0, 0x0
	s_nop 0
	global_load_lds_dwordx4 v[158:159], off
	v_lshl_add_u64 v[166:167], v[74:75], 0, s[30:31]
	s_nop 0
	v_readlane_b32 s21, v215, 53
	s_nop 0
	v_lshl_add_u64 v[168:169], v[76:77], 0, s[30:31]
	s_nop 0
	s_mov_b32 s23, 0
	ds_read_b128 a[16:19], v93
	ds_read_b128 a[20:23], v91
	ds_read_b128 a[24:27], v84 offset:49152
	ds_read_b128 a[28:31], v84 offset:53248
	s_waitcnt lgkmcnt(4)
	v_mfma_f32_32x32x16_bf16 v[48:63], a[0:3], a[8:11], v[48:63]
	v_mfma_f32_32x32x16_bf16 v[32:47], a[4:7], a[8:11], v[32:47]
	v_mfma_f32_32x32x16_bf16 v[16:31], a[0:3], a[12:15], v[16:31]
	s_and_b32 m0, s32, 7
	s_lshl_b32 m0, m0, 12
	s_add_i32 m0, m0, 0x400
	s_nop 0
	global_load_lds_dwordx4 v[160:161], off
	v_mfma_f32_32x32x16_bf16 v[0:15], a[4:7], a[12:15], v[0:15]
	ds_read_b128 a[0:3], v95
	ds_read_b128 a[4:7], v94
	ds_read_b128 a[8:11], v86 offset:49152
	ds_read_b128 a[12:15], v86 offset:53248
	s_waitcnt lgkmcnt(5)
	v_mfma_f32_32x32x16_bf16 v[48:63], a[16:19], a[24:27], v[48:63]
	v_mfma_f32_32x32x16_bf16 v[32:47], a[20:23], a[24:27], v[32:47]
	s_and_b32 m0, s32, 7
	s_lshl_b32 m0, m0, 12
	s_add_i32 m0, m0, 0x800
	s_nop 0
	global_load_lds_dwordx4 v[162:163], off
	s_waitcnt lgkmcnt(4)
	v_mfma_f32_32x32x16_bf16 v[16:31], a[16:19], a[28:31], v[16:31]
	v_mfma_f32_32x32x16_bf16 v[0:15], a[20:23], a[28:31], v[0:15]
	ds_read_b128 a[16:19], v97
	ds_read_b128 a[20:23], v96
	ds_read_b128 a[24:27], v88 offset:49152
	ds_read_b128 a[28:31], v88 offset:53248
	s_waitcnt lgkmcnt(5)
	v_mfma_f32_32x32x16_bf16 v[48:63], a[0:3], a[8:11], v[48:63]
	s_and_b32 m0, s32, 7
	s_lshl_b32 m0, m0, 12
	s_add_i32 m0, m0, 0xc00
	s_nop 0
	global_load_lds_dwordx4 v[164:165], off
	v_mfma_f32_32x32x16_bf16 v[32:47], a[4:7], a[8:11], v[32:47]
	s_waitcnt lgkmcnt(4)
	v_mfma_f32_32x32x16_bf16 v[16:31], a[0:3], a[12:15], v[16:31]
	v_mfma_f32_32x32x16_bf16 v[0:15], a[4:7], a[12:15], v[0:15]
	s_and_b32 m0, s32, 7
	s_lshl_b32 m0, m0, 11
	s_add_i32 m0, m0, 0x8000
	s_nop 0
	global_load_lds_dwordx4 v[166:167], off
	s_waitcnt lgkmcnt(1)
	v_mfma_f32_32x32x16_bf16 v[48:63], a[16:19], a[24:27], v[48:63]
	v_mfma_f32_32x32x16_bf16 v[32:47], a[20:23], a[24:27], v[32:47]
	s_and_b32 m0, s32, 7
	s_lshl_b32 m0, m0, 11
	s_add_i32 m0, m0, 0x8400
	s_nop 0
	global_load_lds_dwordx4 v[168:169], off
	s_waitcnt vmcnt(6)
	s_waitcnt lgkmcnt(0)
	s_barrier
	ds_read_b128 a[12:15], v101
	ds_read_b128 a[8:11], v100
	ds_read_b128 a[4:7], v99
	ds_read_b128 a[0:3], v98
	v_mfma_f32_32x32x16_bf16 v[16:31], a[16:19], a[28:31], v[16:31]
	v_mfma_f32_32x32x16_bf16 v[0:15], a[20:23], a[28:31], v[0:15]
	ds_read_b128 a[16:19], v102
	ds_read_b128 a[20:23], v103
	ds_read_b128 a[24:27], v104
	ds_read_b128 a[28:31], v105
	s_waitcnt lgkmcnt(4)
	v_mfma_f32_32x32x16_bf16 v[48:63], a[0:3], a[8:11], v[48:63]
	v_mfma_f32_32x32x16_bf16 v[32:47], a[4:7], a[8:11], v[32:47]
	v_mfma_f32_32x32x16_bf16 v[16:31], a[0:3], a[12:15], v[16:31]
	v_mfma_f32_32x32x16_bf16 v[0:15], a[4:7], a[12:15], v[0:15]
	ds_read_b128 a[0:3], v106
	ds_read_b128 a[4:7], v107
	ds_read_b128 a[8:11], v108
	ds_read_b128 a[12:15], v109
	s_waitcnt lgkmcnt(5)
	v_mfma_f32_32x32x16_bf16 v[48:63], a[16:19], a[24:27], v[48:63]
	v_mfma_f32_32x32x16_bf16 v[32:47], a[20:23], a[24:27], v[32:47]
	s_waitcnt lgkmcnt(4)
	v_mfma_f32_32x32x16_bf16 v[16:31], a[16:19], a[28:31], v[16:31]
	v_mfma_f32_32x32x16_bf16 v[0:15], a[20:23], a[28:31], v[0:15]
	ds_read_b128 a[16:19], v110
	ds_read_b128 a[20:23], v111
	ds_read_b128 a[24:27], v112
	ds_read_b128 a[28:31], v113
	s_waitcnt lgkmcnt(5)
	v_mfma_f32_32x32x16_bf16 v[48:63], a[0:3], a[8:11], v[48:63]
	v_mfma_f32_32x32x16_bf16 v[32:47], a[4:7], a[8:11], v[32:47]
	s_waitcnt lgkmcnt(4)
	v_mfma_f32_32x32x16_bf16 v[16:31], a[0:3], a[12:15], v[16:31]
	v_mfma_f32_32x32x16_bf16 v[0:15], a[4:7], a[12:15], v[0:15]
	s_waitcnt lgkmcnt(1)
	v_mfma_f32_32x32x16_bf16 v[48:63], a[16:19], a[24:27], v[48:63]
	v_mfma_f32_32x32x16_bf16 v[32:47], a[20:23], a[24:27], v[32:47]
	s_waitcnt vmcnt(0)
	s_waitcnt lgkmcnt(0)
	s_barrier
	ds_read_b128 a[12:15], v82 offset:4096
	ds_read_b128 a[8:11], v82
	ds_read_b128 a[4:7], v83 offset:36864
	ds_read_b128 a[0:3], v83 offset:32768
	v_mfma_f32_32x32x16_bf16 v[16:31], a[16:19], a[28:31], v[16:31]
	v_mfma_f32_32x32x16_bf16 v[0:15], a[20:23], a[28:31], v[0:15]
	ds_read_b128 a[16:19], v85 offset:32768
	ds_read_b128 a[20:23], v85 offset:36864
	ds_read_b128 a[24:27], v84
	ds_read_b128 a[28:31], v84 offset:4096
	s_waitcnt lgkmcnt(4)
	v_mfma_f32_32x32x16_bf16 v[48:63], a[0:3], a[8:11], v[48:63]
	v_mfma_f32_32x32x16_bf16 v[32:47], a[4:7], a[8:11], v[32:47]
	v_mfma_f32_32x32x16_bf16 v[16:31], a[0:3], a[12:15], v[16:31]
	v_mfma_f32_32x32x16_bf16 v[0:15], a[4:7], a[12:15], v[0:15]
	ds_read_b128 a[0:3], v87 offset:32768
	ds_read_b128 a[4:7], v87 offset:36864
	ds_read_b128 a[8:11], v86
	ds_read_b128 a[12:15], v86 offset:4096
	s_waitcnt lgkmcnt(5)
	v_mfma_f32_32x32x16_bf16 v[48:63], a[16:19], a[24:27], v[48:63]
	v_mfma_f32_32x32x16_bf16 v[32:47], a[20:23], a[24:27], v[32:47]
	s_waitcnt lgkmcnt(4)
	v_mfma_f32_32x32x16_bf16 v[16:31], a[16:19], a[28:31], v[16:31]
	v_mfma_f32_32x32x16_bf16 v[0:15], a[20:23], a[28:31], v[0:15]
	s_waitcnt lgkmcnt(1)
	v_mfma_f32_32x32x16_bf16 v[48:63], a[0:3], a[8:11], v[48:63]
	v_mfma_f32_32x32x16_bf16 v[32:47], a[4:7], a[8:11], v[32:47]
	s_waitcnt lgkmcnt(0)
	v_mfma_f32_32x32x16_bf16 v[0:15], a[4:7], a[12:15], v[0:15]
	v_mfma_f32_32x32x16_bf16 v[16:31], a[0:3], a[12:15], v[16:31]
	ds_read_b128 v[66:69], v89 offset:32768
	ds_read_b128 v[70:73], v88
	ds_read_b128 v[74:77], v89 offset:36864
	ds_read_b128 v[82:85], v88 offset:4096
	s_waitcnt lgkmcnt(0)
	s_barrier
	s_waitcnt lgkmcnt(0)
	v_mfma_f32_32x32x16_bf16 v[48:63], v[66:69], v[70:73], v[48:63]
	v_mfma_f32_32x32x16_bf16 v[32:47], v[74:77], v[70:73], v[32:47]
	s_nop 10
	ds_write_b128 v64, v[48:51]
	ds_write_b128 v64, v[52:55] offset:32
	ds_write_b128 v64, v[56:59] offset:64
	ds_write_b128 v64, v[60:63] offset:96
	ds_write_b128 v64, v[32:35] offset:128
	v_mfma_f32_32x32x16_bf16 v[0:15], v[74:77], v[82:85], v[0:15]
	v_mfma_f32_32x32x16_bf16 v[16:31], v[66:69], v[82:85], v[16:31]
	ds_write_b128 v64, v[36:39] offset:160
	ds_write_b128 v64, v[40:43] offset:192
	ds_write_b128 v64, v[44:47] offset:224
	s_nop 8
	ds_write_b128 v64, v[16:19] offset:16896
	ds_write_b128 v64, v[20:23] offset:16928
	ds_write_b128 v64, v[24:27] offset:16960
	ds_write_b128 v64, v[28:31] offset:16992
	ds_write_b128 v64, v[0:3] offset:17024
	ds_write_b128 v64, v[4:7] offset:17056
	ds_write_b128 v64, v[8:11] offset:17088
	ds_write_b128 v64, v[12:15] offset:17120
	s_waitcnt lgkmcnt(0)
	s_barrier
	v_lshl_or_b32 v0, v79, 2, s0
	v_ashrrev_i32_e32 v1, 31, v0
	v_lshl_add_u32 v4, v79, 4, 0
	v_cmp_eq_u32_e64 s[0:1], 0, v79
	v_lshl_add_u64 v[6:7], v[0:1], 2, s[92:93]
	v_lshl_add_u64 v[8:9], v[0:1], 1, s[20:21]
	s_branch .LBB0_96

.LBB0_159:
	v_mov_b32_e32 v78, v133
	s_lshl_b32 s22, s2, 8
	v_ashrrev_i32_e32 v6, 6, v78
	v_bfe_u32 v7, v78, 3, 3
	v_lshl_or_b32 v8, v6, 5, v7
	v_add_u32_e32 v0, s22, v8
	s_waitcnt lgkmcnt(0)
	v_ashrrev_i32_e32 v1, 31, v0
	v_lshlrev_b64 v[2:3], 11, v[0:1]
	v_bfe_u32 v1, v78, 4, 2
	v_readlane_b32 s0, v214, 4
	v_xor_b32_e32 v1, v1, v78
	v_readlane_b32 s1, v214, 5
	v_lshlrev_b32_e32 v1, 4, v1
	v_and_b32_e32 v64, 0x70, v1
	v_lshl_add_u64 v[2:3], s[0:1], 0, v[2:3]
	v_or_b32_e32 v1, 8, v8
	v_lshl_add_u64 v[66:67], v[2:3], 0, v[64:65]
	v_add_u32_e32 v2, s22, v1
	v_lshrrev_b32_e32 v1, 1, v1
	v_xor_b32_e32 v1, v1, v78
	v_ashrrev_i32_e32 v3, 31, v2
	v_lshlrev_b32_e32 v1, 4, v1
	v_or_b32_e32 v0, 16, v0
	v_lshlrev_b64 v[2:3], 11, v[2:3]
	v_and_b32_e32 v4, 0x70, v1
	v_ashrrev_i32_e32 v1, 31, v0
	v_lshl_add_u64 v[2:3], s[0:1], 0, v[2:3]
	v_mov_b32_e32 v5, v65
	v_lshlrev_b64 v[0:1], 11, v[0:1]
	v_lshl_add_u64 v[68:69], v[2:3], 0, v[4:5]
	v_lshl_add_u64 v[0:1], s[0:1], 0, v[0:1]
	v_or_b32_e32 v2, 24, v8
	v_lshl_add_u64 v[70:71], v[0:1], 0, v[64:65]
	v_add_u32_e32 v0, s22, v2
	v_lshrrev_b32_e32 v2, 1, v2
	v_ashrrev_i32_e32 v1, 31, v0
	v_xor_b32_e32 v2, v2, v78
	v_lshlrev_b64 v[0:1], 11, v[0:1]
	v_lshlrev_b32_e32 v2, 4, v2
	v_lshl_add_u64 v[0:1], s[0:1], 0, v[0:1]
	v_and_b32_e32 v2, 0x70, v2
	v_mov_b32_e32 v3, v65
	v_lshl_add_u64 v[72:73], v[0:1], 0, v[2:3]
	v_lshl_or_b32 v2, v6, 4, v7
	v_readlane_b32 s31, v214, 58
	v_lshlrev_b32_e32 v3, 12, v6
	v_add_u32_e32 v126, 0, v3
	v_add_u32_e32 v0, s31, v2
	v_ashrrev_i32_e32 v1, 31, v0
	v_lshlrev_b64 v[0:1], 11, v[0:1]
	s_waitcnt vmcnt(0)
	v_readfirstlane_b32 s37, v126
	v_add_u32_e32 v127, 0x400, v126
	v_lshl_add_u64 v[0:1], s[40:41], 0, v[0:1]
	v_or_b32_e32 v2, 8, v2
	s_waitcnt lgkmcnt(0)
	s_barrier
	s_mov_b32 m0, s37
	v_readfirstlane_b32 s38, v127
	v_add_u32_e32 v128, 0x800, v126
	v_lshlrev_b32_e32 v5, 11, v6
	v_and_b32_e32 v80, 1, v6
	v_lshl_add_u64 v[74:75], v[0:1], 0, v[64:65]
	v_add_u32_e32 v0, s31, v2
	v_lshrrev_b32_e32 v2, 1, v2
	global_load_lds_dwordx4 v[66:67], off
	s_mov_b32 m0, s38
	v_readfirstlane_b32 s39, v128
	v_add_u32_e32 v129, 0xc00, v126
	v_add_u32_e32 v6, 0, v5
	v_ashrrev_i32_e32 v1, 31, v0
	v_xor_b32_e32 v2, v2, v78
	global_load_lds_dwordx4 v[68:69], off
	s_mov_b32 m0, s39
	v_readfirstlane_b32 s48, v129
	v_add_u32_e32 v131, 0x8000, v6
	v_lshlrev_b64 v[0:1], 11, v[0:1]
	v_lshlrev_b32_e32 v2, 4, v2
	global_load_lds_dwordx4 v[70:71], off
	s_mov_b32 m0, s48
	v_readfirstlane_b32 s49, v131
	v_add_u32_e32 v130, 0x8400, v6
	v_lshl_add_u64 v[0:1], s[40:41], 0, v[0:1]
	v_and_b32_e32 v64, 0x70, v2
	global_load_lds_dwordx4 v[72:73], off
	s_mov_b32 m0, s49
	v_readfirstlane_b32 s53, v130
	v_add_u32_e32 v120, 0xc000, v126
	v_lshl_add_u64 v[76:77], v[0:1], 0, v[64:65]
	global_load_lds_dwordx4 v[74:75], off
	s_mov_b32 m0, s53
	s_mov_b64 s[0:1], 0x80
	v_readfirstlane_b32 s28, v120
	v_add_u32_e32 v121, 0xc400, v126
	global_load_lds_dwordx4 v[76:77], off
	v_lshl_add_u64 v[0:1], v[66:67], 0, s[0:1]
	s_mov_b32 m0, s28
	v_readfirstlane_b32 s29, v121
	v_add_u32_e32 v122, 0xc800, v126
	global_load_lds_dwordx4 v[0:1], off
	v_lshl_add_u64 v[0:1], v[68:69], 0, s[0:1]
	s_mov_b32 m0, s29
	v_readfirstlane_b32 s33, v122
	v_add_u32_e32 v123, 0xcc00, v126
	global_load_lds_dwordx4 v[0:1], off
	v_lshl_add_u64 v[0:1], v[70:71], 0, s[0:1]
	s_mov_b32 m0, s33
	v_readfirstlane_b32 s34, v123
	v_add_u32_e32 v124, s85, v5
	global_load_lds_dwordx4 v[0:1], off
	v_lshl_add_u64 v[0:1], v[72:73], 0, s[0:1]
	s_mov_b32 m0, s34
	v_readfirstlane_b32 s35, v124
	v_add_u32_e32 v125, 0x14400, v6
	global_load_lds_dwordx4 v[0:1], off
	v_lshl_add_u64 v[0:1], v[74:75], 0, s[0:1]
	s_mov_b32 m0, s35
	v_readfirstlane_b32 s36, v125
	global_load_lds_dwordx4 v[0:1], off
	v_lshl_add_u64 v[0:1], v[76:77], 0, s[0:1]
	s_mov_b32 m0, s36
	v_lshrrev_b32_e32 v2, 1, v78
	v_bfe_u32 v64, v78, 5, 1
	global_load_lds_dwordx4 v[0:1], off
	v_add_u32_e32 v114, s3, v3
	v_bitop3_b32 v0, v2, v64, 7 bitop3:0x6c
	s_waitcnt vmcnt(6)
	s_mov_b64 s[46:47], 0x100
	v_readfirstlane_b32 s0, v114
	v_add_u32_e32 v115, 0x400, v114
	v_lshlrev_b32_e32 v132, 4, v0
	s_waitcnt lgkmcnt(0)
	s_barrier
	v_lshl_add_u64 v[0:1], v[66:67], 0, s[46:47]
	s_mov_b32 m0, s0
	v_readfirstlane_b32 s1, v115
	v_add_u32_e32 v116, 0x800, v114
	global_load_lds_dwordx4 v[0:1], off
	v_lshl_add_u64 v[0:1], v[68:69], 0, s[46:47]
	s_mov_b32 m0, s1
	v_readfirstlane_b32 s20, v116
	v_add_u32_e32 v117, 0xc00, v114
	v_readlane_b32 s23, v212, 31
	v_and_b32_e32 v79, 31, v78
	global_load_lds_dwordx4 v[0:1], off
	v_lshl_add_u64 v[0:1], v[70:71], 0, s[46:47]
	s_mov_b32 m0, s20
	v_readfirstlane_b32 s21, v117
	v_add_u32_e32 v118, s23, v5
	v_add_u32_e32 v2, s3, v5
	v_lshlrev_b32_e32 v4, 7, v79
	global_load_lds_dwordx4 v[0:1], off
	v_lshl_add_u64 v[0:1], v[72:73], 0, s[46:47]
	s_mov_b32 m0, s21
	v_readfirstlane_b32 s23, v118
	v_add_u32_e32 v119, 0x8400, v2
	v_lshl_or_b32 v102, v80, 13, v4
	global_load_lds_dwordx4 v[0:1], off
	v_lshl_add_u64 v[0:1], v[74:75], 0, s[46:47]
	s_mov_b32 m0, s23
	v_readfirstlane_b32 s24, v119
	global_load_lds_dwordx4 v[0:1], off
	v_lshl_add_u64 v[0:1], v[76:77], 0, s[46:47]
	s_mov_b32 m0, s24
	v_add_u32_e32 v100, 0, v102
	global_load_lds_dwordx4 v[0:1], off
	v_add_u32_e32 v83, v100, v132
	v_ashrrev_i32_e32 v81, 7, v78
	ds_read_b128 a[0:3], v83 offset:32768
	ds_read_b128 a[4:7], v83 offset:36864
	v_lshl_or_b32 v134, v81, 13, v4
	v_add_u32_e32 v101, 0, v134
	v_add_u32_e32 v82, v101, v132
	ds_read_b128 a[8:11], v82
	ds_read_b128 a[12:15], v82 offset:4096
	v_lshrrev_b32_e32 v182, 6, v133
	s_nop 0
	v_readfirstlane_b32 s32, v182
	s_waitcnt lgkmcnt(1)
	v_mfma_f32_32x32x16_bf16 v[48:63], a[0:3], a[8:11], 0
	v_bfe_u32 v103, v78, 1, 3
	s_mov_b64 s[46:47], 0x180
	s_add_i32 s30, 0, 0xc000
	v_or_b32_e32 v143, 0x8000, v102
	v_or_b32_e32 v144, 0x9000, v102
	v_add_u32_e32 v145, s3, v134
	s_waitcnt vmcnt(12)
	v_mfma_f32_32x32x16_bf16 v[32:47], a[4:7], a[8:11], 0
	v_lshl_or_b32 v81, v81, 6, v79
	v_mul_lo_u32 v81, v81, s26
	s_mov_b64 s[80:81], 0x200
	s_waitcnt lgkmcnt(0)
	v_mfma_f32_32x32x16_bf16 v[16:31], a[0:3], a[12:15], 0
	v_bitop3_b32 v0, v64, v103, 2 bitop3:0x36
	v_lshlrev_b32_e32 v138, 4, v0
	v_add_u32_e32 v84, v101, v138
	ds_read_b128 a[28:31], v84 offset:4096
	ds_read_b128 a[24:27], v84
	v_add_u32_e32 v85, v100, v138
	ds_read_b128 a[20:23], v85 offset:36864
	ds_read_b128 a[16:19], v85 offset:32768
	v_mfma_f32_32x32x16_bf16 v[0:15], a[4:7], a[12:15], 0
	s_waitcnt lgkmcnt(0)
	v_mfma_f32_32x32x16_bf16 v[48:63], a[16:19], a[24:27], v[48:63]
	v_mfma_f32_32x32x16_bf16 v[32:47], a[20:23], a[24:27], v[32:47]
	v_mfma_f32_32x32x16_bf16 v[16:31], a[16:19], a[28:31], v[16:31]
	v_bitop3_b32 v86, v64, v103, 4 bitop3:0x36
	v_lshlrev_b32_e32 v139, 4, v86
	v_add_u32_e32 v86, v101, v139
	ds_read_b128 a[12:15], v86 offset:4096
	ds_read_b128 a[8:11], v86
	v_add_u32_e32 v87, v100, v139
	ds_read_b128 a[4:7], v87 offset:36864
	ds_read_b128 a[0:3], v87 offset:32768
	v_mfma_f32_32x32x16_bf16 v[0:15], a[20:23], a[28:31], v[0:15]
	s_waitcnt lgkmcnt(0)
	v_mfma_f32_32x32x16_bf16 v[48:63], a[0:3], a[8:11], v[48:63]
	v_mfma_f32_32x32x16_bf16 v[32:47], a[4:7], a[8:11], v[32:47]
	v_mfma_f32_32x32x16_bf16 v[16:31], a[0:3], a[12:15], v[16:31]
	v_bitop3_b32 v88, v64, v103, 6 bitop3:0x36
	v_lshlrev_b32_e32 v142, 4, v88
	v_add_u32_e32 v88, v101, v142
	ds_read_b128 a[28:31], v88 offset:4096
	ds_read_b128 a[24:27], v88
	v_add_u32_e32 v89, v100, v142
	ds_read_b128 a[20:23], v89 offset:36864
	ds_read_b128 a[16:19], v89 offset:32768
	v_lshlrev_b32_e32 v64, 4, v64
	v_lshl_or_b32 v64, v80, 8, v64
	v_add3_u32 v64, 0, v81, v64
	v_mfma_f32_32x32x16_bf16 v[0:15], a[4:7], a[12:15], v[0:15]
	s_waitcnt lgkmcnt(0)
	v_mfma_f32_32x32x16_bf16 v[48:63], a[16:19], a[24:27], v[48:63]
	v_mfma_f32_32x32x16_bf16 v[32:47], a[20:23], a[24:27], v[32:47]
	s_waitcnt vmcnt(6)
	s_waitcnt lgkmcnt(0)
	s_barrier
	ds_read_b128 a[12:15], v82 offset:53248
	ds_read_b128 a[8:11], v82 offset:49152
	v_add_u32_e32 v90, s30, v132
	v_add_u32_e32 v92, v90, v143
	v_add_u32_e32 v90, v90, v144
	ds_read_b128 a[4:7], v90
	ds_read_b128 a[0:3], v92
	v_mfma_f32_32x32x16_bf16 v[16:31], a[16:19], a[28:31], v[16:31]
	v_lshl_add_u64 v[158:159], v[66:67], 0, s[46:47]
	v_lshl_add_u64 v[160:161], v[68:69], 0, s[46:47]
	v_lshl_add_u64 v[162:163], v[70:71], 0, s[46:47]
	v_mfma_f32_32x32x16_bf16 v[0:15], a[20:23], a[28:31], v[0:15]
	s_and_b32 m0, s32, 7
	s_lshl_b32 m0, m0, 12
	s_add_i32 m0, m0, 0x0
	s_nop 0
	global_load_lds_dwordx4 v[158:159], off
	v_lshl_add_u64 v[164:165], v[72:73], 0, s[46:47]
	v_lshl_add_u64 v[166:167], v[74:75], 0, s[46:47]
	v_lshl_add_u64 v[168:169], v[76:77], 0, s[46:47]
	s_mov_b64 s[46:47], 0x200
	v_add_u32_e32 v91, s30, v138
	v_add_u32_e32 v93, v91, v143
	ds_read_b128 a[16:19], v93
	v_add_u32_e32 v91, v91, v144
	ds_read_b128 a[20:23], v91
	ds_read_b128 a[24:27], v84 offset:49152
	ds_read_b128 a[28:31], v84 offset:53248
	s_waitcnt lgkmcnt(4)
	v_mfma_f32_32x32x16_bf16 v[48:63], a[0:3], a[8:11], v[48:63]
	v_mfma_f32_32x32x16_bf16 v[32:47], a[4:7], a[8:11], v[32:47]
	v_mfma_f32_32x32x16_bf16 v[16:31], a[0:3], a[12:15], v[16:31]
	s_and_b32 m0, s32, 7
	s_lshl_b32 m0, m0, 12
	s_add_i32 m0, m0, 0x400
	s_nop 0
	global_load_lds_dwordx4 v[160:161], off
	v_mfma_f32_32x32x16_bf16 v[0:15], a[4:7], a[12:15], v[0:15]
	v_add_u32_e32 v94, s30, v139
	v_add_u32_e32 v95, v94, v143
	ds_read_b128 a[0:3], v95
	v_add_u32_e32 v94, v94, v144
	ds_read_b128 a[4:7], v94
	ds_read_b128 a[8:11], v86 offset:49152
	ds_read_b128 a[12:15], v86 offset:53248
	s_waitcnt lgkmcnt(5)
	v_mfma_f32_32x32x16_bf16 v[48:63], a[16:19], a[24:27], v[48:63]
	v_mfma_f32_32x32x16_bf16 v[32:47], a[20:23], a[24:27], v[32:47]
	s_and_b32 m0, s32, 7
	s_lshl_b32 m0, m0, 12
	s_add_i32 m0, m0, 0x800
	s_nop 0
	global_load_lds_dwordx4 v[162:163], off
	s_waitcnt lgkmcnt(4)
	v_mfma_f32_32x32x16_bf16 v[16:31], a[16:19], a[28:31], v[16:31]
	v_mfma_f32_32x32x16_bf16 v[0:15], a[20:23], a[28:31], v[0:15]
	v_add_u32_e32 v96, s30, v142
	v_add_u32_e32 v97, v96, v143
	ds_read_b128 a[16:19], v97
	v_add_u32_e32 v96, v96, v144
	ds_read_b128 a[20:23], v96
	ds_read_b128 a[24:27], v88 offset:49152
	ds_read_b128 a[28:31], v88 offset:53248
	s_waitcnt lgkmcnt(5)
	v_mfma_f32_32x32x16_bf16 v[48:63], a[0:3], a[8:11], v[48:63]
	s_and_b32 m0, s32, 7
	s_lshl_b32 m0, m0, 12
	s_add_i32 m0, m0, 0xc00
	s_nop 0
	global_load_lds_dwordx4 v[164:165], off
	v_mfma_f32_32x32x16_bf16 v[32:47], a[4:7], a[8:11], v[32:47]
	s_waitcnt lgkmcnt(4)
	v_mfma_f32_32x32x16_bf16 v[16:31], a[0:3], a[12:15], v[16:31]
	v_mfma_f32_32x32x16_bf16 v[0:15], a[4:7], a[12:15], v[0:15]
	s_and_b32 m0, s32, 7
	s_lshl_b32 m0, m0, 11
	s_add_i32 m0, m0, 0x8000
	s_nop 0
	global_load_lds_dwordx4 v[166:167], off
	s_waitcnt lgkmcnt(1)
	v_mfma_f32_32x32x16_bf16 v[48:63], a[16:19], a[24:27], v[48:63]
	v_mfma_f32_32x32x16_bf16 v[32:47], a[20:23], a[24:27], v[32:47]
	s_and_b32 m0, s32, 7
	s_lshl_b32 m0, m0, 11
	s_add_i32 m0, m0, 0x8400
	s_nop 0
	global_load_lds_dwordx4 v[168:169], off
	s_waitcnt vmcnt(6)
	s_waitcnt lgkmcnt(0)
	s_barrier
	v_add_u32_e32 v100, v145, v132
	ds_read_b128 a[8:11], v100
	v_add_u32_e32 v101, s3, v132
	v_add_u32_e32 v99, v101, v144
	ds_read_b128 a[4:7], v99
	v_add_u32_e32 v98, v101, v143
	v_or_b32_e32 v132, 0x1000, v134
	v_add_u32_e32 v101, v101, v132
	ds_read_b128 a[12:15], v101
	ds_read_b128 a[0:3], v98
	v_mfma_f32_32x32x16_bf16 v[16:31], a[16:19], a[28:31], v[16:31]
	v_lshl_add_u64 v[170:171], v[66:67], 0, s[46:47]
	v_lshl_add_u64 v[172:173], v[68:69], 0, s[46:47]
	v_lshl_add_u64 v[174:175], v[70:71], 0, s[46:47]
	v_mfma_f32_32x32x16_bf16 v[0:15], a[20:23], a[28:31], v[0:15]
	s_and_b32 m0, s32, 7
	s_lshl_b32 m0, m0, 12
	s_add_i32 m0, m0, 0xc000
	s_nop 0
	global_load_lds_dwordx4 v[170:171], off
	v_lshl_add_u64 v[176:177], v[72:73], 0, s[46:47]
	v_lshl_add_u64 v[178:179], v[74:75], 0, s[46:47]
	v_lshl_add_u64 v[180:181], v[76:77], 0, s[46:47]
	s_mov_b64 s[46:47], 0x280
	v_add_u32_e32 v105, s3, v138
	v_add_u32_e32 v102, v105, v143
	ds_read_b128 a[16:19], v102
	v_add_u32_e32 v103, v105, v144
	ds_read_b128 a[20:23], v103
	v_add_u32_e32 v104, v145, v138
	ds_read_b128 a[24:27], v104
	v_add_u32_e32 v105, v105, v132
	ds_read_b128 a[28:31], v105
	s_waitcnt lgkmcnt(4)
	v_mfma_f32_32x32x16_bf16 v[48:63], a[0:3], a[8:11], v[48:63]
	v_mfma_f32_32x32x16_bf16 v[32:47], a[4:7], a[8:11], v[32:47]
	v_mfma_f32_32x32x16_bf16 v[16:31], a[0:3], a[12:15], v[16:31]
	s_and_b32 m0, s32, 7
	s_lshl_b32 m0, m0, 12
	s_add_i32 m0, m0, 0xc400
	s_nop 0
	global_load_lds_dwordx4 v[172:173], off
	v_mfma_f32_32x32x16_bf16 v[0:15], a[4:7], a[12:15], v[0:15]
	v_add_u32_e32 v109, s3, v139
	v_add_u32_e32 v106, v109, v143
	ds_read_b128 a[0:3], v106
	v_add_u32_e32 v107, v109, v144
	ds_read_b128 a[4:7], v107
	v_add_u32_e32 v108, v145, v139
	ds_read_b128 a[8:11], v108
	v_add_u32_e32 v109, v109, v132
	ds_read_b128 a[12:15], v109
	s_waitcnt lgkmcnt(5)
	v_mfma_f32_32x32x16_bf16 v[48:63], a[16:19], a[24:27], v[48:63]
	v_mfma_f32_32x32x16_bf16 v[32:47], a[20:23], a[24:27], v[32:47]
	s_and_b32 m0, s32, 7
	s_lshl_b32 m0, m0, 12
	s_add_i32 m0, m0, 0xc800
	s_nop 0
	global_load_lds_dwordx4 v[174:175], off
	s_waitcnt lgkmcnt(4)
	v_mfma_f32_32x32x16_bf16 v[16:31], a[16:19], a[28:31], v[16:31]
	v_mfma_f32_32x32x16_bf16 v[0:15], a[20:23], a[28:31], v[0:15]
	v_add_u32_e32 v113, s3, v142
	v_add_u32_e32 v110, v113, v143
	ds_read_b128 a[16:19], v110
	v_add_u32_e32 v111, v113, v144
	ds_read_b128 a[20:23], v111
	v_add_u32_e32 v112, v145, v142
	ds_read_b128 a[24:27], v112
	v_add_u32_e32 v113, v113, v132
	ds_read_b128 a[28:31], v113
	s_waitcnt lgkmcnt(5)
	v_mfma_f32_32x32x16_bf16 v[48:63], a[0:3], a[8:11], v[48:63]
	s_and_b32 m0, s32, 7
	s_lshl_b32 m0, m0, 12
	s_add_i32 m0, m0, 0xcc00
	s_nop 0
	global_load_lds_dwordx4 v[176:177], off
	v_mfma_f32_32x32x16_bf16 v[32:47], a[4:7], a[8:11], v[32:47]
	s_waitcnt lgkmcnt(4)
	v_mfma_f32_32x32x16_bf16 v[16:31], a[0:3], a[12:15], v[16:31]
	v_mfma_f32_32x32x16_bf16 v[0:15], a[4:7], a[12:15], v[0:15]
	s_and_b32 m0, s32, 7
	s_lshl_b32 m0, m0, 11
	s_add_i32 m0, m0, 0x14000
	s_nop 0
	global_load_lds_dwordx4 v[178:179], off
	s_waitcnt lgkmcnt(1)
	v_mfma_f32_32x32x16_bf16 v[48:63], a[16:19], a[24:27], v[48:63]
	v_mfma_f32_32x32x16_bf16 v[32:47], a[20:23], a[24:27], v[32:47]
	s_and_b32 m0, s32, 7
	s_lshl_b32 m0, m0, 11
	s_add_i32 m0, m0, 0x14400
	s_nop 0
	global_load_lds_dwordx4 v[180:181], off
	s_waitcnt vmcnt(6)
	s_waitcnt lgkmcnt(0)
	s_barrier
	ds_read_b128 a[12:15], v82 offset:4096
	ds_read_b128 a[8:11], v82
	ds_read_b128 a[4:7], v83 offset:36864
	ds_read_b128 a[0:3], v83 offset:32768
	v_mfma_f32_32x32x16_bf16 v[16:31], a[16:19], a[28:31], v[16:31]
	v_lshl_add_u64 v[158:159], v[66:67], 0, s[46:47]
	v_lshl_add_u64 v[160:161], v[68:69], 0, s[46:47]
	v_lshl_add_u64 v[162:163], v[70:71], 0, s[46:47]
	v_mfma_f32_32x32x16_bf16 v[0:15], a[20:23], a[28:31], v[0:15]
	s_and_b32 m0, s32, 7
	s_lshl_b32 m0, m0, 12
	s_add_i32 m0, m0, 0x18000
	s_nop 0
	global_load_lds_dwordx4 v[158:159], off
	v_lshl_add_u64 v[164:165], v[72:73], 0, s[46:47]
	v_lshl_add_u64 v[166:167], v[74:75], 0, s[46:47]
	v_lshl_add_u64 v[168:169], v[76:77], 0, s[46:47]
	s_mov_b64 s[46:47], 0x300
	ds_read_b128 a[16:19], v85 offset:32768
	ds_read_b128 a[20:23], v85 offset:36864
	ds_read_b128 a[24:27], v84
	ds_read_b128 a[28:31], v84 offset:4096
	s_waitcnt lgkmcnt(4)
	v_mfma_f32_32x32x16_bf16 v[48:63], a[0:3], a[8:11], v[48:63]
	v_mfma_f32_32x32x16_bf16 v[32:47], a[4:7], a[8:11], v[32:47]
	v_mfma_f32_32x32x16_bf16 v[16:31], a[0:3], a[12:15], v[16:31]
	s_and_b32 m0, s32, 7
	s_lshl_b32 m0, m0, 12
	s_add_i32 m0, m0, 0x18400
	s_nop 0
	global_load_lds_dwordx4 v[160:161], off
	v_mfma_f32_32x32x16_bf16 v[0:15], a[4:7], a[12:15], v[0:15]
	ds_read_b128 a[0:3], v87 offset:32768
	ds_read_b128 a[4:7], v87 offset:36864
	ds_read_b128 a[8:11], v86
	ds_read_b128 a[12:15], v86 offset:4096
	s_waitcnt lgkmcnt(5)
	v_mfma_f32_32x32x16_bf16 v[48:63], a[16:19], a[24:27], v[48:63]
	v_mfma_f32_32x32x16_bf16 v[32:47], a[20:23], a[24:27], v[32:47]
	s_and_b32 m0, s32, 7
	s_lshl_b32 m0, m0, 12
	s_add_i32 m0, m0, 0x18800
	s_nop 0
	global_load_lds_dwordx4 v[162:163], off
	s_waitcnt lgkmcnt(4)
	v_mfma_f32_32x32x16_bf16 v[16:31], a[16:19], a[28:31], v[16:31]
	v_mfma_f32_32x32x16_bf16 v[0:15], a[20:23], a[28:31], v[0:15]
	ds_read_b128 a[16:19], v89 offset:32768
	ds_read_b128 a[20:23], v89 offset:36864
	ds_read_b128 a[24:27], v88
	ds_read_b128 a[28:31], v88 offset:4096
	s_waitcnt lgkmcnt(5)
	v_mfma_f32_32x32x16_bf16 v[48:63], a[0:3], a[8:11], v[48:63]
	s_and_b32 m0, s32, 7
	s_lshl_b32 m0, m0, 12
	s_add_i32 m0, m0, 0x18c00
	s_nop 0
	global_load_lds_dwordx4 v[164:165], off
	v_mfma_f32_32x32x16_bf16 v[32:47], a[4:7], a[8:11], v[32:47]
	s_waitcnt lgkmcnt(4)
	v_mfma_f32_32x32x16_bf16 v[16:31], a[0:3], a[12:15], v[16:31]
	v_mfma_f32_32x32x16_bf16 v[0:15], a[4:7], a[12:15], v[0:15]
	s_and_b32 m0, s32, 7
	s_lshl_b32 m0, m0, 11
	s_add_i32 m0, m0, 0x20000
	s_nop 0
	global_load_lds_dwordx4 v[166:167], off
	s_waitcnt lgkmcnt(1)
	v_mfma_f32_32x32x16_bf16 v[48:63], a[16:19], a[24:27], v[48:63]
	v_mfma_f32_32x32x16_bf16 v[32:47], a[20:23], a[24:27], v[32:47]
	s_and_b32 m0, s32, 7
	s_lshl_b32 m0, m0, 11
	s_add_i32 m0, m0, 0x20400
	s_nop 0
	global_load_lds_dwordx4 v[168:169], off
	s_waitcnt vmcnt(6)
	s_waitcnt lgkmcnt(0)
	s_barrier
	ds_read_b128 a[12:15], v82 offset:53248
	ds_read_b128 a[8:11], v82 offset:49152
	ds_read_b128 a[4:7], v90
	ds_read_b128 a[0:3], v92
	v_mfma_f32_32x32x16_bf16 v[16:31], a[16:19], a[28:31], v[16:31]
	v_lshl_add_u64 v[170:171], v[66:67], 0, s[46:47]
	v_lshl_add_u64 v[172:173], v[68:69], 0, s[46:47]
	v_lshl_add_u64 v[174:175], v[70:71], 0, s[46:47]
	v_mfma_f32_32x32x16_bf16 v[0:15], a[20:23], a[28:31], v[0:15]
	s_and_b32 m0, s32, 7
	s_lshl_b32 m0, m0, 12
	s_add_i32 m0, m0, 0x0
	s_nop 0
	global_load_lds_dwordx4 v[170:171], off
	v_lshl_add_u64 v[176:177], v[72:73], 0, s[46:47]
	s_mov_b64 s[38:39], 0x380
	v_lshl_add_u64 v[178:179], v[74:75], 0, s[46:47]
	s_nop 0
	v_readfirstlane_b32 s48, v117
	s_nop 0
	v_lshl_add_u64 v[180:181], v[76:77], 0, s[46:47]
	s_nop 0
	s_mov_b64 s[46:47], 0x580
	ds_read_b128 a[16:19], v93
	ds_read_b128 a[20:23], v91
	ds_read_b128 a[24:27], v84 offset:49152
	ds_read_b128 a[28:31], v84 offset:53248
	s_waitcnt lgkmcnt(4)
	v_mfma_f32_32x32x16_bf16 v[48:63], a[0:3], a[8:11], v[48:63]
	s_nop 0
	v_readfirstlane_b32 s49, v118
	v_readfirstlane_b32 s53, v119
	v_mfma_f32_32x32x16_bf16 v[32:47], a[4:7], a[8:11], v[32:47]
	v_mfma_f32_32x32x16_bf16 v[16:31], a[0:3], a[12:15], v[16:31]
	s_and_b32 m0, s32, 7
	s_lshl_b32 m0, m0, 12
	s_add_i32 m0, m0, 0x400
	s_nop 0
	global_load_lds_dwordx4 v[172:173], off
	v_mfma_f32_32x32x16_bf16 v[0:15], a[4:7], a[12:15], v[0:15]
	ds_read_b128 a[0:3], v95
	ds_read_b128 a[4:7], v94
	ds_read_b128 a[8:11], v86 offset:49152
	ds_read_b128 a[12:15], v86 offset:53248
	s_waitcnt lgkmcnt(5)
	v_mfma_f32_32x32x16_bf16 v[48:63], a[16:19], a[24:27], v[48:63]
	v_mfma_f32_32x32x16_bf16 v[32:47], a[20:23], a[24:27], v[32:47]
	s_and_b32 m0, s32, 7
	s_lshl_b32 m0, m0, 12
	s_add_i32 m0, m0, 0x800
	s_nop 0
	global_load_lds_dwordx4 v[174:175], off
	s_waitcnt lgkmcnt(4)
	v_mfma_f32_32x32x16_bf16 v[16:31], a[16:19], a[28:31], v[16:31]
	v_mfma_f32_32x32x16_bf16 v[0:15], a[20:23], a[28:31], v[0:15]
	ds_read_b128 a[16:19], v97
	ds_read_b128 a[20:23], v96
	ds_read_b128 a[24:27], v88 offset:49152
	ds_read_b128 a[28:31], v88 offset:53248
	s_waitcnt lgkmcnt(5)
	v_mfma_f32_32x32x16_bf16 v[48:63], a[0:3], a[8:11], v[48:63]
	s_and_b32 m0, s32, 7
	s_lshl_b32 m0, m0, 12
	s_add_i32 m0, m0, 0xc00
	s_nop 0
	global_load_lds_dwordx4 v[176:177], off
	v_mfma_f32_32x32x16_bf16 v[32:47], a[4:7], a[8:11], v[32:47]
	s_waitcnt lgkmcnt(4)
	v_mfma_f32_32x32x16_bf16 v[16:31], a[0:3], a[12:15], v[16:31]
	v_mfma_f32_32x32x16_bf16 v[0:15], a[4:7], a[12:15], v[0:15]
	s_and_b32 m0, s32, 7
	s_lshl_b32 m0, m0, 11
	s_add_i32 m0, m0, 0x8000
	s_nop 0
	global_load_lds_dwordx4 v[178:179], off
	s_waitcnt lgkmcnt(1)
	v_mfma_f32_32x32x16_bf16 v[48:63], a[16:19], a[24:27], v[48:63]
	v_mfma_f32_32x32x16_bf16 v[32:47], a[20:23], a[24:27], v[32:47]
	s_and_b32 m0, s32, 7
	s_lshl_b32 m0, m0, 11
	s_add_i32 m0, m0, 0x8400
	s_nop 0
	global_load_lds_dwordx4 v[180:181], off
	s_waitcnt vmcnt(6)
	s_waitcnt lgkmcnt(0)
	s_barrier
	ds_read_b128 a[12:15], v101
	ds_read_b128 a[8:11], v100
	ds_read_b128 a[4:7], v99
	ds_read_b128 a[0:3], v98
	v_mfma_f32_32x32x16_bf16 v[16:31], a[16:19], a[28:31], v[16:31]
	v_lshl_add_u64 v[158:159], v[66:67], 0, s[38:39]
	v_lshl_add_u64 v[160:161], v[68:69], 0, s[38:39]
	s_mov_b64 s[28:29], 0x400
	v_lshl_add_u64 v[162:163], v[70:71], 0, s[38:39]
	v_mfma_f32_32x32x16_bf16 v[0:15], a[20:23], a[28:31], v[0:15]
	s_and_b32 m0, s32, 7
	s_lshl_b32 m0, m0, 12
	s_add_i32 m0, m0, 0xc000
	s_nop 0
	global_load_lds_dwordx4 v[158:159], off
	v_lshl_add_u64 v[164:165], v[72:73], 0, s[38:39]
	s_nop 0
	v_readfirstlane_b32 s33, v122
	s_nop 0
	v_lshl_add_u64 v[166:167], v[74:75], 0, s[38:39]
	s_nop 0
	v_readfirstlane_b32 s34, v123
	s_nop 0
	v_lshl_add_u64 v[168:169], v[76:77], 0, s[38:39]
	s_nop 0
	s_mov_b64 s[36:37], 0x500
	ds_read_b128 a[16:19], v102
	ds_read_b128 a[20:23], v103
	ds_read_b128 a[24:27], v104
	ds_read_b128 a[28:31], v105
	s_waitcnt lgkmcnt(4)
	v_mfma_f32_32x32x16_bf16 v[48:63], a[0:3], a[8:11], v[48:63]
	s_nop 0
	v_readfirstlane_b32 s0, v126
	v_readfirstlane_b32 s35, v124
	v_readfirstlane_b32 s38, v115
	v_readfirstlane_b32 s39, v116
	v_mfma_f32_32x32x16_bf16 v[32:47], a[4:7], a[8:11], v[32:47]
	v_mfma_f32_32x32x16_bf16 v[16:31], a[0:3], a[12:15], v[16:31]
	s_and_b32 m0, s32, 7
	s_lshl_b32 m0, m0, 12
	s_add_i32 m0, m0, 0xc400
	s_nop 0
	global_load_lds_dwordx4 v[160:161], off
	v_mfma_f32_32x32x16_bf16 v[0:15], a[4:7], a[12:15], v[0:15]
	ds_read_b128 a[0:3], v106
	ds_read_b128 a[4:7], v107
	ds_read_b128 a[8:11], v108
	ds_read_b128 a[12:15], v109
	s_waitcnt lgkmcnt(5)
	v_mfma_f32_32x32x16_bf16 v[48:63], a[16:19], a[24:27], v[48:63]
	v_mfma_f32_32x32x16_bf16 v[32:47], a[20:23], a[24:27], v[32:47]
	s_and_b32 m0, s32, 7
	s_lshl_b32 m0, m0, 12
	s_add_i32 m0, m0, 0xc800
	s_nop 0
	global_load_lds_dwordx4 v[162:163], off
	s_waitcnt lgkmcnt(4)
	v_mfma_f32_32x32x16_bf16 v[16:31], a[16:19], a[28:31], v[16:31]
	v_mfma_f32_32x32x16_bf16 v[0:15], a[20:23], a[28:31], v[0:15]
	ds_read_b128 a[16:19], v110
	ds_read_b128 a[20:23], v111
	ds_read_b128 a[24:27], v112
	ds_read_b128 a[28:31], v113
	s_waitcnt lgkmcnt(5)
	v_mfma_f32_32x32x16_bf16 v[48:63], a[0:3], a[8:11], v[48:63]
	s_and_b32 m0, s32, 7
	s_lshl_b32 m0, m0, 12
	s_add_i32 m0, m0, 0xcc00
	s_nop 0
	global_load_lds_dwordx4 v[164:165], off
	v_mfma_f32_32x32x16_bf16 v[32:47], a[4:7], a[8:11], v[32:47]
	s_waitcnt lgkmcnt(4)
	v_mfma_f32_32x32x16_bf16 v[16:31], a[0:3], a[12:15], v[16:31]
	v_mfma_f32_32x32x16_bf16 v[0:15], a[4:7], a[12:15], v[0:15]
	s_and_b32 m0, s32, 7
	s_lshl_b32 m0, m0, 11
	s_add_i32 m0, m0, 0x14000
	s_nop 0
	global_load_lds_dwordx4 v[166:167], off
	s_waitcnt lgkmcnt(1)
	v_mfma_f32_32x32x16_bf16 v[48:63], a[16:19], a[24:27], v[48:63]
	v_mfma_f32_32x32x16_bf16 v[32:47], a[20:23], a[24:27], v[32:47]
	s_and_b32 m0, s32, 7
	s_lshl_b32 m0, m0, 11
	s_add_i32 m0, m0, 0x14400
	s_nop 0
	global_load_lds_dwordx4 v[168:169], off
	s_waitcnt vmcnt(6)
	s_waitcnt lgkmcnt(0)
	s_barrier
	ds_read_b128 a[12:15], v82 offset:4096
	ds_read_b128 a[8:11], v82
	ds_read_b128 a[4:7], v83 offset:36864
	ds_read_b128 a[0:3], v83 offset:32768
	v_mfma_f32_32x32x16_bf16 v[16:31], a[16:19], a[28:31], v[16:31]
	v_lshl_add_u64 v[170:171], v[66:67], 0, s[28:29]
	v_lshl_add_u64 v[172:173], v[68:69], 0, s[28:29]
	s_nop 0
	v_readfirstlane_b32 s1, v127
	s_nop 0
	v_lshl_add_u64 v[174:175], v[70:71], 0, s[28:29]
	s_nop 0
	v_mfma_f32_32x32x16_bf16 v[0:15], a[20:23], a[28:31], v[0:15]
	s_and_b32 m0, s32, 7
	s_lshl_b32 m0, m0, 12
	s_add_i32 m0, m0, 0x18000
	s_nop 0
	global_load_lds_dwordx4 v[170:171], off
	v_lshl_add_u64 v[176:177], v[72:73], 0, s[28:29]
	s_nop 0
	v_readfirstlane_b32 s20, v128
	s_nop 0
	v_lshl_add_u64 v[178:179], v[74:75], 0, s[28:29]
	s_nop 0
	v_readfirstlane_b32 s21, v129
	s_nop 0
	v_lshl_add_u64 v[180:181], v[76:77], 0, s[28:29]
	s_nop 0
	s_mov_b64 s[28:29], 0x480
	ds_read_b128 a[16:19], v85 offset:32768
	ds_read_b128 a[20:23], v85 offset:36864
	ds_read_b128 a[24:27], v84
	ds_read_b128 a[28:31], v84 offset:4096
	s_waitcnt lgkmcnt(4)
	v_mfma_f32_32x32x16_bf16 v[48:63], a[0:3], a[8:11], v[48:63]
	s_nop 0
	v_lshl_add_u64 v[162:163], v[70:71], 0, s[28:29]
	v_readfirstlane_b32 s23, v131
	v_readfirstlane_b32 s24, v130
	v_mfma_f32_32x32x16_bf16 v[32:47], a[4:7], a[8:11], v[32:47]
	v_mfma_f32_32x32x16_bf16 v[16:31], a[0:3], a[12:15], v[16:31]
	s_and_b32 m0, s32, 7
	s_lshl_b32 m0, m0, 12
	s_add_i32 m0, m0, 0x18400
	s_nop 0
	global_load_lds_dwordx4 v[172:173], off
	v_mfma_f32_32x32x16_bf16 v[0:15], a[4:7], a[12:15], v[0:15]
	ds_read_b128 a[0:3], v87 offset:32768
	ds_read_b128 a[4:7], v87 offset:36864
	ds_read_b128 a[8:11], v86
	ds_read_b128 a[12:15], v86 offset:4096
	s_waitcnt lgkmcnt(5)
	v_mfma_f32_32x32x16_bf16 v[48:63], a[16:19], a[24:27], v[48:63]
	v_mfma_f32_32x32x16_bf16 v[32:47], a[20:23], a[24:27], v[32:47]
	s_and_b32 m0, s32, 7
	s_lshl_b32 m0, m0, 12
	s_add_i32 m0, m0, 0x18800
	s_nop 0
	global_load_lds_dwordx4 v[174:175], off
	s_waitcnt lgkmcnt(4)
	v_mfma_f32_32x32x16_bf16 v[16:31], a[16:19], a[28:31], v[16:31]
	v_mfma_f32_32x32x16_bf16 v[0:15], a[20:23], a[28:31], v[0:15]
	ds_read_b128 a[16:19], v89 offset:32768
	ds_read_b128 a[20:23], v89 offset:36864
	ds_read_b128 a[24:27], v88
	ds_read_b128 a[28:31], v88 offset:4096
	s_waitcnt lgkmcnt(5)
	v_mfma_f32_32x32x16_bf16 v[48:63], a[0:3], a[8:11], v[48:63]
	s_and_b32 m0, s32, 7
	s_lshl_b32 m0, m0, 12
	s_add_i32 m0, m0, 0x18c00
	s_nop 0
	global_load_lds_dwordx4 v[176:177], off
	v_mfma_f32_32x32x16_bf16 v[32:47], a[4:7], a[8:11], v[32:47]
	s_waitcnt lgkmcnt(4)
	v_mfma_f32_32x32x16_bf16 v[16:31], a[0:3], a[12:15], v[16:31]
	v_mfma_f32_32x32x16_bf16 v[0:15], a[4:7], a[12:15], v[0:15]
	s_and_b32 m0, s32, 7
	s_lshl_b32 m0, m0, 11
	s_add_i32 m0, m0, 0x20000
	s_nop 0
	global_load_lds_dwordx4 v[178:179], off
	s_waitcnt lgkmcnt(1)
	v_mfma_f32_32x32x16_bf16 v[48:63], a[16:19], a[24:27], v[48:63]
	v_mfma_f32_32x32x16_bf16 v[32:47], a[20:23], a[24:27], v[32:47]
	s_and_b32 m0, s32, 7
	s_lshl_b32 m0, m0, 11
	s_add_i32 m0, m0, 0x20400
	s_nop 0
	global_load_lds_dwordx4 v[180:181], off
	s_waitcnt vmcnt(6)
	s_waitcnt lgkmcnt(0)
	s_barrier
	ds_read_b128 a[12:15], v82 offset:53248
	ds_read_b128 a[8:11], v82 offset:49152
	ds_read_b128 a[4:7], v90
	ds_read_b128 a[0:3], v92
	v_mfma_f32_32x32x16_bf16 v[16:31], a[16:19], a[28:31], v[16:31]
	v_lshl_add_u64 v[158:159], v[66:67], 0, s[28:29]
	v_lshl_add_u64 v[160:161], v[68:69], 0, s[28:29]
	v_mfma_f32_32x32x16_bf16 v[0:15], a[20:23], a[28:31], v[0:15]
	s_and_b32 m0, s32, 7
	s_lshl_b32 m0, m0, 12
	s_add_i32 m0, m0, 0x0
	s_nop 0
	global_load_lds_dwordx4 v[158:159], off
	v_lshl_add_u64 v[164:165], v[72:73], 0, s[28:29]
	v_lshl_add_u64 v[166:167], v[74:75], 0, s[28:29]
	v_lshl_add_u64 v[168:169], v[76:77], 0, s[28:29]
	s_nop 0
	v_readfirstlane_b32 s28, v120
	s_nop 0
	s_nop 0
	s_nop 0
	s_nop 0
	ds_read_b128 a[16:19], v93
	ds_read_b128 a[20:23], v91
	ds_read_b128 a[24:27], v84 offset:49152
	ds_read_b128 a[28:31], v84 offset:53248
	s_waitcnt lgkmcnt(4)
	v_mfma_f32_32x32x16_bf16 v[48:63], a[0:3], a[8:11], v[48:63]
	s_nop 0
	v_readfirstlane_b32 s29, v121
	v_lshl_add_u64 v[174:175], v[70:71], 0, s[36:37]
	v_mfma_f32_32x32x16_bf16 v[32:47], a[4:7], a[8:11], v[32:47]
	v_mfma_f32_32x32x16_bf16 v[16:31], a[0:3], a[12:15], v[16:31]
	s_and_b32 m0, s32, 7
	s_lshl_b32 m0, m0, 12
	s_add_i32 m0, m0, 0x400
	s_nop 0
	global_load_lds_dwordx4 v[160:161], off
	v_mfma_f32_32x32x16_bf16 v[0:15], a[4:7], a[12:15], v[0:15]
	ds_read_b128 a[0:3], v95
	ds_read_b128 a[4:7], v94
	ds_read_b128 a[8:11], v86 offset:49152
	ds_read_b128 a[12:15], v86 offset:53248
	s_waitcnt lgkmcnt(5)
	v_mfma_f32_32x32x16_bf16 v[48:63], a[16:19], a[24:27], v[48:63]
	v_mfma_f32_32x32x16_bf16 v[32:47], a[20:23], a[24:27], v[32:47]
	s_and_b32 m0, s32, 7
	s_lshl_b32 m0, m0, 12
	s_add_i32 m0, m0, 0x800
	s_nop 0
	global_load_lds_dwordx4 v[162:163], off
	s_waitcnt lgkmcnt(4)
	v_mfma_f32_32x32x16_bf16 v[16:31], a[16:19], a[28:31], v[16:31]
	v_mfma_f32_32x32x16_bf16 v[0:15], a[20:23], a[28:31], v[0:15]
	ds_read_b128 a[16:19], v97
	ds_read_b128 a[20:23], v96
	ds_read_b128 a[24:27], v88 offset:49152
	ds_read_b128 a[28:31], v88 offset:53248
	s_waitcnt lgkmcnt(5)
	v_mfma_f32_32x32x16_bf16 v[48:63], a[0:3], a[8:11], v[48:63]
	s_and_b32 m0, s32, 7
	s_lshl_b32 m0, m0, 12
	s_add_i32 m0, m0, 0xc00
	s_nop 0
	global_load_lds_dwordx4 v[164:165], off
	v_mfma_f32_32x32x16_bf16 v[32:47], a[4:7], a[8:11], v[32:47]
	s_waitcnt lgkmcnt(4)
	v_mfma_f32_32x32x16_bf16 v[16:31], a[0:3], a[12:15], v[16:31]
	v_mfma_f32_32x32x16_bf16 v[0:15], a[4:7], a[12:15], v[0:15]
	s_and_b32 m0, s32, 7
	s_lshl_b32 m0, m0, 11
	s_add_i32 m0, m0, 0x8000
	s_nop 0
	global_load_lds_dwordx4 v[166:167], off
	s_waitcnt lgkmcnt(1)
	v_mfma_f32_32x32x16_bf16 v[48:63], a[16:19], a[24:27], v[48:63]
	v_mfma_f32_32x32x16_bf16 v[32:47], a[20:23], a[24:27], v[32:47]
	s_and_b32 m0, s32, 7
	s_lshl_b32 m0, m0, 11
	s_add_i32 m0, m0, 0x8400
	s_nop 0
	global_load_lds_dwordx4 v[168:169], off
	s_waitcnt vmcnt(6)
	s_waitcnt lgkmcnt(0)
	s_barrier
	ds_read_b128 a[12:15], v101
	ds_read_b128 a[8:11], v100
	ds_read_b128 a[4:7], v99
	ds_read_b128 a[0:3], v98
	v_mfma_f32_32x32x16_bf16 v[16:31], a[16:19], a[28:31], v[16:31]
	v_lshl_add_u64 v[170:171], v[66:67], 0, s[36:37]
	v_lshl_add_u64 v[172:173], v[68:69], 0, s[36:37]
	v_mfma_f32_32x32x16_bf16 v[0:15], a[20:23], a[28:31], v[0:15]
	s_and_b32 m0, s32, 7
	s_lshl_b32 m0, m0, 12
	s_add_i32 m0, m0, 0xc000
	s_nop 0
	global_load_lds_dwordx4 v[170:171], off
	v_lshl_add_u64 v[176:177], v[72:73], 0, s[36:37]
	v_lshl_add_u64 v[178:179], v[74:75], 0, s[36:37]
	s_nop 0
	v_lshl_add_u64 v[180:181], v[76:77], 0, s[36:37]
	v_readfirstlane_b32 s36, v125
	s_nop 0
	v_readfirstlane_b32 s37, v114
	s_nop 0
	s_nop 0
	s_nop 0
	s_nop 0
	ds_read_b128 a[16:19], v102
	ds_read_b128 a[20:23], v103
	ds_read_b128 a[24:27], v104
	ds_read_b128 a[28:31], v105
	s_waitcnt lgkmcnt(4)
	v_mfma_f32_32x32x16_bf16 v[48:63], a[0:3], a[8:11], v[48:63]
	v_lshl_add_u64 v[162:163], v[70:71], 0, s[46:47]
	v_mfma_f32_32x32x16_bf16 v[32:47], a[4:7], a[8:11], v[32:47]
	v_mfma_f32_32x32x16_bf16 v[16:31], a[0:3], a[12:15], v[16:31]
	s_and_b32 m0, s32, 7
	s_lshl_b32 m0, m0, 12
	s_add_i32 m0, m0, 0xc400
	s_nop 0
	global_load_lds_dwordx4 v[172:173], off
	v_mfma_f32_32x32x16_bf16 v[0:15], a[4:7], a[12:15], v[0:15]
	ds_read_b128 a[0:3], v106
	ds_read_b128 a[4:7], v107
	ds_read_b128 a[8:11], v108
	ds_read_b128 a[12:15], v109
	s_waitcnt lgkmcnt(5)
	v_mfma_f32_32x32x16_bf16 v[48:63], a[16:19], a[24:27], v[48:63]
	v_mfma_f32_32x32x16_bf16 v[32:47], a[20:23], a[24:27], v[32:47]
	s_and_b32 m0, s32, 7
	s_lshl_b32 m0, m0, 12
	s_add_i32 m0, m0, 0xc800
	s_nop 0
	global_load_lds_dwordx4 v[174:175], off
	s_waitcnt lgkmcnt(4)
	v_mfma_f32_32x32x16_bf16 v[16:31], a[16:19], a[28:31], v[16:31]
	v_mfma_f32_32x32x16_bf16 v[0:15], a[20:23], a[28:31], v[0:15]
	ds_read_b128 a[16:19], v110
	ds_read_b128 a[20:23], v111
	ds_read_b128 a[24:27], v112
	ds_read_b128 a[28:31], v113
	s_waitcnt lgkmcnt(5)
	v_mfma_f32_32x32x16_bf16 v[48:63], a[0:3], a[8:11], v[48:63]
	s_and_b32 m0, s32, 7
	s_lshl_b32 m0, m0, 12
	s_add_i32 m0, m0, 0xcc00
	s_nop 0
	global_load_lds_dwordx4 v[176:177], off
	v_mfma_f32_32x32x16_bf16 v[32:47], a[4:7], a[8:11], v[32:47]
	s_waitcnt lgkmcnt(4)
	v_mfma_f32_32x32x16_bf16 v[16:31], a[0:3], a[12:15], v[16:31]
	v_mfma_f32_32x32x16_bf16 v[0:15], a[4:7], a[12:15], v[0:15]
	s_and_b32 m0, s32, 7
	s_lshl_b32 m0, m0, 11
	s_add_i32 m0, m0, 0x14000
	s_nop 0
	global_load_lds_dwordx4 v[178:179], off
	s_waitcnt lgkmcnt(1)
	v_mfma_f32_32x32x16_bf16 v[48:63], a[16:19], a[24:27], v[48:63]
	v_mfma_f32_32x32x16_bf16 v[32:47], a[20:23], a[24:27], v[32:47]
	s_and_b32 m0, s32, 7
	s_lshl_b32 m0, m0, 11
	s_add_i32 m0, m0, 0x14400
	s_nop 0
	global_load_lds_dwordx4 v[180:181], off
	s_waitcnt vmcnt(6)
	s_waitcnt lgkmcnt(0)
	s_barrier
	ds_read_b128 a[12:15], v82 offset:4096
	ds_read_b128 a[8:11], v82
	ds_read_b128 a[4:7], v83 offset:36864
	ds_read_b128 a[0:3], v83 offset:32768
	v_mfma_f32_32x32x16_bf16 v[16:31], a[16:19], a[28:31], v[16:31]
	v_lshl_add_u64 v[158:159], v[66:67], 0, s[46:47]
	v_lshl_add_u64 v[160:161], v[68:69], 0, s[46:47]
	v_mfma_f32_32x32x16_bf16 v[0:15], a[20:23], a[28:31], v[0:15]
	s_and_b32 m0, s32, 7
	s_lshl_b32 m0, m0, 12
	s_add_i32 m0, m0, 0x18000
	s_nop 0
	global_load_lds_dwordx4 v[158:159], off
	v_lshl_add_u64 v[164:165], v[72:73], 0, s[46:47]
	v_lshl_add_u64 v[166:167], v[74:75], 0, s[46:47]
	v_lshl_add_u64 v[168:169], v[76:77], 0, s[46:47]
	s_mov_b64 s[46:47], 0x600
	ds_read_b128 a[16:19], v85 offset:32768
	ds_read_b128 a[20:23], v85 offset:36864
	ds_read_b128 a[24:27], v84
	ds_read_b128 a[28:31], v84 offset:4096
	s_waitcnt lgkmcnt(4)
	v_mfma_f32_32x32x16_bf16 v[48:63], a[0:3], a[8:11], v[48:63]
	v_mfma_f32_32x32x16_bf16 v[32:47], a[4:7], a[8:11], v[32:47]
	v_mfma_f32_32x32x16_bf16 v[16:31], a[0:3], a[12:15], v[16:31]
	s_and_b32 m0, s32, 7
	s_lshl_b32 m0, m0, 12
	s_add_i32 m0, m0, 0x18400
	s_nop 0
	global_load_lds_dwordx4 v[160:161], off
	v_mfma_f32_32x32x16_bf16 v[0:15], a[4:7], a[12:15], v[0:15]
	ds_read_b128 a[0:3], v87 offset:32768
	ds_read_b128 a[4:7], v87 offset:36864
	ds_read_b128 a[8:11], v86
	ds_read_b128 a[12:15], v86 offset:4096
	s_waitcnt lgkmcnt(5)
	v_mfma_f32_32x32x16_bf16 v[48:63], a[16:19], a[24:27], v[48:63]
	v_mfma_f32_32x32x16_bf16 v[32:47], a[20:23], a[24:27], v[32:47]
	s_and_b32 m0, s32, 7
	s_lshl_b32 m0, m0, 12
	s_add_i32 m0, m0, 0x18800
	s_nop 0
	global_load_lds_dwordx4 v[162:163], off
	s_waitcnt lgkmcnt(4)
	v_mfma_f32_32x32x16_bf16 v[16:31], a[16:19], a[28:31], v[16:31]
	v_mfma_f32_32x32x16_bf16 v[0:15], a[20:23], a[28:31], v[0:15]
	ds_read_b128 a[16:19], v89 offset:32768
	ds_read_b128 a[20:23], v89 offset:36864
	ds_read_b128 a[24:27], v88
	ds_read_b128 a[28:31], v88 offset:4096
	s_waitcnt lgkmcnt(5)
	v_mfma_f32_32x32x16_bf16 v[48:63], a[0:3], a[8:11], v[48:63]
	s_and_b32 m0, s32, 7
	s_lshl_b32 m0, m0, 12
	s_add_i32 m0, m0, 0x18c00
	s_nop 0
	global_load_lds_dwordx4 v[164:165], off
	v_mfma_f32_32x32x16_bf16 v[32:47], a[4:7], a[8:11], v[32:47]
	s_waitcnt lgkmcnt(4)
	v_mfma_f32_32x32x16_bf16 v[16:31], a[0:3], a[12:15], v[16:31]
	v_mfma_f32_32x32x16_bf16 v[0:15], a[4:7], a[12:15], v[0:15]
	s_and_b32 m0, s32, 7
	s_lshl_b32 m0, m0, 11
	s_add_i32 m0, m0, 0x20000
	s_nop 0
	global_load_lds_dwordx4 v[166:167], off
	s_waitcnt lgkmcnt(1)
	v_mfma_f32_32x32x16_bf16 v[48:63], a[16:19], a[24:27], v[48:63]
	v_mfma_f32_32x32x16_bf16 v[32:47], a[20:23], a[24:27], v[32:47]
	s_and_b32 m0, s32, 7
	s_lshl_b32 m0, m0, 11
	s_add_i32 m0, m0, 0x20400
	s_nop 0
	global_load_lds_dwordx4 v[168:169], off
	s_waitcnt vmcnt(6)
	s_waitcnt lgkmcnt(0)
	s_barrier
	ds_read_b128 a[12:15], v82 offset:53248
	ds_read_b128 a[8:11], v82 offset:49152
	ds_read_b128 a[4:7], v90
	ds_read_b128 a[0:3], v92
	v_mfma_f32_32x32x16_bf16 v[16:31], a[16:19], a[28:31], v[16:31]
	v_lshl_add_u64 v[170:171], v[66:67], 0, s[46:47]
	v_lshl_add_u64 v[172:173], v[68:69], 0, s[46:47]
	v_lshl_add_u64 v[174:175], v[70:71], 0, s[46:47]
	v_mfma_f32_32x32x16_bf16 v[0:15], a[20:23], a[28:31], v[0:15]
	s_and_b32 m0, s32, 7
	s_lshl_b32 m0, m0, 12
	s_add_i32 m0, m0, 0x0
	s_nop 0
	global_load_lds_dwordx4 v[170:171], off
	v_lshl_add_u64 v[176:177], v[72:73], 0, s[46:47]
	v_lshl_add_u64 v[178:179], v[74:75], 0, s[46:47]
	v_lshl_add_u64 v[180:181], v[76:77], 0, s[46:47]
	s_mov_b64 s[46:47], 0x680
	ds_read_b128 a[16:19], v93
	ds_read_b128 a[20:23], v91
	ds_read_b128 a[24:27], v84 offset:49152
	ds_read_b128 a[28:31], v84 offset:53248
	s_waitcnt lgkmcnt(4)
	v_mfma_f32_32x32x16_bf16 v[48:63], a[0:3], a[8:11], v[48:63]
	v_mfma_f32_32x32x16_bf16 v[32:47], a[4:7], a[8:11], v[32:47]
	v_mfma_f32_32x32x16_bf16 v[16:31], a[0:3], a[12:15], v[16:31]
	s_and_b32 m0, s32, 7
	s_lshl_b32 m0, m0, 12
	s_add_i32 m0, m0, 0x400
	s_nop 0
	global_load_lds_dwordx4 v[172:173], off
	v_mfma_f32_32x32x16_bf16 v[0:15], a[4:7], a[12:15], v[0:15]
	ds_read_b128 a[0:3], v95
	ds_read_b128 a[4:7], v94
	ds_read_b128 a[8:11], v86 offset:49152
	ds_read_b128 a[12:15], v86 offset:53248
	s_waitcnt lgkmcnt(5)
	v_mfma_f32_32x32x16_bf16 v[48:63], a[16:19], a[24:27], v[48:63]
	v_mfma_f32_32x32x16_bf16 v[32:47], a[20:23], a[24:27], v[32:47]
	s_and_b32 m0, s32, 7
	s_lshl_b32 m0, m0, 12
	s_add_i32 m0, m0, 0x800
	s_nop 0
	global_load_lds_dwordx4 v[174:175], off
	s_waitcnt lgkmcnt(4)
	v_mfma_f32_32x32x16_bf16 v[16:31], a[16:19], a[28:31], v[16:31]
	v_mfma_f32_32x32x16_bf16 v[0:15], a[20:23], a[28:31], v[0:15]
	ds_read_b128 a[16:19], v97
	ds_read_b128 a[20:23], v96
	ds_read_b128 a[24:27], v88 offset:49152
	ds_read_b128 a[28:31], v88 offset:53248
	s_waitcnt lgkmcnt(5)
	v_mfma_f32_32x32x16_bf16 v[48:63], a[0:3], a[8:11], v[48:63]
	s_and_b32 m0, s32, 7
	s_lshl_b32 m0, m0, 12
	s_add_i32 m0, m0, 0xc00
	s_nop 0
	global_load_lds_dwordx4 v[176:177], off
	v_mfma_f32_32x32x16_bf16 v[32:47], a[4:7], a[8:11], v[32:47]
	s_waitcnt lgkmcnt(4)
	v_mfma_f32_32x32x16_bf16 v[16:31], a[0:3], a[12:15], v[16:31]
	v_mfma_f32_32x32x16_bf16 v[0:15], a[4:7], a[12:15], v[0:15]
	s_and_b32 m0, s32, 7
	s_lshl_b32 m0, m0, 11
	s_add_i32 m0, m0, 0x8000
	s_nop 0
	global_load_lds_dwordx4 v[178:179], off
	s_waitcnt lgkmcnt(1)
	v_mfma_f32_32x32x16_bf16 v[48:63], a[16:19], a[24:27], v[48:63]
	v_mfma_f32_32x32x16_bf16 v[32:47], a[20:23], a[24:27], v[32:47]
	s_and_b32 m0, s32, 7
	s_lshl_b32 m0, m0, 11
	s_add_i32 m0, m0, 0x8400
	s_nop 0
	global_load_lds_dwordx4 v[180:181], off
	s_waitcnt vmcnt(6)
	s_waitcnt lgkmcnt(0)
	s_barrier
	ds_read_b128 a[12:15], v101
	ds_read_b128 a[8:11], v100
	ds_read_b128 a[4:7], v99
	ds_read_b128 a[0:3], v98
	v_mfma_f32_32x32x16_bf16 v[16:31], a[16:19], a[28:31], v[16:31]
	v_lshl_add_u64 v[158:159], v[66:67], 0, s[46:47]
	v_lshl_add_u64 v[160:161], v[68:69], 0, s[46:47]
	s_mov_b64 s[28:29], 0x700
	v_lshl_add_u64 v[162:163], v[70:71], 0, s[46:47]
	v_mfma_f32_32x32x16_bf16 v[0:15], a[20:23], a[28:31], v[0:15]
	s_and_b32 m0, s32, 7
	s_lshl_b32 m0, m0, 12
	s_add_i32 m0, m0, 0xc000
	s_nop 0
	global_load_lds_dwordx4 v[158:159], off
	v_lshl_add_u64 v[164:165], v[72:73], 0, s[46:47]
	v_lshl_add_u64 v[166:167], v[74:75], 0, s[46:47]
	v_lshl_add_u64 v[168:169], v[76:77], 0, s[46:47]
	ds_read_b128 a[16:19], v102
	ds_read_b128 a[20:23], v103
	ds_read_b128 a[24:27], v104
	ds_read_b128 a[28:31], v105
	s_waitcnt lgkmcnt(4)
	v_mfma_f32_32x32x16_bf16 v[48:63], a[0:3], a[8:11], v[48:63]
	v_mfma_f32_32x32x16_bf16 v[32:47], a[4:7], a[8:11], v[32:47]
	v_mfma_f32_32x32x16_bf16 v[16:31], a[0:3], a[12:15], v[16:31]
	s_and_b32 m0, s32, 7
	s_lshl_b32 m0, m0, 12
	s_add_i32 m0, m0, 0xc400
	s_nop 0
	global_load_lds_dwordx4 v[160:161], off
	v_mfma_f32_32x32x16_bf16 v[0:15], a[4:7], a[12:15], v[0:15]
	ds_read_b128 a[0:3], v106
	ds_read_b128 a[4:7], v107
	ds_read_b128 a[8:11], v108
	ds_read_b128 a[12:15], v109
	s_waitcnt lgkmcnt(5)
	v_mfma_f32_32x32x16_bf16 v[48:63], a[16:19], a[24:27], v[48:63]
	v_mfma_f32_32x32x16_bf16 v[32:47], a[20:23], a[24:27], v[32:47]
	s_and_b32 m0, s32, 7
	s_lshl_b32 m0, m0, 12
	s_add_i32 m0, m0, 0xc800
	s_nop 0
	global_load_lds_dwordx4 v[162:163], off
	s_waitcnt lgkmcnt(4)
	v_mfma_f32_32x32x16_bf16 v[16:31], a[16:19], a[28:31], v[16:31]
	v_mfma_f32_32x32x16_bf16 v[0:15], a[20:23], a[28:31], v[0:15]
	ds_read_b128 a[16:19], v110
	ds_read_b128 a[20:23], v111
	ds_read_b128 a[24:27], v112
	ds_read_b128 a[28:31], v113
	s_waitcnt lgkmcnt(5)
	v_mfma_f32_32x32x16_bf16 v[48:63], a[0:3], a[8:11], v[48:63]
	s_and_b32 m0, s32, 7
	s_lshl_b32 m0, m0, 12
	s_add_i32 m0, m0, 0xcc00
	s_nop 0
	global_load_lds_dwordx4 v[164:165], off
	v_mfma_f32_32x32x16_bf16 v[32:47], a[4:7], a[8:11], v[32:47]
	s_waitcnt lgkmcnt(4)
	v_mfma_f32_32x32x16_bf16 v[16:31], a[0:3], a[12:15], v[16:31]
	v_mfma_f32_32x32x16_bf16 v[0:15], a[4:7], a[12:15], v[0:15]
	s_and_b32 m0, s32, 7
	s_lshl_b32 m0, m0, 11
	s_add_i32 m0, m0, 0x14000
	s_nop 0
	global_load_lds_dwordx4 v[166:167], off
	s_waitcnt lgkmcnt(1)
	v_mfma_f32_32x32x16_bf16 v[48:63], a[16:19], a[24:27], v[48:63]
	v_mfma_f32_32x32x16_bf16 v[32:47], a[20:23], a[24:27], v[32:47]
	s_and_b32 m0, s32, 7
	s_lshl_b32 m0, m0, 11
	s_add_i32 m0, m0, 0x14400
	s_nop 0
	global_load_lds_dwordx4 v[168:169], off
	s_waitcnt vmcnt(6)
	s_waitcnt lgkmcnt(0)
	s_barrier
	ds_read_b128 a[12:15], v82 offset:4096
	ds_read_b128 a[8:11], v82
	ds_read_b128 a[4:7], v83 offset:36864
	ds_read_b128 a[0:3], v83 offset:32768
	v_mfma_f32_32x32x16_bf16 v[16:31], a[16:19], a[28:31], v[16:31]
	v_lshl_add_u64 v[170:171], v[66:67], 0, s[28:29]
	v_lshl_add_u64 v[172:173], v[68:69], 0, s[28:29]
	v_lshl_add_u64 v[174:175], v[70:71], 0, s[28:29]
	v_mfma_f32_32x32x16_bf16 v[0:15], a[20:23], a[28:31], v[0:15]
	s_and_b32 m0, s32, 7
	s_lshl_b32 m0, m0, 12
	s_add_i32 m0, m0, 0x18000
	s_nop 0
	global_load_lds_dwordx4 v[170:171], off
	v_lshl_add_u64 v[176:177], v[72:73], 0, s[28:29]
	v_lshl_add_u64 v[178:179], v[74:75], 0, s[28:29]
	v_lshl_add_u64 v[180:181], v[76:77], 0, s[28:29]
	s_mov_b64 s[28:29], 0x780
	ds_read_b128 a[16:19], v85 offset:32768
	ds_read_b128 a[20:23], v85 offset:36864
	ds_read_b128 a[24:27], v84
	ds_read_b128 a[28:31], v84 offset:4096
	s_waitcnt lgkmcnt(4)
	v_mfma_f32_32x32x16_bf16 v[48:63], a[0:3], a[8:11], v[48:63]
	v_lshl_add_u64 v[158:159], v[66:67], 0, s[28:29]
	v_mfma_f32_32x32x16_bf16 v[32:47], a[4:7], a[8:11], v[32:47]
	v_mfma_f32_32x32x16_bf16 v[16:31], a[0:3], a[12:15], v[16:31]
	s_and_b32 m0, s32, 7
	s_lshl_b32 m0, m0, 12
	s_add_i32 m0, m0, 0x18400
	s_nop 0
	global_load_lds_dwordx4 v[172:173], off
	v_mfma_f32_32x32x16_bf16 v[0:15], a[4:7], a[12:15], v[0:15]
	ds_read_b128 a[0:3], v87 offset:32768
	ds_read_b128 a[4:7], v87 offset:36864
	ds_read_b128 a[8:11], v86
	ds_read_b128 a[12:15], v86 offset:4096
	s_waitcnt lgkmcnt(5)
	v_mfma_f32_32x32x16_bf16 v[48:63], a[16:19], a[24:27], v[48:63]
	v_mfma_f32_32x32x16_bf16 v[32:47], a[20:23], a[24:27], v[32:47]
	s_and_b32 m0, s32, 7
	s_lshl_b32 m0, m0, 12
	s_add_i32 m0, m0, 0x18800
	s_nop 0
	global_load_lds_dwordx4 v[174:175], off
	s_waitcnt lgkmcnt(4)
	v_mfma_f32_32x32x16_bf16 v[16:31], a[16:19], a[28:31], v[16:31]
	v_mfma_f32_32x32x16_bf16 v[0:15], a[20:23], a[28:31], v[0:15]
	ds_read_b128 a[16:19], v89 offset:32768
	ds_read_b128 a[20:23], v89 offset:36864
	ds_read_b128 a[24:27], v88
	ds_read_b128 a[28:31], v88 offset:4096
	s_waitcnt lgkmcnt(5)
	v_mfma_f32_32x32x16_bf16 v[48:63], a[0:3], a[8:11], v[48:63]
	s_and_b32 m0, s32, 7
	s_lshl_b32 m0, m0, 12
	s_add_i32 m0, m0, 0x18c00
	s_nop 0
	global_load_lds_dwordx4 v[176:177], off
	v_mfma_f32_32x32x16_bf16 v[32:47], a[4:7], a[8:11], v[32:47]
	s_waitcnt lgkmcnt(4)
	v_mfma_f32_32x32x16_bf16 v[16:31], a[0:3], a[12:15], v[16:31]
	v_mfma_f32_32x32x16_bf16 v[0:15], a[4:7], a[12:15], v[0:15]
	s_and_b32 m0, s32, 7
	s_lshl_b32 m0, m0, 11
	s_add_i32 m0, m0, 0x20000
	s_nop 0
	global_load_lds_dwordx4 v[178:179], off
	s_waitcnt lgkmcnt(1)
	v_mfma_f32_32x32x16_bf16 v[48:63], a[16:19], a[24:27], v[48:63]
	v_mfma_f32_32x32x16_bf16 v[32:47], a[20:23], a[24:27], v[32:47]
	s_and_b32 m0, s32, 7
	s_lshl_b32 m0, m0, 11
	s_add_i32 m0, m0, 0x20400
	s_nop 0
	global_load_lds_dwordx4 v[180:181], off
	s_waitcnt vmcnt(6)
	s_waitcnt lgkmcnt(0)
	s_barrier
	ds_read_b128 a[12:15], v82 offset:53248
	ds_read_b128 a[8:11], v82 offset:49152
	ds_read_b128 a[4:7], v90
	ds_read_b128 a[0:3], v92
	v_lshl_add_u64 v[160:161], v[68:69], 0, s[28:29]
	v_mfma_f32_32x32x16_bf16 v[16:31], a[16:19], a[28:31], v[16:31]
	v_lshl_add_u64 v[162:163], v[70:71], 0, s[28:29]
	v_cmp_eq_u32_e64 s[0:1], 0, v79
	v_lshl_add_u64 v[164:165], v[72:73], 0, s[28:29]
	v_mfma_f32_32x32x16_bf16 v[0:15], a[20:23], a[28:31], v[0:15]
	s_and_b32 m0, s32, 7
	s_lshl_b32 m0, m0, 12
	s_add_i32 m0, m0, 0x0
	s_nop 0
	global_load_lds_dwordx4 v[158:159], off
	v_lshl_add_u64 v[166:167], v[74:75], 0, s[28:29]
	s_nop 0
	v_readlane_b32 s20, v215, 52
	s_nop 0
	v_lshl_add_u64 v[168:169], v[76:77], 0, s[28:29]
	s_nop 0
	v_readlane_b32 s21, v215, 53
	s_nop 0
	s_nop 0
	s_nop 0
	s_nop 0
	ds_read_b128 a[16:19], v93
	ds_read_b128 a[20:23], v91
	ds_read_b128 a[24:27], v84 offset:49152
	ds_read_b128 a[28:31], v84 offset:53248
	s_waitcnt lgkmcnt(4)
	v_mfma_f32_32x32x16_bf16 v[48:63], a[0:3], a[8:11], v[48:63]
	s_mov_b32 s23, 0
	v_mfma_f32_32x32x16_bf16 v[32:47], a[4:7], a[8:11], v[32:47]
	v_mfma_f32_32x32x16_bf16 v[16:31], a[0:3], a[12:15], v[16:31]
	s_and_b32 m0, s32, 7
	s_lshl_b32 m0, m0, 12
	s_add_i32 m0, m0, 0x400
	s_nop 0
	global_load_lds_dwordx4 v[160:161], off
	v_mfma_f32_32x32x16_bf16 v[0:15], a[4:7], a[12:15], v[0:15]
	ds_read_b128 a[0:3], v95
	ds_read_b128 a[4:7], v94
	ds_read_b128 a[8:11], v86 offset:49152
	ds_read_b128 a[12:15], v86 offset:53248
	s_waitcnt lgkmcnt(5)
	v_mfma_f32_32x32x16_bf16 v[48:63], a[16:19], a[24:27], v[48:63]
	v_mfma_f32_32x32x16_bf16 v[32:47], a[20:23], a[24:27], v[32:47]
	s_and_b32 m0, s32, 7
	s_lshl_b32 m0, m0, 12
	s_add_i32 m0, m0, 0x800
	s_nop 0
	global_load_lds_dwordx4 v[162:163], off
	s_waitcnt lgkmcnt(4)
	v_mfma_f32_32x32x16_bf16 v[16:31], a[16:19], a[28:31], v[16:31]
	v_mfma_f32_32x32x16_bf16 v[0:15], a[20:23], a[28:31], v[0:15]
	ds_read_b128 a[16:19], v97
	ds_read_b128 a[20:23], v96
	ds_read_b128 a[24:27], v88 offset:49152
	ds_read_b128 a[28:31], v88 offset:53248
	s_waitcnt lgkmcnt(5)
	v_mfma_f32_32x32x16_bf16 v[48:63], a[0:3], a[8:11], v[48:63]
	s_and_b32 m0, s32, 7
	s_lshl_b32 m0, m0, 12
	s_add_i32 m0, m0, 0xc00
	s_nop 0
	global_load_lds_dwordx4 v[164:165], off
	v_mfma_f32_32x32x16_bf16 v[32:47], a[4:7], a[8:11], v[32:47]
	s_waitcnt lgkmcnt(4)
	v_mfma_f32_32x32x16_bf16 v[16:31], a[0:3], a[12:15], v[16:31]
	v_mfma_f32_32x32x16_bf16 v[0:15], a[4:7], a[12:15], v[0:15]
	s_and_b32 m0, s32, 7
	s_lshl_b32 m0, m0, 11
	s_add_i32 m0, m0, 0x8000
	s_nop 0
	global_load_lds_dwordx4 v[166:167], off
	s_waitcnt lgkmcnt(1)
	v_mfma_f32_32x32x16_bf16 v[48:63], a[16:19], a[24:27], v[48:63]
	v_mfma_f32_32x32x16_bf16 v[32:47], a[20:23], a[24:27], v[32:47]
	s_and_b32 m0, s32, 7
	s_lshl_b32 m0, m0, 11
	s_add_i32 m0, m0, 0x8400
	s_nop 0
	global_load_lds_dwordx4 v[168:169], off
	s_waitcnt vmcnt(6)
	s_waitcnt lgkmcnt(0)
	s_barrier
	ds_read_b128 a[12:15], v101
	ds_read_b128 a[8:11], v100
	ds_read_b128 a[4:7], v99
	ds_read_b128 a[0:3], v98
	v_mfma_f32_32x32x16_bf16 v[16:31], a[16:19], a[28:31], v[16:31]
	v_mfma_f32_32x32x16_bf16 v[0:15], a[20:23], a[28:31], v[0:15]
	ds_read_b128 a[16:19], v102
	ds_read_b128 a[20:23], v103
	ds_read_b128 a[24:27], v104
	ds_read_b128 a[28:31], v105
	s_waitcnt lgkmcnt(4)
	v_mfma_f32_32x32x16_bf16 v[48:63], a[0:3], a[8:11], v[48:63]
	v_mfma_f32_32x32x16_bf16 v[32:47], a[4:7], a[8:11], v[32:47]
	v_mfma_f32_32x32x16_bf16 v[16:31], a[0:3], a[12:15], v[16:31]
	v_mfma_f32_32x32x16_bf16 v[0:15], a[4:7], a[12:15], v[0:15]
	ds_read_b128 a[0:3], v106
	ds_read_b128 a[4:7], v107
	ds_read_b128 a[8:11], v108
	ds_read_b128 a[12:15], v109
	s_waitcnt lgkmcnt(5)
	v_mfma_f32_32x32x16_bf16 v[48:63], a[16:19], a[24:27], v[48:63]
	v_mfma_f32_32x32x16_bf16 v[32:47], a[20:23], a[24:27], v[32:47]
	s_waitcnt lgkmcnt(4)
	v_mfma_f32_32x32x16_bf16 v[16:31], a[16:19], a[28:31], v[16:31]
	v_mfma_f32_32x32x16_bf16 v[0:15], a[20:23], a[28:31], v[0:15]
	ds_read_b128 a[16:19], v110
	ds_read_b128 a[20:23], v111
	ds_read_b128 a[24:27], v112
	ds_read_b128 a[28:31], v113
	s_waitcnt lgkmcnt(5)
	v_mfma_f32_32x32x16_bf16 v[48:63], a[0:3], a[8:11], v[48:63]
	v_mfma_f32_32x32x16_bf16 v[32:47], a[4:7], a[8:11], v[32:47]
	s_waitcnt lgkmcnt(4)
	v_mfma_f32_32x32x16_bf16 v[16:31], a[0:3], a[12:15], v[16:31]
	v_mfma_f32_32x32x16_bf16 v[0:15], a[4:7], a[12:15], v[0:15]
	s_waitcnt lgkmcnt(1)
	v_mfma_f32_32x32x16_bf16 v[48:63], a[16:19], a[24:27], v[48:63]
	v_mfma_f32_32x32x16_bf16 v[32:47], a[20:23], a[24:27], v[32:47]
	s_waitcnt vmcnt(0)
	s_waitcnt lgkmcnt(0)
	s_barrier
	ds_read_b128 a[12:15], v82 offset:4096
	ds_read_b128 a[8:11], v82
	ds_read_b128 a[4:7], v83 offset:36864
	ds_read_b128 a[0:3], v83 offset:32768
	v_mfma_f32_32x32x16_bf16 v[16:31], a[16:19], a[28:31], v[16:31]
	v_mfma_f32_32x32x16_bf16 v[0:15], a[20:23], a[28:31], v[0:15]
	ds_read_b128 a[16:19], v85 offset:32768
	ds_read_b128 a[20:23], v85 offset:36864
	ds_read_b128 a[24:27], v84
	ds_read_b128 a[28:31], v84 offset:4096
	s_waitcnt lgkmcnt(4)
	v_mfma_f32_32x32x16_bf16 v[48:63], a[0:3], a[8:11], v[48:63]
	v_mfma_f32_32x32x16_bf16 v[32:47], a[4:7], a[8:11], v[32:47]
	v_mfma_f32_32x32x16_bf16 v[16:31], a[0:3], a[12:15], v[16:31]
	v_mfma_f32_32x32x16_bf16 v[0:15], a[4:7], a[12:15], v[0:15]
	ds_read_b128 a[0:3], v87 offset:32768
	ds_read_b128 a[4:7], v87 offset:36864
	ds_read_b128 a[8:11], v86
	ds_read_b128 a[12:15], v86 offset:4096
	s_waitcnt lgkmcnt(5)
	v_mfma_f32_32x32x16_bf16 v[48:63], a[16:19], a[24:27], v[48:63]
	v_mfma_f32_32x32x16_bf16 v[32:47], a[20:23], a[24:27], v[32:47]
	s_waitcnt lgkmcnt(4)
	v_mfma_f32_32x32x16_bf16 v[16:31], a[16:19], a[28:31], v[16:31]
	v_mfma_f32_32x32x16_bf16 v[0:15], a[20:23], a[28:31], v[0:15]
	s_waitcnt lgkmcnt(1)
	v_mfma_f32_32x32x16_bf16 v[48:63], a[0:3], a[8:11], v[48:63]
	v_mfma_f32_32x32x16_bf16 v[32:47], a[4:7], a[8:11], v[32:47]
	s_waitcnt lgkmcnt(0)
	v_mfma_f32_32x32x16_bf16 v[0:15], a[4:7], a[12:15], v[0:15]
	v_mfma_f32_32x32x16_bf16 v[16:31], a[0:3], a[12:15], v[16:31]
	ds_read_b128 v[66:69], v89 offset:32768
	ds_read_b128 v[70:73], v88
	ds_read_b128 v[74:77], v89 offset:36864
	ds_read_b128 v[82:85], v88 offset:4096
	s_waitcnt lgkmcnt(0)
	s_barrier
	s_waitcnt lgkmcnt(0)
	v_mfma_f32_32x32x16_bf16 v[48:63], v[66:69], v[70:73], v[48:63]
	v_mfma_f32_32x32x16_bf16 v[32:47], v[74:77], v[70:73], v[32:47]
	s_nop 10
	ds_write_b128 v64, v[48:51]
	ds_write_b128 v64, v[52:55] offset:32
	ds_write_b128 v64, v[56:59] offset:64
	ds_write_b128 v64, v[60:63] offset:96
	ds_write_b128 v64, v[32:35] offset:128
	v_mfma_f32_32x32x16_bf16 v[0:15], v[74:77], v[82:85], v[0:15]
	v_mfma_f32_32x32x16_bf16 v[16:31], v[66:69], v[82:85], v[16:31]
	ds_write_b128 v64, v[36:39] offset:160
	ds_write_b128 v64, v[40:43] offset:192
	ds_write_b128 v64, v[44:47] offset:224
	s_nop 8
	ds_write_b128 v64, v[16:19] offset:16896
	ds_write_b128 v64, v[20:23] offset:16928
	ds_write_b128 v64, v[24:27] offset:16960
	ds_write_b128 v64, v[28:31] offset:16992
	ds_write_b128 v64, v[0:3] offset:17024
	ds_write_b128 v64, v[4:7] offset:17056
	ds_write_b128 v64, v[8:11] offset:17088
	ds_write_b128 v64, v[12:15] offset:17120
	s_waitcnt lgkmcnt(0)
	s_barrier
	v_lshl_or_b32 v0, v79, 2, s31
	v_ashrrev_i32_e32 v1, 31, v0
	v_lshl_add_u32 v4, v79, 4, 0
	v_lshl_add_u64 v[6:7], v[0:1], 2, s[92:93]
	v_lshl_add_u64 v[8:9], v[0:1], 1, s[20:21]
	s_branch .LBB0_161

.LBB0_585:
	s_and_b64 vcc, exec, s[0:1]
	s_cbranch_vccz .LBB0_518
	s_mul_hi_i32 s0, s33, 0x51eb851f
	s_lshr_b32 s1, s0, 31
	s_ashr_i32 s0, s0, 3
	v_mov_b32_e32 v78, v133
	s_add_i32 s21, s0, s1
	s_lshl_b32 s20, s21, 8
	v_ashrrev_i32_e32 v6, 6, v78
	v_bfe_u32 v7, v78, 3, 3
	v_lshl_or_b32 v8, v6, 5, v7
	v_add_u32_e32 v0, s20, v8
	s_waitcnt lgkmcnt(0)
	v_ashrrev_i32_e32 v1, 31, v0
	v_lshlrev_b64 v[2:3], 11, v[0:1]
	v_bfe_u32 v1, v78, 4, 2
	v_readlane_b32 s0, v215, 52
	v_xor_b32_e32 v1, v1, v78
	v_readlane_b32 s1, v215, 53
	v_lshlrev_b32_e32 v1, 4, v1
	v_and_b32_e32 v64, 0x70, v1
	v_lshl_add_u64 v[2:3], s[0:1], 0, v[2:3]
	v_or_b32_e32 v1, 8, v8
	v_lshl_add_u64 v[66:67], v[2:3], 0, v[64:65]
	v_add_u32_e32 v2, s20, v1
	v_lshrrev_b32_e32 v1, 1, v1
	v_xor_b32_e32 v1, v1, v78
	v_ashrrev_i32_e32 v3, 31, v2
	v_lshlrev_b32_e32 v1, 4, v1
	v_or_b32_e32 v0, 16, v0
	v_lshlrev_b64 v[2:3], 11, v[2:3]
	v_and_b32_e32 v4, 0x70, v1
	v_ashrrev_i32_e32 v1, 31, v0
	v_lshl_add_u64 v[2:3], s[0:1], 0, v[2:3]
	v_mov_b32_e32 v5, v65
	v_lshlrev_b64 v[0:1], 11, v[0:1]
	v_lshl_add_u64 v[68:69], v[2:3], 0, v[4:5]
	v_lshl_add_u64 v[0:1], s[0:1], 0, v[0:1]
	v_or_b32_e32 v2, 24, v8
	v_lshl_add_u64 v[70:71], v[0:1], 0, v[64:65]
	v_add_u32_e32 v0, s20, v2
	v_lshrrev_b32_e32 v2, 1, v2
	v_ashrrev_i32_e32 v1, 31, v0
	v_xor_b32_e32 v2, v2, v78
	v_lshlrev_b64 v[0:1], 11, v[0:1]
	v_lshlrev_b32_e32 v2, 4, v2
	v_lshl_add_u64 v[0:1], s[0:1], 0, v[0:1]
	v_and_b32_e32 v2, 0x70, v2
	v_mov_b32_e32 v3, v65
	v_lshl_or_b32 v4, v6, 4, v7
	s_mulk_i32 s21, 0xc80
	v_lshl_add_u64 v[72:73], v[0:1], 0, v[2:3]
	v_subrev_u32_e32 v0, s21, v4
	v_add_u32_e32 v0, s23, v0
	v_ashrrev_i32_e32 v1, 31, v0
	v_lshlrev_b64 v[2:3], 11, v[0:1]
	v_lshl_add_u64 v[2:3], s[96:97], 0, v[2:3]
	v_lshl_add_u64 v[74:75], v[2:3], 0, v[64:65]
	v_lshlrev_b32_e32 v3, 12, v6
	v_add_u32_e32 v126, 0, v3
	s_waitcnt vmcnt(0)
	v_add_u32_e32 v127, 0x400, v126
	v_readfirstlane_b32 s41, v126
	v_or_b32_e32 v2, 8, v4
	s_waitcnt lgkmcnt(0)
	s_barrier
	s_mov_b32 m0, s41
	v_readfirstlane_b32 s42, v127
	v_add_u32_e32 v128, 0x800, v126
	v_lshlrev_b32_e32 v5, 11, v6
	v_and_b32_e32 v79, 1, v6
	v_add_u32_e32 v0, 8, v0
	v_lshrrev_b32_e32 v2, 1, v2
	global_load_lds_dwordx4 v[66:67], off
	s_mov_b32 m0, s42
	v_readfirstlane_b32 s43, v128
	v_add_u32_e32 v129, 0xc00, v126
	v_add_u32_e32 v6, 0, v5
	v_ashrrev_i32_e32 v1, 31, v0
	v_xor_b32_e32 v2, v2, v78
	global_load_lds_dwordx4 v[68:69], off
	s_mov_b32 m0, s43
	v_readfirstlane_b32 s44, v129
	v_add_u32_e32 v131, 0x8000, v6
	v_lshlrev_b64 v[0:1], 11, v[0:1]
	v_lshlrev_b32_e32 v2, 4, v2
	global_load_lds_dwordx4 v[70:71], off
	s_mov_b32 m0, s44
	v_readfirstlane_b32 s45, v131
	v_add_u32_e32 v130, 0x8400, v6
	v_lshl_add_u64 v[0:1], s[96:97], 0, v[0:1]
	v_and_b32_e32 v64, 0x70, v2
	global_load_lds_dwordx4 v[72:73], off
	s_mov_b32 m0, s45
	v_readfirstlane_b32 s46, v130
	v_add_u32_e32 v120, 0xc000, v126
	v_lshl_add_u64 v[76:77], v[0:1], 0, v[64:65]
	global_load_lds_dwordx4 v[74:75], off
	s_mov_b32 m0, s46
	s_mov_b64 s[0:1], 0x80
	v_readfirstlane_b32 s35, v120
	v_add_u32_e32 v121, 0xc400, v126
	global_load_lds_dwordx4 v[76:77], off
	v_lshl_add_u64 v[0:1], v[66:67], 0, s[0:1]
	s_mov_b32 m0, s35
	v_readfirstlane_b32 s36, v121
	v_add_u32_e32 v122, 0xc800, v126
	global_load_lds_dwordx4 v[0:1], off
	v_lshl_add_u64 v[0:1], v[68:69], 0, s[0:1]
	s_mov_b32 m0, s36
	v_readfirstlane_b32 s37, v122
	v_add_u32_e32 v123, 0xcc00, v126
	global_load_lds_dwordx4 v[0:1], off
	v_lshl_add_u64 v[0:1], v[70:71], 0, s[0:1]
	s_mov_b32 m0, s37
	v_readfirstlane_b32 s38, v123
	v_add_u32_e32 v124, s85, v5
	global_load_lds_dwordx4 v[0:1], off
	v_lshl_add_u64 v[0:1], v[72:73], 0, s[0:1]
	s_mov_b32 m0, s38
	v_readfirstlane_b32 s39, v124
	v_add_u32_e32 v125, 0x14400, v6
	global_load_lds_dwordx4 v[0:1], off
	v_lshl_add_u64 v[0:1], v[74:75], 0, s[0:1]
	s_mov_b32 m0, s39
	v_readfirstlane_b32 s40, v125
	global_load_lds_dwordx4 v[0:1], off
	v_lshl_add_u64 v[0:1], v[76:77], 0, s[0:1]
	s_mov_b32 m0, s40
	v_lshrrev_b32_e32 v2, 1, v78
	v_bfe_u32 v64, v78, 5, 1
	global_load_lds_dwordx4 v[0:1], off
	v_add_u32_e32 v114, s3, v3
	v_bitop3_b32 v0, v2, v64, 7 bitop3:0x6c
	s_waitcnt vmcnt(6)
	s_mov_b64 s[30:31], 0x100
	v_readfirstlane_b32 s0, v114
	v_add_u32_e32 v115, 0x400, v114
	v_lshlrev_b32_e32 v132, 4, v0
	s_waitcnt lgkmcnt(0)
	s_barrier
	v_lshl_add_u64 v[0:1], v[66:67], 0, s[30:31]
	s_mov_b32 m0, s0
	v_readfirstlane_b32 s1, v115
	v_add_u32_e32 v116, 0x800, v114
	global_load_lds_dwordx4 v[0:1], off
	v_lshl_add_u64 v[0:1], v[68:69], 0, s[30:31]
	s_mov_b32 m0, s1
	v_readfirstlane_b32 s24, v116
	v_add_u32_e32 v117, 0xc00, v114
	v_readlane_b32 s29, v212, 31
	v_and_b32_e32 v81, 31, v78
	global_load_lds_dwordx4 v[0:1], off
	v_lshl_add_u64 v[0:1], v[70:71], 0, s[30:31]
	s_mov_b32 m0, s24
	v_readfirstlane_b32 s28, v117
	v_add_u32_e32 v118, s29, v5
	v_add_u32_e32 v2, s3, v5
	v_lshlrev_b32_e32 v4, 7, v81
	global_load_lds_dwordx4 v[0:1], off
	v_lshl_add_u64 v[0:1], v[72:73], 0, s[30:31]
	s_mov_b32 m0, s28
	v_readfirstlane_b32 s29, v118
	v_add_u32_e32 v119, 0x8400, v2
	v_lshl_or_b32 v102, v79, 13, v4
	global_load_lds_dwordx4 v[0:1], off
	v_lshl_add_u64 v[0:1], v[74:75], 0, s[30:31]
	s_mov_b32 m0, s29
	v_readfirstlane_b32 s34, v119
	global_load_lds_dwordx4 v[0:1], off
	v_lshl_add_u64 v[0:1], v[76:77], 0, s[30:31]
	s_mov_b32 m0, s34
	v_add_u32_e32 v100, 0, v102
	global_load_lds_dwordx4 v[0:1], off
	v_add_u32_e32 v83, v100, v132
	v_ashrrev_i32_e32 v80, 7, v78
	ds_read_b128 a[0:3], v83 offset:32768
	ds_read_b128 a[4:7], v83 offset:36864
	v_lshl_or_b32 v134, v80, 13, v4
	v_add_u32_e32 v101, 0, v134
	v_add_u32_e32 v82, v101, v132
	ds_read_b128 a[8:11], v82
	ds_read_b128 a[12:15], v82 offset:4096
	v_lshrrev_b32_e32 v182, 6, v133
	s_nop 0
	v_readfirstlane_b32 s32, v182
	s_waitcnt lgkmcnt(1)
	v_mfma_f32_32x32x16_bf16 v[48:63], a[0:3], a[8:11], 0
	v_bfe_u32 v103, v78, 1, 3
	s_mov_b64 s[30:31], 0x180
	v_or_b32_e32 v143, 0x8000, v102
	v_or_b32_e32 v144, 0x9000, v102
	v_add_u32_e32 v145, s3, v134
	s_mov_b64 s[80:81], 0x200
	s_waitcnt vmcnt(12)
	v_mfma_f32_32x32x16_bf16 v[32:47], a[4:7], a[8:11], 0
	s_waitcnt lgkmcnt(0)
	v_mfma_f32_32x32x16_bf16 v[16:31], a[0:3], a[12:15], 0
	v_bitop3_b32 v0, v64, v103, 2 bitop3:0x36
	v_lshlrev_b32_e32 v138, 4, v0
	v_add_u32_e32 v84, v101, v138
	ds_read_b128 a[28:31], v84 offset:4096
	ds_read_b128 a[24:27], v84
	v_add_u32_e32 v85, v100, v138
	ds_read_b128 a[20:23], v85 offset:36864
	ds_read_b128 a[16:19], v85 offset:32768
	v_mfma_f32_32x32x16_bf16 v[0:15], a[4:7], a[12:15], 0
	s_waitcnt lgkmcnt(0)
	v_mfma_f32_32x32x16_bf16 v[48:63], a[16:19], a[24:27], v[48:63]
	v_mfma_f32_32x32x16_bf16 v[32:47], a[20:23], a[24:27], v[32:47]
	v_mfma_f32_32x32x16_bf16 v[16:31], a[16:19], a[28:31], v[16:31]
	v_bitop3_b32 v86, v64, v103, 4 bitop3:0x36
	v_lshlrev_b32_e32 v139, 4, v86
	v_add_u32_e32 v86, v101, v139
	ds_read_b128 a[12:15], v86 offset:4096
	ds_read_b128 a[8:11], v86
	v_add_u32_e32 v87, v100, v139
	ds_read_b128 a[4:7], v87 offset:36864
	ds_read_b128 a[0:3], v87 offset:32768
	v_mfma_f32_32x32x16_bf16 v[0:15], a[20:23], a[28:31], v[0:15]
	s_waitcnt lgkmcnt(0)
	v_mfma_f32_32x32x16_bf16 v[48:63], a[0:3], a[8:11], v[48:63]
	v_mfma_f32_32x32x16_bf16 v[32:47], a[4:7], a[8:11], v[32:47]
	v_mfma_f32_32x32x16_bf16 v[16:31], a[0:3], a[12:15], v[16:31]
	v_bitop3_b32 v88, v64, v103, 6 bitop3:0x36
	v_lshlrev_b32_e32 v142, 4, v88
	v_add_u32_e32 v88, v101, v142
	ds_read_b128 a[28:31], v88 offset:4096
	ds_read_b128 a[24:27], v88
	v_add_u32_e32 v89, v100, v142
	ds_read_b128 a[20:23], v89 offset:36864
	ds_read_b128 a[16:19], v89 offset:32768
	v_mfma_f32_32x32x16_bf16 v[0:15], a[4:7], a[12:15], v[0:15]
	s_waitcnt lgkmcnt(0)
	v_mfma_f32_32x32x16_bf16 v[48:63], a[16:19], a[24:27], v[48:63]
	v_mfma_f32_32x32x16_bf16 v[32:47], a[20:23], a[24:27], v[32:47]
	s_waitcnt vmcnt(6)
	s_waitcnt lgkmcnt(0)
	s_barrier
	ds_read_b128 a[12:15], v82 offset:53248
	ds_read_b128 a[8:11], v82 offset:49152
	v_mfma_f32_32x32x16_bf16 v[16:31], a[16:19], a[28:31], v[16:31]
	v_lshl_add_u64 v[158:159], v[66:67], 0, s[30:31]
	v_lshl_add_u64 v[160:161], v[68:69], 0, s[30:31]
	v_lshl_add_u64 v[162:163], v[70:71], 0, s[30:31]
	v_mfma_f32_32x32x16_bf16 v[0:15], a[20:23], a[28:31], v[0:15]
	s_and_b32 m0, s32, 7
	s_lshl_b32 m0, m0, 12
	s_add_i32 m0, m0, 0x0
	s_nop 0
	global_load_lds_dwordx4 v[158:159], off
	v_lshl_add_u64 v[164:165], v[72:73], 0, s[30:31]
	v_lshl_add_u64 v[166:167], v[74:75], 0, s[30:31]
	v_lshl_add_u64 v[168:169], v[76:77], 0, s[30:31]
	s_add_i32 s30, 0, 0xc000
	v_add_u32_e32 v90, s30, v132
	v_add_u32_e32 v92, v90, v143
	v_add_u32_e32 v90, v90, v144
	ds_read_b128 a[4:7], v90
	ds_read_b128 a[0:3], v92
	v_add_u32_e32 v91, s30, v138
	v_add_u32_e32 v93, v91, v143
	ds_read_b128 a[16:19], v93
	v_add_u32_e32 v91, v91, v144
	ds_read_b128 a[20:23], v91
	ds_read_b128 a[24:27], v84 offset:49152
	ds_read_b128 a[28:31], v84 offset:53248
	s_waitcnt lgkmcnt(4)
	v_mfma_f32_32x32x16_bf16 v[48:63], a[0:3], a[8:11], v[48:63]
	v_mfma_f32_32x32x16_bf16 v[32:47], a[4:7], a[8:11], v[32:47]
	v_mfma_f32_32x32x16_bf16 v[16:31], a[0:3], a[12:15], v[16:31]
	s_and_b32 m0, s32, 7
	s_lshl_b32 m0, m0, 12
	s_add_i32 m0, m0, 0x400
	s_nop 0
	global_load_lds_dwordx4 v[160:161], off
	v_mfma_f32_32x32x16_bf16 v[0:15], a[4:7], a[12:15], v[0:15]
	v_add_u32_e32 v94, s30, v139
	v_add_u32_e32 v95, v94, v143
	ds_read_b128 a[0:3], v95
	v_add_u32_e32 v94, v94, v144
	ds_read_b128 a[4:7], v94
	ds_read_b128 a[8:11], v86 offset:49152
	ds_read_b128 a[12:15], v86 offset:53248
	s_waitcnt lgkmcnt(5)
	v_mfma_f32_32x32x16_bf16 v[48:63], a[16:19], a[24:27], v[48:63]
	v_mfma_f32_32x32x16_bf16 v[32:47], a[20:23], a[24:27], v[32:47]
	s_and_b32 m0, s32, 7
	s_lshl_b32 m0, m0, 12
	s_add_i32 m0, m0, 0x800
	s_nop 0
	global_load_lds_dwordx4 v[162:163], off
	s_waitcnt lgkmcnt(4)
	v_mfma_f32_32x32x16_bf16 v[16:31], a[16:19], a[28:31], v[16:31]
	v_mfma_f32_32x32x16_bf16 v[0:15], a[20:23], a[28:31], v[0:15]
	v_add_u32_e32 v96, s30, v142
	v_add_u32_e32 v97, v96, v143
	ds_read_b128 a[16:19], v97
	v_add_u32_e32 v96, v96, v144
	ds_read_b128 a[20:23], v96
	ds_read_b128 a[24:27], v88 offset:49152
	ds_read_b128 a[28:31], v88 offset:53248
	s_waitcnt lgkmcnt(5)
	v_mfma_f32_32x32x16_bf16 v[48:63], a[0:3], a[8:11], v[48:63]
	s_and_b32 m0, s32, 7
	s_lshl_b32 m0, m0, 12
	s_add_i32 m0, m0, 0xc00
	s_nop 0
	global_load_lds_dwordx4 v[164:165], off
	v_mfma_f32_32x32x16_bf16 v[32:47], a[4:7], a[8:11], v[32:47]
	s_waitcnt lgkmcnt(4)
	v_mfma_f32_32x32x16_bf16 v[16:31], a[0:3], a[12:15], v[16:31]
	s_mov_b64 s[30:31], 0x200
	v_mfma_f32_32x32x16_bf16 v[0:15], a[4:7], a[12:15], v[0:15]
	s_and_b32 m0, s32, 7
	s_lshl_b32 m0, m0, 11
	s_add_i32 m0, m0, 0x8000
	s_nop 0
	global_load_lds_dwordx4 v[166:167], off
	s_waitcnt lgkmcnt(1)
	v_mfma_f32_32x32x16_bf16 v[48:63], a[16:19], a[24:27], v[48:63]
	v_mfma_f32_32x32x16_bf16 v[32:47], a[20:23], a[24:27], v[32:47]
	s_and_b32 m0, s32, 7
	s_lshl_b32 m0, m0, 11
	s_add_i32 m0, m0, 0x8400
	s_nop 0
	global_load_lds_dwordx4 v[168:169], off
	s_waitcnt vmcnt(6)
	s_waitcnt lgkmcnt(0)
	s_barrier
	v_add_u32_e32 v100, v145, v132
	ds_read_b128 a[8:11], v100
	v_add_u32_e32 v101, s3, v132
	v_add_u32_e32 v99, v101, v144
	ds_read_b128 a[4:7], v99
	v_add_u32_e32 v98, v101, v143
	v_or_b32_e32 v132, 0x1000, v134
	v_add_u32_e32 v101, v101, v132
	ds_read_b128 a[12:15], v101
	ds_read_b128 a[0:3], v98
	v_mfma_f32_32x32x16_bf16 v[16:31], a[16:19], a[28:31], v[16:31]
	v_lshl_add_u64 v[170:171], v[66:67], 0, s[30:31]
	v_lshl_add_u64 v[172:173], v[68:69], 0, s[30:31]
	v_lshl_add_u64 v[174:175], v[70:71], 0, s[30:31]
	v_mfma_f32_32x32x16_bf16 v[0:15], a[20:23], a[28:31], v[0:15]
	s_and_b32 m0, s32, 7
	s_lshl_b32 m0, m0, 12
	s_add_i32 m0, m0, 0xc000
	s_nop 0
	global_load_lds_dwordx4 v[170:171], off
	v_lshl_add_u64 v[176:177], v[72:73], 0, s[30:31]
	v_lshl_add_u64 v[178:179], v[74:75], 0, s[30:31]
	v_lshl_add_u64 v[180:181], v[76:77], 0, s[30:31]
	s_mov_b64 s[30:31], 0x280
	v_add_u32_e32 v105, s3, v138
	v_add_u32_e32 v102, v105, v143
	ds_read_b128 a[16:19], v102
	v_add_u32_e32 v103, v105, v144
	ds_read_b128 a[20:23], v103
	v_add_u32_e32 v104, v145, v138
	ds_read_b128 a[24:27], v104
	v_add_u32_e32 v105, v105, v132
	ds_read_b128 a[28:31], v105
	s_waitcnt lgkmcnt(4)
	v_mfma_f32_32x32x16_bf16 v[48:63], a[0:3], a[8:11], v[48:63]
	v_mfma_f32_32x32x16_bf16 v[32:47], a[4:7], a[8:11], v[32:47]
	v_mfma_f32_32x32x16_bf16 v[16:31], a[0:3], a[12:15], v[16:31]
	s_and_b32 m0, s32, 7
	s_lshl_b32 m0, m0, 12
	s_add_i32 m0, m0, 0xc400
	s_nop 0
	global_load_lds_dwordx4 v[172:173], off
	v_mfma_f32_32x32x16_bf16 v[0:15], a[4:7], a[12:15], v[0:15]
	v_add_u32_e32 v109, s3, v139
	v_add_u32_e32 v106, v109, v143
	ds_read_b128 a[0:3], v106
	v_add_u32_e32 v107, v109, v144
	ds_read_b128 a[4:7], v107
	v_add_u32_e32 v108, v145, v139
	ds_read_b128 a[8:11], v108
	v_add_u32_e32 v109, v109, v132
	ds_read_b128 a[12:15], v109
	s_waitcnt lgkmcnt(5)
	v_mfma_f32_32x32x16_bf16 v[48:63], a[16:19], a[24:27], v[48:63]
	v_mfma_f32_32x32x16_bf16 v[32:47], a[20:23], a[24:27], v[32:47]
	s_and_b32 m0, s32, 7
	s_lshl_b32 m0, m0, 12
	s_add_i32 m0, m0, 0xc800
	s_nop 0
	global_load_lds_dwordx4 v[174:175], off
	s_waitcnt lgkmcnt(4)
	v_mfma_f32_32x32x16_bf16 v[16:31], a[16:19], a[28:31], v[16:31]
	v_mfma_f32_32x32x16_bf16 v[0:15], a[20:23], a[28:31], v[0:15]
	v_add_u32_e32 v113, s3, v142
	v_add_u32_e32 v110, v113, v143
	ds_read_b128 a[16:19], v110
	v_add_u32_e32 v111, v113, v144
	ds_read_b128 a[20:23], v111
	v_add_u32_e32 v112, v145, v142
	ds_read_b128 a[24:27], v112
	v_add_u32_e32 v113, v113, v132
	ds_read_b128 a[28:31], v113
	s_waitcnt lgkmcnt(5)
	v_mfma_f32_32x32x16_bf16 v[48:63], a[0:3], a[8:11], v[48:63]
	s_and_b32 m0, s32, 7
	s_lshl_b32 m0, m0, 12
	s_add_i32 m0, m0, 0xcc00
	s_nop 0
	global_load_lds_dwordx4 v[176:177], off
	v_mfma_f32_32x32x16_bf16 v[32:47], a[4:7], a[8:11], v[32:47]
	s_waitcnt lgkmcnt(4)
	v_mfma_f32_32x32x16_bf16 v[16:31], a[0:3], a[12:15], v[16:31]
	v_mfma_f32_32x32x16_bf16 v[0:15], a[4:7], a[12:15], v[0:15]
	s_and_b32 m0, s32, 7
	s_lshl_b32 m0, m0, 11
	s_add_i32 m0, m0, 0x14000
	s_nop 0
	global_load_lds_dwordx4 v[178:179], off
	s_waitcnt lgkmcnt(1)
	v_mfma_f32_32x32x16_bf16 v[48:63], a[16:19], a[24:27], v[48:63]
	v_mfma_f32_32x32x16_bf16 v[32:47], a[20:23], a[24:27], v[32:47]
	s_and_b32 m0, s32, 7
	s_lshl_b32 m0, m0, 11
	s_add_i32 m0, m0, 0x14400
	s_nop 0
	global_load_lds_dwordx4 v[180:181], off
	s_waitcnt vmcnt(6)
	s_waitcnt lgkmcnt(0)
	s_barrier
	ds_read_b128 a[12:15], v82 offset:4096
	ds_read_b128 a[8:11], v82
	ds_read_b128 a[4:7], v83 offset:36864
	ds_read_b128 a[0:3], v83 offset:32768
	v_mfma_f32_32x32x16_bf16 v[16:31], a[16:19], a[28:31], v[16:31]
	v_lshl_add_u64 v[158:159], v[66:67], 0, s[30:31]
	v_lshl_add_u64 v[160:161], v[68:69], 0, s[30:31]
	v_lshl_add_u64 v[162:163], v[70:71], 0, s[30:31]
	v_mfma_f32_32x32x16_bf16 v[0:15], a[20:23], a[28:31], v[0:15]
	s_and_b32 m0, s32, 7
	s_lshl_b32 m0, m0, 12
	s_add_i32 m0, m0, 0x18000
	s_nop 0
	global_load_lds_dwordx4 v[158:159], off
	v_lshl_add_u64 v[164:165], v[72:73], 0, s[30:31]
	v_lshl_add_u64 v[166:167], v[74:75], 0, s[30:31]
	v_lshl_add_u64 v[168:169], v[76:77], 0, s[30:31]
	s_mov_b64 s[30:31], 0x300
	ds_read_b128 a[16:19], v85 offset:32768
	ds_read_b128 a[20:23], v85 offset:36864
	ds_read_b128 a[24:27], v84
	ds_read_b128 a[28:31], v84 offset:4096
	s_waitcnt lgkmcnt(4)
	v_mfma_f32_32x32x16_bf16 v[48:63], a[0:3], a[8:11], v[48:63]
	s_nop 0
	v_readfirstlane_b32 s41, v114
	v_mfma_f32_32x32x16_bf16 v[32:47], a[4:7], a[8:11], v[32:47]
	v_mfma_f32_32x32x16_bf16 v[16:31], a[0:3], a[12:15], v[16:31]
	s_and_b32 m0, s32, 7
	s_lshl_b32 m0, m0, 12
	s_add_i32 m0, m0, 0x18400
	s_nop 0
	global_load_lds_dwordx4 v[160:161], off
	v_mfma_f32_32x32x16_bf16 v[0:15], a[4:7], a[12:15], v[0:15]
	ds_read_b128 a[0:3], v87 offset:32768
	ds_read_b128 a[4:7], v87 offset:36864
	ds_read_b128 a[8:11], v86
	ds_read_b128 a[12:15], v86 offset:4096
	s_waitcnt lgkmcnt(5)
	v_mfma_f32_32x32x16_bf16 v[48:63], a[16:19], a[24:27], v[48:63]
	v_mfma_f32_32x32x16_bf16 v[32:47], a[20:23], a[24:27], v[32:47]
	s_and_b32 m0, s32, 7
	s_lshl_b32 m0, m0, 12
	s_add_i32 m0, m0, 0x18800
	s_nop 0
	global_load_lds_dwordx4 v[162:163], off
	s_waitcnt lgkmcnt(4)
	v_mfma_f32_32x32x16_bf16 v[16:31], a[16:19], a[28:31], v[16:31]
	v_mfma_f32_32x32x16_bf16 v[0:15], a[20:23], a[28:31], v[0:15]
	ds_read_b128 a[16:19], v89 offset:32768
	ds_read_b128 a[20:23], v89 offset:36864
	ds_read_b128 a[24:27], v88
	ds_read_b128 a[28:31], v88 offset:4096
	s_waitcnt lgkmcnt(5)
	v_mfma_f32_32x32x16_bf16 v[48:63], a[0:3], a[8:11], v[48:63]
	s_and_b32 m0, s32, 7
	s_lshl_b32 m0, m0, 12
	s_add_i32 m0, m0, 0x18c00
	s_nop 0
	global_load_lds_dwordx4 v[164:165], off
	v_mfma_f32_32x32x16_bf16 v[32:47], a[4:7], a[8:11], v[32:47]
	s_waitcnt lgkmcnt(4)
	v_mfma_f32_32x32x16_bf16 v[16:31], a[0:3], a[12:15], v[16:31]
	v_mfma_f32_32x32x16_bf16 v[0:15], a[4:7], a[12:15], v[0:15]
	s_and_b32 m0, s32, 7
	s_lshl_b32 m0, m0, 11
	s_add_i32 m0, m0, 0x20000
	s_nop 0
	global_load_lds_dwordx4 v[166:167], off
	s_waitcnt lgkmcnt(1)
	v_mfma_f32_32x32x16_bf16 v[48:63], a[16:19], a[24:27], v[48:63]
	v_mfma_f32_32x32x16_bf16 v[32:47], a[20:23], a[24:27], v[32:47]
	s_and_b32 m0, s32, 7
	s_lshl_b32 m0, m0, 11
	s_add_i32 m0, m0, 0x20400
	s_nop 0
	global_load_lds_dwordx4 v[168:169], off
	s_waitcnt vmcnt(6)
	s_waitcnt lgkmcnt(0)
	s_barrier
	ds_read_b128 a[12:15], v82 offset:53248
	ds_read_b128 a[8:11], v82 offset:49152
	ds_read_b128 a[4:7], v90
	ds_read_b128 a[0:3], v92
	v_mfma_f32_32x32x16_bf16 v[16:31], a[16:19], a[28:31], v[16:31]
	v_lshl_add_u64 v[170:171], v[66:67], 0, s[30:31]
	v_lshl_add_u64 v[172:173], v[68:69], 0, s[30:31]
	s_nop 0
	v_readfirstlane_b32 s42, v115
	s_nop 0
	v_lshl_add_u64 v[174:175], v[70:71], 0, s[30:31]
	s_nop 0
	v_mfma_f32_32x32x16_bf16 v[0:15], a[20:23], a[28:31], v[0:15]
	s_and_b32 m0, s32, 7
	s_lshl_b32 m0, m0, 12
	s_add_i32 m0, m0, 0x0
	s_nop 0
	global_load_lds_dwordx4 v[170:171], off
	v_lshl_add_u64 v[176:177], v[72:73], 0, s[30:31]
	s_nop 0
	v_readfirstlane_b32 s43, v116
	s_nop 0
	v_lshl_add_u64 v[178:179], v[74:75], 0, s[30:31]
	s_nop 0
	v_readfirstlane_b32 s44, v117
	s_nop 0
	v_lshl_add_u64 v[180:181], v[76:77], 0, s[30:31]
	s_nop 0
	s_mov_b64 s[30:31], 0x380
	ds_read_b128 a[16:19], v93
	ds_read_b128 a[20:23], v91
	ds_read_b128 a[24:27], v84 offset:49152
	ds_read_b128 a[28:31], v84 offset:53248
	s_waitcnt lgkmcnt(4)
	v_mfma_f32_32x32x16_bf16 v[48:63], a[0:3], a[8:11], v[48:63]
	s_nop 0
	v_readfirstlane_b32 s35, v120
	v_readfirstlane_b32 s45, v118
	v_readfirstlane_b32 s46, v119
	v_mfma_f32_32x32x16_bf16 v[32:47], a[4:7], a[8:11], v[32:47]
	v_mfma_f32_32x32x16_bf16 v[16:31], a[0:3], a[12:15], v[16:31]
	s_and_b32 m0, s32, 7
	s_lshl_b32 m0, m0, 12
	s_add_i32 m0, m0, 0x400
	s_nop 0
	global_load_lds_dwordx4 v[172:173], off
	v_mfma_f32_32x32x16_bf16 v[0:15], a[4:7], a[12:15], v[0:15]
	ds_read_b128 a[0:3], v95
	ds_read_b128 a[4:7], v94
	ds_read_b128 a[8:11], v86 offset:49152
	ds_read_b128 a[12:15], v86 offset:53248
	s_waitcnt lgkmcnt(5)
	v_mfma_f32_32x32x16_bf16 v[48:63], a[16:19], a[24:27], v[48:63]
	v_mfma_f32_32x32x16_bf16 v[32:47], a[20:23], a[24:27], v[32:47]
	s_and_b32 m0, s32, 7
	s_lshl_b32 m0, m0, 12
	s_add_i32 m0, m0, 0x800
	s_nop 0
	global_load_lds_dwordx4 v[174:175], off
	s_waitcnt lgkmcnt(4)
	v_mfma_f32_32x32x16_bf16 v[16:31], a[16:19], a[28:31], v[16:31]
	v_mfma_f32_32x32x16_bf16 v[0:15], a[20:23], a[28:31], v[0:15]
	ds_read_b128 a[16:19], v97
	ds_read_b128 a[20:23], v96
	ds_read_b128 a[24:27], v88 offset:49152
	ds_read_b128 a[28:31], v88 offset:53248
	s_waitcnt lgkmcnt(5)
	v_mfma_f32_32x32x16_bf16 v[48:63], a[0:3], a[8:11], v[48:63]
	s_and_b32 m0, s32, 7
	s_lshl_b32 m0, m0, 12
	s_add_i32 m0, m0, 0xc00
	s_nop 0
	global_load_lds_dwordx4 v[176:177], off
	v_mfma_f32_32x32x16_bf16 v[32:47], a[4:7], a[8:11], v[32:47]
	s_waitcnt lgkmcnt(4)
	v_mfma_f32_32x32x16_bf16 v[16:31], a[0:3], a[12:15], v[16:31]
	v_mfma_f32_32x32x16_bf16 v[0:15], a[4:7], a[12:15], v[0:15]
	s_and_b32 m0, s32, 7
	s_lshl_b32 m0, m0, 11
	s_add_i32 m0, m0, 0x8000
	s_nop 0
	global_load_lds_dwordx4 v[178:179], off
	s_waitcnt lgkmcnt(1)
	v_mfma_f32_32x32x16_bf16 v[48:63], a[16:19], a[24:27], v[48:63]
	v_mfma_f32_32x32x16_bf16 v[32:47], a[20:23], a[24:27], v[32:47]
	s_and_b32 m0, s32, 7
	s_lshl_b32 m0, m0, 11
	s_add_i32 m0, m0, 0x8400
	s_nop 0
	global_load_lds_dwordx4 v[180:181], off
	s_waitcnt vmcnt(6)
	s_waitcnt lgkmcnt(0)
	s_barrier
	ds_read_b128 a[12:15], v101
	ds_read_b128 a[8:11], v100
	ds_read_b128 a[4:7], v99
	ds_read_b128 a[0:3], v98
	v_mfma_f32_32x32x16_bf16 v[16:31], a[16:19], a[28:31], v[16:31]
	v_lshl_add_u64 v[158:159], v[66:67], 0, s[30:31]
	v_lshl_add_u64 v[160:161], v[68:69], 0, s[30:31]
	s_nop 0
	v_readfirstlane_b32 s36, v121
	s_nop 0
	v_lshl_add_u64 v[162:163], v[70:71], 0, s[30:31]
	s_nop 0
	v_mfma_f32_32x32x16_bf16 v[0:15], a[20:23], a[28:31], v[0:15]
	s_and_b32 m0, s32, 7
	s_lshl_b32 m0, m0, 12
	s_add_i32 m0, m0, 0xc000
	s_nop 0
	global_load_lds_dwordx4 v[158:159], off
	v_lshl_add_u64 v[164:165], v[72:73], 0, s[30:31]
	s_nop 0
	v_readfirstlane_b32 s37, v122
	s_nop 0
	v_lshl_add_u64 v[166:167], v[74:75], 0, s[30:31]
	s_nop 0
	v_readfirstlane_b32 s38, v123
	s_nop 0
	v_lshl_add_u64 v[168:169], v[76:77], 0, s[30:31]
	s_nop 0
	s_mov_b64 s[30:31], 0x400
	ds_read_b128 a[16:19], v102
	ds_read_b128 a[20:23], v103
	ds_read_b128 a[24:27], v104
	ds_read_b128 a[28:31], v105
	s_waitcnt lgkmcnt(4)
	v_mfma_f32_32x32x16_bf16 v[48:63], a[0:3], a[8:11], v[48:63]
	s_nop 0
	v_readfirstlane_b32 s0, v126
	v_readfirstlane_b32 s39, v124
	v_readfirstlane_b32 s40, v125
	v_mfma_f32_32x32x16_bf16 v[32:47], a[4:7], a[8:11], v[32:47]
	v_mfma_f32_32x32x16_bf16 v[16:31], a[0:3], a[12:15], v[16:31]
	s_and_b32 m0, s32, 7
	s_lshl_b32 m0, m0, 12
	s_add_i32 m0, m0, 0xc400
	s_nop 0
	global_load_lds_dwordx4 v[160:161], off
	v_mfma_f32_32x32x16_bf16 v[0:15], a[4:7], a[12:15], v[0:15]
	ds_read_b128 a[0:3], v106
	ds_read_b128 a[4:7], v107
	ds_read_b128 a[8:11], v108
	ds_read_b128 a[12:15], v109
	s_waitcnt lgkmcnt(5)
	v_mfma_f32_32x32x16_bf16 v[48:63], a[16:19], a[24:27], v[48:63]
	v_mfma_f32_32x32x16_bf16 v[32:47], a[20:23], a[24:27], v[32:47]
	s_and_b32 m0, s32, 7
	s_lshl_b32 m0, m0, 12
	s_add_i32 m0, m0, 0xc800
	s_nop 0
	global_load_lds_dwordx4 v[162:163], off
	s_waitcnt lgkmcnt(4)
	v_mfma_f32_32x32x16_bf16 v[16:31], a[16:19], a[28:31], v[16:31]
	v_mfma_f32_32x32x16_bf16 v[0:15], a[20:23], a[28:31], v[0:15]
	ds_read_b128 a[16:19], v110
	ds_read_b128 a[20:23], v111
	ds_read_b128 a[24:27], v112
	ds_read_b128 a[28:31], v113
	s_waitcnt lgkmcnt(5)
	v_mfma_f32_32x32x16_bf16 v[48:63], a[0:3], a[8:11], v[48:63]
	s_and_b32 m0, s32, 7
	s_lshl_b32 m0, m0, 12
	s_add_i32 m0, m0, 0xcc00
	s_nop 0
	global_load_lds_dwordx4 v[164:165], off
	v_mfma_f32_32x32x16_bf16 v[32:47], a[4:7], a[8:11], v[32:47]
	s_waitcnt lgkmcnt(4)
	v_mfma_f32_32x32x16_bf16 v[16:31], a[0:3], a[12:15], v[16:31]
	v_mfma_f32_32x32x16_bf16 v[0:15], a[4:7], a[12:15], v[0:15]
	s_and_b32 m0, s32, 7
	s_lshl_b32 m0, m0, 11
	s_add_i32 m0, m0, 0x14000
	s_nop 0
	global_load_lds_dwordx4 v[166:167], off
	s_waitcnt lgkmcnt(1)
	v_mfma_f32_32x32x16_bf16 v[48:63], a[16:19], a[24:27], v[48:63]
	v_mfma_f32_32x32x16_bf16 v[32:47], a[20:23], a[24:27], v[32:47]
	s_and_b32 m0, s32, 7
	s_lshl_b32 m0, m0, 11
	s_add_i32 m0, m0, 0x14400
	s_nop 0
	global_load_lds_dwordx4 v[168:169], off
	s_waitcnt vmcnt(6)
	s_waitcnt lgkmcnt(0)
	s_barrier
	ds_read_b128 a[12:15], v82 offset:4096
	ds_read_b128 a[8:11], v82
	ds_read_b128 a[4:7], v83 offset:36864
	ds_read_b128 a[0:3], v83 offset:32768
	v_mfma_f32_32x32x16_bf16 v[16:31], a[16:19], a[28:31], v[16:31]
	v_lshl_add_u64 v[170:171], v[66:67], 0, s[30:31]
	v_lshl_add_u64 v[172:173], v[68:69], 0, s[30:31]
	s_nop 0
	v_readfirstlane_b32 s1, v127
	s_nop 0
	v_lshl_add_u64 v[174:175], v[70:71], 0, s[30:31]
	s_nop 0
	v_mfma_f32_32x32x16_bf16 v[0:15], a[20:23], a[28:31], v[0:15]
	s_and_b32 m0, s32, 7
	s_lshl_b32 m0, m0, 12
	s_add_i32 m0, m0, 0x18000
	s_nop 0
	global_load_lds_dwordx4 v[170:171], off
	v_lshl_add_u64 v[176:177], v[72:73], 0, s[30:31]
	s_nop 0
	v_readfirstlane_b32 s24, v128
	s_nop 0
	v_lshl_add_u64 v[178:179], v[74:75], 0, s[30:31]
	s_nop 0
	v_readfirstlane_b32 s28, v129
	s_nop 0
	v_lshl_add_u64 v[180:181], v[76:77], 0, s[30:31]
	s_nop 0
	s_mov_b64 s[30:31], 0x480
	ds_read_b128 a[16:19], v85 offset:32768
	ds_read_b128 a[20:23], v85 offset:36864
	ds_read_b128 a[24:27], v84
	ds_read_b128 a[28:31], v84 offset:4096
	s_waitcnt lgkmcnt(4)
	v_mfma_f32_32x32x16_bf16 v[48:63], a[0:3], a[8:11], v[48:63]
	s_nop 0
	v_lshl_add_u64 v[162:163], v[70:71], 0, s[30:31]
	v_readfirstlane_b32 s29, v131
	v_readfirstlane_b32 s34, v130
	v_mfma_f32_32x32x16_bf16 v[32:47], a[4:7], a[8:11], v[32:47]
	v_mfma_f32_32x32x16_bf16 v[16:31], a[0:3], a[12:15], v[16:31]
	s_and_b32 m0, s32, 7
	s_lshl_b32 m0, m0, 12
	s_add_i32 m0, m0, 0x18400
	s_nop 0
	global_load_lds_dwordx4 v[172:173], off
	v_mfma_f32_32x32x16_bf16 v[0:15], a[4:7], a[12:15], v[0:15]
	ds_read_b128 a[0:3], v87 offset:32768
	ds_read_b128 a[4:7], v87 offset:36864
	ds_read_b128 a[8:11], v86
	ds_read_b128 a[12:15], v86 offset:4096
	s_waitcnt lgkmcnt(5)
	v_mfma_f32_32x32x16_bf16 v[48:63], a[16:19], a[24:27], v[48:63]
	v_mfma_f32_32x32x16_bf16 v[32:47], a[20:23], a[24:27], v[32:47]
	s_and_b32 m0, s32, 7
	s_lshl_b32 m0, m0, 12
	s_add_i32 m0, m0, 0x18800
	s_nop 0
	global_load_lds_dwordx4 v[174:175], off
	s_waitcnt lgkmcnt(4)
	v_mfma_f32_32x32x16_bf16 v[16:31], a[16:19], a[28:31], v[16:31]
	v_mfma_f32_32x32x16_bf16 v[0:15], a[20:23], a[28:31], v[0:15]
	ds_read_b128 a[16:19], v89 offset:32768
	ds_read_b128 a[20:23], v89 offset:36864
	ds_read_b128 a[24:27], v88
	ds_read_b128 a[28:31], v88 offset:4096
	s_waitcnt lgkmcnt(5)
	v_mfma_f32_32x32x16_bf16 v[48:63], a[0:3], a[8:11], v[48:63]
	s_and_b32 m0, s32, 7
	s_lshl_b32 m0, m0, 12
	s_add_i32 m0, m0, 0x18c00
	s_nop 0
	global_load_lds_dwordx4 v[176:177], off
	v_mfma_f32_32x32x16_bf16 v[32:47], a[4:7], a[8:11], v[32:47]
	s_waitcnt lgkmcnt(4)
	v_mfma_f32_32x32x16_bf16 v[16:31], a[0:3], a[12:15], v[16:31]
	v_mfma_f32_32x32x16_bf16 v[0:15], a[4:7], a[12:15], v[0:15]
	s_and_b32 m0, s32, 7
	s_lshl_b32 m0, m0, 11
	s_add_i32 m0, m0, 0x20000
	s_nop 0
	global_load_lds_dwordx4 v[178:179], off
	s_waitcnt lgkmcnt(1)
	v_mfma_f32_32x32x16_bf16 v[48:63], a[16:19], a[24:27], v[48:63]
	v_mfma_f32_32x32x16_bf16 v[32:47], a[20:23], a[24:27], v[32:47]
	s_and_b32 m0, s32, 7
	s_lshl_b32 m0, m0, 11
	s_add_i32 m0, m0, 0x20400
	s_nop 0
	global_load_lds_dwordx4 v[180:181], off
	s_waitcnt vmcnt(6)
	s_waitcnt lgkmcnt(0)
	s_barrier
	ds_read_b128 a[12:15], v82 offset:53248
	ds_read_b128 a[8:11], v82 offset:49152
	ds_read_b128 a[4:7], v90
	ds_read_b128 a[0:3], v92
	v_mfma_f32_32x32x16_bf16 v[16:31], a[16:19], a[28:31], v[16:31]
	v_lshl_add_u64 v[158:159], v[66:67], 0, s[30:31]
	v_lshl_add_u64 v[160:161], v[68:69], 0, s[30:31]
	v_mfma_f32_32x32x16_bf16 v[0:15], a[20:23], a[28:31], v[0:15]
	s_and_b32 m0, s32, 7
	s_lshl_b32 m0, m0, 12
	s_add_i32 m0, m0, 0x0
	s_nop 0
	global_load_lds_dwordx4 v[158:159], off
	v_lshl_add_u64 v[164:165], v[72:73], 0, s[30:31]
	v_lshl_add_u64 v[166:167], v[74:75], 0, s[30:31]
	v_lshl_add_u64 v[168:169], v[76:77], 0, s[30:31]
	s_mov_b64 s[30:31], 0x500
	ds_read_b128 a[16:19], v93
	ds_read_b128 a[20:23], v91
	ds_read_b128 a[24:27], v84 offset:49152
	ds_read_b128 a[28:31], v84 offset:53248
	s_waitcnt lgkmcnt(4)
	v_mfma_f32_32x32x16_bf16 v[48:63], a[0:3], a[8:11], v[48:63]
	v_lshl_add_u64 v[174:175], v[70:71], 0, s[30:31]
	v_mfma_f32_32x32x16_bf16 v[32:47], a[4:7], a[8:11], v[32:47]
	v_mfma_f32_32x32x16_bf16 v[16:31], a[0:3], a[12:15], v[16:31]
	s_and_b32 m0, s32, 7
	s_lshl_b32 m0, m0, 12
	s_add_i32 m0, m0, 0x400
	s_nop 0
	global_load_lds_dwordx4 v[160:161], off
	v_mfma_f32_32x32x16_bf16 v[0:15], a[4:7], a[12:15], v[0:15]
	ds_read_b128 a[0:3], v95
	ds_read_b128 a[4:7], v94
	ds_read_b128 a[8:11], v86 offset:49152
	ds_read_b128 a[12:15], v86 offset:53248
	s_waitcnt lgkmcnt(5)
	v_mfma_f32_32x32x16_bf16 v[48:63], a[16:19], a[24:27], v[48:63]
	v_mfma_f32_32x32x16_bf16 v[32:47], a[20:23], a[24:27], v[32:47]
	s_and_b32 m0, s32, 7
	s_lshl_b32 m0, m0, 12
	s_add_i32 m0, m0, 0x800
	s_nop 0
	global_load_lds_dwordx4 v[162:163], off
	s_waitcnt lgkmcnt(4)
	v_mfma_f32_32x32x16_bf16 v[16:31], a[16:19], a[28:31], v[16:31]
	v_mfma_f32_32x32x16_bf16 v[0:15], a[20:23], a[28:31], v[0:15]
	ds_read_b128 a[16:19], v97
	ds_read_b128 a[20:23], v96
	ds_read_b128 a[24:27], v88 offset:49152
	ds_read_b128 a[28:31], v88 offset:53248
	s_waitcnt lgkmcnt(5)
	v_mfma_f32_32x32x16_bf16 v[48:63], a[0:3], a[8:11], v[48:63]
	s_and_b32 m0, s32, 7
	s_lshl_b32 m0, m0, 12
	s_add_i32 m0, m0, 0xc00
	s_nop 0
	global_load_lds_dwordx4 v[164:165], off
	v_mfma_f32_32x32x16_bf16 v[32:47], a[4:7], a[8:11], v[32:47]
	s_waitcnt lgkmcnt(4)
	v_mfma_f32_32x32x16_bf16 v[16:31], a[0:3], a[12:15], v[16:31]
	v_mfma_f32_32x32x16_bf16 v[0:15], a[4:7], a[12:15], v[0:15]
	s_and_b32 m0, s32, 7
	s_lshl_b32 m0, m0, 11
	s_add_i32 m0, m0, 0x8000
	s_nop 0
	global_load_lds_dwordx4 v[166:167], off
	s_waitcnt lgkmcnt(1)
	v_mfma_f32_32x32x16_bf16 v[48:63], a[16:19], a[24:27], v[48:63]
	v_mfma_f32_32x32x16_bf16 v[32:47], a[20:23], a[24:27], v[32:47]
	s_and_b32 m0, s32, 7
	s_lshl_b32 m0, m0, 11
	s_add_i32 m0, m0, 0x8400
	s_nop 0
	global_load_lds_dwordx4 v[168:169], off
	s_waitcnt vmcnt(6)
	s_waitcnt lgkmcnt(0)
	s_barrier
	ds_read_b128 a[12:15], v101
	ds_read_b128 a[8:11], v100
	ds_read_b128 a[4:7], v99
	ds_read_b128 a[0:3], v98
	v_mfma_f32_32x32x16_bf16 v[16:31], a[16:19], a[28:31], v[16:31]
	v_lshl_add_u64 v[170:171], v[66:67], 0, s[30:31]
	v_lshl_add_u64 v[172:173], v[68:69], 0, s[30:31]
	v_mfma_f32_32x32x16_bf16 v[0:15], a[20:23], a[28:31], v[0:15]
	s_and_b32 m0, s32, 7
	s_lshl_b32 m0, m0, 12
	s_add_i32 m0, m0, 0xc000
	s_nop 0
	global_load_lds_dwordx4 v[170:171], off
	v_lshl_add_u64 v[176:177], v[72:73], 0, s[30:31]
	v_lshl_add_u64 v[178:179], v[74:75], 0, s[30:31]
	v_lshl_add_u64 v[180:181], v[76:77], 0, s[30:31]
	s_mov_b64 s[30:31], 0x580
	ds_read_b128 a[16:19], v102
	ds_read_b128 a[20:23], v103
	ds_read_b128 a[24:27], v104
	ds_read_b128 a[28:31], v105
	s_waitcnt lgkmcnt(4)
	v_mfma_f32_32x32x16_bf16 v[48:63], a[0:3], a[8:11], v[48:63]
	v_lshl_add_u64 v[162:163], v[70:71], 0, s[30:31]
	v_mfma_f32_32x32x16_bf16 v[32:47], a[4:7], a[8:11], v[32:47]
	v_mfma_f32_32x32x16_bf16 v[16:31], a[0:3], a[12:15], v[16:31]
	s_and_b32 m0, s32, 7
	s_lshl_b32 m0, m0, 12
	s_add_i32 m0, m0, 0xc400
	s_nop 0
	global_load_lds_dwordx4 v[172:173], off
	v_mfma_f32_32x32x16_bf16 v[0:15], a[4:7], a[12:15], v[0:15]
	ds_read_b128 a[0:3], v106
	ds_read_b128 a[4:7], v107
	ds_read_b128 a[8:11], v108
	ds_read_b128 a[12:15], v109
	s_waitcnt lgkmcnt(5)
	v_mfma_f32_32x32x16_bf16 v[48:63], a[16:19], a[24:27], v[48:63]
	v_mfma_f32_32x32x16_bf16 v[32:47], a[20:23], a[24:27], v[32:47]
	s_and_b32 m0, s32, 7
	s_lshl_b32 m0, m0, 12
	s_add_i32 m0, m0, 0xc800
	s_nop 0
	global_load_lds_dwordx4 v[174:175], off
	s_waitcnt lgkmcnt(4)
	v_mfma_f32_32x32x16_bf16 v[16:31], a[16:19], a[28:31], v[16:31]
	v_mfma_f32_32x32x16_bf16 v[0:15], a[20:23], a[28:31], v[0:15]
	ds_read_b128 a[16:19], v110
	ds_read_b128 a[20:23], v111
	ds_read_b128 a[24:27], v112
	ds_read_b128 a[28:31], v113
	s_waitcnt lgkmcnt(5)
	v_mfma_f32_32x32x16_bf16 v[48:63], a[0:3], a[8:11], v[48:63]
	s_and_b32 m0, s32, 7
	s_lshl_b32 m0, m0, 12
	s_add_i32 m0, m0, 0xcc00
	s_nop 0
	global_load_lds_dwordx4 v[176:177], off
	v_mfma_f32_32x32x16_bf16 v[32:47], a[4:7], a[8:11], v[32:47]
	s_waitcnt lgkmcnt(4)
	v_mfma_f32_32x32x16_bf16 v[16:31], a[0:3], a[12:15], v[16:31]
	v_mfma_f32_32x32x16_bf16 v[0:15], a[4:7], a[12:15], v[0:15]
	s_and_b32 m0, s32, 7
	s_lshl_b32 m0, m0, 11
	s_add_i32 m0, m0, 0x14000
	s_nop 0
	global_load_lds_dwordx4 v[178:179], off
	s_waitcnt lgkmcnt(1)
	v_mfma_f32_32x32x16_bf16 v[48:63], a[16:19], a[24:27], v[48:63]
	v_mfma_f32_32x32x16_bf16 v[32:47], a[20:23], a[24:27], v[32:47]
	s_and_b32 m0, s32, 7
	s_lshl_b32 m0, m0, 11
	s_add_i32 m0, m0, 0x14400
	s_nop 0
	global_load_lds_dwordx4 v[180:181], off
	s_waitcnt vmcnt(6)
	s_waitcnt lgkmcnt(0)
	s_barrier
	ds_read_b128 a[12:15], v82 offset:4096
	ds_read_b128 a[8:11], v82
	ds_read_b128 a[4:7], v83 offset:36864
	ds_read_b128 a[0:3], v83 offset:32768
	v_mfma_f32_32x32x16_bf16 v[16:31], a[16:19], a[28:31], v[16:31]
	v_lshl_add_u64 v[158:159], v[66:67], 0, s[30:31]
	v_lshl_add_u64 v[160:161], v[68:69], 0, s[30:31]
	v_mfma_f32_32x32x16_bf16 v[0:15], a[20:23], a[28:31], v[0:15]
	s_and_b32 m0, s32, 7
	s_lshl_b32 m0, m0, 12
	s_add_i32 m0, m0, 0x18000
	s_nop 0
	global_load_lds_dwordx4 v[158:159], off
	v_lshl_add_u64 v[164:165], v[72:73], 0, s[30:31]
	v_lshl_add_u64 v[166:167], v[74:75], 0, s[30:31]
	v_lshl_add_u64 v[168:169], v[76:77], 0, s[30:31]
	s_mov_b64 s[30:31], 0x600
	ds_read_b128 a[16:19], v85 offset:32768
	ds_read_b128 a[20:23], v85 offset:36864
	ds_read_b128 a[24:27], v84
	ds_read_b128 a[28:31], v84 offset:4096
	s_waitcnt lgkmcnt(4)
	v_mfma_f32_32x32x16_bf16 v[48:63], a[0:3], a[8:11], v[48:63]
	v_mfma_f32_32x32x16_bf16 v[32:47], a[4:7], a[8:11], v[32:47]
	v_mfma_f32_32x32x16_bf16 v[16:31], a[0:3], a[12:15], v[16:31]
	s_and_b32 m0, s32, 7
	s_lshl_b32 m0, m0, 12
	s_add_i32 m0, m0, 0x18400
	s_nop 0
	global_load_lds_dwordx4 v[160:161], off
	v_mfma_f32_32x32x16_bf16 v[0:15], a[4:7], a[12:15], v[0:15]
	ds_read_b128 a[0:3], v87 offset:32768
	ds_read_b128 a[4:7], v87 offset:36864
	ds_read_b128 a[8:11], v86
	ds_read_b128 a[12:15], v86 offset:4096
	s_waitcnt lgkmcnt(5)
	v_mfma_f32_32x32x16_bf16 v[48:63], a[16:19], a[24:27], v[48:63]
	v_mfma_f32_32x32x16_bf16 v[32:47], a[20:23], a[24:27], v[32:47]
	s_and_b32 m0, s32, 7
	s_lshl_b32 m0, m0, 12
	s_add_i32 m0, m0, 0x18800
	s_nop 0
	global_load_lds_dwordx4 v[162:163], off
	s_waitcnt lgkmcnt(4)
	v_mfma_f32_32x32x16_bf16 v[16:31], a[16:19], a[28:31], v[16:31]
	v_mfma_f32_32x32x16_bf16 v[0:15], a[20:23], a[28:31], v[0:15]
	ds_read_b128 a[16:19], v89 offset:32768
	ds_read_b128 a[20:23], v89 offset:36864
	ds_read_b128 a[24:27], v88
	ds_read_b128 a[28:31], v88 offset:4096
	s_waitcnt lgkmcnt(5)
	v_mfma_f32_32x32x16_bf16 v[48:63], a[0:3], a[8:11], v[48:63]
	s_and_b32 m0, s32, 7
	s_lshl_b32 m0, m0, 12
	s_add_i32 m0, m0, 0x18c00
	s_nop 0
	global_load_lds_dwordx4 v[164:165], off
	v_mfma_f32_32x32x16_bf16 v[32:47], a[4:7], a[8:11], v[32:47]
	s_waitcnt lgkmcnt(4)
	v_mfma_f32_32x32x16_bf16 v[16:31], a[0:3], a[12:15], v[16:31]
	v_mfma_f32_32x32x16_bf16 v[0:15], a[4:7], a[12:15], v[0:15]
	s_and_b32 m0, s32, 7
	s_lshl_b32 m0, m0, 11
	s_add_i32 m0, m0, 0x20000
	s_nop 0
	global_load_lds_dwordx4 v[166:167], off
	s_waitcnt lgkmcnt(1)
	v_mfma_f32_32x32x16_bf16 v[48:63], a[16:19], a[24:27], v[48:63]
	v_mfma_f32_32x32x16_bf16 v[32:47], a[20:23], a[24:27], v[32:47]
	s_and_b32 m0, s32, 7
	s_lshl_b32 m0, m0, 11
	s_add_i32 m0, m0, 0x20400
	s_nop 0
	global_load_lds_dwordx4 v[168:169], off
	s_waitcnt vmcnt(6)
	s_waitcnt lgkmcnt(0)
	s_barrier
	ds_read_b128 a[12:15], v82 offset:53248
	ds_read_b128 a[8:11], v82 offset:49152
	ds_read_b128 a[4:7], v90
	ds_read_b128 a[0:3], v92
	v_mfma_f32_32x32x16_bf16 v[16:31], a[16:19], a[28:31], v[16:31]
	v_lshl_add_u64 v[170:171], v[66:67], 0, s[30:31]
	v_lshl_add_u64 v[172:173], v[68:69], 0, s[30:31]
	v_lshl_add_u64 v[174:175], v[70:71], 0, s[30:31]
	v_mfma_f32_32x32x16_bf16 v[0:15], a[20:23], a[28:31], v[0:15]
	s_and_b32 m0, s32, 7
	s_lshl_b32 m0, m0, 12
	s_add_i32 m0, m0, 0x0
	s_nop 0
	global_load_lds_dwordx4 v[170:171], off
	v_lshl_add_u64 v[176:177], v[72:73], 0, s[30:31]
	v_lshl_add_u64 v[178:179], v[74:75], 0, s[30:31]
	v_lshl_add_u64 v[180:181], v[76:77], 0, s[30:31]
	s_mov_b64 s[30:31], 0x680
	ds_read_b128 a[16:19], v93
	ds_read_b128 a[20:23], v91
	ds_read_b128 a[24:27], v84 offset:49152
	ds_read_b128 a[28:31], v84 offset:53248
	s_waitcnt lgkmcnt(4)
	v_mfma_f32_32x32x16_bf16 v[48:63], a[0:3], a[8:11], v[48:63]
	v_mfma_f32_32x32x16_bf16 v[32:47], a[4:7], a[8:11], v[32:47]
	v_mfma_f32_32x32x16_bf16 v[16:31], a[0:3], a[12:15], v[16:31]
	s_and_b32 m0, s32, 7
	s_lshl_b32 m0, m0, 12
	s_add_i32 m0, m0, 0x400
	s_nop 0
	global_load_lds_dwordx4 v[172:173], off
	v_mfma_f32_32x32x16_bf16 v[0:15], a[4:7], a[12:15], v[0:15]
	ds_read_b128 a[0:3], v95
	ds_read_b128 a[4:7], v94
	ds_read_b128 a[8:11], v86 offset:49152
	ds_read_b128 a[12:15], v86 offset:53248
	s_waitcnt lgkmcnt(5)
	v_mfma_f32_32x32x16_bf16 v[48:63], a[16:19], a[24:27], v[48:63]
	v_mfma_f32_32x32x16_bf16 v[32:47], a[20:23], a[24:27], v[32:47]
	s_and_b32 m0, s32, 7
	s_lshl_b32 m0, m0, 12
	s_add_i32 m0, m0, 0x800
	s_nop 0
	global_load_lds_dwordx4 v[174:175], off
	s_waitcnt lgkmcnt(4)
	v_mfma_f32_32x32x16_bf16 v[16:31], a[16:19], a[28:31], v[16:31]
	v_mfma_f32_32x32x16_bf16 v[0:15], a[20:23], a[28:31], v[0:15]
	ds_read_b128 a[16:19], v97
	ds_read_b128 a[20:23], v96
	ds_read_b128 a[24:27], v88 offset:49152
	ds_read_b128 a[28:31], v88 offset:53248
	s_waitcnt lgkmcnt(5)
	v_mfma_f32_32x32x16_bf16 v[48:63], a[0:3], a[8:11], v[48:63]
	s_and_b32 m0, s32, 7
	s_lshl_b32 m0, m0, 12
	s_add_i32 m0, m0, 0xc00
	s_nop 0
	global_load_lds_dwordx4 v[176:177], off
	v_mfma_f32_32x32x16_bf16 v[32:47], a[4:7], a[8:11], v[32:47]
	s_waitcnt lgkmcnt(4)
	v_mfma_f32_32x32x16_bf16 v[16:31], a[0:3], a[12:15], v[16:31]
	v_mfma_f32_32x32x16_bf16 v[0:15], a[4:7], a[12:15], v[0:15]
	s_and_b32 m0, s32, 7
	s_lshl_b32 m0, m0, 11
	s_add_i32 m0, m0, 0x8000
	s_nop 0
	global_load_lds_dwordx4 v[178:179], off
	s_waitcnt lgkmcnt(1)
	v_mfma_f32_32x32x16_bf16 v[48:63], a[16:19], a[24:27], v[48:63]
	v_mfma_f32_32x32x16_bf16 v[32:47], a[20:23], a[24:27], v[32:47]
	s_and_b32 m0, s32, 7
	s_lshl_b32 m0, m0, 11
	s_add_i32 m0, m0, 0x8400
	s_nop 0
	global_load_lds_dwordx4 v[180:181], off
	s_waitcnt vmcnt(6)
	s_waitcnt lgkmcnt(0)
	s_barrier
	ds_read_b128 a[12:15], v101
	ds_read_b128 a[8:11], v100
	ds_read_b128 a[4:7], v99
	ds_read_b128 a[0:3], v98
	v_mfma_f32_32x32x16_bf16 v[16:31], a[16:19], a[28:31], v[16:31]
	v_lshl_add_u64 v[158:159], v[66:67], 0, s[30:31]
	v_lshl_add_u64 v[160:161], v[68:69], 0, s[30:31]
	v_lshl_add_u64 v[162:163], v[70:71], 0, s[30:31]
	v_mfma_f32_32x32x16_bf16 v[0:15], a[20:23], a[28:31], v[0:15]
	s_and_b32 m0, s32, 7
	s_lshl_b32 m0, m0, 12
	s_add_i32 m0, m0, 0xc000
	s_nop 0
	global_load_lds_dwordx4 v[158:159], off
	v_lshl_add_u64 v[164:165], v[72:73], 0, s[30:31]
	v_lshl_add_u64 v[166:167], v[74:75], 0, s[30:31]
	v_lshl_add_u64 v[168:169], v[76:77], 0, s[30:31]
	s_mov_b64 s[30:31], 0x700
	ds_read_b128 a[16:19], v102
	ds_read_b128 a[20:23], v103
	ds_read_b128 a[24:27], v104
	ds_read_b128 a[28:31], v105
	s_waitcnt lgkmcnt(4)
	v_mfma_f32_32x32x16_bf16 v[48:63], a[0:3], a[8:11], v[48:63]
	v_mfma_f32_32x32x16_bf16 v[32:47], a[4:7], a[8:11], v[32:47]
	v_mfma_f32_32x32x16_bf16 v[16:31], a[0:3], a[12:15], v[16:31]
	s_and_b32 m0, s32, 7
	s_lshl_b32 m0, m0, 12
	s_add_i32 m0, m0, 0xc400
	s_nop 0
	global_load_lds_dwordx4 v[160:161], off
	v_mfma_f32_32x32x16_bf16 v[0:15], a[4:7], a[12:15], v[0:15]
	ds_read_b128 a[0:3], v106
	ds_read_b128 a[4:7], v107
	ds_read_b128 a[8:11], v108
	ds_read_b128 a[12:15], v109
	s_waitcnt lgkmcnt(5)
	v_mfma_f32_32x32x16_bf16 v[48:63], a[16:19], a[24:27], v[48:63]
	v_mfma_f32_32x32x16_bf16 v[32:47], a[20:23], a[24:27], v[32:47]
	s_and_b32 m0, s32, 7
	s_lshl_b32 m0, m0, 12
	s_add_i32 m0, m0, 0xc800
	s_nop 0
	global_load_lds_dwordx4 v[162:163], off
	s_waitcnt lgkmcnt(4)
	v_mfma_f32_32x32x16_bf16 v[16:31], a[16:19], a[28:31], v[16:31]
	v_mfma_f32_32x32x16_bf16 v[0:15], a[20:23], a[28:31], v[0:15]
	ds_read_b128 a[16:19], v110
	ds_read_b128 a[20:23], v111
	ds_read_b128 a[24:27], v112
	ds_read_b128 a[28:31], v113
	s_waitcnt lgkmcnt(5)
	v_mfma_f32_32x32x16_bf16 v[48:63], a[0:3], a[8:11], v[48:63]
	s_and_b32 m0, s32, 7
	s_lshl_b32 m0, m0, 12
	s_add_i32 m0, m0, 0xcc00
	s_nop 0
	global_load_lds_dwordx4 v[164:165], off
	v_mfma_f32_32x32x16_bf16 v[32:47], a[4:7], a[8:11], v[32:47]
	s_waitcnt lgkmcnt(4)
	v_mfma_f32_32x32x16_bf16 v[16:31], a[0:3], a[12:15], v[16:31]
	v_mfma_f32_32x32x16_bf16 v[0:15], a[4:7], a[12:15], v[0:15]
	s_and_b32 m0, s32, 7
	s_lshl_b32 m0, m0, 11
	s_add_i32 m0, m0, 0x14000
	s_nop 0
	global_load_lds_dwordx4 v[166:167], off
	s_waitcnt lgkmcnt(1)
	v_mfma_f32_32x32x16_bf16 v[48:63], a[16:19], a[24:27], v[48:63]
	v_mfma_f32_32x32x16_bf16 v[32:47], a[20:23], a[24:27], v[32:47]
	s_and_b32 m0, s32, 7
	s_lshl_b32 m0, m0, 11
	s_add_i32 m0, m0, 0x14400
	s_nop 0
	global_load_lds_dwordx4 v[168:169], off
	s_waitcnt vmcnt(6)
	s_waitcnt lgkmcnt(0)
	s_barrier
	ds_read_b128 a[12:15], v82 offset:4096
	ds_read_b128 a[8:11], v82
	ds_read_b128 a[4:7], v83 offset:36864
	ds_read_b128 a[0:3], v83 offset:32768
	v_mfma_f32_32x32x16_bf16 v[16:31], a[16:19], a[28:31], v[16:31]
	v_lshl_add_u64 v[170:171], v[66:67], 0, s[30:31]
	v_lshl_add_u64 v[172:173], v[68:69], 0, s[30:31]
	v_lshl_add_u64 v[174:175], v[70:71], 0, s[30:31]
	v_mfma_f32_32x32x16_bf16 v[0:15], a[20:23], a[28:31], v[0:15]
	s_and_b32 m0, s32, 7
	s_lshl_b32 m0, m0, 12
	s_add_i32 m0, m0, 0x18000
	s_nop 0
	global_load_lds_dwordx4 v[170:171], off
	v_lshl_add_u64 v[176:177], v[72:73], 0, s[30:31]
	v_lshl_add_u64 v[178:179], v[74:75], 0, s[30:31]
	v_lshl_add_u64 v[180:181], v[76:77], 0, s[30:31]
	s_mov_b64 s[30:31], 0x780
	ds_read_b128 a[16:19], v85 offset:32768
	ds_read_b128 a[20:23], v85 offset:36864
	ds_read_b128 a[24:27], v84
	ds_read_b128 a[28:31], v84 offset:4096
	s_waitcnt lgkmcnt(4)
	v_mfma_f32_32x32x16_bf16 v[48:63], a[0:3], a[8:11], v[48:63]
	v_lshl_add_u64 v[158:159], v[66:67], 0, s[30:31]
	v_mfma_f32_32x32x16_bf16 v[32:47], a[4:7], a[8:11], v[32:47]
	v_mfma_f32_32x32x16_bf16 v[16:31], a[0:3], a[12:15], v[16:31]
	s_and_b32 m0, s32, 7
	s_lshl_b32 m0, m0, 12
	s_add_i32 m0, m0, 0x18400
	s_nop 0
	global_load_lds_dwordx4 v[172:173], off
	v_mfma_f32_32x32x16_bf16 v[0:15], a[4:7], a[12:15], v[0:15]
	ds_read_b128 a[0:3], v87 offset:32768
	ds_read_b128 a[4:7], v87 offset:36864
	ds_read_b128 a[8:11], v86
	ds_read_b128 a[12:15], v86 offset:4096
	s_waitcnt lgkmcnt(5)
	v_mfma_f32_32x32x16_bf16 v[48:63], a[16:19], a[24:27], v[48:63]
	v_mfma_f32_32x32x16_bf16 v[32:47], a[20:23], a[24:27], v[32:47]
	s_and_b32 m0, s32, 7
	s_lshl_b32 m0, m0, 12
	s_add_i32 m0, m0, 0x18800
	s_nop 0
	global_load_lds_dwordx4 v[174:175], off
	s_waitcnt lgkmcnt(4)
	v_mfma_f32_32x32x16_bf16 v[16:31], a[16:19], a[28:31], v[16:31]
	v_mfma_f32_32x32x16_bf16 v[0:15], a[20:23], a[28:31], v[0:15]
	ds_read_b128 a[16:19], v89 offset:32768
	ds_read_b128 a[20:23], v89 offset:36864
	ds_read_b128 a[24:27], v88
	ds_read_b128 a[28:31], v88 offset:4096
	s_waitcnt lgkmcnt(5)
	v_mfma_f32_32x32x16_bf16 v[48:63], a[0:3], a[8:11], v[48:63]
	s_and_b32 m0, s32, 7
	s_lshl_b32 m0, m0, 12
	s_add_i32 m0, m0, 0x18c00
	s_nop 0
	global_load_lds_dwordx4 v[176:177], off
	v_mfma_f32_32x32x16_bf16 v[32:47], a[4:7], a[8:11], v[32:47]
	s_waitcnt lgkmcnt(4)
	v_mfma_f32_32x32x16_bf16 v[16:31], a[0:3], a[12:15], v[16:31]
	v_mfma_f32_32x32x16_bf16 v[0:15], a[4:7], a[12:15], v[0:15]
	s_and_b32 m0, s32, 7
	s_lshl_b32 m0, m0, 11
	s_add_i32 m0, m0, 0x20000
	s_nop 0
	global_load_lds_dwordx4 v[178:179], off
	s_waitcnt lgkmcnt(1)
	v_mfma_f32_32x32x16_bf16 v[48:63], a[16:19], a[24:27], v[48:63]
	v_mfma_f32_32x32x16_bf16 v[32:47], a[20:23], a[24:27], v[32:47]
	s_and_b32 m0, s32, 7
	s_lshl_b32 m0, m0, 11
	s_add_i32 m0, m0, 0x20400
	s_nop 0
	global_load_lds_dwordx4 v[180:181], off
	s_waitcnt vmcnt(6)
	s_waitcnt lgkmcnt(0)
	s_barrier
	ds_read_b128 a[12:15], v82 offset:53248
	ds_read_b128 a[8:11], v82 offset:49152
	ds_read_b128 a[4:7], v90
	ds_read_b128 a[0:3], v92
	v_lshl_add_u64 v[160:161], v[68:69], 0, s[30:31]
	v_mfma_f32_32x32x16_bf16 v[16:31], a[16:19], a[28:31], v[16:31]
	v_lshl_add_u64 v[162:163], v[70:71], 0, s[30:31]
	v_lshl_add_u64 v[164:165], v[72:73], 0, s[30:31]
	v_mfma_f32_32x32x16_bf16 v[0:15], a[20:23], a[28:31], v[0:15]
	s_and_b32 m0, s32, 7
	s_lshl_b32 m0, m0, 12
	s_add_i32 m0, m0, 0x0
	s_nop 0
	global_load_lds_dwordx4 v[158:159], off
	v_lshl_add_u64 v[166:167], v[74:75], 0, s[30:31]
	v_lshl_add_u64 v[168:169], v[76:77], 0, s[30:31]
	ds_read_b128 a[16:19], v93
	ds_read_b128 a[20:23], v91
	ds_read_b128 a[24:27], v84 offset:49152
	ds_read_b128 a[28:31], v84 offset:53248
	s_waitcnt lgkmcnt(4)
	v_mfma_f32_32x32x16_bf16 v[48:63], a[0:3], a[8:11], v[48:63]
	v_mfma_f32_32x32x16_bf16 v[32:47], a[4:7], a[8:11], v[32:47]
	v_mfma_f32_32x32x16_bf16 v[16:31], a[0:3], a[12:15], v[16:31]
	s_and_b32 m0, s32, 7
	s_lshl_b32 m0, m0, 12
	s_add_i32 m0, m0, 0x400
	s_nop 0
	global_load_lds_dwordx4 v[160:161], off
	v_mfma_f32_32x32x16_bf16 v[0:15], a[4:7], a[12:15], v[0:15]
	ds_read_b128 a[0:3], v95
	ds_read_b128 a[4:7], v94
	ds_read_b128 a[8:11], v86 offset:49152
	ds_read_b128 a[12:15], v86 offset:53248
	s_waitcnt lgkmcnt(5)
	v_mfma_f32_32x32x16_bf16 v[48:63], a[16:19], a[24:27], v[48:63]
	v_mfma_f32_32x32x16_bf16 v[32:47], a[20:23], a[24:27], v[32:47]
	s_and_b32 m0, s32, 7
	s_lshl_b32 m0, m0, 12
	s_add_i32 m0, m0, 0x800
	s_nop 0
	global_load_lds_dwordx4 v[162:163], off
	s_waitcnt lgkmcnt(4)
	v_mfma_f32_32x32x16_bf16 v[16:31], a[16:19], a[28:31], v[16:31]
	v_mfma_f32_32x32x16_bf16 v[0:15], a[20:23], a[28:31], v[0:15]
	ds_read_b128 a[16:19], v97
	ds_read_b128 a[20:23], v96
	ds_read_b128 a[24:27], v88 offset:49152
	ds_read_b128 a[28:31], v88 offset:53248
	s_waitcnt lgkmcnt(5)
	v_mfma_f32_32x32x16_bf16 v[48:63], a[0:3], a[8:11], v[48:63]
	s_and_b32 m0, s32, 7
	s_lshl_b32 m0, m0, 12
	s_add_i32 m0, m0, 0xc00
	s_nop 0
	global_load_lds_dwordx4 v[164:165], off
	v_mfma_f32_32x32x16_bf16 v[32:47], a[4:7], a[8:11], v[32:47]
	s_waitcnt lgkmcnt(4)
	v_mfma_f32_32x32x16_bf16 v[16:31], a[0:3], a[12:15], v[16:31]
	v_mfma_f32_32x32x16_bf16 v[0:15], a[4:7], a[12:15], v[0:15]
	s_and_b32 m0, s32, 7
	s_lshl_b32 m0, m0, 11
	s_add_i32 m0, m0, 0x8000
	s_nop 0
	global_load_lds_dwordx4 v[166:167], off
	s_waitcnt lgkmcnt(1)
	v_mfma_f32_32x32x16_bf16 v[48:63], a[16:19], a[24:27], v[48:63]
	v_mfma_f32_32x32x16_bf16 v[32:47], a[20:23], a[24:27], v[32:47]
	s_and_b32 m0, s32, 7
	s_lshl_b32 m0, m0, 11
	s_add_i32 m0, m0, 0x8400
	s_nop 0
	global_load_lds_dwordx4 v[168:169], off
	s_waitcnt vmcnt(6)
	s_waitcnt lgkmcnt(0)
	s_barrier
	ds_read_b128 a[12:15], v101
	ds_read_b128 a[8:11], v100
	ds_read_b128 a[4:7], v99
	ds_read_b128 a[0:3], v98
	v_mfma_f32_32x32x16_bf16 v[16:31], a[16:19], a[28:31], v[16:31]
	v_mfma_f32_32x32x16_bf16 v[0:15], a[20:23], a[28:31], v[0:15]
	ds_read_b128 a[16:19], v102
	ds_read_b128 a[20:23], v103
	ds_read_b128 a[24:27], v104
	ds_read_b128 a[28:31], v105
	s_waitcnt lgkmcnt(4)
	v_mfma_f32_32x32x16_bf16 v[48:63], a[0:3], a[8:11], v[48:63]
	v_mfma_f32_32x32x16_bf16 v[32:47], a[4:7], a[8:11], v[32:47]
	v_mfma_f32_32x32x16_bf16 v[16:31], a[0:3], a[12:15], v[16:31]
	v_mfma_f32_32x32x16_bf16 v[0:15], a[4:7], a[12:15], v[0:15]
	ds_read_b128 a[0:3], v106
	ds_read_b128 a[4:7], v107
	ds_read_b128 a[8:11], v108
	ds_read_b128 a[12:15], v109
	s_waitcnt lgkmcnt(5)
	v_mfma_f32_32x32x16_bf16 v[48:63], a[16:19], a[24:27], v[48:63]
	v_mfma_f32_32x32x16_bf16 v[32:47], a[20:23], a[24:27], v[32:47]
	s_waitcnt lgkmcnt(4)
	v_mfma_f32_32x32x16_bf16 v[16:31], a[16:19], a[28:31], v[16:31]
	v_mfma_f32_32x32x16_bf16 v[0:15], a[20:23], a[28:31], v[0:15]
	ds_read_b128 a[16:19], v110
	ds_read_b128 a[20:23], v111
	ds_read_b128 a[24:27], v112
	ds_read_b128 a[28:31], v113
	s_waitcnt lgkmcnt(5)
	v_mfma_f32_32x32x16_bf16 v[48:63], a[0:3], a[8:11], v[48:63]
	v_mfma_f32_32x32x16_bf16 v[32:47], a[4:7], a[8:11], v[32:47]
	s_waitcnt lgkmcnt(4)
	v_mfma_f32_32x32x16_bf16 v[16:31], a[0:3], a[12:15], v[16:31]
	v_mfma_f32_32x32x16_bf16 v[0:15], a[4:7], a[12:15], v[0:15]
	s_waitcnt lgkmcnt(1)
	v_mfma_f32_32x32x16_bf16 v[48:63], a[16:19], a[24:27], v[48:63]
	v_mfma_f32_32x32x16_bf16 v[32:47], a[20:23], a[24:27], v[32:47]
	s_waitcnt vmcnt(0)
	s_waitcnt lgkmcnt(0)
	s_barrier
	ds_read_b128 a[12:15], v82 offset:4096
	ds_read_b128 a[8:11], v82
	ds_read_b128 a[4:7], v83 offset:36864
	ds_read_b128 a[0:3], v83 offset:32768
	v_mfma_f32_32x32x16_bf16 v[16:31], a[16:19], a[28:31], v[16:31]
	v_mfma_f32_32x32x16_bf16 v[0:15], a[20:23], a[28:31], v[0:15]
	ds_read_b128 a[16:19], v85 offset:32768
	ds_read_b128 a[20:23], v85 offset:36864
	ds_read_b128 a[24:27], v84
	ds_read_b128 a[28:31], v84 offset:4096
	s_waitcnt lgkmcnt(4)
	v_mfma_f32_32x32x16_bf16 v[48:63], a[0:3], a[8:11], v[48:63]
	v_mfma_f32_32x32x16_bf16 v[32:47], a[4:7], a[8:11], v[32:47]
	v_mfma_f32_32x32x16_bf16 v[16:31], a[0:3], a[12:15], v[16:31]
	v_mfma_f32_32x32x16_bf16 v[0:15], a[4:7], a[12:15], v[0:15]
	ds_read_b128 a[0:3], v87 offset:32768
	ds_read_b128 a[4:7], v87 offset:36864
	ds_read_b128 a[8:11], v86
	ds_read_b128 a[12:15], v86 offset:4096
	s_waitcnt lgkmcnt(5)
	v_mfma_f32_32x32x16_bf16 v[48:63], a[16:19], a[24:27], v[48:63]
	v_mfma_f32_32x32x16_bf16 v[32:47], a[20:23], a[24:27], v[32:47]
	s_waitcnt lgkmcnt(4)
	v_mfma_f32_32x32x16_bf16 v[16:31], a[16:19], a[28:31], v[16:31]
	v_mfma_f32_32x32x16_bf16 v[0:15], a[20:23], a[28:31], v[0:15]
	s_waitcnt lgkmcnt(1)
	v_mfma_f32_32x32x16_bf16 v[48:63], a[0:3], a[8:11], v[48:63]
	v_mfma_f32_32x32x16_bf16 v[32:47], a[4:7], a[8:11], v[32:47]
	s_waitcnt lgkmcnt(0)
	v_mfma_f32_32x32x16_bf16 v[16:31], a[0:3], a[12:15], v[16:31]
	v_mfma_f32_32x32x16_bf16 v[0:15], a[4:7], a[12:15], v[0:15]
	ds_read_b128 v[66:69], v89 offset:32768
	ds_read_b128 v[70:73], v88
	ds_read_b128 v[74:77], v89 offset:36864
	ds_read_b128 v[82:85], v88 offset:4096
	s_waitcnt lgkmcnt(0)
	s_barrier
	s_waitcnt lgkmcnt(0)
	v_mfma_f32_32x32x16_bf16 v[48:63], v[66:69], v[70:73], v[48:63]
	v_mfma_f32_32x32x16_bf16 v[32:47], v[74:77], v[70:73], v[32:47]
	v_mov_b32_e32 v70, 0
	v_mfma_f32_32x32x16_bf16 v[16:31], v[66:69], v[82:85], v[16:31]
	v_lshl_or_b32 v69, v80, 6, v81
	v_add_u32_e32 v66, s20, v69
	v_cmp_gt_i32_e32 vcc, s69, v66
	v_mov_b32_e32 v68, 0
	v_ashrrev_i32_e32 v67, 31, v66
	v_mfma_f32_32x32x16_bf16 v[0:15], v[74:77], v[82:85], v[0:15]
	s_and_saveexec_b64 s[0:1], vcc
	s_cbranch_execz .LBB0_588
	v_lshl_add_u64 v[70:71], v[66:67], 2, s[76:77]
	global_load_dword v70, v[70:71], off
	s_waitcnt vmcnt(0)
	v_fmamk_f32 v70, v70, 0x3a800000, v188
	v_mul_f32_e32 v71, 0x4b800000, v70
	v_cmp_gt_f32_e32 vcc, s82, v70
	s_nop 1
	v_cndmask_b32_e32 v70, v70, v71, vcc
	v_rsq_f32_e32 v70, v70
	s_nop 0
	v_mul_f32_e32 v71, 0x45800000, v70
	v_cndmask_b32_e32 v70, v70, v71, vcc

.LBB0_612:
	v_readlane_b32 s0, v212, 1
	s_cmp_ge_i32 s56, s0
	s_mov_b64 s[0:1], -1
	s_cbranch_scc0 .LBB0_742
	s_ashr_i32 s1, s52, 31
	s_lshr_b32 s0, s1, 27
	s_add_i32 s2, s52, s0
	s_ashr_i32 s0, s2, 5
	s_and_b32 s2, s2, 0xffe0
	s_sub_i32 s2, s52, s2
	s_lshr_b32 s1, s1, 30
	s_bfe_i32 s20, s2, 0x80000
	s_add_i32 s1, s52, s1
	s_bfe_u32 s20, s20, 0x2000d
	s_and_b32 s1, s1, 0x1fffffc
	s_add_i32 s2, s2, s20
	s_sub_i32 s23, s52, s1
	s_ashr_i32 s1, s0, 31
	s_bfe_i32 s2, s2, 0x80000
	s_lshl_b64 s[20:21], s[0:1], 20
	v_readlane_b32 s22, v215, 46
	s_sext_i32_i16 s2, s2
	s_add_u32 s20, s22, s20
	v_readlane_b32 s22, v215, 47
	v_mov_b32_e32 v12, v133
	s_addc_u32 s21, s22, s21
	s_lshl_b32 s2, s2, 6
	s_and_b32 s22, s2, 0xffffff00
	v_ashrrev_i32_e32 v6, 6, v12
	v_bfe_u32 v7, v12, 3, 3
	v_lshl_or_b32 v8, v6, 5, v7
	v_add_u32_e32 v0, s22, v8
	s_waitcnt lgkmcnt(0)
	v_ashrrev_i32_e32 v1, 31, v0
	v_lshlrev_b64 v[2:3], 11, v[0:1]
	v_bfe_u32 v1, v12, 4, 2
	v_readlane_b32 s28, v215, 50
	v_xor_b32_e32 v1, v1, v12
	v_readlane_b32 s29, v215, 51
	v_lshlrev_b32_e32 v1, 4, v1
	v_and_b32_e32 v64, 0x70, v1
	v_lshl_add_u64 v[2:3], s[28:29], 0, v[2:3]
	v_or_b32_e32 v1, 8, v8
	v_lshl_add_u64 v[66:67], v[2:3], 0, v[64:65]
	v_add_u32_e32 v2, s22, v1
	v_lshrrev_b32_e32 v1, 1, v1
	v_xor_b32_e32 v1, v1, v12
	v_ashrrev_i32_e32 v3, 31, v2
	v_lshlrev_b32_e32 v1, 4, v1
	v_or_b32_e32 v0, 16, v0
	v_lshlrev_b64 v[2:3], 11, v[2:3]
	v_and_b32_e32 v4, 0x70, v1
	v_ashrrev_i32_e32 v1, 31, v0
	v_lshl_add_u64 v[2:3], s[28:29], 0, v[2:3]
	v_mov_b32_e32 v5, v65
	v_lshlrev_b64 v[0:1], 11, v[0:1]
	v_lshl_add_u64 v[68:69], v[2:3], 0, v[4:5]
	v_lshl_add_u64 v[0:1], s[28:29], 0, v[0:1]
	v_or_b32_e32 v2, 24, v8
	v_lshl_add_u64 v[70:71], v[0:1], 0, v[64:65]
	v_add_u32_e32 v0, s22, v2
	v_lshrrev_b32_e32 v2, 1, v2
	v_ashrrev_i32_e32 v1, 31, v0
	v_xor_b32_e32 v2, v2, v12
	v_lshlrev_b64 v[0:1], 11, v[0:1]
	v_lshlrev_b32_e32 v2, 4, v2
	v_lshl_add_u64 v[0:1], s[28:29], 0, v[0:1]
	v_and_b32_e32 v2, 0x70, v2
	v_mov_b32_e32 v3, v65
	s_lshl_b32 s2, s23, 7
	v_lshl_add_u64 v[72:73], v[0:1], 0, v[2:3]
	v_lshl_or_b32 v2, v6, 4, v7
	v_add_u32_e32 v0, s2, v2
	v_lshlrev_b32_e32 v3, 12, v6
	v_ashrrev_i32_e32 v1, 31, v0
	v_add_u32_e32 v125, 0, v3
	v_lshlrev_b64 v[0:1], 11, v[0:1]
	s_waitcnt vmcnt(0)
	v_readfirstlane_b32 s42, v125
	v_add_u32_e32 v126, 0x400, v125
	v_lshl_add_u64 v[0:1], s[20:21], 0, v[0:1]
	v_or_b32_e32 v2, 8, v2
	s_waitcnt lgkmcnt(0)
	s_barrier
	s_mov_b32 m0, s42
	v_readfirstlane_b32 s43, v126
	v_add_u32_e32 v127, 0x800, v125
	v_lshlrev_b32_e32 v5, 11, v6
	v_and_b32_e32 v79, 1, v6
	v_lshl_add_u64 v[74:75], v[0:1], 0, v[64:65]
	v_add_u32_e32 v0, s2, v2
	v_lshrrev_b32_e32 v2, 1, v2
	global_load_lds_dwordx4 v[66:67], off
	s_mov_b32 m0, s43
	v_readfirstlane_b32 s44, v127
	v_add_u32_e32 v128, 0xc00, v125
	v_add_u32_e32 v6, 0, v5
	v_ashrrev_i32_e32 v1, 31, v0
	v_xor_b32_e32 v2, v2, v12
	global_load_lds_dwordx4 v[68:69], off
	s_mov_b32 m0, s44
	v_readfirstlane_b32 s45, v128
	v_add_u32_e32 v130, 0x8000, v6
	v_lshlrev_b64 v[0:1], 11, v[0:1]
	v_lshlrev_b32_e32 v2, 4, v2
	global_load_lds_dwordx4 v[70:71], off
	s_mov_b32 m0, s45
	v_readfirstlane_b32 s46, v130
	v_add_u32_e32 v129, 0x8400, v6
	v_lshl_add_u64 v[0:1], s[20:21], 0, v[0:1]
	v_and_b32_e32 v64, 0x70, v2
	global_load_lds_dwordx4 v[72:73], off
	s_mov_b32 m0, s46
	v_readfirstlane_b32 s47, v129
	v_add_u32_e32 v119, 0xc000, v125
	v_lshl_add_u64 v[76:77], v[0:1], 0, v[64:65]
	global_load_lds_dwordx4 v[74:75], off
	s_mov_b32 m0, s47
	s_mov_b64 s[20:21], 0x80
	v_readfirstlane_b32 s36, v119
	v_add_u32_e32 v120, 0xc400, v125
	global_load_lds_dwordx4 v[76:77], off
	v_lshl_add_u64 v[0:1], v[66:67], 0, s[20:21]
	s_mov_b32 m0, s36
	v_readfirstlane_b32 s37, v120
	v_add_u32_e32 v121, 0xc800, v125
	global_load_lds_dwordx4 v[0:1], off
	v_lshl_add_u64 v[0:1], v[68:69], 0, s[20:21]
	s_mov_b32 m0, s37
	v_readfirstlane_b32 s38, v121
	v_add_u32_e32 v122, 0xcc00, v125
	global_load_lds_dwordx4 v[0:1], off
	v_lshl_add_u64 v[0:1], v[70:71], 0, s[20:21]
	s_mov_b32 m0, s38
	v_readfirstlane_b32 s39, v122
	v_add_u32_e32 v123, s85, v5
	global_load_lds_dwordx4 v[0:1], off
	v_lshl_add_u64 v[0:1], v[72:73], 0, s[20:21]
	s_mov_b32 m0, s39
	v_readfirstlane_b32 s40, v123
	v_add_u32_e32 v124, 0x14400, v6
	global_load_lds_dwordx4 v[0:1], off
	v_lshl_add_u64 v[0:1], v[74:75], 0, s[20:21]
	s_mov_b32 m0, s40
	v_readfirstlane_b32 s41, v124
	global_load_lds_dwordx4 v[0:1], off
	v_lshl_add_u64 v[0:1], v[76:77], 0, s[20:21]
	s_mov_b32 m0, s41
	v_lshrrev_b32_e32 v2, 1, v12
	v_bfe_u32 v64, v12, 5, 1
	global_load_lds_dwordx4 v[0:1], off
	v_add_u32_e32 v113, s3, v3
	v_bitop3_b32 v0, v2, v64, 7 bitop3:0x6c
	s_waitcnt vmcnt(6)
	s_mov_b64 s[30:31], 0x100
	v_readfirstlane_b32 s20, v113
	v_add_u32_e32 v114, 0x400, v113
	v_lshlrev_b32_e32 v110, 4, v0
	s_waitcnt lgkmcnt(0)
	s_barrier
	v_lshl_add_u64 v[0:1], v[66:67], 0, s[30:31]
	s_mov_b32 m0, s20
	v_readfirstlane_b32 s21, v114
	v_add_u32_e32 v115, 0x800, v113
	global_load_lds_dwordx4 v[0:1], off
	v_lshl_add_u64 v[0:1], v[68:69], 0, s[30:31]
	s_mov_b32 m0, s21
	v_readfirstlane_b32 s23, v115
	v_add_u32_e32 v116, 0xc00, v113
	v_readlane_b32 s29, v212, 31
	v_and_b32_e32 v80, 31, v12
	global_load_lds_dwordx4 v[0:1], off
	v_lshl_add_u64 v[0:1], v[70:71], 0, s[30:31]
	s_mov_b32 m0, s23
	v_readfirstlane_b32 s28, v116
	v_add_u32_e32 v117, s29, v5
	v_add_u32_e32 v2, s3, v5
	v_lshlrev_b32_e32 v4, 7, v80
	global_load_lds_dwordx4 v[0:1], off
	v_lshl_add_u64 v[0:1], v[72:73], 0, s[30:31]
	s_mov_b32 m0, s28
	v_readfirstlane_b32 s29, v117
	v_add_u32_e32 v118, 0x8400, v2
	v_lshl_or_b32 v102, v79, 13, v4
	global_load_lds_dwordx4 v[0:1], off
	v_lshl_add_u64 v[0:1], v[74:75], 0, s[30:31]
	s_mov_b32 m0, s29
	v_readfirstlane_b32 s33, v118
	global_load_lds_dwordx4 v[0:1], off
	v_lshl_add_u64 v[0:1], v[76:77], 0, s[30:31]
	s_mov_b32 m0, s33
	v_add_u32_e32 v100, 0, v102
	global_load_lds_dwordx4 v[0:1], off
	v_add_u32_e32 v82, v100, v110
	v_ashrrev_i32_e32 v78, 7, v12
	ds_read_b128 a[0:3], v82 offset:32768
	ds_read_b128 a[4:7], v82 offset:36864
	v_lshl_or_b32 v111, v78, 13, v4
	v_add_u32_e32 v101, 0, v111
	v_add_u32_e32 v81, v101, v110
	ds_read_b128 a[8:11], v81
	ds_read_b128 a[12:15], v81 offset:4096
	v_lshrrev_b32_e32 v182, 6, v133
	s_nop 0
	v_readfirstlane_b32 s32, v182
	s_waitcnt lgkmcnt(1)
	v_mfma_f32_32x32x16_bf16 v[48:63], a[0:3], a[8:11], 0
	v_bfe_u32 v103, v12, 1, 3
	v_bitop3_b32 v85, v64, v103, 4 bitop3:0x36
	v_lshlrev_b32_e32 v131, 4, v85
	v_add_u32_e32 v85, v101, v131
	s_mov_b64 s[30:31], 0x180
	v_or_b32_e32 v146, 0x8000, v102
	s_waitcnt vmcnt(12)
	v_mfma_f32_32x32x16_bf16 v[32:47], a[4:7], a[8:11], 0
	v_or_b32_e32 v147, 0x9000, v102
	v_add_u32_e32 v138, s3, v110
	v_add_u32_e32 v148, s3, v111
	v_or_b32_e32 v149, 0x1000, v111
	s_mov_b64 s[60:61], 0x80
	s_mov_b64 s[80:81], 0x200
	s_waitcnt lgkmcnt(0)
	v_mfma_f32_32x32x16_bf16 v[16:31], a[0:3], a[12:15], 0
	v_bitop3_b32 v0, v64, v103, 2 bitop3:0x36
	v_lshlrev_b32_e32 v112, 4, v0
	v_add_u32_e32 v83, v101, v112
	ds_read_b128 a[28:31], v83 offset:4096
	ds_read_b128 a[24:27], v83
	v_add_u32_e32 v84, v100, v112
	ds_read_b128 a[20:23], v84 offset:36864
	ds_read_b128 a[16:19], v84 offset:32768
	v_mfma_f32_32x32x16_bf16 v[0:15], a[4:7], a[12:15], 0
	v_add_u32_e32 v142, s3, v112
	v_add_u32_e32 v86, v100, v131
	ds_read_b128 a[0:3], v86 offset:32768
	ds_read_b128 a[4:7], v86 offset:36864
	ds_read_b128 a[8:11], v85
	ds_read_b128 a[12:15], v85 offset:4096
	s_waitcnt lgkmcnt(4)
	v_mfma_f32_32x32x16_bf16 v[48:63], a[16:19], a[24:27], v[48:63]
	v_mfma_f32_32x32x16_bf16 v[32:47], a[20:23], a[24:27], v[32:47]
	v_mfma_f32_32x32x16_bf16 v[16:31], a[16:19], a[28:31], v[16:31]
	v_bitop3_b32 v87, v64, v103, 6 bitop3:0x36
	v_lshlrev_b32_e32 v132, 4, v87
	v_add_u32_e32 v87, v101, v132
	v_lshlrev_b32_e32 v64, 2, v64
	v_mfma_f32_32x32x16_bf16 v[0:15], a[20:23], a[28:31], v[0:15]
	v_add_u32_e32 v88, v100, v132
	ds_read_b128 a[16:19], v88 offset:32768
	ds_read_b128 a[20:23], v88 offset:36864
	ds_read_b128 a[24:27], v87
	ds_read_b128 a[28:31], v87 offset:4096
	s_waitcnt lgkmcnt(5)
	v_mfma_f32_32x32x16_bf16 v[48:63], a[0:3], a[8:11], v[48:63]
	v_mfma_f32_32x32x16_bf16 v[32:47], a[4:7], a[8:11], v[32:47]
	s_waitcnt lgkmcnt(4)
	v_mfma_f32_32x32x16_bf16 v[16:31], a[0:3], a[12:15], v[16:31]
	v_mfma_f32_32x32x16_bf16 v[0:15], a[4:7], a[12:15], v[0:15]
	s_waitcnt lgkmcnt(1)
	v_mfma_f32_32x32x16_bf16 v[48:63], a[16:19], a[24:27], v[48:63]
	v_mfma_f32_32x32x16_bf16 v[32:47], a[20:23], a[24:27], v[32:47]
	s_waitcnt vmcnt(6)
	s_waitcnt lgkmcnt(0)
	s_barrier
	ds_read_b128 a[12:15], v81 offset:53248
	ds_read_b128 a[8:11], v81 offset:49152
	v_mfma_f32_32x32x16_bf16 v[16:31], a[16:19], a[28:31], v[16:31]
	v_lshl_add_u64 v[158:159], v[66:67], 0, s[30:31]
	v_lshl_add_u64 v[160:161], v[68:69], 0, s[30:31]
	v_lshl_add_u64 v[162:163], v[70:71], 0, s[30:31]
	v_mfma_f32_32x32x16_bf16 v[0:15], a[20:23], a[28:31], v[0:15]
	s_and_b32 m0, s32, 7
	s_lshl_b32 m0, m0, 12
	s_add_i32 m0, m0, 0x0
	s_nop 0
	global_load_lds_dwordx4 v[158:159], off
	v_lshl_add_u64 v[164:165], v[72:73], 0, s[30:31]
	v_lshl_add_u64 v[166:167], v[74:75], 0, s[30:31]
	v_lshl_add_u64 v[168:169], v[76:77], 0, s[30:31]
	s_add_i32 s30, 0, 0xc000
	v_add_u32_e32 v89, s30, v110
	v_add_u32_e32 v91, v89, v146
	v_add_u32_e32 v89, v89, v147
	ds_read_b128 a[4:7], v89
	ds_read_b128 a[0:3], v91
	v_add_u32_e32 v90, s30, v112
	v_add_u32_e32 v92, v90, v146
	ds_read_b128 a[16:19], v92
	v_add_u32_e32 v90, v90, v147
	ds_read_b128 a[20:23], v90
	ds_read_b128 a[24:27], v83 offset:49152
	ds_read_b128 a[28:31], v83 offset:53248
	s_waitcnt lgkmcnt(4)
	v_mfma_f32_32x32x16_bf16 v[48:63], a[0:3], a[8:11], v[48:63]
	v_mfma_f32_32x32x16_bf16 v[32:47], a[4:7], a[8:11], v[32:47]
	v_mfma_f32_32x32x16_bf16 v[16:31], a[0:3], a[12:15], v[16:31]
	s_and_b32 m0, s32, 7
	s_lshl_b32 m0, m0, 12
	s_add_i32 m0, m0, 0x400
	s_nop 0
	global_load_lds_dwordx4 v[160:161], off
	v_add_u32_e32 v93, s30, v131
	v_mfma_f32_32x32x16_bf16 v[0:15], a[4:7], a[12:15], v[0:15]
	v_add_u32_e32 v94, v93, v146
	ds_read_b128 a[0:3], v94
	v_add_u32_e32 v93, v93, v147
	ds_read_b128 a[4:7], v93
	ds_read_b128 a[8:11], v85 offset:49152
	ds_read_b128 a[12:15], v85 offset:53248
	s_waitcnt lgkmcnt(5)
	v_mfma_f32_32x32x16_bf16 v[48:63], a[16:19], a[24:27], v[48:63]
	v_mfma_f32_32x32x16_bf16 v[32:47], a[20:23], a[24:27], v[32:47]
	s_and_b32 m0, s32, 7
	s_lshl_b32 m0, m0, 12
	s_add_i32 m0, m0, 0x800
	s_nop 0
	global_load_lds_dwordx4 v[162:163], off
	s_waitcnt lgkmcnt(4)
	v_mfma_f32_32x32x16_bf16 v[16:31], a[16:19], a[28:31], v[16:31]
	v_add_u32_e32 v95, s30, v132
	s_mov_b64 s[30:31], 0x200
	v_mfma_f32_32x32x16_bf16 v[0:15], a[20:23], a[28:31], v[0:15]
	v_add_u32_e32 v96, v95, v146
	ds_read_b128 a[16:19], v96
	v_add_u32_e32 v95, v95, v147
	ds_read_b128 a[20:23], v95
	ds_read_b128 a[24:27], v87 offset:49152
	ds_read_b128 a[28:31], v87 offset:53248
	s_waitcnt lgkmcnt(5)
	v_mfma_f32_32x32x16_bf16 v[48:63], a[0:3], a[8:11], v[48:63]
	s_and_b32 m0, s32, 7
	s_lshl_b32 m0, m0, 12
	s_add_i32 m0, m0, 0xc00
	s_nop 0
	global_load_lds_dwordx4 v[164:165], off
	v_mfma_f32_32x32x16_bf16 v[32:47], a[4:7], a[8:11], v[32:47]
	s_waitcnt lgkmcnt(4)
	v_mfma_f32_32x32x16_bf16 v[16:31], a[0:3], a[12:15], v[16:31]
	v_add_u32_e32 v97, v138, v146
	v_mfma_f32_32x32x16_bf16 v[0:15], a[4:7], a[12:15], v[0:15]
	s_and_b32 m0, s32, 7
	s_lshl_b32 m0, m0, 11
	s_add_i32 m0, m0, 0x8000
	s_nop 0
	global_load_lds_dwordx4 v[166:167], off
	s_waitcnt lgkmcnt(1)
	v_mfma_f32_32x32x16_bf16 v[48:63], a[16:19], a[24:27], v[48:63]
	v_mfma_f32_32x32x16_bf16 v[32:47], a[20:23], a[24:27], v[32:47]
	s_and_b32 m0, s32, 7
	s_lshl_b32 m0, m0, 11
	s_add_i32 m0, m0, 0x8400
	s_nop 0
	global_load_lds_dwordx4 v[168:169], off
	s_waitcnt vmcnt(6)
	s_waitcnt lgkmcnt(0)
	s_barrier
	v_add_u32_e32 v100, v138, v149
	ds_read_b128 a[12:15], v100
	v_add_u32_e32 v99, v148, v110
	ds_read_b128 a[8:11], v99
	v_add_u32_e32 v98, v138, v147
	ds_read_b128 a[4:7], v98
	ds_read_b128 a[0:3], v97
	v_mfma_f32_32x32x16_bf16 v[16:31], a[16:19], a[28:31], v[16:31]
	v_lshl_add_u64 v[170:171], v[66:67], 0, s[30:31]
	v_lshl_add_u64 v[172:173], v[68:69], 0, s[30:31]
	v_lshl_add_u64 v[174:175], v[70:71], 0, s[30:31]
	v_mfma_f32_32x32x16_bf16 v[0:15], a[20:23], a[28:31], v[0:15]
	s_and_b32 m0, s32, 7
	s_lshl_b32 m0, m0, 12
	s_add_i32 m0, m0, 0xc000
	s_nop 0
	global_load_lds_dwordx4 v[170:171], off
	v_lshl_add_u64 v[176:177], v[72:73], 0, s[30:31]
	v_lshl_add_u64 v[178:179], v[74:75], 0, s[30:31]
	v_lshl_add_u64 v[180:181], v[76:77], 0, s[30:31]
	s_mov_b64 s[30:31], 0x280
	v_add_u32_e32 v101, v142, v146
	ds_read_b128 a[16:19], v101
	v_add_u32_e32 v102, v142, v147
	ds_read_b128 a[20:23], v102
	v_add_u32_e32 v103, v148, v112
	ds_read_b128 a[24:27], v103
	v_add_u32_e32 v104, v142, v149
	ds_read_b128 a[28:31], v104
	s_waitcnt lgkmcnt(4)
	v_mfma_f32_32x32x16_bf16 v[48:63], a[0:3], a[8:11], v[48:63]
	v_mfma_f32_32x32x16_bf16 v[32:47], a[4:7], a[8:11], v[32:47]
	v_add_u32_e32 v112, s3, v131
	v_mfma_f32_32x32x16_bf16 v[16:31], a[0:3], a[12:15], v[16:31]
	s_and_b32 m0, s32, 7
	s_lshl_b32 m0, m0, 12
	s_add_i32 m0, m0, 0xc400
	s_nop 0
	global_load_lds_dwordx4 v[172:173], off
	v_mfma_f32_32x32x16_bf16 v[0:15], a[4:7], a[12:15], v[0:15]
	v_add_u32_e32 v105, v112, v146
	ds_read_b128 a[0:3], v105
	v_add_u32_e32 v106, v112, v147
	ds_read_b128 a[4:7], v106
	v_add_u32_e32 v107, v148, v131
	ds_read_b128 a[8:11], v107
	v_add_u32_e32 v108, v112, v149
	ds_read_b128 a[12:15], v108
	s_waitcnt lgkmcnt(5)
	v_mfma_f32_32x32x16_bf16 v[48:63], a[16:19], a[24:27], v[48:63]
	v_mfma_f32_32x32x16_bf16 v[32:47], a[20:23], a[24:27], v[32:47]
	s_and_b32 m0, s32, 7
	s_lshl_b32 m0, m0, 12
	s_add_i32 m0, m0, 0xc800
	s_nop 0
	global_load_lds_dwordx4 v[174:175], off
	s_waitcnt lgkmcnt(4)
	v_mfma_f32_32x32x16_bf16 v[16:31], a[16:19], a[28:31], v[16:31]
	v_mfma_f32_32x32x16_bf16 v[0:15], a[20:23], a[28:31], v[0:15]
	v_add_u32_e32 v112, s3, v132
	v_add_u32_e32 v109, v112, v146
	ds_read_b128 a[16:19], v109
	v_add_u32_e32 v110, v112, v147
	ds_read_b128 a[20:23], v110
	v_add_u32_e32 v111, v148, v132
	ds_read_b128 a[24:27], v111
	v_add_u32_e32 v112, v112, v149
	ds_read_b128 a[28:31], v112
	s_waitcnt lgkmcnt(5)
	v_mfma_f32_32x32x16_bf16 v[48:63], a[0:3], a[8:11], v[48:63]
	s_and_b32 m0, s32, 7
	s_lshl_b32 m0, m0, 12
	s_add_i32 m0, m0, 0xcc00
	s_nop 0
	global_load_lds_dwordx4 v[176:177], off
	v_mfma_f32_32x32x16_bf16 v[32:47], a[4:7], a[8:11], v[32:47]
	s_waitcnt lgkmcnt(4)
	v_mfma_f32_32x32x16_bf16 v[16:31], a[0:3], a[12:15], v[16:31]
	v_mfma_f32_32x32x16_bf16 v[0:15], a[4:7], a[12:15], v[0:15]
	s_and_b32 m0, s32, 7
	s_lshl_b32 m0, m0, 11
	s_add_i32 m0, m0, 0x14000
	s_nop 0
	global_load_lds_dwordx4 v[178:179], off
	s_waitcnt lgkmcnt(1)
	v_mfma_f32_32x32x16_bf16 v[48:63], a[16:19], a[24:27], v[48:63]
	v_mfma_f32_32x32x16_bf16 v[32:47], a[20:23], a[24:27], v[32:47]
	s_and_b32 m0, s32, 7
	s_lshl_b32 m0, m0, 11
	s_add_i32 m0, m0, 0x14400
	s_nop 0
	global_load_lds_dwordx4 v[180:181], off
	s_waitcnt vmcnt(6)
	s_waitcnt lgkmcnt(0)
	s_barrier
	ds_read_b128 a[12:15], v81 offset:4096
	ds_read_b128 a[8:11], v81
	ds_read_b128 a[4:7], v82 offset:36864
	ds_read_b128 a[0:3], v82 offset:32768
	v_mfma_f32_32x32x16_bf16 v[16:31], a[16:19], a[28:31], v[16:31]
	v_lshl_add_u64 v[158:159], v[66:67], 0, s[30:31]
	v_lshl_add_u64 v[160:161], v[68:69], 0, s[30:31]
	v_lshl_add_u64 v[162:163], v[70:71], 0, s[30:31]
	v_mfma_f32_32x32x16_bf16 v[0:15], a[20:23], a[28:31], v[0:15]
	s_and_b32 m0, s32, 7
	s_lshl_b32 m0, m0, 12
	s_add_i32 m0, m0, 0x18000
	s_nop 0
	global_load_lds_dwordx4 v[158:159], off
	v_lshl_add_u64 v[164:165], v[72:73], 0, s[30:31]
	v_lshl_add_u64 v[166:167], v[74:75], 0, s[30:31]
	v_lshl_add_u64 v[168:169], v[76:77], 0, s[30:31]
	s_mov_b64 s[30:31], 0x300
	ds_read_b128 a[16:19], v84 offset:32768
	ds_read_b128 a[20:23], v84 offset:36864
	ds_read_b128 a[24:27], v83
	ds_read_b128 a[28:31], v83 offset:4096
	s_waitcnt lgkmcnt(4)
	v_mfma_f32_32x32x16_bf16 v[48:63], a[0:3], a[8:11], v[48:63]
	s_nop 0
	v_readfirstlane_b32 s42, v113
	v_mfma_f32_32x32x16_bf16 v[32:47], a[4:7], a[8:11], v[32:47]
	v_mfma_f32_32x32x16_bf16 v[16:31], a[0:3], a[12:15], v[16:31]
	s_and_b32 m0, s32, 7
	s_lshl_b32 m0, m0, 12
	s_add_i32 m0, m0, 0x18400
	s_nop 0
	global_load_lds_dwordx4 v[160:161], off
	v_mfma_f32_32x32x16_bf16 v[0:15], a[4:7], a[12:15], v[0:15]
	ds_read_b128 a[0:3], v86 offset:32768
	ds_read_b128 a[4:7], v86 offset:36864
	ds_read_b128 a[8:11], v85
	ds_read_b128 a[12:15], v85 offset:4096
	s_waitcnt lgkmcnt(5)
	v_mfma_f32_32x32x16_bf16 v[48:63], a[16:19], a[24:27], v[48:63]
	v_mfma_f32_32x32x16_bf16 v[32:47], a[20:23], a[24:27], v[32:47]
	s_and_b32 m0, s32, 7
	s_lshl_b32 m0, m0, 12
	s_add_i32 m0, m0, 0x18800
	s_nop 0
	global_load_lds_dwordx4 v[162:163], off
	s_waitcnt lgkmcnt(4)
	v_mfma_f32_32x32x16_bf16 v[16:31], a[16:19], a[28:31], v[16:31]
	v_mfma_f32_32x32x16_bf16 v[0:15], a[20:23], a[28:31], v[0:15]
	ds_read_b128 a[16:19], v88 offset:32768
	ds_read_b128 a[20:23], v88 offset:36864
	ds_read_b128 a[24:27], v87
	ds_read_b128 a[28:31], v87 offset:4096
	s_waitcnt lgkmcnt(5)
	v_mfma_f32_32x32x16_bf16 v[48:63], a[0:3], a[8:11], v[48:63]
	s_and_b32 m0, s32, 7
	s_lshl_b32 m0, m0, 12
	s_add_i32 m0, m0, 0x18c00
	s_nop 0
	global_load_lds_dwordx4 v[164:165], off
	v_mfma_f32_32x32x16_bf16 v[32:47], a[4:7], a[8:11], v[32:47]
	s_waitcnt lgkmcnt(4)
	v_mfma_f32_32x32x16_bf16 v[16:31], a[0:3], a[12:15], v[16:31]
	v_mfma_f32_32x32x16_bf16 v[0:15], a[4:7], a[12:15], v[0:15]
	s_and_b32 m0, s32, 7
	s_lshl_b32 m0, m0, 11
	s_add_i32 m0, m0, 0x20000
	s_nop 0
	global_load_lds_dwordx4 v[166:167], off
	s_waitcnt lgkmcnt(1)
	v_mfma_f32_32x32x16_bf16 v[48:63], a[16:19], a[24:27], v[48:63]
	v_mfma_f32_32x32x16_bf16 v[32:47], a[20:23], a[24:27], v[32:47]
	s_and_b32 m0, s32, 7
	s_lshl_b32 m0, m0, 11
	s_add_i32 m0, m0, 0x20400
	s_nop 0
	global_load_lds_dwordx4 v[168:169], off
	s_waitcnt vmcnt(6)
	s_waitcnt lgkmcnt(0)
	s_barrier
	ds_read_b128 a[12:15], v81 offset:53248
	ds_read_b128 a[8:11], v81 offset:49152
	ds_read_b128 a[4:7], v89
	ds_read_b128 a[0:3], v91
	v_mfma_f32_32x32x16_bf16 v[16:31], a[16:19], a[28:31], v[16:31]
	v_lshl_add_u64 v[170:171], v[66:67], 0, s[30:31]
	v_lshl_add_u64 v[172:173], v[68:69], 0, s[30:31]
	s_nop 0
	v_readfirstlane_b32 s43, v114
	s_nop 0
	v_lshl_add_u64 v[174:175], v[70:71], 0, s[30:31]
	s_nop 0
	v_mfma_f32_32x32x16_bf16 v[0:15], a[20:23], a[28:31], v[0:15]
	s_and_b32 m0, s32, 7
	s_lshl_b32 m0, m0, 12
	s_add_i32 m0, m0, 0x0
	s_nop 0
	global_load_lds_dwordx4 v[170:171], off
	v_lshl_add_u64 v[176:177], v[72:73], 0, s[30:31]
	s_nop 0
	v_readfirstlane_b32 s44, v115
	s_nop 0
	v_lshl_add_u64 v[178:179], v[74:75], 0, s[30:31]
	s_nop 0
	v_readfirstlane_b32 s45, v116
	s_nop 0
	v_lshl_add_u64 v[180:181], v[76:77], 0, s[30:31]
	s_nop 0
	s_mov_b64 s[30:31], 0x380
	ds_read_b128 a[16:19], v92
	ds_read_b128 a[20:23], v90
	ds_read_b128 a[24:27], v83 offset:49152
	ds_read_b128 a[28:31], v83 offset:53248
	s_waitcnt lgkmcnt(4)
	v_mfma_f32_32x32x16_bf16 v[48:63], a[0:3], a[8:11], v[48:63]
	s_nop 0
	v_readfirstlane_b32 s36, v119
	v_readfirstlane_b32 s46, v117
	v_readfirstlane_b32 s47, v118
	v_mfma_f32_32x32x16_bf16 v[32:47], a[4:7], a[8:11], v[32:47]
	v_mfma_f32_32x32x16_bf16 v[16:31], a[0:3], a[12:15], v[16:31]
	s_and_b32 m0, s32, 7
	s_lshl_b32 m0, m0, 12
	s_add_i32 m0, m0, 0x400
	s_nop 0
	global_load_lds_dwordx4 v[172:173], off
	v_mfma_f32_32x32x16_bf16 v[0:15], a[4:7], a[12:15], v[0:15]
	ds_read_b128 a[0:3], v94
	ds_read_b128 a[4:7], v93
	ds_read_b128 a[8:11], v85 offset:49152
	ds_read_b128 a[12:15], v85 offset:53248
	s_waitcnt lgkmcnt(5)
	v_mfma_f32_32x32x16_bf16 v[48:63], a[16:19], a[24:27], v[48:63]
	v_mfma_f32_32x32x16_bf16 v[32:47], a[20:23], a[24:27], v[32:47]
	s_and_b32 m0, s32, 7
	s_lshl_b32 m0, m0, 12
	s_add_i32 m0, m0, 0x800
	s_nop 0
	global_load_lds_dwordx4 v[174:175], off
	s_waitcnt lgkmcnt(4)
	v_mfma_f32_32x32x16_bf16 v[16:31], a[16:19], a[28:31], v[16:31]
	v_mfma_f32_32x32x16_bf16 v[0:15], a[20:23], a[28:31], v[0:15]
	ds_read_b128 a[16:19], v96
	ds_read_b128 a[20:23], v95
	ds_read_b128 a[24:27], v87 offset:49152
	ds_read_b128 a[28:31], v87 offset:53248
	s_waitcnt lgkmcnt(5)
	v_mfma_f32_32x32x16_bf16 v[48:63], a[0:3], a[8:11], v[48:63]
	s_and_b32 m0, s32, 7
	s_lshl_b32 m0, m0, 12
	s_add_i32 m0, m0, 0xc00
	s_nop 0
	global_load_lds_dwordx4 v[176:177], off
	v_mfma_f32_32x32x16_bf16 v[32:47], a[4:7], a[8:11], v[32:47]
	s_waitcnt lgkmcnt(4)
	v_mfma_f32_32x32x16_bf16 v[16:31], a[0:3], a[12:15], v[16:31]
	v_mfma_f32_32x32x16_bf16 v[0:15], a[4:7], a[12:15], v[0:15]
	s_and_b32 m0, s32, 7
	s_lshl_b32 m0, m0, 11
	s_add_i32 m0, m0, 0x8000
	s_nop 0
	global_load_lds_dwordx4 v[178:179], off
	s_waitcnt lgkmcnt(1)
	v_mfma_f32_32x32x16_bf16 v[48:63], a[16:19], a[24:27], v[48:63]
	v_mfma_f32_32x32x16_bf16 v[32:47], a[20:23], a[24:27], v[32:47]
	s_and_b32 m0, s32, 7
	s_lshl_b32 m0, m0, 11
	s_add_i32 m0, m0, 0x8400
	s_nop 0
	global_load_lds_dwordx4 v[180:181], off
	s_waitcnt vmcnt(6)
	s_waitcnt lgkmcnt(0)
	s_barrier
	ds_read_b128 a[12:15], v100
	ds_read_b128 a[8:11], v99
	ds_read_b128 a[4:7], v98
	ds_read_b128 a[0:3], v97
	v_mfma_f32_32x32x16_bf16 v[16:31], a[16:19], a[28:31], v[16:31]
	v_lshl_add_u64 v[158:159], v[66:67], 0, s[30:31]
	v_lshl_add_u64 v[160:161], v[68:69], 0, s[30:31]
	s_nop 0
	v_readfirstlane_b32 s37, v120
	s_nop 0
	v_lshl_add_u64 v[162:163], v[70:71], 0, s[30:31]
	s_nop 0
	v_mfma_f32_32x32x16_bf16 v[0:15], a[20:23], a[28:31], v[0:15]
	s_and_b32 m0, s32, 7
	s_lshl_b32 m0, m0, 12
	s_add_i32 m0, m0, 0xc000
	s_nop 0
	global_load_lds_dwordx4 v[158:159], off
	v_lshl_add_u64 v[164:165], v[72:73], 0, s[30:31]
	s_nop 0
	v_readfirstlane_b32 s38, v121
	s_nop 0
	v_lshl_add_u64 v[166:167], v[74:75], 0, s[30:31]
	s_nop 0
	v_readfirstlane_b32 s39, v122
	s_nop 0
	v_lshl_add_u64 v[168:169], v[76:77], 0, s[30:31]
	s_nop 0
	s_mov_b64 s[30:31], 0x400
	ds_read_b128 a[16:19], v101
	ds_read_b128 a[20:23], v102
	ds_read_b128 a[24:27], v103
	ds_read_b128 a[28:31], v104
	s_waitcnt lgkmcnt(4)
	v_mfma_f32_32x32x16_bf16 v[48:63], a[0:3], a[8:11], v[48:63]
	s_nop 0
	v_readfirstlane_b32 s20, v125
	v_readfirstlane_b32 s40, v123
	v_readfirstlane_b32 s41, v124
	v_mfma_f32_32x32x16_bf16 v[32:47], a[4:7], a[8:11], v[32:47]
	v_mfma_f32_32x32x16_bf16 v[16:31], a[0:3], a[12:15], v[16:31]
	s_and_b32 m0, s32, 7
	s_lshl_b32 m0, m0, 12
	s_add_i32 m0, m0, 0xc400
	s_nop 0
	global_load_lds_dwordx4 v[160:161], off
	v_mfma_f32_32x32x16_bf16 v[0:15], a[4:7], a[12:15], v[0:15]
	ds_read_b128 a[0:3], v105
	ds_read_b128 a[4:7], v106
	ds_read_b128 a[8:11], v107
	ds_read_b128 a[12:15], v108
	s_waitcnt lgkmcnt(5)
	v_mfma_f32_32x32x16_bf16 v[48:63], a[16:19], a[24:27], v[48:63]
	v_mfma_f32_32x32x16_bf16 v[32:47], a[20:23], a[24:27], v[32:47]
	s_and_b32 m0, s32, 7
	s_lshl_b32 m0, m0, 12
	s_add_i32 m0, m0, 0xc800
	s_nop 0
	global_load_lds_dwordx4 v[162:163], off
	s_waitcnt lgkmcnt(4)
	v_mfma_f32_32x32x16_bf16 v[16:31], a[16:19], a[28:31], v[16:31]
	v_mfma_f32_32x32x16_bf16 v[0:15], a[20:23], a[28:31], v[0:15]
	ds_read_b128 a[16:19], v109
	ds_read_b128 a[20:23], v110
	ds_read_b128 a[24:27], v111
	ds_read_b128 a[28:31], v112
	s_waitcnt lgkmcnt(5)
	v_mfma_f32_32x32x16_bf16 v[48:63], a[0:3], a[8:11], v[48:63]
	s_and_b32 m0, s32, 7
	s_lshl_b32 m0, m0, 12
	s_add_i32 m0, m0, 0xcc00
	s_nop 0
	global_load_lds_dwordx4 v[164:165], off
	v_mfma_f32_32x32x16_bf16 v[32:47], a[4:7], a[8:11], v[32:47]
	s_waitcnt lgkmcnt(4)
	v_mfma_f32_32x32x16_bf16 v[16:31], a[0:3], a[12:15], v[16:31]
	v_mfma_f32_32x32x16_bf16 v[0:15], a[4:7], a[12:15], v[0:15]
	s_and_b32 m0, s32, 7
	s_lshl_b32 m0, m0, 11
	s_add_i32 m0, m0, 0x14000
	s_nop 0
	global_load_lds_dwordx4 v[166:167], off
	s_waitcnt lgkmcnt(1)
	v_mfma_f32_32x32x16_bf16 v[48:63], a[16:19], a[24:27], v[48:63]
	v_mfma_f32_32x32x16_bf16 v[32:47], a[20:23], a[24:27], v[32:47]
	s_and_b32 m0, s32, 7
	s_lshl_b32 m0, m0, 11
	s_add_i32 m0, m0, 0x14400
	s_nop 0
	global_load_lds_dwordx4 v[168:169], off
	s_waitcnt vmcnt(6)
	s_waitcnt lgkmcnt(0)
	s_barrier
	ds_read_b128 a[12:15], v81 offset:4096
	ds_read_b128 a[8:11], v81
	ds_read_b128 a[4:7], v82 offset:36864
	ds_read_b128 a[0:3], v82 offset:32768
	v_mfma_f32_32x32x16_bf16 v[16:31], a[16:19], a[28:31], v[16:31]
	v_lshl_add_u64 v[170:171], v[66:67], 0, s[30:31]
	v_lshl_add_u64 v[172:173], v[68:69], 0, s[30:31]
	s_nop 0
	v_readfirstlane_b32 s21, v126
	s_nop 0
	v_lshl_add_u64 v[174:175], v[70:71], 0, s[30:31]
	s_nop 0
	v_mfma_f32_32x32x16_bf16 v[0:15], a[20:23], a[28:31], v[0:15]
	s_and_b32 m0, s32, 7
	s_lshl_b32 m0, m0, 12
	s_add_i32 m0, m0, 0x18000
	s_nop 0
	global_load_lds_dwordx4 v[170:171], off
	v_lshl_add_u64 v[176:177], v[72:73], 0, s[30:31]
	s_nop 0
	v_readfirstlane_b32 s23, v127
	s_nop 0
	v_lshl_add_u64 v[178:179], v[74:75], 0, s[30:31]
	s_nop 0
	v_readfirstlane_b32 s28, v128
	s_nop 0
	v_lshl_add_u64 v[180:181], v[76:77], 0, s[30:31]
	s_nop 0
	s_mov_b64 s[30:31], 0x480
	ds_read_b128 a[16:19], v84 offset:32768
	ds_read_b128 a[20:23], v84 offset:36864
	ds_read_b128 a[24:27], v83
	ds_read_b128 a[28:31], v83 offset:4096
	s_waitcnt lgkmcnt(4)
	v_mfma_f32_32x32x16_bf16 v[48:63], a[0:3], a[8:11], v[48:63]
	s_nop 0
	v_lshl_add_u64 v[164:165], v[72:73], 0, s[30:31]
	v_readfirstlane_b32 s29, v130
	v_readfirstlane_b32 s33, v129
	v_mfma_f32_32x32x16_bf16 v[32:47], a[4:7], a[8:11], v[32:47]
	v_mfma_f32_32x32x16_bf16 v[16:31], a[0:3], a[12:15], v[16:31]
	s_and_b32 m0, s32, 7
	s_lshl_b32 m0, m0, 12
	s_add_i32 m0, m0, 0x18400
	s_nop 0
	global_load_lds_dwordx4 v[172:173], off
	v_mfma_f32_32x32x16_bf16 v[0:15], a[4:7], a[12:15], v[0:15]
	ds_read_b128 a[0:3], v86 offset:32768
	ds_read_b128 a[4:7], v86 offset:36864
	ds_read_b128 a[8:11], v85
	ds_read_b128 a[12:15], v85 offset:4096
	s_waitcnt lgkmcnt(5)
	v_mfma_f32_32x32x16_bf16 v[48:63], a[16:19], a[24:27], v[48:63]
	v_mfma_f32_32x32x16_bf16 v[32:47], a[20:23], a[24:27], v[32:47]
	s_and_b32 m0, s32, 7
	s_lshl_b32 m0, m0, 12
	s_add_i32 m0, m0, 0x18800
	s_nop 0
	global_load_lds_dwordx4 v[174:175], off
	s_waitcnt lgkmcnt(4)
	v_mfma_f32_32x32x16_bf16 v[16:31], a[16:19], a[28:31], v[16:31]
	v_mfma_f32_32x32x16_bf16 v[0:15], a[20:23], a[28:31], v[0:15]
	ds_read_b128 a[16:19], v88 offset:32768
	ds_read_b128 a[20:23], v88 offset:36864
	ds_read_b128 a[24:27], v87
	ds_read_b128 a[28:31], v87 offset:4096
	s_waitcnt lgkmcnt(5)
	v_mfma_f32_32x32x16_bf16 v[48:63], a[0:3], a[8:11], v[48:63]
	s_and_b32 m0, s32, 7
	s_lshl_b32 m0, m0, 12
	s_add_i32 m0, m0, 0x18c00
	s_nop 0
	global_load_lds_dwordx4 v[176:177], off
	v_mfma_f32_32x32x16_bf16 v[32:47], a[4:7], a[8:11], v[32:47]
	s_waitcnt lgkmcnt(4)
	v_mfma_f32_32x32x16_bf16 v[16:31], a[0:3], a[12:15], v[16:31]
	v_mfma_f32_32x32x16_bf16 v[0:15], a[4:7], a[12:15], v[0:15]
	s_and_b32 m0, s32, 7
	s_lshl_b32 m0, m0, 11
	s_add_i32 m0, m0, 0x20000
	s_nop 0
	global_load_lds_dwordx4 v[178:179], off
	s_waitcnt lgkmcnt(1)
	v_mfma_f32_32x32x16_bf16 v[48:63], a[16:19], a[24:27], v[48:63]
	v_mfma_f32_32x32x16_bf16 v[32:47], a[20:23], a[24:27], v[32:47]
	s_and_b32 m0, s32, 7
	s_lshl_b32 m0, m0, 11
	s_add_i32 m0, m0, 0x20400
	s_nop 0
	global_load_lds_dwordx4 v[180:181], off
	s_waitcnt vmcnt(6)
	s_waitcnt lgkmcnt(0)
	s_barrier
	ds_read_b128 a[12:15], v81 offset:53248
	ds_read_b128 a[8:11], v81 offset:49152
	ds_read_b128 a[4:7], v89
	ds_read_b128 a[0:3], v91
	v_mfma_f32_32x32x16_bf16 v[16:31], a[16:19], a[28:31], v[16:31]
	v_lshl_add_u64 v[158:159], v[66:67], 0, s[30:31]
	v_lshl_add_u64 v[160:161], v[68:69], 0, s[30:31]
	v_lshl_add_u64 v[162:163], v[70:71], 0, s[30:31]
	v_mfma_f32_32x32x16_bf16 v[0:15], a[20:23], a[28:31], v[0:15]
	s_and_b32 m0, s32, 7
	s_lshl_b32 m0, m0, 12
	s_add_i32 m0, m0, 0x0
	s_nop 0
	global_load_lds_dwordx4 v[158:159], off
	v_lshl_add_u64 v[166:167], v[74:75], 0, s[30:31]
	v_lshl_add_u64 v[168:169], v[76:77], 0, s[30:31]
	s_mov_b64 s[30:31], 0x500
	ds_read_b128 a[16:19], v92
	ds_read_b128 a[20:23], v90
	ds_read_b128 a[24:27], v83 offset:49152
	ds_read_b128 a[28:31], v83 offset:53248
	s_waitcnt lgkmcnt(4)
	v_mfma_f32_32x32x16_bf16 v[48:63], a[0:3], a[8:11], v[48:63]
	v_lshl_add_u64 v[176:177], v[72:73], 0, s[30:31]
	v_mfma_f32_32x32x16_bf16 v[32:47], a[4:7], a[8:11], v[32:47]
	v_mfma_f32_32x32x16_bf16 v[16:31], a[0:3], a[12:15], v[16:31]
	s_and_b32 m0, s32, 7
	s_lshl_b32 m0, m0, 12
	s_add_i32 m0, m0, 0x400
	s_nop 0
	global_load_lds_dwordx4 v[160:161], off
	v_mfma_f32_32x32x16_bf16 v[0:15], a[4:7], a[12:15], v[0:15]
	ds_read_b128 a[0:3], v94
	ds_read_b128 a[4:7], v93
	ds_read_b128 a[8:11], v85 offset:49152
	ds_read_b128 a[12:15], v85 offset:53248
	s_waitcnt lgkmcnt(5)
	v_mfma_f32_32x32x16_bf16 v[48:63], a[16:19], a[24:27], v[48:63]
	v_mfma_f32_32x32x16_bf16 v[32:47], a[20:23], a[24:27], v[32:47]
	s_and_b32 m0, s32, 7
	s_lshl_b32 m0, m0, 12
	s_add_i32 m0, m0, 0x800
	s_nop 0
	global_load_lds_dwordx4 v[162:163], off
	s_waitcnt lgkmcnt(4)
	v_mfma_f32_32x32x16_bf16 v[16:31], a[16:19], a[28:31], v[16:31]
	v_mfma_f32_32x32x16_bf16 v[0:15], a[20:23], a[28:31], v[0:15]
	ds_read_b128 a[16:19], v96
	ds_read_b128 a[20:23], v95
	ds_read_b128 a[24:27], v87 offset:49152
	ds_read_b128 a[28:31], v87 offset:53248
	s_waitcnt lgkmcnt(5)
	v_mfma_f32_32x32x16_bf16 v[48:63], a[0:3], a[8:11], v[48:63]
	s_and_b32 m0, s32, 7
	s_lshl_b32 m0, m0, 12
	s_add_i32 m0, m0, 0xc00
	s_nop 0
	global_load_lds_dwordx4 v[164:165], off
	v_mfma_f32_32x32x16_bf16 v[32:47], a[4:7], a[8:11], v[32:47]
	s_waitcnt lgkmcnt(4)
	v_mfma_f32_32x32x16_bf16 v[16:31], a[0:3], a[12:15], v[16:31]
	v_mfma_f32_32x32x16_bf16 v[0:15], a[4:7], a[12:15], v[0:15]
	s_and_b32 m0, s32, 7
	s_lshl_b32 m0, m0, 11
	s_add_i32 m0, m0, 0x8000
	s_nop 0
	global_load_lds_dwordx4 v[166:167], off
	s_waitcnt lgkmcnt(1)
	v_mfma_f32_32x32x16_bf16 v[48:63], a[16:19], a[24:27], v[48:63]
	v_mfma_f32_32x32x16_bf16 v[32:47], a[20:23], a[24:27], v[32:47]
	s_and_b32 m0, s32, 7
	s_lshl_b32 m0, m0, 11
	s_add_i32 m0, m0, 0x8400
	s_nop 0
	global_load_lds_dwordx4 v[168:169], off
	s_waitcnt vmcnt(6)
	s_waitcnt lgkmcnt(0)
	s_barrier
	ds_read_b128 a[12:15], v100
	ds_read_b128 a[8:11], v99
	ds_read_b128 a[4:7], v98
	ds_read_b128 a[0:3], v97
	v_mfma_f32_32x32x16_bf16 v[16:31], a[16:19], a[28:31], v[16:31]
	v_lshl_add_u64 v[170:171], v[66:67], 0, s[30:31]
	v_lshl_add_u64 v[172:173], v[68:69], 0, s[30:31]
	v_lshl_add_u64 v[174:175], v[70:71], 0, s[30:31]
	v_mfma_f32_32x32x16_bf16 v[0:15], a[20:23], a[28:31], v[0:15]
	s_and_b32 m0, s32, 7
	s_lshl_b32 m0, m0, 12
	s_add_i32 m0, m0, 0xc000
	s_nop 0
	global_load_lds_dwordx4 v[170:171], off
	v_lshl_add_u64 v[178:179], v[74:75], 0, s[30:31]
	v_lshl_add_u64 v[180:181], v[76:77], 0, s[30:31]
	s_mov_b64 s[30:31], 0x580
	ds_read_b128 a[16:19], v101
	ds_read_b128 a[20:23], v102
	ds_read_b128 a[24:27], v103
	ds_read_b128 a[28:31], v104
	s_waitcnt lgkmcnt(4)
	v_mfma_f32_32x32x16_bf16 v[48:63], a[0:3], a[8:11], v[48:63]
	v_lshl_add_u64 v[164:165], v[72:73], 0, s[30:31]
	v_mfma_f32_32x32x16_bf16 v[32:47], a[4:7], a[8:11], v[32:47]
	v_mfma_f32_32x32x16_bf16 v[16:31], a[0:3], a[12:15], v[16:31]
	s_and_b32 m0, s32, 7
	s_lshl_b32 m0, m0, 12
	s_add_i32 m0, m0, 0xc400
	s_nop 0
	global_load_lds_dwordx4 v[172:173], off
	v_mfma_f32_32x32x16_bf16 v[0:15], a[4:7], a[12:15], v[0:15]
	ds_read_b128 a[0:3], v105
	ds_read_b128 a[4:7], v106
	ds_read_b128 a[8:11], v107
	ds_read_b128 a[12:15], v108
	s_waitcnt lgkmcnt(5)
	v_mfma_f32_32x32x16_bf16 v[48:63], a[16:19], a[24:27], v[48:63]
	v_mfma_f32_32x32x16_bf16 v[32:47], a[20:23], a[24:27], v[32:47]
	s_and_b32 m0, s32, 7
	s_lshl_b32 m0, m0, 12
	s_add_i32 m0, m0, 0xc800
	s_nop 0
	global_load_lds_dwordx4 v[174:175], off
	s_waitcnt lgkmcnt(4)
	v_mfma_f32_32x32x16_bf16 v[16:31], a[16:19], a[28:31], v[16:31]
	v_mfma_f32_32x32x16_bf16 v[0:15], a[20:23], a[28:31], v[0:15]
	ds_read_b128 a[16:19], v109
	ds_read_b128 a[20:23], v110
	ds_read_b128 a[24:27], v111
	ds_read_b128 a[28:31], v112
	s_waitcnt lgkmcnt(5)
	v_mfma_f32_32x32x16_bf16 v[48:63], a[0:3], a[8:11], v[48:63]
	s_and_b32 m0, s32, 7
	s_lshl_b32 m0, m0, 12
	s_add_i32 m0, m0, 0xcc00
	s_nop 0
	global_load_lds_dwordx4 v[176:177], off
	v_mfma_f32_32x32x16_bf16 v[32:47], a[4:7], a[8:11], v[32:47]
	s_waitcnt lgkmcnt(4)
	v_mfma_f32_32x32x16_bf16 v[16:31], a[0:3], a[12:15], v[16:31]
	v_mfma_f32_32x32x16_bf16 v[0:15], a[4:7], a[12:15], v[0:15]
	s_and_b32 m0, s32, 7
	s_lshl_b32 m0, m0, 11
	s_add_i32 m0, m0, 0x14000
	s_nop 0
	global_load_lds_dwordx4 v[178:179], off
	s_waitcnt lgkmcnt(1)
	v_mfma_f32_32x32x16_bf16 v[48:63], a[16:19], a[24:27], v[48:63]
	v_mfma_f32_32x32x16_bf16 v[32:47], a[20:23], a[24:27], v[32:47]
	s_and_b32 m0, s32, 7
	s_lshl_b32 m0, m0, 11
	s_add_i32 m0, m0, 0x14400
	s_nop 0
	global_load_lds_dwordx4 v[180:181], off
	s_waitcnt vmcnt(6)
	s_waitcnt lgkmcnt(0)
	s_barrier
	ds_read_b128 a[12:15], v81 offset:4096
	ds_read_b128 a[8:11], v81
	ds_read_b128 a[4:7], v82 offset:36864
	ds_read_b128 a[0:3], v82 offset:32768
	v_mfma_f32_32x32x16_bf16 v[16:31], a[16:19], a[28:31], v[16:31]
	v_lshl_add_u64 v[158:159], v[66:67], 0, s[30:31]
	v_lshl_add_u64 v[160:161], v[68:69], 0, s[30:31]
	v_lshl_add_u64 v[162:163], v[70:71], 0, s[30:31]
	v_mfma_f32_32x32x16_bf16 v[0:15], a[20:23], a[28:31], v[0:15]
	s_and_b32 m0, s32, 7
	s_lshl_b32 m0, m0, 12
	s_add_i32 m0, m0, 0x18000
	s_nop 0
	global_load_lds_dwordx4 v[158:159], off
	v_lshl_add_u64 v[166:167], v[74:75], 0, s[30:31]
	v_lshl_add_u64 v[168:169], v[76:77], 0, s[30:31]
	s_mov_b64 s[30:31], 0x600
	ds_read_b128 a[16:19], v84 offset:32768
	ds_read_b128 a[20:23], v84 offset:36864
	ds_read_b128 a[24:27], v83
	ds_read_b128 a[28:31], v83 offset:4096
	s_waitcnt lgkmcnt(4)
	v_mfma_f32_32x32x16_bf16 v[48:63], a[0:3], a[8:11], v[48:63]
	v_mfma_f32_32x32x16_bf16 v[32:47], a[4:7], a[8:11], v[32:47]
	v_mfma_f32_32x32x16_bf16 v[16:31], a[0:3], a[12:15], v[16:31]
	s_and_b32 m0, s32, 7
	s_lshl_b32 m0, m0, 12
	s_add_i32 m0, m0, 0x18400
	s_nop 0
	global_load_lds_dwordx4 v[160:161], off
	v_mfma_f32_32x32x16_bf16 v[0:15], a[4:7], a[12:15], v[0:15]
	ds_read_b128 a[0:3], v86 offset:32768
	ds_read_b128 a[4:7], v86 offset:36864
	ds_read_b128 a[8:11], v85
	ds_read_b128 a[12:15], v85 offset:4096
	s_waitcnt lgkmcnt(5)
	v_mfma_f32_32x32x16_bf16 v[48:63], a[16:19], a[24:27], v[48:63]
	v_mfma_f32_32x32x16_bf16 v[32:47], a[20:23], a[24:27], v[32:47]
	s_and_b32 m0, s32, 7
	s_lshl_b32 m0, m0, 12
	s_add_i32 m0, m0, 0x18800
	s_nop 0
	global_load_lds_dwordx4 v[162:163], off
	s_waitcnt lgkmcnt(4)
	v_mfma_f32_32x32x16_bf16 v[16:31], a[16:19], a[28:31], v[16:31]
	v_mfma_f32_32x32x16_bf16 v[0:15], a[20:23], a[28:31], v[0:15]
	ds_read_b128 a[16:19], v88 offset:32768
	ds_read_b128 a[20:23], v88 offset:36864
	ds_read_b128 a[24:27], v87
	ds_read_b128 a[28:31], v87 offset:4096
	s_waitcnt lgkmcnt(5)
	v_mfma_f32_32x32x16_bf16 v[48:63], a[0:3], a[8:11], v[48:63]
	s_and_b32 m0, s32, 7
	s_lshl_b32 m0, m0, 12
	s_add_i32 m0, m0, 0x18c00
	s_nop 0
	global_load_lds_dwordx4 v[164:165], off
	v_mfma_f32_32x32x16_bf16 v[32:47], a[4:7], a[8:11], v[32:47]
	s_waitcnt lgkmcnt(4)
	v_mfma_f32_32x32x16_bf16 v[16:31], a[0:3], a[12:15], v[16:31]
	v_mfma_f32_32x32x16_bf16 v[0:15], a[4:7], a[12:15], v[0:15]
	s_and_b32 m0, s32, 7
	s_lshl_b32 m0, m0, 11
	s_add_i32 m0, m0, 0x20000
	s_nop 0
	global_load_lds_dwordx4 v[166:167], off
	s_waitcnt lgkmcnt(1)
	v_mfma_f32_32x32x16_bf16 v[48:63], a[16:19], a[24:27], v[48:63]
	v_mfma_f32_32x32x16_bf16 v[32:47], a[20:23], a[24:27], v[32:47]
	s_and_b32 m0, s32, 7
	s_lshl_b32 m0, m0, 11
	s_add_i32 m0, m0, 0x20400
	s_nop 0
	global_load_lds_dwordx4 v[168:169], off
	s_waitcnt vmcnt(6)
	s_waitcnt lgkmcnt(0)
	s_barrier
	ds_read_b128 a[12:15], v81 offset:53248
	ds_read_b128 a[8:11], v81 offset:49152
	ds_read_b128 a[4:7], v89
	ds_read_b128 a[0:3], v91
	v_mfma_f32_32x32x16_bf16 v[16:31], a[16:19], a[28:31], v[16:31]
	v_lshl_add_u64 v[170:171], v[66:67], 0, s[30:31]
	v_lshl_add_u64 v[172:173], v[68:69], 0, s[30:31]
	v_lshl_add_u64 v[174:175], v[70:71], 0, s[30:31]
	v_mfma_f32_32x32x16_bf16 v[0:15], a[20:23], a[28:31], v[0:15]
	s_and_b32 m0, s32, 7
	s_lshl_b32 m0, m0, 12
	s_add_i32 m0, m0, 0x0
	s_nop 0
	global_load_lds_dwordx4 v[170:171], off
	v_lshl_add_u64 v[176:177], v[72:73], 0, s[30:31]
	v_lshl_add_u64 v[178:179], v[74:75], 0, s[30:31]
	v_lshl_add_u64 v[180:181], v[76:77], 0, s[30:31]
	s_mov_b64 s[30:31], 0x680
	ds_read_b128 a[16:19], v92
	ds_read_b128 a[20:23], v90
	ds_read_b128 a[24:27], v83 offset:49152
	ds_read_b128 a[28:31], v83 offset:53248
	s_waitcnt lgkmcnt(4)
	v_mfma_f32_32x32x16_bf16 v[48:63], a[0:3], a[8:11], v[48:63]
	v_mfma_f32_32x32x16_bf16 v[32:47], a[4:7], a[8:11], v[32:47]
	v_mfma_f32_32x32x16_bf16 v[16:31], a[0:3], a[12:15], v[16:31]
	s_and_b32 m0, s32, 7
	s_lshl_b32 m0, m0, 12
	s_add_i32 m0, m0, 0x400
	s_nop 0
	global_load_lds_dwordx4 v[172:173], off
	v_mfma_f32_32x32x16_bf16 v[0:15], a[4:7], a[12:15], v[0:15]
	ds_read_b128 a[0:3], v94
	ds_read_b128 a[4:7], v93
	ds_read_b128 a[8:11], v85 offset:49152
	ds_read_b128 a[12:15], v85 offset:53248
	s_waitcnt lgkmcnt(5)
	v_mfma_f32_32x32x16_bf16 v[48:63], a[16:19], a[24:27], v[48:63]
	v_mfma_f32_32x32x16_bf16 v[32:47], a[20:23], a[24:27], v[32:47]
	s_and_b32 m0, s32, 7
	s_lshl_b32 m0, m0, 12
	s_add_i32 m0, m0, 0x800
	s_nop 0
	global_load_lds_dwordx4 v[174:175], off
	s_waitcnt lgkmcnt(4)
	v_mfma_f32_32x32x16_bf16 v[16:31], a[16:19], a[28:31], v[16:31]
	v_mfma_f32_32x32x16_bf16 v[0:15], a[20:23], a[28:31], v[0:15]
	ds_read_b128 a[16:19], v96
	ds_read_b128 a[20:23], v95
	ds_read_b128 a[24:27], v87 offset:49152
	ds_read_b128 a[28:31], v87 offset:53248
	s_waitcnt lgkmcnt(5)
	v_mfma_f32_32x32x16_bf16 v[48:63], a[0:3], a[8:11], v[48:63]
	s_and_b32 m0, s32, 7
	s_lshl_b32 m0, m0, 12
	s_add_i32 m0, m0, 0xc00
	s_nop 0
	global_load_lds_dwordx4 v[176:177], off
	v_mfma_f32_32x32x16_bf16 v[32:47], a[4:7], a[8:11], v[32:47]
	s_waitcnt lgkmcnt(4)
	v_mfma_f32_32x32x16_bf16 v[16:31], a[0:3], a[12:15], v[16:31]
	v_mfma_f32_32x32x16_bf16 v[0:15], a[4:7], a[12:15], v[0:15]
	s_and_b32 m0, s32, 7
	s_lshl_b32 m0, m0, 11
	s_add_i32 m0, m0, 0x8000
	s_nop 0
	global_load_lds_dwordx4 v[178:179], off
	s_waitcnt lgkmcnt(1)
	v_mfma_f32_32x32x16_bf16 v[48:63], a[16:19], a[24:27], v[48:63]
	v_mfma_f32_32x32x16_bf16 v[32:47], a[20:23], a[24:27], v[32:47]
	s_and_b32 m0, s32, 7
	s_lshl_b32 m0, m0, 11
	s_add_i32 m0, m0, 0x8400
	s_nop 0
	global_load_lds_dwordx4 v[180:181], off
	s_waitcnt vmcnt(6)
	s_waitcnt lgkmcnt(0)
	s_barrier
	ds_read_b128 a[12:15], v100
	ds_read_b128 a[8:11], v99
	ds_read_b128 a[4:7], v98
	ds_read_b128 a[0:3], v97
	v_mfma_f32_32x32x16_bf16 v[16:31], a[16:19], a[28:31], v[16:31]
	v_lshl_add_u64 v[158:159], v[66:67], 0, s[30:31]
	v_lshl_add_u64 v[160:161], v[68:69], 0, s[30:31]
	v_lshl_add_u64 v[162:163], v[70:71], 0, s[30:31]
	v_mfma_f32_32x32x16_bf16 v[0:15], a[20:23], a[28:31], v[0:15]
	s_and_b32 m0, s32, 7
	s_lshl_b32 m0, m0, 12
	s_add_i32 m0, m0, 0xc000
	s_nop 0
	global_load_lds_dwordx4 v[158:159], off
	v_lshl_add_u64 v[164:165], v[72:73], 0, s[30:31]
	v_lshl_add_u64 v[166:167], v[74:75], 0, s[30:31]
	v_lshl_add_u64 v[168:169], v[76:77], 0, s[30:31]
	s_mov_b64 s[30:31], 0x700
	ds_read_b128 a[16:19], v101
	ds_read_b128 a[20:23], v102
	ds_read_b128 a[24:27], v103
	ds_read_b128 a[28:31], v104
	s_waitcnt lgkmcnt(4)
	v_mfma_f32_32x32x16_bf16 v[48:63], a[0:3], a[8:11], v[48:63]
	v_mfma_f32_32x32x16_bf16 v[32:47], a[4:7], a[8:11], v[32:47]
	v_mfma_f32_32x32x16_bf16 v[16:31], a[0:3], a[12:15], v[16:31]
	s_and_b32 m0, s32, 7
	s_lshl_b32 m0, m0, 12
	s_add_i32 m0, m0, 0xc400
	s_nop 0
	global_load_lds_dwordx4 v[160:161], off
	v_mfma_f32_32x32x16_bf16 v[0:15], a[4:7], a[12:15], v[0:15]
	ds_read_b128 a[0:3], v105
	ds_read_b128 a[4:7], v106
	ds_read_b128 a[8:11], v107
	ds_read_b128 a[12:15], v108
	s_waitcnt lgkmcnt(5)
	v_mfma_f32_32x32x16_bf16 v[48:63], a[16:19], a[24:27], v[48:63]
	v_mfma_f32_32x32x16_bf16 v[32:47], a[20:23], a[24:27], v[32:47]
	s_and_b32 m0, s32, 7
	s_lshl_b32 m0, m0, 12
	s_add_i32 m0, m0, 0xc800
	s_nop 0
	global_load_lds_dwordx4 v[162:163], off
	s_waitcnt lgkmcnt(4)
	v_mfma_f32_32x32x16_bf16 v[16:31], a[16:19], a[28:31], v[16:31]
	v_mfma_f32_32x32x16_bf16 v[0:15], a[20:23], a[28:31], v[0:15]
	ds_read_b128 a[16:19], v109
	ds_read_b128 a[20:23], v110
	ds_read_b128 a[24:27], v111
	ds_read_b128 a[28:31], v112
	s_waitcnt lgkmcnt(5)
	v_mfma_f32_32x32x16_bf16 v[48:63], a[0:3], a[8:11], v[48:63]
	s_and_b32 m0, s32, 7
	s_lshl_b32 m0, m0, 12
	s_add_i32 m0, m0, 0xcc00
	s_nop 0
	global_load_lds_dwordx4 v[164:165], off
	v_mfma_f32_32x32x16_bf16 v[32:47], a[4:7], a[8:11], v[32:47]
	s_waitcnt lgkmcnt(4)
	v_mfma_f32_32x32x16_bf16 v[16:31], a[0:3], a[12:15], v[16:31]
	v_mfma_f32_32x32x16_bf16 v[0:15], a[4:7], a[12:15], v[0:15]
	s_and_b32 m0, s32, 7
	s_lshl_b32 m0, m0, 11
	s_add_i32 m0, m0, 0x14000
	s_nop 0
	global_load_lds_dwordx4 v[166:167], off
	s_waitcnt lgkmcnt(1)
	v_mfma_f32_32x32x16_bf16 v[48:63], a[16:19], a[24:27], v[48:63]
	v_mfma_f32_32x32x16_bf16 v[32:47], a[20:23], a[24:27], v[32:47]
	s_and_b32 m0, s32, 7
	s_lshl_b32 m0, m0, 11
	s_add_i32 m0, m0, 0x14400
	s_nop 0
	global_load_lds_dwordx4 v[168:169], off
	s_waitcnt vmcnt(6)
	s_waitcnt lgkmcnt(0)
	s_barrier
	ds_read_b128 a[12:15], v81 offset:4096
	ds_read_b128 a[8:11], v81
	ds_read_b128 a[4:7], v82 offset:36864
	ds_read_b128 a[0:3], v82 offset:32768
	v_mfma_f32_32x32x16_bf16 v[16:31], a[16:19], a[28:31], v[16:31]
	v_lshl_add_u64 v[170:171], v[66:67], 0, s[30:31]
	v_lshl_add_u64 v[172:173], v[68:69], 0, s[30:31]
	v_lshl_add_u64 v[174:175], v[70:71], 0, s[30:31]
	v_mfma_f32_32x32x16_bf16 v[0:15], a[20:23], a[28:31], v[0:15]
	s_and_b32 m0, s32, 7
	s_lshl_b32 m0, m0, 12
	s_add_i32 m0, m0, 0x18000
	s_nop 0
	global_load_lds_dwordx4 v[170:171], off
	v_lshl_add_u64 v[176:177], v[72:73], 0, s[30:31]
	v_lshl_add_u64 v[178:179], v[74:75], 0, s[30:31]
	v_lshl_add_u64 v[180:181], v[76:77], 0, s[30:31]
	s_mov_b64 s[30:31], 0x780
	ds_read_b128 a[16:19], v84 offset:32768
	ds_read_b128 a[20:23], v84 offset:36864
	ds_read_b128 a[24:27], v83
	ds_read_b128 a[28:31], v83 offset:4096
	s_waitcnt lgkmcnt(4)
	v_mfma_f32_32x32x16_bf16 v[48:63], a[0:3], a[8:11], v[48:63]
	v_lshl_add_u64 v[158:159], v[66:67], 0, s[30:31]
	s_nop 0
	v_readlane_b32 s20, v214, 43
	v_mfma_f32_32x32x16_bf16 v[32:47], a[4:7], a[8:11], v[32:47]
	v_mfma_f32_32x32x16_bf16 v[16:31], a[0:3], a[12:15], v[16:31]
	s_and_b32 m0, s32, 7
	s_lshl_b32 m0, m0, 12
	s_add_i32 m0, m0, 0x18400
	s_nop 0
	global_load_lds_dwordx4 v[172:173], off
	v_mfma_f32_32x32x16_bf16 v[0:15], a[4:7], a[12:15], v[0:15]
	ds_read_b128 a[0:3], v86 offset:32768
	ds_read_b128 a[4:7], v86 offset:36864
	ds_read_b128 a[8:11], v85
	ds_read_b128 a[12:15], v85 offset:4096
	s_waitcnt lgkmcnt(5)
	v_mfma_f32_32x32x16_bf16 v[48:63], a[16:19], a[24:27], v[48:63]
	v_mfma_f32_32x32x16_bf16 v[32:47], a[20:23], a[24:27], v[32:47]
	s_and_b32 m0, s32, 7
	s_lshl_b32 m0, m0, 12
	s_add_i32 m0, m0, 0x18800
	s_nop 0
	global_load_lds_dwordx4 v[174:175], off
	s_waitcnt lgkmcnt(4)
	v_mfma_f32_32x32x16_bf16 v[16:31], a[16:19], a[28:31], v[16:31]
	v_mfma_f32_32x32x16_bf16 v[0:15], a[20:23], a[28:31], v[0:15]
	ds_read_b128 a[16:19], v88 offset:32768
	ds_read_b128 a[20:23], v88 offset:36864
	ds_read_b128 a[24:27], v87
	ds_read_b128 a[28:31], v87 offset:4096
	s_waitcnt lgkmcnt(5)
	v_mfma_f32_32x32x16_bf16 v[48:63], a[0:3], a[8:11], v[48:63]
	s_and_b32 m0, s32, 7
	s_lshl_b32 m0, m0, 12
	s_add_i32 m0, m0, 0x18c00
	s_nop 0
	global_load_lds_dwordx4 v[176:177], off
	v_mfma_f32_32x32x16_bf16 v[32:47], a[4:7], a[8:11], v[32:47]
	s_waitcnt lgkmcnt(4)
	v_mfma_f32_32x32x16_bf16 v[16:31], a[0:3], a[12:15], v[16:31]
	v_mfma_f32_32x32x16_bf16 v[0:15], a[4:7], a[12:15], v[0:15]
	s_and_b32 m0, s32, 7
	s_lshl_b32 m0, m0, 11
	s_add_i32 m0, m0, 0x20000
	s_nop 0
	global_load_lds_dwordx4 v[178:179], off
	s_waitcnt lgkmcnt(1)
	v_mfma_f32_32x32x16_bf16 v[48:63], a[16:19], a[24:27], v[48:63]
	v_mfma_f32_32x32x16_bf16 v[32:47], a[20:23], a[24:27], v[32:47]
	s_and_b32 m0, s32, 7
	s_lshl_b32 m0, m0, 11
	s_add_i32 m0, m0, 0x20400
	s_nop 0
	global_load_lds_dwordx4 v[180:181], off
	s_waitcnt vmcnt(6)
	s_waitcnt lgkmcnt(0)
	s_barrier
	ds_read_b128 a[12:15], v81 offset:53248
	ds_read_b128 a[8:11], v81 offset:49152
	ds_read_b128 a[4:7], v89
	ds_read_b128 a[0:3], v91
	v_lshl_add_u64 v[160:161], v[68:69], 0, s[30:31]
	v_mfma_f32_32x32x16_bf16 v[16:31], a[16:19], a[28:31], v[16:31]
	v_lshl_add_u64 v[162:163], v[70:71], 0, s[30:31]
	s_nop 0
	v_readlane_b32 s21, v214, 44
	s_nop 0
	v_lshl_add_u64 v[164:165], v[72:73], 0, s[30:31]
	s_nop 0
	v_mfma_f32_32x32x16_bf16 v[0:15], a[20:23], a[28:31], v[0:15]
	s_and_b32 m0, s32, 7
	s_lshl_b32 m0, m0, 12
	s_add_i32 m0, m0, 0x0
	s_nop 0
	global_load_lds_dwordx4 v[158:159], off
	v_lshl_add_u64 v[166:167], v[74:75], 0, s[30:31]
	s_lshl_b64 s[28:29], s[0:1], 21
	v_lshl_add_u64 v[168:169], v[76:77], 0, s[30:31]
	s_add_u32 s20, s20, s28
	ds_read_b128 a[16:19], v92
	ds_read_b128 a[20:23], v90
	ds_read_b128 a[24:27], v83 offset:49152
	ds_read_b128 a[28:31], v83 offset:53248
	s_waitcnt lgkmcnt(4)
	v_mfma_f32_32x32x16_bf16 v[48:63], a[0:3], a[8:11], v[48:63]
	s_addc_u32 s21, s21, s29
	v_readlane_b32 s23, v214, 41
	s_add_u32 s36, s23, s28
	v_readlane_b32 s23, v214, 42
	s_addc_u32 s37, s23, s29
	v_mfma_f32_32x32x16_bf16 v[32:47], a[4:7], a[8:11], v[32:47]
	v_mfma_f32_32x32x16_bf16 v[16:31], a[0:3], a[12:15], v[16:31]
	s_and_b32 m0, s32, 7
	s_lshl_b32 m0, m0, 12
	s_add_i32 m0, m0, 0x400
	s_nop 0
	global_load_lds_dwordx4 v[160:161], off
	v_mfma_f32_32x32x16_bf16 v[0:15], a[4:7], a[12:15], v[0:15]
	ds_read_b128 a[0:3], v94
	ds_read_b128 a[4:7], v93
	ds_read_b128 a[8:11], v85 offset:49152
	ds_read_b128 a[12:15], v85 offset:53248
	s_waitcnt lgkmcnt(5)
	v_mfma_f32_32x32x16_bf16 v[48:63], a[16:19], a[24:27], v[48:63]
	v_mfma_f32_32x32x16_bf16 v[32:47], a[20:23], a[24:27], v[32:47]
	s_and_b32 m0, s32, 7
	s_lshl_b32 m0, m0, 12
	s_add_i32 m0, m0, 0x800
	s_nop 0
	global_load_lds_dwordx4 v[162:163], off
	s_waitcnt lgkmcnt(4)
	v_mfma_f32_32x32x16_bf16 v[16:31], a[16:19], a[28:31], v[16:31]
	v_mfma_f32_32x32x16_bf16 v[0:15], a[20:23], a[28:31], v[0:15]
	ds_read_b128 a[16:19], v96
	ds_read_b128 a[20:23], v95
	ds_read_b128 a[24:27], v87 offset:49152
	ds_read_b128 a[28:31], v87 offset:53248
	s_waitcnt lgkmcnt(5)
	v_mfma_f32_32x32x16_bf16 v[48:63], a[0:3], a[8:11], v[48:63]
	s_and_b32 m0, s32, 7
	s_lshl_b32 m0, m0, 12
	s_add_i32 m0, m0, 0xc00
	s_nop 0
	global_load_lds_dwordx4 v[164:165], off
	v_mfma_f32_32x32x16_bf16 v[32:47], a[4:7], a[8:11], v[32:47]
	s_waitcnt lgkmcnt(4)
	v_mfma_f32_32x32x16_bf16 v[16:31], a[0:3], a[12:15], v[16:31]
	v_mfma_f32_32x32x16_bf16 v[0:15], a[4:7], a[12:15], v[0:15]
	s_and_b32 m0, s32, 7
	s_lshl_b32 m0, m0, 11
	s_add_i32 m0, m0, 0x8000
	s_nop 0
	global_load_lds_dwordx4 v[166:167], off
	s_waitcnt lgkmcnt(1)
	v_mfma_f32_32x32x16_bf16 v[48:63], a[16:19], a[24:27], v[48:63]
	v_mfma_f32_32x32x16_bf16 v[32:47], a[20:23], a[24:27], v[32:47]
	s_and_b32 m0, s32, 7
	s_lshl_b32 m0, m0, 11
	s_add_i32 m0, m0, 0x8400
	s_nop 0
	global_load_lds_dwordx4 v[168:169], off
	s_waitcnt vmcnt(6)
	s_waitcnt lgkmcnt(0)
	s_barrier
	ds_read_b128 a[12:15], v100
	ds_read_b128 a[8:11], v99
	ds_read_b128 a[4:7], v98
	ds_read_b128 a[0:3], v97
	v_mfma_f32_32x32x16_bf16 v[16:31], a[16:19], a[28:31], v[16:31]
	v_mfma_f32_32x32x16_bf16 v[0:15], a[20:23], a[28:31], v[0:15]
	ds_read_b128 a[16:19], v101
	ds_read_b128 a[20:23], v102
	ds_read_b128 a[24:27], v103
	ds_read_b128 a[28:31], v104
	s_waitcnt lgkmcnt(4)
	v_mfma_f32_32x32x16_bf16 v[48:63], a[0:3], a[8:11], v[48:63]
	v_mfma_f32_32x32x16_bf16 v[32:47], a[4:7], a[8:11], v[32:47]
	v_mfma_f32_32x32x16_bf16 v[16:31], a[0:3], a[12:15], v[16:31]
	v_mfma_f32_32x32x16_bf16 v[0:15], a[4:7], a[12:15], v[0:15]
	ds_read_b128 a[0:3], v105
	ds_read_b128 a[4:7], v106
	ds_read_b128 a[8:11], v107
	ds_read_b128 a[12:15], v108
	s_waitcnt lgkmcnt(5)
	v_mfma_f32_32x32x16_bf16 v[48:63], a[16:19], a[24:27], v[48:63]
	v_mfma_f32_32x32x16_bf16 v[32:47], a[20:23], a[24:27], v[32:47]
	s_waitcnt lgkmcnt(4)
	v_mfma_f32_32x32x16_bf16 v[16:31], a[16:19], a[28:31], v[16:31]
	v_mfma_f32_32x32x16_bf16 v[0:15], a[20:23], a[28:31], v[0:15]
	ds_read_b128 a[16:19], v109
	ds_read_b128 a[20:23], v110
	ds_read_b128 a[24:27], v111
	ds_read_b128 a[28:31], v112
	s_waitcnt lgkmcnt(5)
	v_mfma_f32_32x32x16_bf16 v[48:63], a[0:3], a[8:11], v[48:63]
	v_mfma_f32_32x32x16_bf16 v[32:47], a[4:7], a[8:11], v[32:47]
	s_waitcnt lgkmcnt(4)
	v_mfma_f32_32x32x16_bf16 v[16:31], a[0:3], a[12:15], v[16:31]
	v_mfma_f32_32x32x16_bf16 v[0:15], a[4:7], a[12:15], v[0:15]
	s_waitcnt lgkmcnt(1)
	v_mfma_f32_32x32x16_bf16 v[48:63], a[16:19], a[24:27], v[48:63]
	v_mfma_f32_32x32x16_bf16 v[32:47], a[20:23], a[24:27], v[32:47]
	s_waitcnt vmcnt(0)
	s_waitcnt lgkmcnt(0)
	s_barrier
	ds_read_b128 a[12:15], v81 offset:4096
	ds_read_b128 a[8:11], v81
	ds_read_b128 a[4:7], v82 offset:36864
	ds_read_b128 a[0:3], v82 offset:32768
	v_mfma_f32_32x32x16_bf16 v[16:31], a[16:19], a[28:31], v[16:31]
	v_mfma_f32_32x32x16_bf16 v[0:15], a[20:23], a[28:31], v[0:15]
	ds_read_b128 a[16:19], v84 offset:32768
	ds_read_b128 a[20:23], v84 offset:36864
	ds_read_b128 a[24:27], v83
	ds_read_b128 a[28:31], v83 offset:4096
	s_waitcnt lgkmcnt(4)
	v_mfma_f32_32x32x16_bf16 v[48:63], a[0:3], a[8:11], v[48:63]
	v_mfma_f32_32x32x16_bf16 v[32:47], a[4:7], a[8:11], v[32:47]
	v_mfma_f32_32x32x16_bf16 v[16:31], a[0:3], a[12:15], v[16:31]
	v_mfma_f32_32x32x16_bf16 v[0:15], a[4:7], a[12:15], v[0:15]
	ds_read_b128 a[0:3], v86 offset:32768
	ds_read_b128 a[4:7], v86 offset:36864
	ds_read_b128 a[8:11], v85
	ds_read_b128 a[12:15], v85 offset:4096
	s_waitcnt lgkmcnt(5)
	v_mfma_f32_32x32x16_bf16 v[48:63], a[16:19], a[24:27], v[48:63]
	v_mfma_f32_32x32x16_bf16 v[32:47], a[20:23], a[24:27], v[32:47]
	s_waitcnt lgkmcnt(4)
	v_mfma_f32_32x32x16_bf16 v[16:31], a[16:19], a[28:31], v[16:31]
	v_mfma_f32_32x32x16_bf16 v[0:15], a[20:23], a[28:31], v[0:15]
	s_waitcnt lgkmcnt(1)
	v_mfma_f32_32x32x16_bf16 v[48:63], a[0:3], a[8:11], v[48:63]
	v_mfma_f32_32x32x16_bf16 v[32:47], a[4:7], a[8:11], v[32:47]
	s_waitcnt lgkmcnt(0)
	v_mfma_f32_32x32x16_bf16 v[16:31], a[0:3], a[12:15], v[16:31]
	v_mfma_f32_32x32x16_bf16 v[0:15], a[4:7], a[12:15], v[0:15]
	ds_read_b128 v[66:69], v88 offset:32768
	ds_read_b128 v[70:73], v87
	ds_read_b128 v[74:77], v88 offset:36864
	ds_read_b128 v[82:85], v87 offset:4096
	s_waitcnt lgkmcnt(0)
	v_mfma_f32_32x32x16_bf16 v[48:63], v[66:69], v[70:73], v[48:63]
	v_mfma_f32_32x32x16_bf16 v[32:47], v[74:77], v[70:73], v[32:47]
	v_or_b32_e32 v70, s22, v80
	v_lshl_add_u32 v70, v78, 6, v70
	v_ashrrev_i32_e32 v71, 31, v70
	v_lshlrev_b64 v[72:73], 10, v[70:71]
	v_lshl_add_u64 v[86:87], s[36:37], 0, v[72:73]
	v_mfma_f32_32x32x16_bf16 v[16:31], v[66:69], v[82:85], v[16:31]
	v_lshlrev_b32_e32 v66, 6, v79
	v_or3_b32 v66, v66, v64, s2
	s_movk_i32 s2, 0xff
	v_cmp_lt_i32_e32 vcc, s2, v66
	v_mfma_f32_32x32x16_bf16 v[0:15], v[74:77], v[82:85], v[0:15]
	s_and_saveexec_b64 s[22:23], vcc
	s_xor_b64 s[28:29], exec, s[22:23]
	v_mov_b32_e32 v67, v65
	s_movk_i32 s22, 0xfc00
	v_lshl_add_u64 v[68:69], v[66:67], 2, v[86:87]
	s_mov_b32 s23, -1
	v_lshl_add_u64 v[68:69], v[68:69], 0, s[22:23]
	s_or_saveexec_b64 s[28:29], s[28:29]
	v_lshl_add_u64 v[90:91], s[20:21], 0, v[72:73]
	v_ashrrev_i32_e32 v67, 31, v66
	s_xor_b64 exec, exec, s[28:29]
	v_lshl_add_u64 v[68:69], v[66:67], 2, v[90:91]
	s_or_b64 exec, exec, s[28:29]
	s_lshl_b64 s[0:1], s[0:1], 19
	s_lshl_b64 s[22:23], s[0:1], 1
	v_readlane_b32 s0, v214, 37
	v_readlane_b32 s1, v214, 38
	s_add_u32 s0, s0, s22
	s_addc_u32 s1, s1, s23
	v_readlane_b32 s28, v214, 39
	v_readlane_b32 s29, v214, 40
	s_add_u32 s54, s28, s22
	v_and_b32_e32 v74, 0xdf, v70
	v_ashrrev_i32_e32 v71, 6, v70
	global_store_dwordx4 v[68:69], v[48:51], off
	v_add_u32_e32 v68, 0xffffff00, v66
	v_lshlrev_b32_e32 v69, 9, v66
	s_addc_u32 s55, s29, s23
	v_and_b32_e32 v71, -4, v71
	v_lshrrev_b32_e32 v92, 6, v68
	v_and_b32_e32 v72, 0x7800, v69
	v_lshlrev_b32_e32 v88, 1, v74
	s_and_saveexec_b64 s[22:23], vcc
	s_xor_b64 s[28:29], exec, s[22:23]
	s_cbranch_execz .LBB0_619
	v_add_u32_e32 v68, v92, v71
	v_ashrrev_i32_e32 v69, 31, v68
	v_lshlrev_b64 v[68:69], 15, v[68:69]
	v_lshl_add_u64 v[68:69], s[54:55], 0, v[68:69]
	v_mov_b32_e32 v73, v65
	v_lshl_add_u64 v[68:69], v[68:69], 0, v[72:73]
	v_mov_b32_e32 v89, v65
	v_bfe_u32 v73, v48, 16, 1
	v_lshl_add_u64 v[68:69], v[68:69], 0, v[88:89]
	v_add3_u32 v73, v48, v73, s27
	global_store_short_d16_hi v[68:69], v73, off
	v_bfe_u32 v73, v49, 16, 1
	v_add3_u32 v73, v49, v73, s27
	global_store_short_d16_hi v[68:69], v73, off offset:512
	v_bfe_u32 v73, v50, 16, 1
	v_add3_u32 v73, v50, v73, s27
	global_store_short_d16_hi v[68:69], v73, off offset:1024
	v_bfe_u32 v73, v51, 16, 1
	v_add3_u32 v73, v51, v73, s27
	global_store_short_d16_hi v[68:69], v73, off offset:1536

.LBB0_747:
	v_mov_b32_e32 v78, v133
	s_lshl_b32 s2, s2, 8
	v_ashrrev_i32_e32 v6, 6, v78
	v_bfe_u32 v7, v78, 3, 3
	v_lshl_or_b32 v8, v6, 5, v7
	v_add_u32_e32 v0, s2, v8
	s_waitcnt lgkmcnt(0)
	v_ashrrev_i32_e32 v1, 31, v0
	v_lshlrev_b64 v[2:3], 11, v[0:1]
	v_bfe_u32 v1, v78, 4, 2
	v_readlane_b32 s0, v215, 52
	v_xor_b32_e32 v1, v1, v78
	v_readlane_b32 s1, v215, 53
	v_lshlrev_b32_e32 v1, 4, v1
	v_and_b32_e32 v64, 0x70, v1
	v_lshl_add_u64 v[2:3], s[0:1], 0, v[2:3]
	v_or_b32_e32 v1, 8, v8
	v_lshl_add_u64 v[66:67], v[2:3], 0, v[64:65]
	v_add_u32_e32 v2, s2, v1
	v_lshrrev_b32_e32 v1, 1, v1
	v_xor_b32_e32 v1, v1, v78
	v_ashrrev_i32_e32 v3, 31, v2
	v_lshlrev_b32_e32 v1, 4, v1
	v_or_b32_e32 v0, 16, v0
	v_lshlrev_b64 v[2:3], 11, v[2:3]
	v_and_b32_e32 v4, 0x70, v1
	v_ashrrev_i32_e32 v1, 31, v0
	v_lshl_add_u64 v[2:3], s[0:1], 0, v[2:3]
	v_mov_b32_e32 v5, v65
	v_lshlrev_b64 v[0:1], 11, v[0:1]
	v_lshl_add_u64 v[68:69], v[2:3], 0, v[4:5]
	v_lshl_add_u64 v[0:1], s[0:1], 0, v[0:1]
	v_or_b32_e32 v2, 24, v8
	v_lshl_add_u64 v[70:71], v[0:1], 0, v[64:65]
	v_add_u32_e32 v0, s2, v2
	v_lshrrev_b32_e32 v2, 1, v2
	v_ashrrev_i32_e32 v1, 31, v0
	v_xor_b32_e32 v2, v2, v78
	v_lshlrev_b64 v[0:1], 11, v[0:1]
	v_lshlrev_b32_e32 v2, 4, v2
	v_lshl_add_u64 v[0:1], s[0:1], 0, v[0:1]
	v_and_b32_e32 v2, 0x70, v2
	v_mov_b32_e32 v3, v65
	v_lshl_add_u64 v[72:73], v[0:1], 0, v[2:3]
	v_lshl_or_b32 v2, v6, 4, v7
	v_add_u32_e32 v0, s20, v2
	v_lshlrev_b32_e32 v3, 12, v6
	v_ashrrev_i32_e32 v1, 31, v0
	v_add_u32_e32 v131, 0, v3
	v_lshlrev_b64 v[0:1], 11, v[0:1]
	s_waitcnt vmcnt(0)
	v_readfirstlane_b32 s40, v131
	v_add_u32_e32 v130, 0x400, v131
	v_lshl_add_u64 v[0:1], s[96:97], 0, v[0:1]
	v_or_b32_e32 v2, 8, v2
	s_waitcnt lgkmcnt(0)
	s_barrier
	s_mov_b32 m0, s40
	v_readfirstlane_b32 s41, v130
	v_add_u32_e32 v128, 0x800, v131
	v_lshlrev_b32_e32 v5, 11, v6
	v_and_b32_e32 v79, 1, v6
	v_lshl_add_u64 v[74:75], v[0:1], 0, v[64:65]
	v_add_u32_e32 v0, s20, v2
	v_lshrrev_b32_e32 v2, 1, v2
	global_load_lds_dwordx4 v[66:67], off
	s_mov_b32 m0, s41
	v_readfirstlane_b32 s42, v128
	v_add_u32_e32 v126, 0xc00, v131
	v_add_u32_e32 v6, 0, v5
	v_ashrrev_i32_e32 v1, 31, v0
	v_xor_b32_e32 v2, v2, v78
	global_load_lds_dwordx4 v[68:69], off
	s_mov_b32 m0, s42
	v_readfirstlane_b32 s43, v126
	v_add_u32_e32 v129, 0x8000, v6
	v_lshlrev_b64 v[0:1], 11, v[0:1]
	v_lshlrev_b32_e32 v2, 4, v2
	global_load_lds_dwordx4 v[70:71], off
	s_mov_b32 m0, s43
	v_readfirstlane_b32 s44, v129
	v_add_u32_e32 v127, 0x8400, v6
	v_lshl_add_u64 v[0:1], s[96:97], 0, v[0:1]
	v_and_b32_e32 v64, 0x70, v2
	global_load_lds_dwordx4 v[72:73], off
	s_mov_b32 m0, s44
	v_readfirstlane_b32 s45, v127
	v_add_u32_e32 v125, 0xc000, v131
	v_lshl_add_u64 v[76:77], v[0:1], 0, v[64:65]
	global_load_lds_dwordx4 v[74:75], off
	s_mov_b32 m0, s45
	s_mov_b64 s[0:1], 0x80
	v_readfirstlane_b32 s29, v125
	v_add_u32_e32 v120, 0xc400, v131
	global_load_lds_dwordx4 v[76:77], off
	v_lshl_add_u64 v[0:1], v[66:67], 0, s[0:1]
	s_mov_b32 m0, s29
	v_readfirstlane_b32 s33, v120
	v_add_u32_e32 v121, 0xc800, v131
	global_load_lds_dwordx4 v[0:1], off
	v_lshl_add_u64 v[0:1], v[68:69], 0, s[0:1]
	s_mov_b32 m0, s33
	v_readfirstlane_b32 s36, v121
	v_add_u32_e32 v122, 0xcc00, v131
	global_load_lds_dwordx4 v[0:1], off
	v_lshl_add_u64 v[0:1], v[70:71], 0, s[0:1]
	s_mov_b32 m0, s36
	v_readfirstlane_b32 s37, v122
	v_add_u32_e32 v123, s85, v5
	global_load_lds_dwordx4 v[0:1], off
	v_lshl_add_u64 v[0:1], v[72:73], 0, s[0:1]
	s_mov_b32 m0, s37
	v_readfirstlane_b32 s38, v123
	v_add_u32_e32 v124, 0x14400, v6
	global_load_lds_dwordx4 v[0:1], off
	v_lshl_add_u64 v[0:1], v[74:75], 0, s[0:1]
	s_mov_b32 m0, s38
	v_readfirstlane_b32 s39, v124
	global_load_lds_dwordx4 v[0:1], off
	v_lshl_add_u64 v[0:1], v[76:77], 0, s[0:1]
	s_mov_b32 m0, s39
	v_lshrrev_b32_e32 v2, 1, v78
	v_bfe_u32 v64, v78, 5, 1
	global_load_lds_dwordx4 v[0:1], off
	v_add_u32_e32 v119, s3, v3
	v_bitop3_b32 v0, v2, v64, 7 bitop3:0x6c
	s_waitcnt vmcnt(6)
	s_mov_b64 s[30:31], 0x100
	v_readfirstlane_b32 s0, v119
	v_add_u32_e32 v114, 0x400, v119
	v_lshlrev_b32_e32 v132, 4, v0
	s_waitcnt lgkmcnt(0)
	s_barrier
	v_lshl_add_u64 v[0:1], v[66:67], 0, s[30:31]
	s_mov_b32 m0, s0
	v_readfirstlane_b32 s1, v114
	v_add_u32_e32 v115, 0x800, v119
	global_load_lds_dwordx4 v[0:1], off
	v_lshl_add_u64 v[0:1], v[68:69], 0, s[30:31]
	s_mov_b32 m0, s1
	v_readfirstlane_b32 s21, v115
	v_add_u32_e32 v116, 0xc00, v119
	v_readlane_b32 s23, v212, 31
	v_and_b32_e32 v81, 31, v78
	global_load_lds_dwordx4 v[0:1], off
	v_lshl_add_u64 v[0:1], v[70:71], 0, s[30:31]
	s_mov_b32 m0, s21
	v_readfirstlane_b32 s22, v116
	v_add_u32_e32 v117, s23, v5
	v_add_u32_e32 v2, s3, v5
	v_lshlrev_b32_e32 v4, 7, v81
	global_load_lds_dwordx4 v[0:1], off
	v_lshl_add_u64 v[0:1], v[72:73], 0, s[30:31]
	s_mov_b32 m0, s22
	v_readfirstlane_b32 s23, v117
	v_add_u32_e32 v118, 0x8400, v2
	v_lshl_or_b32 v102, v79, 13, v4
	global_load_lds_dwordx4 v[0:1], off
	v_lshl_add_u64 v[0:1], v[74:75], 0, s[30:31]
	s_mov_b32 m0, s23
	v_readfirstlane_b32 s28, v118
	global_load_lds_dwordx4 v[0:1], off
	v_lshl_add_u64 v[0:1], v[76:77], 0, s[30:31]
	s_mov_b32 m0, s28
	v_add_u32_e32 v100, 0, v102
	global_load_lds_dwordx4 v[0:1], off
	v_add_u32_e32 v85, v100, v132
	v_ashrrev_i32_e32 v80, 7, v78
	ds_read_b128 v[0:3], v85 offset:32768
	ds_read_b128 v[86:89], v85 offset:36864
	v_lshl_or_b32 v134, v80, 13, v4
	v_add_u32_e32 v101, 0, v134
	v_add_u32_e32 v84, v101, v132
	ds_read_b128 v[4:7], v84
	v_bfe_u32 v103, v78, 1, 3
	s_waitcnt lgkmcnt(0)
	v_lshrrev_b32_e32 v182, 6, v133
	s_nop 0
	v_readfirstlane_b32 s32, v182
	v_mfma_f32_32x32x16_bf16 v[48:63], v[0:3], v[4:7], 0
	v_bitop3_b32 v8, v64, v103, 2 bitop3:0x36
	v_lshlrev_b32_e32 v135, 4, v8
	v_add_u32_e32 v83, v100, v135
	ds_read_b128 v[8:11], v83 offset:32768
	ds_read_b128 v[90:93], v83 offset:36864
	v_add_u32_e32 v82, v101, v135
	ds_read_b128 v[12:15], v82
	ds_read_b128 v[94:97], v82 offset:4096
	s_waitcnt vmcnt(12)
	v_mfma_f32_32x32x16_bf16 v[32:47], v[86:89], v[4:7], 0
	ds_read_b128 v[4:7], v84 offset:4096
	s_mov_b64 s[30:31], 0x180
	v_or_b32_e32 v143, 0x8000, v102
	v_or_b32_e32 v144, 0x9000, v102
	v_add_u32_e32 v145, s3, v134
	s_mov_b64 s[80:81], 0x200
	s_waitcnt lgkmcnt(0)
	v_mfma_f32_32x32x16_bf16 v[16:31], v[0:3], v[4:7], 0
	v_mfma_f32_32x32x16_bf16 v[48:63], v[8:11], v[12:15], v[48:63]
	v_mfma_f32_32x32x16_bf16 v[32:47], v[90:93], v[12:15], v[32:47]
	v_mfma_f32_32x32x16_bf16 v[16:31], v[8:11], v[94:97], v[16:31]
	v_mfma_f32_32x32x16_bf16 v[0:15], v[86:89], v[4:7], 0
	v_bitop3_b32 v86, v64, v103, 4 bitop3:0x36
	v_lshlrev_b32_e32 v138, 4, v86
	v_add_u32_e32 v87, v100, v138
	v_add_u32_e32 v86, v101, v138
	v_mfma_f32_32x32x16_bf16 v[0:15], v[90:93], v[94:97], v[0:15]
	ds_read_b128 v[88:91], v87 offset:32768
	ds_read_b128 v[92:95], v86
	ds_read_b128 v[96:99], v87 offset:36864
	s_waitcnt lgkmcnt(1)
	v_mfma_f32_32x32x16_bf16 v[48:63], v[88:91], v[92:95], v[48:63]
	s_waitcnt lgkmcnt(0)
	v_mfma_f32_32x32x16_bf16 v[32:47], v[96:99], v[92:95], v[32:47]
	ds_read_b128 v[92:95], v86 offset:4096
	s_waitcnt lgkmcnt(0)
	v_mfma_f32_32x32x16_bf16 v[16:31], v[88:91], v[92:95], v[16:31]
	v_bitop3_b32 v88, v64, v103, 6 bitop3:0x36
	v_lshlrev_b32_e32 v142, 4, v88
	v_add_u32_e32 v89, v100, v142
	v_add_u32_e32 v88, v101, v142
	v_mfma_f32_32x32x16_bf16 v[0:15], v[96:99], v[92:95], v[0:15]
	ds_read_b128 v[90:93], v89 offset:32768
	ds_read_b128 v[94:97], v88
	ds_read_b128 v[98:101], v89 offset:36864
	s_waitcnt lgkmcnt(1)
	v_mfma_f32_32x32x16_bf16 v[48:63], v[90:93], v[94:97], v[48:63]
	s_waitcnt lgkmcnt(0)
	v_mfma_f32_32x32x16_bf16 v[32:47], v[98:101], v[94:97], v[32:47]
	ds_read_b128 v[94:97], v88 offset:4096
	s_waitcnt vmcnt(6)
	s_waitcnt lgkmcnt(0)
	s_barrier
	s_waitcnt lgkmcnt(0)
	v_mfma_f32_32x32x16_bf16 v[16:31], v[90:93], v[94:97], v[16:31]
	v_lshl_add_u64 v[158:159], v[66:67], 0, s[30:31]
	v_lshl_add_u64 v[160:161], v[68:69], 0, s[30:31]
	v_lshl_add_u64 v[162:163], v[70:71], 0, s[30:31]
	v_mfma_f32_32x32x16_bf16 v[0:15], v[98:101], v[94:97], v[0:15]
	s_and_b32 m0, s32, 7
	s_lshl_b32 m0, m0, 12
	s_add_i32 m0, m0, 0x0
	s_nop 0
	global_load_lds_dwordx4 v[158:159], off
	v_lshl_add_u64 v[164:165], v[72:73], 0, s[30:31]
	v_lshl_add_u64 v[166:167], v[74:75], 0, s[30:31]
	v_lshl_add_u64 v[168:169], v[76:77], 0, s[30:31]
	s_add_i32 s30, 0, 0xc000
	v_add_u32_e32 v90, s30, v132
	v_add_u32_e32 v91, v90, v143
	v_add_u32_e32 v90, v90, v144
	ds_read_b128 v[92:95], v91
	ds_read_b128 v[96:99], v84 offset:49152
	ds_read_b128 v[100:103], v90
	ds_read_b128 v[150:153], v84 offset:53248
	s_waitcnt lgkmcnt(1)
	v_mfma_f32_32x32x16_bf16 v[48:63], v[92:95], v[96:99], v[48:63]
	v_mfma_f32_32x32x16_bf16 v[32:47], v[100:103], v[96:99], v[32:47]
	s_waitcnt lgkmcnt(0)
	v_mfma_f32_32x32x16_bf16 v[16:31], v[92:95], v[150:153], v[16:31]
	s_and_b32 m0, s32, 7
	s_lshl_b32 m0, m0, 12
	s_add_i32 m0, m0, 0x400
	s_nop 0
	global_load_lds_dwordx4 v[160:161], off
	v_add_u32_e32 v92, s30, v135
	v_add_u32_e32 v94, v92, v143
	v_add_u32_e32 v92, v92, v144
	v_add_u32_e32 v93, s30, v138
	v_add_u32_e32 v95, v93, v143
	v_add_u32_e32 v93, v93, v144
	v_mfma_f32_32x32x16_bf16 v[0:15], v[100:103], v[150:153], v[0:15]
	ds_read_b128 v[96:99], v94
	ds_read_b128 v[100:103], v82 offset:49152
	ds_read_b128 v[104:107], v92
	ds_read_b128 v[154:157], v82 offset:53248
	s_waitcnt lgkmcnt(1)
	v_mfma_f32_32x32x16_bf16 v[48:63], v[96:99], v[100:103], v[48:63]
	v_mfma_f32_32x32x16_bf16 v[32:47], v[104:107], v[100:103], v[32:47]
	s_and_b32 m0, s32, 7
	s_lshl_b32 m0, m0, 12
	s_add_i32 m0, m0, 0x800
	s_nop 0
	global_load_lds_dwordx4 v[162:163], off
	s_waitcnt lgkmcnt(0)
	v_mfma_f32_32x32x16_bf16 v[16:31], v[96:99], v[154:157], v[16:31]
	v_mfma_f32_32x32x16_bf16 v[0:15], v[104:107], v[154:157], v[0:15]
	ds_read_b128 v[96:99], v95
	ds_read_b128 v[100:103], v86 offset:49152
	ds_read_b128 v[104:107], v93
	ds_read_b128 v[150:153], v86 offset:53248
	s_waitcnt lgkmcnt(1)
	v_mfma_f32_32x32x16_bf16 v[48:63], v[96:99], v[100:103], v[48:63]
	s_and_b32 m0, s32, 7
	s_lshl_b32 m0, m0, 12
	s_add_i32 m0, m0, 0xc00
	s_nop 0
	global_load_lds_dwordx4 v[164:165], off
	v_mfma_f32_32x32x16_bf16 v[32:47], v[104:107], v[100:103], v[32:47]
	s_waitcnt lgkmcnt(0)
	v_mfma_f32_32x32x16_bf16 v[16:31], v[96:99], v[150:153], v[16:31]
	v_add_u32_e32 v96, s30, v142
	v_add_u32_e32 v97, v96, v143
	v_add_u32_e32 v96, v96, v144
	s_mov_b64 s[30:31], 0x200
	v_mfma_f32_32x32x16_bf16 v[0:15], v[104:107], v[150:153], v[0:15]
	s_and_b32 m0, s32, 7
	s_lshl_b32 m0, m0, 11
	s_add_i32 m0, m0, 0x8000
	s_nop 0
	global_load_lds_dwordx4 v[166:167], off
	ds_read_b128 v[98:101], v97
	ds_read_b128 v[102:105], v88 offset:49152
	ds_read_b128 v[106:109], v96
	ds_read_b128 v[154:157], v88 offset:53248
	s_waitcnt lgkmcnt(1)
	v_mfma_f32_32x32x16_bf16 v[48:63], v[98:101], v[102:105], v[48:63]
	v_mfma_f32_32x32x16_bf16 v[32:47], v[106:109], v[102:105], v[32:47]
	s_and_b32 m0, s32, 7
	s_lshl_b32 m0, m0, 11
	s_add_i32 m0, m0, 0x8400
	s_nop 0
	global_load_lds_dwordx4 v[168:169], off
	s_waitcnt vmcnt(6)
	s_waitcnt lgkmcnt(0)
	s_barrier
	s_waitcnt lgkmcnt(0)
	v_mfma_f32_32x32x16_bf16 v[16:31], v[98:101], v[154:157], v[16:31]
	v_lshl_add_u64 v[170:171], v[66:67], 0, s[30:31]
	v_lshl_add_u64 v[172:173], v[68:69], 0, s[30:31]
	v_add_u32_e32 v101, s3, v132
	v_lshl_add_u64 v[174:175], v[70:71], 0, s[30:31]
	v_mfma_f32_32x32x16_bf16 v[0:15], v[106:109], v[154:157], v[0:15]
	s_and_b32 m0, s32, 7
	s_lshl_b32 m0, m0, 12
	s_add_i32 m0, m0, 0xc000
	s_nop 0
	global_load_lds_dwordx4 v[170:171], off
	v_lshl_add_u64 v[176:177], v[72:73], 0, s[30:31]
	v_add_u32_e32 v100, v145, v132
	v_lshl_add_u64 v[178:179], v[74:75], 0, s[30:31]
	v_or_b32_e32 v132, 0x1000, v134
	v_lshl_add_u64 v[180:181], v[76:77], 0, s[30:31]
	s_mov_b64 s[30:31], 0x280
	v_add_u32_e32 v98, v101, v143
	v_add_u32_e32 v99, v101, v144
	ds_read_b128 v[110:113], v98
	ds_read_b128 v[106:109], v99
	ds_read_b128 v[102:105], v100
	v_add_u32_e32 v101, v101, v132
	ds_read_b128 v[150:153], v101
	s_waitcnt lgkmcnt(1)
	v_mfma_f32_32x32x16_bf16 v[48:63], v[110:113], v[102:105], v[48:63]
	v_mfma_f32_32x32x16_bf16 v[32:47], v[106:109], v[102:105], v[32:47]
	s_waitcnt lgkmcnt(0)
	v_mfma_f32_32x32x16_bf16 v[16:31], v[110:113], v[150:153], v[16:31]
	s_and_b32 m0, s32, 7
	s_lshl_b32 m0, m0, 12
	s_add_i32 m0, m0, 0xc400
	s_nop 0
	global_load_lds_dwordx4 v[172:173], off
	v_mfma_f32_32x32x16_bf16 v[0:15], v[106:109], v[150:153], v[0:15]
	v_add_u32_e32 v105, s3, v135
	v_add_u32_e32 v103, v105, v143
	v_add_u32_e32 v102, v105, v144
	ds_read_b128 v[106:109], v103
	v_add_u32_e32 v104, v145, v135
	ds_read_b128 v[134:137], v102
	ds_read_b128 v[110:113], v104
	v_add_u32_e32 v105, v105, v132
	ds_read_b128 v[154:157], v105
	s_waitcnt lgkmcnt(1)
	v_mfma_f32_32x32x16_bf16 v[48:63], v[106:109], v[110:113], v[48:63]
	v_mfma_f32_32x32x16_bf16 v[32:47], v[134:137], v[110:113], v[32:47]
	s_and_b32 m0, s32, 7
	s_lshl_b32 m0, m0, 12
	s_add_i32 m0, m0, 0xc800
	s_nop 0
	global_load_lds_dwordx4 v[174:175], off
	s_waitcnt lgkmcnt(0)
	v_mfma_f32_32x32x16_bf16 v[16:31], v[106:109], v[154:157], v[16:31]
	v_add_u32_e32 v109, s3, v138
	v_add_u32_e32 v107, v109, v143
	v_add_u32_e32 v106, v109, v144
	v_add_u32_e32 v108, v145, v138
	ds_read_b128 v[138:141], v106
	v_add_u32_e32 v109, v109, v132
	v_mfma_f32_32x32x16_bf16 v[0:15], v[134:137], v[154:157], v[0:15]
	ds_read_b128 v[110:113], v107
	ds_read_b128 v[134:137], v108
	ds_read_b128 v[150:153], v109
	s_waitcnt lgkmcnt(1)
	v_mfma_f32_32x32x16_bf16 v[48:63], v[110:113], v[134:137], v[48:63]
	s_and_b32 m0, s32, 7
	s_lshl_b32 m0, m0, 12
	s_add_i32 m0, m0, 0xcc00
	s_nop 0
	global_load_lds_dwordx4 v[176:177], off
	v_mfma_f32_32x32x16_bf16 v[32:47], v[138:141], v[134:137], v[32:47]
	s_waitcnt lgkmcnt(0)
	v_mfma_f32_32x32x16_bf16 v[16:31], v[110:113], v[150:153], v[16:31]
	v_add_u32_e32 v113, s3, v142
	v_add_u32_e32 v111, v113, v143
	v_add_u32_e32 v110, v113, v144
	v_add_u32_e32 v112, v145, v142
	ds_read_b128 v[142:145], v110
	v_add_u32_e32 v113, v113, v132
	v_mfma_f32_32x32x16_bf16 v[0:15], v[138:141], v[150:153], v[0:15]
	s_and_b32 m0, s32, 7
	s_lshl_b32 m0, m0, 11
	s_add_i32 m0, m0, 0x14000
	s_nop 0
	global_load_lds_dwordx4 v[178:179], off
	ds_read_b128 v[134:137], v111
	ds_read_b128 v[138:141], v112
	ds_read_b128 v[154:157], v113
	s_waitcnt lgkmcnt(1)
	v_mfma_f32_32x32x16_bf16 v[48:63], v[134:137], v[138:141], v[48:63]
	v_mfma_f32_32x32x16_bf16 v[32:47], v[142:145], v[138:141], v[32:47]
	s_and_b32 m0, s32, 7
	s_lshl_b32 m0, m0, 11
	s_add_i32 m0, m0, 0x14400
	s_nop 0
	global_load_lds_dwordx4 v[180:181], off
	s_waitcnt vmcnt(6)
	s_waitcnt lgkmcnt(0)
	s_barrier
	s_waitcnt lgkmcnt(0)
	v_mfma_f32_32x32x16_bf16 v[16:31], v[134:137], v[154:157], v[16:31]
	v_lshl_add_u64 v[158:159], v[66:67], 0, s[30:31]
	v_lshl_add_u64 v[160:161], v[68:69], 0, s[30:31]
	v_lshl_add_u64 v[162:163], v[70:71], 0, s[30:31]
	v_mfma_f32_32x32x16_bf16 v[0:15], v[142:145], v[154:157], v[0:15]
	s_and_b32 m0, s32, 7
	s_lshl_b32 m0, m0, 12
	s_add_i32 m0, m0, 0x18000
	s_nop 0
	global_load_lds_dwordx4 v[158:159], off
	v_lshl_add_u64 v[164:165], v[72:73], 0, s[30:31]
	v_lshl_add_u64 v[166:167], v[74:75], 0, s[30:31]
	v_lshl_add_u64 v[168:169], v[76:77], 0, s[30:31]
	s_mov_b64 s[30:31], 0x300
	ds_read_b128 v[134:137], v85 offset:32768
	ds_read_b128 v[138:141], v84
	ds_read_b128 v[142:145], v85 offset:36864
	ds_read_b128 v[150:153], v84 offset:4096
	s_waitcnt lgkmcnt(1)
	v_mfma_f32_32x32x16_bf16 v[48:63], v[134:137], v[138:141], v[48:63]
	s_nop 0
	v_readfirstlane_b32 s40, v119
	v_mfma_f32_32x32x16_bf16 v[32:47], v[142:145], v[138:141], v[32:47]
	s_waitcnt lgkmcnt(0)
	v_mfma_f32_32x32x16_bf16 v[16:31], v[134:137], v[150:153], v[16:31]
	s_and_b32 m0, s32, 7
	s_lshl_b32 m0, m0, 12
	s_add_i32 m0, m0, 0x18400
	s_nop 0
	global_load_lds_dwordx4 v[160:161], off
	v_mfma_f32_32x32x16_bf16 v[0:15], v[142:145], v[150:153], v[0:15]
	ds_read_b128 v[134:137], v83 offset:32768
	ds_read_b128 v[138:141], v82
	ds_read_b128 v[142:145], v83 offset:36864
	ds_read_b128 v[154:157], v82 offset:4096
	s_waitcnt lgkmcnt(1)
	v_mfma_f32_32x32x16_bf16 v[48:63], v[134:137], v[138:141], v[48:63]
	v_mfma_f32_32x32x16_bf16 v[32:47], v[142:145], v[138:141], v[32:47]
	s_and_b32 m0, s32, 7
	s_lshl_b32 m0, m0, 12
	s_add_i32 m0, m0, 0x18800
	s_nop 0
	global_load_lds_dwordx4 v[162:163], off
	s_waitcnt lgkmcnt(0)
	v_mfma_f32_32x32x16_bf16 v[16:31], v[134:137], v[154:157], v[16:31]
	v_mfma_f32_32x32x16_bf16 v[0:15], v[142:145], v[154:157], v[0:15]
	ds_read_b128 v[134:137], v87 offset:32768
	ds_read_b128 v[138:141], v86
	ds_read_b128 v[142:145], v87 offset:36864
	ds_read_b128 v[150:153], v86 offset:4096
	s_waitcnt lgkmcnt(1)
	v_mfma_f32_32x32x16_bf16 v[48:63], v[134:137], v[138:141], v[48:63]
	s_and_b32 m0, s32, 7
	s_lshl_b32 m0, m0, 12
	s_add_i32 m0, m0, 0x18c00
	s_nop 0
	global_load_lds_dwordx4 v[164:165], off
	v_mfma_f32_32x32x16_bf16 v[32:47], v[142:145], v[138:141], v[32:47]
	s_waitcnt lgkmcnt(0)
	v_mfma_f32_32x32x16_bf16 v[16:31], v[134:137], v[150:153], v[16:31]
	v_mfma_f32_32x32x16_bf16 v[0:15], v[142:145], v[150:153], v[0:15]
	s_and_b32 m0, s32, 7
	s_lshl_b32 m0, m0, 11
	s_add_i32 m0, m0, 0x20000
	s_nop 0
	global_load_lds_dwordx4 v[166:167], off
	ds_read_b128 v[134:137], v89 offset:32768
	ds_read_b128 v[138:141], v88
	ds_read_b128 v[142:145], v89 offset:36864
	ds_read_b128 v[154:157], v88 offset:4096
	s_waitcnt lgkmcnt(1)
	v_mfma_f32_32x32x16_bf16 v[48:63], v[134:137], v[138:141], v[48:63]
	v_mfma_f32_32x32x16_bf16 v[32:47], v[142:145], v[138:141], v[32:47]
	s_and_b32 m0, s32, 7
	s_lshl_b32 m0, m0, 11
	s_add_i32 m0, m0, 0x20400
	s_nop 0
	global_load_lds_dwordx4 v[168:169], off
	s_waitcnt vmcnt(6)
	s_waitcnt lgkmcnt(0)
	s_barrier
	s_waitcnt lgkmcnt(0)
	v_mfma_f32_32x32x16_bf16 v[16:31], v[134:137], v[154:157], v[16:31]
	v_lshl_add_u64 v[170:171], v[66:67], 0, s[30:31]
	v_lshl_add_u64 v[172:173], v[68:69], 0, s[30:31]
	s_nop 0
	v_readfirstlane_b32 s41, v114
	s_nop 0
	v_lshl_add_u64 v[174:175], v[70:71], 0, s[30:31]
	s_nop 0
	v_mfma_f32_32x32x16_bf16 v[0:15], v[142:145], v[154:157], v[0:15]
	s_and_b32 m0, s32, 7
	s_lshl_b32 m0, m0, 12
	s_add_i32 m0, m0, 0x0
	s_nop 0
	global_load_lds_dwordx4 v[170:171], off
	v_lshl_add_u64 v[176:177], v[72:73], 0, s[30:31]
	s_nop 0
	v_readfirstlane_b32 s42, v115
	s_nop 0
	v_lshl_add_u64 v[178:179], v[74:75], 0, s[30:31]
	s_nop 0
	v_readfirstlane_b32 s43, v116
	s_nop 0
	v_lshl_add_u64 v[180:181], v[76:77], 0, s[30:31]
	s_nop 0
	s_mov_b64 s[30:31], 0x380
	ds_read_b128 v[134:137], v91
	ds_read_b128 v[138:141], v84 offset:49152
	ds_read_b128 v[142:145], v90
	ds_read_b128 v[150:153], v84 offset:53248
	s_waitcnt lgkmcnt(1)
	v_mfma_f32_32x32x16_bf16 v[48:63], v[134:137], v[138:141], v[48:63]
	s_nop 0
	v_readfirstlane_b32 s29, v125
	v_readfirstlane_b32 s44, v117
	v_readfirstlane_b32 s45, v118
	v_mfma_f32_32x32x16_bf16 v[32:47], v[142:145], v[138:141], v[32:47]
	s_waitcnt lgkmcnt(0)
	v_mfma_f32_32x32x16_bf16 v[16:31], v[134:137], v[150:153], v[16:31]
	s_and_b32 m0, s32, 7
	s_lshl_b32 m0, m0, 12
	s_add_i32 m0, m0, 0x400
	s_nop 0
	global_load_lds_dwordx4 v[172:173], off
	v_mfma_f32_32x32x16_bf16 v[0:15], v[142:145], v[150:153], v[0:15]
	ds_read_b128 v[134:137], v94
	ds_read_b128 v[138:141], v82 offset:49152
	ds_read_b128 v[142:145], v92
	ds_read_b128 v[154:157], v82 offset:53248
	s_waitcnt lgkmcnt(1)
	v_mfma_f32_32x32x16_bf16 v[48:63], v[134:137], v[138:141], v[48:63]
	v_mfma_f32_32x32x16_bf16 v[32:47], v[142:145], v[138:141], v[32:47]
	s_and_b32 m0, s32, 7
	s_lshl_b32 m0, m0, 12
	s_add_i32 m0, m0, 0x800
	s_nop 0
	global_load_lds_dwordx4 v[174:175], off
	s_waitcnt lgkmcnt(0)
	v_mfma_f32_32x32x16_bf16 v[16:31], v[134:137], v[154:157], v[16:31]
	v_mfma_f32_32x32x16_bf16 v[0:15], v[142:145], v[154:157], v[0:15]
	ds_read_b128 v[134:137], v95
	ds_read_b128 v[138:141], v86 offset:49152
	ds_read_b128 v[142:145], v93
	ds_read_b128 v[150:153], v86 offset:53248
	s_waitcnt lgkmcnt(1)
	v_mfma_f32_32x32x16_bf16 v[48:63], v[134:137], v[138:141], v[48:63]
	s_and_b32 m0, s32, 7
	s_lshl_b32 m0, m0, 12
	s_add_i32 m0, m0, 0xc00
	s_nop 0
	global_load_lds_dwordx4 v[176:177], off
	v_mfma_f32_32x32x16_bf16 v[32:47], v[142:145], v[138:141], v[32:47]
	s_waitcnt lgkmcnt(0)
	v_mfma_f32_32x32x16_bf16 v[16:31], v[134:137], v[150:153], v[16:31]
	v_mfma_f32_32x32x16_bf16 v[0:15], v[142:145], v[150:153], v[0:15]
	s_and_b32 m0, s32, 7
	s_lshl_b32 m0, m0, 11
	s_add_i32 m0, m0, 0x8000
	s_nop 0
	global_load_lds_dwordx4 v[178:179], off
	ds_read_b128 v[134:137], v97
	ds_read_b128 v[138:141], v88 offset:49152
	ds_read_b128 v[142:145], v96
	ds_read_b128 v[154:157], v88 offset:53248
	s_waitcnt lgkmcnt(1)
	v_mfma_f32_32x32x16_bf16 v[48:63], v[134:137], v[138:141], v[48:63]
	v_mfma_f32_32x32x16_bf16 v[32:47], v[142:145], v[138:141], v[32:47]
	s_and_b32 m0, s32, 7
	s_lshl_b32 m0, m0, 11
	s_add_i32 m0, m0, 0x8400
	s_nop 0
	global_load_lds_dwordx4 v[180:181], off
	s_waitcnt vmcnt(6)
	s_waitcnt lgkmcnt(0)
	s_barrier
	s_waitcnt lgkmcnt(0)
	v_mfma_f32_32x32x16_bf16 v[16:31], v[134:137], v[154:157], v[16:31]
	v_lshl_add_u64 v[158:159], v[66:67], 0, s[30:31]
	v_lshl_add_u64 v[160:161], v[68:69], 0, s[30:31]
	s_nop 0
	v_readfirstlane_b32 s33, v120
	s_nop 0
	v_lshl_add_u64 v[162:163], v[70:71], 0, s[30:31]
	s_nop 0
	v_mfma_f32_32x32x16_bf16 v[0:15], v[142:145], v[154:157], v[0:15]
	s_and_b32 m0, s32, 7
	s_lshl_b32 m0, m0, 12
	s_add_i32 m0, m0, 0xc000
	s_nop 0
	global_load_lds_dwordx4 v[158:159], off
	v_lshl_add_u64 v[164:165], v[72:73], 0, s[30:31]
	s_nop 0
	v_readfirstlane_b32 s36, v121
	s_nop 0
	v_lshl_add_u64 v[166:167], v[74:75], 0, s[30:31]
	s_nop 0
	v_readfirstlane_b32 s37, v122
	s_nop 0
	v_lshl_add_u64 v[168:169], v[76:77], 0, s[30:31]
	s_nop 0
	s_mov_b64 s[30:31], 0x400
	ds_read_b128 v[134:137], v98
	ds_read_b128 v[138:141], v100
	ds_read_b128 v[142:145], v99
	ds_read_b128 v[150:153], v101
	s_waitcnt lgkmcnt(1)
	v_mfma_f32_32x32x16_bf16 v[48:63], v[134:137], v[138:141], v[48:63]
	s_nop 0
	v_readfirstlane_b32 s0, v131
	v_readfirstlane_b32 s38, v123
	v_readfirstlane_b32 s39, v124
	v_mfma_f32_32x32x16_bf16 v[32:47], v[142:145], v[138:141], v[32:47]
	s_waitcnt lgkmcnt(0)
	v_mfma_f32_32x32x16_bf16 v[16:31], v[134:137], v[150:153], v[16:31]
	s_and_b32 m0, s32, 7
	s_lshl_b32 m0, m0, 12
	s_add_i32 m0, m0, 0xc400
	s_nop 0
	global_load_lds_dwordx4 v[160:161], off
	v_mfma_f32_32x32x16_bf16 v[0:15], v[142:145], v[150:153], v[0:15]
	ds_read_b128 v[134:137], v103
	ds_read_b128 v[138:141], v104
	ds_read_b128 v[142:145], v102
	ds_read_b128 v[154:157], v105
	s_waitcnt lgkmcnt(1)
	v_mfma_f32_32x32x16_bf16 v[48:63], v[134:137], v[138:141], v[48:63]
	v_mfma_f32_32x32x16_bf16 v[32:47], v[142:145], v[138:141], v[32:47]
	s_and_b32 m0, s32, 7
	s_lshl_b32 m0, m0, 12
	s_add_i32 m0, m0, 0xc800
	s_nop 0
	global_load_lds_dwordx4 v[162:163], off
	s_waitcnt lgkmcnt(0)
	v_mfma_f32_32x32x16_bf16 v[16:31], v[134:137], v[154:157], v[16:31]
	v_mfma_f32_32x32x16_bf16 v[0:15], v[142:145], v[154:157], v[0:15]
	ds_read_b128 v[134:137], v107
	ds_read_b128 v[138:141], v108
	ds_read_b128 v[142:145], v106
	ds_read_b128 v[150:153], v109
	s_waitcnt lgkmcnt(1)
	v_mfma_f32_32x32x16_bf16 v[48:63], v[134:137], v[138:141], v[48:63]
	s_and_b32 m0, s32, 7
	s_lshl_b32 m0, m0, 12
	s_add_i32 m0, m0, 0xcc00
	s_nop 0
	global_load_lds_dwordx4 v[164:165], off
	v_mfma_f32_32x32x16_bf16 v[32:47], v[142:145], v[138:141], v[32:47]
	s_waitcnt lgkmcnt(0)
	v_mfma_f32_32x32x16_bf16 v[16:31], v[134:137], v[150:153], v[16:31]
	v_mfma_f32_32x32x16_bf16 v[0:15], v[142:145], v[150:153], v[0:15]
	s_and_b32 m0, s32, 7
	s_lshl_b32 m0, m0, 11
	s_add_i32 m0, m0, 0x14000
	s_nop 0
	global_load_lds_dwordx4 v[166:167], off
	ds_read_b128 v[134:137], v111
	ds_read_b128 v[138:141], v112
	ds_read_b128 v[142:145], v110
	ds_read_b128 v[154:157], v113
	s_waitcnt lgkmcnt(1)
	v_mfma_f32_32x32x16_bf16 v[48:63], v[134:137], v[138:141], v[48:63]
	v_mfma_f32_32x32x16_bf16 v[32:47], v[142:145], v[138:141], v[32:47]
	s_and_b32 m0, s32, 7
	s_lshl_b32 m0, m0, 11
	s_add_i32 m0, m0, 0x14400
	s_nop 0
	global_load_lds_dwordx4 v[168:169], off
	s_waitcnt vmcnt(6)
	s_waitcnt lgkmcnt(0)
	s_barrier
	s_waitcnt lgkmcnt(0)
	v_mfma_f32_32x32x16_bf16 v[16:31], v[134:137], v[154:157], v[16:31]
	v_lshl_add_u64 v[170:171], v[66:67], 0, s[30:31]
	v_lshl_add_u64 v[172:173], v[68:69], 0, s[30:31]
	s_nop 0
	v_readfirstlane_b32 s1, v130
	s_nop 0
	v_lshl_add_u64 v[174:175], v[70:71], 0, s[30:31]
	s_nop 0
	v_mfma_f32_32x32x16_bf16 v[0:15], v[142:145], v[154:157], v[0:15]
	s_and_b32 m0, s32, 7
	s_lshl_b32 m0, m0, 12
	s_add_i32 m0, m0, 0x18000
	s_nop 0
	global_load_lds_dwordx4 v[170:171], off
	v_lshl_add_u64 v[176:177], v[72:73], 0, s[30:31]
	s_nop 0
	v_readfirstlane_b32 s21, v128
	s_nop 0
	v_lshl_add_u64 v[178:179], v[74:75], 0, s[30:31]
	s_nop 0
	v_readfirstlane_b32 s22, v126
	s_nop 0
	v_lshl_add_u64 v[180:181], v[76:77], 0, s[30:31]
	s_nop 0
	s_mov_b64 s[30:31], 0x480
	ds_read_b128 v[134:137], v85 offset:32768
	ds_read_b128 v[138:141], v84
	ds_read_b128 v[142:145], v85 offset:36864
	ds_read_b128 v[150:153], v84 offset:4096
	s_waitcnt lgkmcnt(1)
	v_mfma_f32_32x32x16_bf16 v[48:63], v[134:137], v[138:141], v[48:63]
	s_nop 0
	v_lshl_add_u64 v[160:161], v[68:69], 0, s[30:31]
	v_readfirstlane_b32 s23, v129
	v_lshl_add_u64 v[166:167], v[74:75], 0, s[30:31]
	v_readfirstlane_b32 s28, v127
	v_lshl_add_u64 v[168:169], v[76:77], 0, s[30:31]
	v_mfma_f32_32x32x16_bf16 v[32:47], v[142:145], v[138:141], v[32:47]
	s_waitcnt lgkmcnt(0)
	v_mfma_f32_32x32x16_bf16 v[16:31], v[134:137], v[150:153], v[16:31]
	s_and_b32 m0, s32, 7
	s_lshl_b32 m0, m0, 12
	s_add_i32 m0, m0, 0x18400
	s_nop 0
	global_load_lds_dwordx4 v[172:173], off
	v_mfma_f32_32x32x16_bf16 v[0:15], v[142:145], v[150:153], v[0:15]
	ds_read_b128 v[134:137], v83 offset:32768
	ds_read_b128 v[138:141], v82
	ds_read_b128 v[142:145], v83 offset:36864
	ds_read_b128 v[154:157], v82 offset:4096
	s_waitcnt lgkmcnt(1)
	v_mfma_f32_32x32x16_bf16 v[48:63], v[134:137], v[138:141], v[48:63]
	v_mfma_f32_32x32x16_bf16 v[32:47], v[142:145], v[138:141], v[32:47]
	s_and_b32 m0, s32, 7
	s_lshl_b32 m0, m0, 12
	s_add_i32 m0, m0, 0x18800
	s_nop 0
	global_load_lds_dwordx4 v[174:175], off
	s_waitcnt lgkmcnt(0)
	v_mfma_f32_32x32x16_bf16 v[16:31], v[134:137], v[154:157], v[16:31]
	v_mfma_f32_32x32x16_bf16 v[0:15], v[142:145], v[154:157], v[0:15]
	ds_read_b128 v[134:137], v87 offset:32768
	ds_read_b128 v[138:141], v86
	ds_read_b128 v[142:145], v87 offset:36864
	ds_read_b128 v[150:153], v86 offset:4096
	s_waitcnt lgkmcnt(1)
	v_mfma_f32_32x32x16_bf16 v[48:63], v[134:137], v[138:141], v[48:63]
	s_and_b32 m0, s32, 7
	s_lshl_b32 m0, m0, 12
	s_add_i32 m0, m0, 0x18c00
	s_nop 0
	global_load_lds_dwordx4 v[176:177], off
	v_mfma_f32_32x32x16_bf16 v[32:47], v[142:145], v[138:141], v[32:47]
	s_waitcnt lgkmcnt(0)
	v_mfma_f32_32x32x16_bf16 v[16:31], v[134:137], v[150:153], v[16:31]
	v_mfma_f32_32x32x16_bf16 v[0:15], v[142:145], v[150:153], v[0:15]
	s_and_b32 m0, s32, 7
	s_lshl_b32 m0, m0, 11
	s_add_i32 m0, m0, 0x20000
	s_nop 0
	global_load_lds_dwordx4 v[178:179], off
	ds_read_b128 v[134:137], v89 offset:32768
	ds_read_b128 v[138:141], v88
	ds_read_b128 v[142:145], v89 offset:36864
	ds_read_b128 v[154:157], v88 offset:4096
	s_waitcnt lgkmcnt(1)
	v_mfma_f32_32x32x16_bf16 v[48:63], v[134:137], v[138:141], v[48:63]
	v_mfma_f32_32x32x16_bf16 v[32:47], v[142:145], v[138:141], v[32:47]
	s_and_b32 m0, s32, 7
	s_lshl_b32 m0, m0, 11
	s_add_i32 m0, m0, 0x20400
	s_nop 0
	global_load_lds_dwordx4 v[180:181], off
	s_waitcnt vmcnt(6)
	s_waitcnt lgkmcnt(0)
	s_barrier
	s_waitcnt lgkmcnt(0)
	v_mfma_f32_32x32x16_bf16 v[16:31], v[134:137], v[154:157], v[16:31]
	v_lshl_add_u64 v[158:159], v[66:67], 0, s[30:31]
	v_lshl_add_u64 v[162:163], v[70:71], 0, s[30:31]
	v_mfma_f32_32x32x16_bf16 v[0:15], v[142:145], v[154:157], v[0:15]
	s_and_b32 m0, s32, 7
	s_lshl_b32 m0, m0, 12
	s_add_i32 m0, m0, 0x0
	s_nop 0
	global_load_lds_dwordx4 v[158:159], off
	v_lshl_add_u64 v[164:165], v[72:73], 0, s[30:31]
	s_mov_b64 s[30:31], 0x500
	v_lshl_add_u64 v[174:175], v[70:71], 0, s[30:31]
	ds_read_b128 v[126:129], v91
	ds_read_b128 v[134:137], v84 offset:49152
	ds_read_b128 v[138:141], v90
	ds_read_b128 v[150:153], v84 offset:53248
	s_waitcnt lgkmcnt(1)
	v_mfma_f32_32x32x16_bf16 v[48:63], v[126:129], v[134:137], v[48:63]
	v_mfma_f32_32x32x16_bf16 v[32:47], v[138:141], v[134:137], v[32:47]
	s_waitcnt lgkmcnt(0)
	v_mfma_f32_32x32x16_bf16 v[16:31], v[126:129], v[150:153], v[16:31]
	s_and_b32 m0, s32, 7
	s_lshl_b32 m0, m0, 12
	s_add_i32 m0, m0, 0x400
	s_nop 0
	global_load_lds_dwordx4 v[160:161], off
	v_mfma_f32_32x32x16_bf16 v[0:15], v[138:141], v[150:153], v[0:15]
	ds_read_b128 v[126:129], v94
	ds_read_b128 v[134:137], v82 offset:49152
	ds_read_b128 v[138:141], v92
	ds_read_b128 v[154:157], v82 offset:53248
	s_waitcnt lgkmcnt(1)
	v_mfma_f32_32x32x16_bf16 v[48:63], v[126:129], v[134:137], v[48:63]
	v_mfma_f32_32x32x16_bf16 v[32:47], v[138:141], v[134:137], v[32:47]
	s_and_b32 m0, s32, 7
	s_lshl_b32 m0, m0, 12
	s_add_i32 m0, m0, 0x800
	s_nop 0
	global_load_lds_dwordx4 v[162:163], off
	s_waitcnt lgkmcnt(0)
	v_mfma_f32_32x32x16_bf16 v[16:31], v[126:129], v[154:157], v[16:31]
	v_mfma_f32_32x32x16_bf16 v[0:15], v[138:141], v[154:157], v[0:15]
	ds_read_b128 v[126:129], v95
	ds_read_b128 v[134:137], v86 offset:49152
	ds_read_b128 v[138:141], v93
	ds_read_b128 v[150:153], v86 offset:53248
	s_waitcnt lgkmcnt(1)
	v_mfma_f32_32x32x16_bf16 v[48:63], v[126:129], v[134:137], v[48:63]
	s_and_b32 m0, s32, 7
	s_lshl_b32 m0, m0, 12
	s_add_i32 m0, m0, 0xc00
	s_nop 0
	global_load_lds_dwordx4 v[164:165], off
	v_mfma_f32_32x32x16_bf16 v[32:47], v[138:141], v[134:137], v[32:47]
	s_waitcnt lgkmcnt(0)
	v_mfma_f32_32x32x16_bf16 v[16:31], v[126:129], v[150:153], v[16:31]
	v_mfma_f32_32x32x16_bf16 v[0:15], v[138:141], v[150:153], v[0:15]
	s_and_b32 m0, s32, 7
	s_lshl_b32 m0, m0, 11
	s_add_i32 m0, m0, 0x8000
	s_nop 0
	global_load_lds_dwordx4 v[166:167], off
	ds_read_b128 v[126:129], v97
	ds_read_b128 v[134:137], v88 offset:49152
	ds_read_b128 v[138:141], v96
	ds_read_b128 v[154:157], v88 offset:53248
	s_waitcnt lgkmcnt(1)
	v_mfma_f32_32x32x16_bf16 v[48:63], v[126:129], v[134:137], v[48:63]
	v_mfma_f32_32x32x16_bf16 v[32:47], v[138:141], v[134:137], v[32:47]
	s_and_b32 m0, s32, 7
	s_lshl_b32 m0, m0, 11
	s_add_i32 m0, m0, 0x8400
	s_nop 0
	global_load_lds_dwordx4 v[168:169], off
	s_waitcnt vmcnt(6)
	s_waitcnt lgkmcnt(0)
	s_barrier
	s_waitcnt lgkmcnt(0)
	v_mfma_f32_32x32x16_bf16 v[16:31], v[126:129], v[154:157], v[16:31]
	v_lshl_add_u64 v[170:171], v[66:67], 0, s[30:31]
	v_lshl_add_u64 v[172:173], v[68:69], 0, s[30:31]
	v_mfma_f32_32x32x16_bf16 v[0:15], v[138:141], v[154:157], v[0:15]
	s_and_b32 m0, s32, 7
	s_lshl_b32 m0, m0, 12
	s_add_i32 m0, m0, 0xc000
	s_nop 0
	global_load_lds_dwordx4 v[170:171], off
	v_lshl_add_u64 v[176:177], v[72:73], 0, s[30:31]
	v_lshl_add_u64 v[178:179], v[74:75], 0, s[30:31]
	v_lshl_add_u64 v[180:181], v[76:77], 0, s[30:31]
	s_mov_b64 s[30:31], 0x580
	ds_read_b128 v[120:123], v98
	ds_read_b128 v[124:127], v100
	ds_read_b128 v[128:131], v99
	ds_read_b128 v[150:153], v101
	s_waitcnt lgkmcnt(1)
	v_mfma_f32_32x32x16_bf16 v[48:63], v[120:123], v[124:127], v[48:63]
	v_lshl_add_u64 v[162:163], v[70:71], 0, s[30:31]
	v_mfma_f32_32x32x16_bf16 v[32:47], v[128:131], v[124:127], v[32:47]
	s_waitcnt lgkmcnt(0)
	v_mfma_f32_32x32x16_bf16 v[16:31], v[120:123], v[150:153], v[16:31]
	s_and_b32 m0, s32, 7
	s_lshl_b32 m0, m0, 12
	s_add_i32 m0, m0, 0xc400
	s_nop 0
	global_load_lds_dwordx4 v[172:173], off
	v_mfma_f32_32x32x16_bf16 v[0:15], v[128:131], v[150:153], v[0:15]
	ds_read_b128 v[120:123], v103
	ds_read_b128 v[124:127], v104
	ds_read_b128 v[128:131], v102
	ds_read_b128 v[154:157], v105
	s_waitcnt lgkmcnt(1)
	v_mfma_f32_32x32x16_bf16 v[48:63], v[120:123], v[124:127], v[48:63]
	v_mfma_f32_32x32x16_bf16 v[32:47], v[128:131], v[124:127], v[32:47]
	s_and_b32 m0, s32, 7
	s_lshl_b32 m0, m0, 12
	s_add_i32 m0, m0, 0xc800
	s_nop 0
	global_load_lds_dwordx4 v[174:175], off
	s_waitcnt lgkmcnt(0)
	v_mfma_f32_32x32x16_bf16 v[16:31], v[120:123], v[154:157], v[16:31]
	v_mfma_f32_32x32x16_bf16 v[0:15], v[128:131], v[154:157], v[0:15]
	ds_read_b128 v[120:123], v107
	ds_read_b128 v[124:127], v108
	ds_read_b128 v[128:131], v106
	ds_read_b128 v[150:153], v109
	s_waitcnt lgkmcnt(1)
	v_mfma_f32_32x32x16_bf16 v[48:63], v[120:123], v[124:127], v[48:63]
	s_and_b32 m0, s32, 7
	s_lshl_b32 m0, m0, 12
	s_add_i32 m0, m0, 0xcc00
	s_nop 0
	global_load_lds_dwordx4 v[176:177], off
	v_mfma_f32_32x32x16_bf16 v[32:47], v[128:131], v[124:127], v[32:47]
	s_waitcnt lgkmcnt(0)
	v_mfma_f32_32x32x16_bf16 v[16:31], v[120:123], v[150:153], v[16:31]
	v_mfma_f32_32x32x16_bf16 v[0:15], v[128:131], v[150:153], v[0:15]
	s_and_b32 m0, s32, 7
	s_lshl_b32 m0, m0, 11
	s_add_i32 m0, m0, 0x14000
	s_nop 0
	global_load_lds_dwordx4 v[178:179], off
	ds_read_b128 v[120:123], v111
	ds_read_b128 v[124:127], v112
	ds_read_b128 v[128:131], v110
	ds_read_b128 v[154:157], v113
	s_waitcnt lgkmcnt(1)
	v_mfma_f32_32x32x16_bf16 v[48:63], v[120:123], v[124:127], v[48:63]
	v_mfma_f32_32x32x16_bf16 v[32:47], v[128:131], v[124:127], v[32:47]
	s_and_b32 m0, s32, 7
	s_lshl_b32 m0, m0, 11
	s_add_i32 m0, m0, 0x14400
	s_nop 0
	global_load_lds_dwordx4 v[180:181], off
	s_waitcnt vmcnt(6)
	s_waitcnt lgkmcnt(0)
	s_barrier
	s_waitcnt lgkmcnt(0)
	v_mfma_f32_32x32x16_bf16 v[16:31], v[120:123], v[154:157], v[16:31]
	v_lshl_add_u64 v[158:159], v[66:67], 0, s[30:31]
	v_lshl_add_u64 v[160:161], v[68:69], 0, s[30:31]
	v_mfma_f32_32x32x16_bf16 v[0:15], v[128:131], v[154:157], v[0:15]
	s_and_b32 m0, s32, 7
	s_lshl_b32 m0, m0, 12
	s_add_i32 m0, m0, 0x18000
	s_nop 0
	global_load_lds_dwordx4 v[158:159], off
	v_lshl_add_u64 v[164:165], v[72:73], 0, s[30:31]
	v_lshl_add_u64 v[166:167], v[74:75], 0, s[30:31]
	v_lshl_add_u64 v[168:169], v[76:77], 0, s[30:31]
	s_mov_b64 s[30:31], 0x600
	ds_read_b128 v[114:117], v85 offset:32768
	ds_read_b128 v[118:121], v84
	ds_read_b128 v[122:125], v85 offset:36864
	ds_read_b128 v[150:153], v84 offset:4096
	s_waitcnt lgkmcnt(1)
	v_mfma_f32_32x32x16_bf16 v[48:63], v[114:117], v[118:121], v[48:63]
	v_mfma_f32_32x32x16_bf16 v[32:47], v[122:125], v[118:121], v[32:47]
	s_waitcnt lgkmcnt(0)
	v_mfma_f32_32x32x16_bf16 v[16:31], v[114:117], v[150:153], v[16:31]
	s_and_b32 m0, s32, 7
	s_lshl_b32 m0, m0, 12
	s_add_i32 m0, m0, 0x18400
	s_nop 0
	global_load_lds_dwordx4 v[160:161], off
	v_mfma_f32_32x32x16_bf16 v[0:15], v[122:125], v[150:153], v[0:15]
	ds_read_b128 v[114:117], v83 offset:32768
	ds_read_b128 v[118:121], v82
	ds_read_b128 v[122:125], v83 offset:36864
	ds_read_b128 v[154:157], v82 offset:4096
	s_waitcnt lgkmcnt(1)
	v_mfma_f32_32x32x16_bf16 v[48:63], v[114:117], v[118:121], v[48:63]
	v_mfma_f32_32x32x16_bf16 v[32:47], v[122:125], v[118:121], v[32:47]
	s_and_b32 m0, s32, 7
	s_lshl_b32 m0, m0, 12
	s_add_i32 m0, m0, 0x18800
	s_nop 0
	global_load_lds_dwordx4 v[162:163], off
	s_waitcnt lgkmcnt(0)
	v_mfma_f32_32x32x16_bf16 v[16:31], v[114:117], v[154:157], v[16:31]
	v_mfma_f32_32x32x16_bf16 v[0:15], v[122:125], v[154:157], v[0:15]
	ds_read_b128 v[114:117], v87 offset:32768
	ds_read_b128 v[118:121], v86
	ds_read_b128 v[122:125], v87 offset:36864
	ds_read_b128 v[150:153], v86 offset:4096
	s_waitcnt lgkmcnt(1)
	v_mfma_f32_32x32x16_bf16 v[48:63], v[114:117], v[118:121], v[48:63]
	s_and_b32 m0, s32, 7
	s_lshl_b32 m0, m0, 12
	s_add_i32 m0, m0, 0x18c00
	s_nop 0
	global_load_lds_dwordx4 v[164:165], off
	v_mfma_f32_32x32x16_bf16 v[32:47], v[122:125], v[118:121], v[32:47]
	s_waitcnt lgkmcnt(0)
	v_mfma_f32_32x32x16_bf16 v[16:31], v[114:117], v[150:153], v[16:31]
	v_mfma_f32_32x32x16_bf16 v[0:15], v[122:125], v[150:153], v[0:15]
	s_and_b32 m0, s32, 7
	s_lshl_b32 m0, m0, 11
	s_add_i32 m0, m0, 0x20000
	s_nop 0
	global_load_lds_dwordx4 v[166:167], off
	ds_read_b128 v[114:117], v89 offset:32768
	ds_read_b128 v[118:121], v88
	ds_read_b128 v[122:125], v89 offset:36864
	ds_read_b128 v[154:157], v88 offset:4096
	s_waitcnt lgkmcnt(1)
	v_mfma_f32_32x32x16_bf16 v[48:63], v[114:117], v[118:121], v[48:63]
	v_mfma_f32_32x32x16_bf16 v[32:47], v[122:125], v[118:121], v[32:47]
	s_and_b32 m0, s32, 7
	s_lshl_b32 m0, m0, 11
	s_add_i32 m0, m0, 0x20400
	s_nop 0
	global_load_lds_dwordx4 v[168:169], off
	s_waitcnt vmcnt(6)
	s_waitcnt lgkmcnt(0)
	s_barrier
	s_waitcnt lgkmcnt(0)
	v_mfma_f32_32x32x16_bf16 v[16:31], v[114:117], v[154:157], v[16:31]
	v_lshl_add_u64 v[170:171], v[66:67], 0, s[30:31]
	v_lshl_add_u64 v[172:173], v[68:69], 0, s[30:31]
	v_lshl_add_u64 v[174:175], v[70:71], 0, s[30:31]
	v_mfma_f32_32x32x16_bf16 v[0:15], v[122:125], v[154:157], v[0:15]
	s_and_b32 m0, s32, 7
	s_lshl_b32 m0, m0, 12
	s_add_i32 m0, m0, 0x0
	s_nop 0
	global_load_lds_dwordx4 v[170:171], off
	v_lshl_add_u64 v[176:177], v[72:73], 0, s[30:31]
	v_lshl_add_u64 v[178:179], v[74:75], 0, s[30:31]
	v_lshl_add_u64 v[180:181], v[76:77], 0, s[30:31]
	s_mov_b64 s[30:31], 0x680
	ds_read_b128 v[114:117], v91
	ds_read_b128 v[118:121], v84 offset:49152
	ds_read_b128 v[122:125], v90
	ds_read_b128 v[150:153], v84 offset:53248
	s_waitcnt lgkmcnt(1)
	v_mfma_f32_32x32x16_bf16 v[48:63], v[114:117], v[118:121], v[48:63]
	v_mfma_f32_32x32x16_bf16 v[32:47], v[122:125], v[118:121], v[32:47]
	s_waitcnt lgkmcnt(0)
	v_mfma_f32_32x32x16_bf16 v[16:31], v[114:117], v[150:153], v[16:31]
	s_and_b32 m0, s32, 7
	s_lshl_b32 m0, m0, 12
	s_add_i32 m0, m0, 0x400
	s_nop 0
	global_load_lds_dwordx4 v[172:173], off
	v_mfma_f32_32x32x16_bf16 v[0:15], v[122:125], v[150:153], v[0:15]
	ds_read_b128 v[114:117], v94
	ds_read_b128 v[118:121], v82 offset:49152
	ds_read_b128 v[122:125], v92
	ds_read_b128 v[154:157], v82 offset:53248
	s_waitcnt lgkmcnt(1)
	v_mfma_f32_32x32x16_bf16 v[48:63], v[114:117], v[118:121], v[48:63]
	v_mfma_f32_32x32x16_bf16 v[32:47], v[122:125], v[118:121], v[32:47]
	s_and_b32 m0, s32, 7
	s_lshl_b32 m0, m0, 12
	s_add_i32 m0, m0, 0x800
	s_nop 0
	global_load_lds_dwordx4 v[174:175], off
	s_waitcnt lgkmcnt(0)
	v_mfma_f32_32x32x16_bf16 v[16:31], v[114:117], v[154:157], v[16:31]
	v_mfma_f32_32x32x16_bf16 v[0:15], v[122:125], v[154:157], v[0:15]
	ds_read_b128 v[114:117], v95
	ds_read_b128 v[118:121], v86 offset:49152
	ds_read_b128 v[122:125], v93
	ds_read_b128 v[150:153], v86 offset:53248
	s_waitcnt lgkmcnt(1)
	v_mfma_f32_32x32x16_bf16 v[48:63], v[114:117], v[118:121], v[48:63]
	s_and_b32 m0, s32, 7
	s_lshl_b32 m0, m0, 12
	s_add_i32 m0, m0, 0xc00
	s_nop 0
	global_load_lds_dwordx4 v[176:177], off
	v_mfma_f32_32x32x16_bf16 v[32:47], v[122:125], v[118:121], v[32:47]
	s_waitcnt lgkmcnt(0)
	v_mfma_f32_32x32x16_bf16 v[16:31], v[114:117], v[150:153], v[16:31]
	v_mfma_f32_32x32x16_bf16 v[0:15], v[122:125], v[150:153], v[0:15]
	s_and_b32 m0, s32, 7
	s_lshl_b32 m0, m0, 11
	s_add_i32 m0, m0, 0x8000
	s_nop 0
	global_load_lds_dwordx4 v[178:179], off
	ds_read_b128 v[114:117], v97
	ds_read_b128 v[118:121], v88 offset:49152
	ds_read_b128 v[122:125], v96
	ds_read_b128 v[154:157], v88 offset:53248
	s_waitcnt lgkmcnt(1)
	v_mfma_f32_32x32x16_bf16 v[48:63], v[114:117], v[118:121], v[48:63]
	v_mfma_f32_32x32x16_bf16 v[32:47], v[122:125], v[118:121], v[32:47]
	s_and_b32 m0, s32, 7
	s_lshl_b32 m0, m0, 11
	s_add_i32 m0, m0, 0x8400
	s_nop 0
	global_load_lds_dwordx4 v[180:181], off
	s_waitcnt vmcnt(6)
	s_waitcnt lgkmcnt(0)
	s_barrier
	s_waitcnt lgkmcnt(0)
	v_mfma_f32_32x32x16_bf16 v[16:31], v[114:117], v[154:157], v[16:31]
	v_lshl_add_u64 v[158:159], v[66:67], 0, s[30:31]
	v_lshl_add_u64 v[160:161], v[68:69], 0, s[30:31]
	v_lshl_add_u64 v[162:163], v[70:71], 0, s[30:31]
	v_mfma_f32_32x32x16_bf16 v[0:15], v[122:125], v[154:157], v[0:15]
	s_and_b32 m0, s32, 7
	s_lshl_b32 m0, m0, 12
	s_add_i32 m0, m0, 0xc000
	s_nop 0
	global_load_lds_dwordx4 v[158:159], off
	v_lshl_add_u64 v[164:165], v[72:73], 0, s[30:31]
	v_lshl_add_u64 v[166:167], v[74:75], 0, s[30:31]
	v_lshl_add_u64 v[168:169], v[76:77], 0, s[30:31]
	s_mov_b64 s[30:31], 0x700
	ds_read_b128 v[114:117], v98
	ds_read_b128 v[118:121], v100
	ds_read_b128 v[122:125], v99
	ds_read_b128 v[150:153], v101
	s_waitcnt lgkmcnt(1)
	v_mfma_f32_32x32x16_bf16 v[48:63], v[114:117], v[118:121], v[48:63]
	v_mfma_f32_32x32x16_bf16 v[32:47], v[122:125], v[118:121], v[32:47]
	s_waitcnt lgkmcnt(0)
	v_mfma_f32_32x32x16_bf16 v[16:31], v[114:117], v[150:153], v[16:31]
	s_and_b32 m0, s32, 7
	s_lshl_b32 m0, m0, 12
	s_add_i32 m0, m0, 0xc400
	s_nop 0
	global_load_lds_dwordx4 v[160:161], off
	v_mfma_f32_32x32x16_bf16 v[0:15], v[122:125], v[150:153], v[0:15]
	ds_read_b128 v[114:117], v103
	ds_read_b128 v[118:121], v104
	ds_read_b128 v[122:125], v102
	ds_read_b128 v[154:157], v105
	s_waitcnt lgkmcnt(1)
	v_mfma_f32_32x32x16_bf16 v[48:63], v[114:117], v[118:121], v[48:63]
	v_mfma_f32_32x32x16_bf16 v[32:47], v[122:125], v[118:121], v[32:47]
	s_and_b32 m0, s32, 7
	s_lshl_b32 m0, m0, 12
	s_add_i32 m0, m0, 0xc800
	s_nop 0
	global_load_lds_dwordx4 v[162:163], off
	s_waitcnt lgkmcnt(0)
	v_mfma_f32_32x32x16_bf16 v[16:31], v[114:117], v[154:157], v[16:31]
	v_mfma_f32_32x32x16_bf16 v[0:15], v[122:125], v[154:157], v[0:15]
	ds_read_b128 v[114:117], v107
	ds_read_b128 v[118:121], v108
	ds_read_b128 v[122:125], v106
	ds_read_b128 v[150:153], v109
	s_waitcnt lgkmcnt(1)
	v_mfma_f32_32x32x16_bf16 v[48:63], v[114:117], v[118:121], v[48:63]
	s_and_b32 m0, s32, 7
	s_lshl_b32 m0, m0, 12
	s_add_i32 m0, m0, 0xcc00
	s_nop 0
	global_load_lds_dwordx4 v[164:165], off
	v_mfma_f32_32x32x16_bf16 v[32:47], v[122:125], v[118:121], v[32:47]
	s_waitcnt lgkmcnt(0)
	v_mfma_f32_32x32x16_bf16 v[16:31], v[114:117], v[150:153], v[16:31]
	v_mfma_f32_32x32x16_bf16 v[0:15], v[122:125], v[150:153], v[0:15]
	s_and_b32 m0, s32, 7
	s_lshl_b32 m0, m0, 11
	s_add_i32 m0, m0, 0x14000
	s_nop 0
	global_load_lds_dwordx4 v[166:167], off
	ds_read_b128 v[114:117], v111
	ds_read_b128 v[118:121], v112
	ds_read_b128 v[122:125], v110
	ds_read_b128 v[154:157], v113
	s_waitcnt lgkmcnt(1)
	v_mfma_f32_32x32x16_bf16 v[48:63], v[114:117], v[118:121], v[48:63]
	v_mfma_f32_32x32x16_bf16 v[32:47], v[122:125], v[118:121], v[32:47]
	s_and_b32 m0, s32, 7
	s_lshl_b32 m0, m0, 11
	s_add_i32 m0, m0, 0x14400
	s_nop 0
	global_load_lds_dwordx4 v[168:169], off
	s_waitcnt vmcnt(6)
	s_waitcnt lgkmcnt(0)
	s_barrier
	s_waitcnt lgkmcnt(0)
	v_mfma_f32_32x32x16_bf16 v[16:31], v[114:117], v[154:157], v[16:31]
	v_lshl_add_u64 v[170:171], v[66:67], 0, s[30:31]
	v_lshl_add_u64 v[172:173], v[68:69], 0, s[30:31]
	v_lshl_add_u64 v[174:175], v[70:71], 0, s[30:31]
	v_mfma_f32_32x32x16_bf16 v[0:15], v[122:125], v[154:157], v[0:15]
	s_and_b32 m0, s32, 7
	s_lshl_b32 m0, m0, 12
	s_add_i32 m0, m0, 0x18000
	s_nop 0
	global_load_lds_dwordx4 v[170:171], off
	v_lshl_add_u64 v[176:177], v[72:73], 0, s[30:31]
	v_lshl_add_u64 v[178:179], v[74:75], 0, s[30:31]
	v_lshl_add_u64 v[180:181], v[76:77], 0, s[30:31]
	s_mov_b64 s[30:31], 0x780
	ds_read_b128 v[114:117], v85 offset:32768
	ds_read_b128 v[118:121], v84
	ds_read_b128 v[122:125], v85 offset:36864
	ds_read_b128 v[150:153], v84 offset:4096
	s_waitcnt lgkmcnt(1)
	v_mfma_f32_32x32x16_bf16 v[48:63], v[114:117], v[118:121], v[48:63]
	v_lshl_add_u64 v[158:159], v[66:67], 0, s[30:31]
	v_mfma_f32_32x32x16_bf16 v[32:47], v[122:125], v[118:121], v[32:47]
	s_waitcnt lgkmcnt(0)
	v_mfma_f32_32x32x16_bf16 v[16:31], v[114:117], v[150:153], v[16:31]
	s_and_b32 m0, s32, 7
	s_lshl_b32 m0, m0, 12
	s_add_i32 m0, m0, 0x18400
	s_nop 0
	global_load_lds_dwordx4 v[172:173], off
	v_mfma_f32_32x32x16_bf16 v[0:15], v[122:125], v[150:153], v[0:15]
	ds_read_b128 v[114:117], v83 offset:32768
	ds_read_b128 v[118:121], v82
	ds_read_b128 v[122:125], v83 offset:36864
	ds_read_b128 v[154:157], v82 offset:4096
	s_waitcnt lgkmcnt(1)
	v_mfma_f32_32x32x16_bf16 v[48:63], v[114:117], v[118:121], v[48:63]
	v_mfma_f32_32x32x16_bf16 v[32:47], v[122:125], v[118:121], v[32:47]
	s_and_b32 m0, s32, 7
	s_lshl_b32 m0, m0, 12
	s_add_i32 m0, m0, 0x18800
	s_nop 0
	global_load_lds_dwordx4 v[174:175], off
	s_waitcnt lgkmcnt(0)
	v_mfma_f32_32x32x16_bf16 v[16:31], v[114:117], v[154:157], v[16:31]
	v_mfma_f32_32x32x16_bf16 v[0:15], v[122:125], v[154:157], v[0:15]
	ds_read_b128 v[114:117], v87 offset:32768
	ds_read_b128 v[118:121], v86
	ds_read_b128 v[122:125], v87 offset:36864
	ds_read_b128 v[150:153], v86 offset:4096
	s_waitcnt lgkmcnt(1)
	v_mfma_f32_32x32x16_bf16 v[48:63], v[114:117], v[118:121], v[48:63]
	s_and_b32 m0, s32, 7
	s_lshl_b32 m0, m0, 12
	s_add_i32 m0, m0, 0x18c00
	s_nop 0
	global_load_lds_dwordx4 v[176:177], off
	v_mfma_f32_32x32x16_bf16 v[32:47], v[122:125], v[118:121], v[32:47]
	s_waitcnt lgkmcnt(0)
	v_mfma_f32_32x32x16_bf16 v[16:31], v[114:117], v[150:153], v[16:31]
	v_mfma_f32_32x32x16_bf16 v[0:15], v[122:125], v[150:153], v[0:15]
	s_and_b32 m0, s32, 7
	s_lshl_b32 m0, m0, 11
	s_add_i32 m0, m0, 0x20000
	s_nop 0
	global_load_lds_dwordx4 v[178:179], off
	ds_read_b128 v[114:117], v89 offset:32768
	ds_read_b128 v[118:121], v88
	ds_read_b128 v[122:125], v89 offset:36864
	ds_read_b128 v[154:157], v88 offset:4096
	s_waitcnt lgkmcnt(1)
	v_mfma_f32_32x32x16_bf16 v[48:63], v[114:117], v[118:121], v[48:63]
	v_mfma_f32_32x32x16_bf16 v[32:47], v[122:125], v[118:121], v[32:47]
	s_and_b32 m0, s32, 7
	s_lshl_b32 m0, m0, 11
	s_add_i32 m0, m0, 0x20400
	s_nop 0
	global_load_lds_dwordx4 v[180:181], off
	s_waitcnt vmcnt(6)
	s_waitcnt lgkmcnt(0)
	s_barrier
	v_lshl_add_u64 v[160:161], v[68:69], 0, s[30:31]
	s_waitcnt lgkmcnt(0)
	v_mfma_f32_32x32x16_bf16 v[16:31], v[114:117], v[154:157], v[16:31]
	v_lshl_add_u64 v[162:163], v[70:71], 0, s[30:31]
	v_lshl_add_u64 v[164:165], v[72:73], 0, s[30:31]
	v_mfma_f32_32x32x16_bf16 v[0:15], v[122:125], v[154:157], v[0:15]
	s_and_b32 m0, s32, 7
	s_lshl_b32 m0, m0, 12
	s_add_i32 m0, m0, 0x0
	s_nop 0
	global_load_lds_dwordx4 v[158:159], off
	v_lshl_add_u64 v[166:167], v[74:75], 0, s[30:31]
	v_lshl_add_u64 v[168:169], v[76:77], 0, s[30:31]
	ds_read_b128 v[66:69], v91
	ds_read_b128 v[70:73], v84 offset:49152
	ds_read_b128 v[74:77], v90
	ds_read_b128 v[150:153], v84 offset:53248
	s_waitcnt lgkmcnt(1)
	v_mfma_f32_32x32x16_bf16 v[48:63], v[66:69], v[70:73], v[48:63]
	v_mfma_f32_32x32x16_bf16 v[32:47], v[74:77], v[70:73], v[32:47]
	s_waitcnt lgkmcnt(0)
	v_mfma_f32_32x32x16_bf16 v[16:31], v[66:69], v[150:153], v[16:31]
	s_and_b32 m0, s32, 7
	s_lshl_b32 m0, m0, 12
	s_add_i32 m0, m0, 0x400
	s_nop 0
	global_load_lds_dwordx4 v[160:161], off
	v_mfma_f32_32x32x16_bf16 v[0:15], v[74:77], v[150:153], v[0:15]
	ds_read_b128 v[66:69], v94
	ds_read_b128 v[70:73], v82 offset:49152
	ds_read_b128 v[74:77], v92
	ds_read_b128 v[154:157], v82 offset:53248
	s_waitcnt lgkmcnt(1)
	v_mfma_f32_32x32x16_bf16 v[48:63], v[66:69], v[70:73], v[48:63]
	v_mfma_f32_32x32x16_bf16 v[32:47], v[74:77], v[70:73], v[32:47]
	s_and_b32 m0, s32, 7
	s_lshl_b32 m0, m0, 12
	s_add_i32 m0, m0, 0x800
	s_nop 0
	global_load_lds_dwordx4 v[162:163], off
	s_waitcnt lgkmcnt(0)
	v_mfma_f32_32x32x16_bf16 v[16:31], v[66:69], v[154:157], v[16:31]
	v_mfma_f32_32x32x16_bf16 v[0:15], v[74:77], v[154:157], v[0:15]
	ds_read_b128 v[66:69], v95
	ds_read_b128 v[70:73], v86 offset:49152
	ds_read_b128 v[74:77], v93
	ds_read_b128 v[150:153], v86 offset:53248
	s_waitcnt lgkmcnt(1)
	v_mfma_f32_32x32x16_bf16 v[48:63], v[66:69], v[70:73], v[48:63]
	s_and_b32 m0, s32, 7
	s_lshl_b32 m0, m0, 12
	s_add_i32 m0, m0, 0xc00
	s_nop 0
	global_load_lds_dwordx4 v[164:165], off
	v_mfma_f32_32x32x16_bf16 v[32:47], v[74:77], v[70:73], v[32:47]
	s_waitcnt lgkmcnt(0)
	v_mfma_f32_32x32x16_bf16 v[16:31], v[66:69], v[150:153], v[16:31]
	v_mfma_f32_32x32x16_bf16 v[0:15], v[74:77], v[150:153], v[0:15]
	s_and_b32 m0, s32, 7
	s_lshl_b32 m0, m0, 11
	s_add_i32 m0, m0, 0x8000
	s_nop 0
	global_load_lds_dwordx4 v[166:167], off
	ds_read_b128 v[66:69], v97
	ds_read_b128 v[70:73], v88 offset:49152
	ds_read_b128 v[74:77], v96
	ds_read_b128 v[154:157], v88 offset:53248
	s_waitcnt lgkmcnt(1)
	v_mfma_f32_32x32x16_bf16 v[48:63], v[66:69], v[70:73], v[48:63]
	v_mfma_f32_32x32x16_bf16 v[32:47], v[74:77], v[70:73], v[32:47]
	s_and_b32 m0, s32, 7
	s_lshl_b32 m0, m0, 11
	s_add_i32 m0, m0, 0x8400
	s_nop 0
	global_load_lds_dwordx4 v[168:169], off
	s_waitcnt vmcnt(6)
	s_waitcnt lgkmcnt(0)
	s_barrier
	s_waitcnt lgkmcnt(0)
	v_mfma_f32_32x32x16_bf16 v[16:31], v[66:69], v[154:157], v[16:31]
	v_lshrrev_b32_e32 v183, 7, v133
	v_and_b32_e32 v184, 31, v133
	v_lshl_or_b32 v183, v183, 6, v184
	v_add_u32_e32 v183, s2, v183
	v_lshlrev_b32_e32 v183, 2, v183
	global_load_dword v184, v183, s[76:77]
	global_load_dword v185, v183, s[76:77] offset:128
	v_mfma_f32_32x32x16_bf16 v[0:15], v[74:77], v[154:157], v[0:15]
	ds_read_b128 v[66:69], v98
	ds_read_b128 v[70:73], v100
	ds_read_b128 v[74:77], v99
	ds_read_b128 v[150:153], v101
	s_waitcnt lgkmcnt(1)
	v_mfma_f32_32x32x16_bf16 v[48:63], v[66:69], v[70:73], v[48:63]
	v_mfma_f32_32x32x16_bf16 v[32:47], v[74:77], v[70:73], v[32:47]
	s_waitcnt lgkmcnt(0)
	v_mfma_f32_32x32x16_bf16 v[16:31], v[66:69], v[150:153], v[16:31]
	v_mfma_f32_32x32x16_bf16 v[0:15], v[74:77], v[150:153], v[0:15]
	ds_read_b128 v[66:69], v103
	ds_read_b128 v[70:73], v104
	ds_read_b128 v[74:77], v102
	ds_read_b128 v[154:157], v105
	s_waitcnt lgkmcnt(1)
	v_mfma_f32_32x32x16_bf16 v[48:63], v[66:69], v[70:73], v[48:63]
	v_mfma_f32_32x32x16_bf16 v[32:47], v[74:77], v[70:73], v[32:47]
	s_waitcnt lgkmcnt(0)
	v_mfma_f32_32x32x16_bf16 v[16:31], v[66:69], v[154:157], v[16:31]
	v_mfma_f32_32x32x16_bf16 v[0:15], v[74:77], v[154:157], v[0:15]
	ds_read_b128 v[66:69], v107
	ds_read_b128 v[70:73], v108
	ds_read_b128 v[74:77], v106
	ds_read_b128 v[150:153], v109
	s_waitcnt lgkmcnt(1)
	v_mfma_f32_32x32x16_bf16 v[48:63], v[66:69], v[70:73], v[48:63]
	v_mfma_f32_32x32x16_bf16 v[32:47], v[74:77], v[70:73], v[32:47]
	s_waitcnt lgkmcnt(0)
	v_mfma_f32_32x32x16_bf16 v[16:31], v[66:69], v[150:153], v[16:31]
	v_mfma_f32_32x32x16_bf16 v[0:15], v[74:77], v[150:153], v[0:15]
	ds_read_b128 v[66:69], v111
	ds_read_b128 v[70:73], v112
	ds_read_b128 v[74:77], v110
	ds_read_b128 v[154:157], v113
	s_waitcnt lgkmcnt(1)
	v_mfma_f32_32x32x16_bf16 v[48:63], v[66:69], v[70:73], v[48:63]
	v_mfma_f32_32x32x16_bf16 v[32:47], v[74:77], v[70:73], v[32:47]
	s_waitcnt vmcnt(0)
	s_waitcnt lgkmcnt(0)
	s_barrier
	s_waitcnt lgkmcnt(0)
	v_mfma_f32_32x32x16_bf16 v[16:31], v[66:69], v[154:157], v[16:31]
	v_mfma_f32_32x32x16_bf16 v[0:15], v[74:77], v[154:157], v[0:15]
	ds_read_b128 v[66:69], v85 offset:32768
	ds_read_b128 v[70:73], v84
	ds_read_b128 v[74:77], v85 offset:36864
	ds_read_b128 v[150:153], v84 offset:4096
	s_waitcnt lgkmcnt(1)
	v_mfma_f32_32x32x16_bf16 v[48:63], v[66:69], v[70:73], v[48:63]
	v_mfma_f32_32x32x16_bf16 v[32:47], v[74:77], v[70:73], v[32:47]
	s_waitcnt lgkmcnt(0)
	v_mfma_f32_32x32x16_bf16 v[16:31], v[66:69], v[150:153], v[16:31]
	v_mfma_f32_32x32x16_bf16 v[0:15], v[74:77], v[150:153], v[0:15]
	ds_read_b128 v[66:69], v83 offset:32768
	ds_read_b128 v[70:73], v82
	ds_read_b128 v[74:77], v83 offset:36864
	ds_read_b128 v[154:157], v82 offset:4096
	s_waitcnt lgkmcnt(1)
	v_mfma_f32_32x32x16_bf16 v[48:63], v[66:69], v[70:73], v[48:63]
	v_mfma_f32_32x32x16_bf16 v[32:47], v[74:77], v[70:73], v[32:47]
	s_waitcnt lgkmcnt(0)
	v_mfma_f32_32x32x16_bf16 v[16:31], v[66:69], v[154:157], v[16:31]
	v_mfma_f32_32x32x16_bf16 v[0:15], v[74:77], v[154:157], v[0:15]
	ds_read_b128 v[66:69], v87 offset:32768
	ds_read_b128 v[70:73], v86
	ds_read_b128 v[74:77], v87 offset:36864
	ds_read_b128 v[150:153], v86 offset:4096
	s_waitcnt lgkmcnt(1)
	v_mfma_f32_32x32x16_bf16 v[48:63], v[66:69], v[70:73], v[48:63]
	v_mfma_f32_32x32x16_bf16 v[32:47], v[74:77], v[70:73], v[32:47]
	s_waitcnt lgkmcnt(0)
	v_mfma_f32_32x32x16_bf16 v[16:31], v[66:69], v[150:153], v[16:31]
	v_mfma_f32_32x32x16_bf16 v[0:15], v[74:77], v[150:153], v[0:15]
	ds_read_b128 v[70:73], v89 offset:32768
	ds_read_b128 v[66:69], v88
	ds_read_b128 v[74:77], v89 offset:36864
	ds_read_b128 v[82:85], v88 offset:4096
	s_waitcnt lgkmcnt(0)
	s_barrier
	s_waitcnt lgkmcnt(0)
	v_mfma_f32_32x32x16_bf16 v[48:63], v[70:73], v[66:69], v[48:63]
	v_mfma_f32_32x32x16_bf16 v[32:47], v[74:77], v[66:69], v[32:47]
	v_lshl_or_b32 v69, v80, 6, v81
	v_add_u32_e32 v66, s2, v69
	v_cmp_gt_i32_e32 vcc, s69, v66
	v_ashrrev_i32_e32 v67, 31, v66
	v_mov_b32_e32 v68, 0
	v_mfma_f32_32x32x16_bf16 v[16:31], v[70:73], v[82:85], v[16:31]
	v_mov_b32_e32 v70, 0
	v_mfma_f32_32x32x16_bf16 v[0:15], v[74:77], v[82:85], v[0:15]
	s_and_saveexec_b64 s[0:1], vcc
	s_cbranch_execz .LBB0_749
	v_lshl_add_u64 v[70:71], v[66:67], 2, s[76:77]
	v_mov_b32_e32 v70, v184
	v_fmamk_f32 v70, v70, 0x3a800000, v188
	v_mul_f32_e32 v71, 0x4b800000, v70
	v_cmp_gt_f32_e32 vcc, s82, v70
	s_nop 1
	v_cndmask_b32_e32 v70, v70, v71, vcc
	v_rsq_f32_e32 v70, v70
	s_nop 0
	v_mul_f32_e32 v71, 0x45800000, v70
	v_cndmask_b32_e32 v70, v70, v71, vcc
